# g4 plus: last ds_read of a fragment group moved into the m0-write to LDS-DMA gap (replaces s_nop) in GEMM K-loops
# baseline (speedup 1.0000x reference)
; #define PG8_STAGE(bufoff, gbase, voff) do { _Pragma("unroll") for (int _i = 0; _i < 2; ++_i) \
;         __builtin_amdgcn_global_load_lds((const unsigned*)((const char*)(gbase) + (voff)[_i]), (LAS unsigned*)(lds + (bufoff) + ldsw + _i * 8192), 16, 0, 0); } while (0)
; #define PG8_LDA(dst, b, h) do { _Pragma("unroll") for (int m = 0; m < 4; ++m) _Pragma("unroll") for (int k = 0; k < 2; ++k) dst[m][k] = *(const LAS bf16x8*)(lds + PG8_SA(b, h) + aoff + m * 2048 + k * 1024); } while (0)
; #define PG8_LDB(dst, b, h) do { _Pragma("unroll") for (int n = 0; n < 2; ++n) _Pragma("unroll") for (int k = 0; k < 2; ++k) dst[n][k] = *(const LAS bf16x8*)(lds + PG8_SB(b, h) + boff + n * 2048 + k * 1024); } while (0)
; #define PG8_WAIT_V(n) asm volatile("s_waitcnt vmcnt(" #n ")" ::: "memory")
; #define PG8_WAIT_L(n) asm volatile("s_waitcnt lgkmcnt(" #n ")" ::: "memory")
; #define PG8_BAR __builtin_amdgcn_s_barrier()
; #define PG8_SCHED __builtin_amdgcn_sched_barrier(0)
; template <class Epi>
; __device__ __forceinline__ void gemm_phase(LAS unsigned char* lds, const Gemm g, const StaticOrder& S, const Epi& E) {
;     ...
;             const bool last = (t == nt - 2);
;             const char* a1 = cA + (size_t)(t + 1) * kstep;
;             const char* a2 = last ? nA : cA + (size_t)(t + 2) * kstep; const char* b2 = last ? nB : cB + (size_t)(t + 2) * kstep;
;             const char* a3 = a2 + kstep; const char* b3 = b2 + kstep;
;             PG8_LDB(B0, 0, 0); PG8_SCHED; PG8_LDA(At, 0, 0); PG8_STAGE(PG8_SA(1, 1), a1 + hA, voffA);
;             PG8_WAIT_L(8); PG8_BAR; PG8_WAIT_L(0); PG8_MMA(0, 0, At, B0); PG8_BAR; PG8_SCHED;
;             PG8_LDB(B1, 0, 1); PG8_STAGE(PG8_SB(0, 0), b2, voffB);
;             PG8_BAR; PG8_WAIT_L(0); PG8_MMA(0, 1, At, B1); PG8_BAR;
;             PG8_LDA(At, 0, 1); PG8_STAGE(PG8_SA(0, 0), a2, voffA);
;             PG8_BAR; PG8_WAIT_L(0); PG8_MMA(1, 0, At, B0); PG8_BAR; PG8_SCHED;
;             PG8_STAGE(PG8_SB(0, 1), b2 + hB, voffB);
;             PG8_WAIT_V(6); PG8_BAR; PG8_MMA(1, 1, At, B1); PG8_BAR;
;             PG8_LDB(B0, 1, 0); PG8_SCHED; PG8_LDA(At, 1, 0); PG8_STAGE(PG8_SA(0, 1), a2 + hA, voffA);
;             PG8_WAIT_L(8); PG8_BAR; PG8_WAIT_L(0); PG8_MMA(0, 0, At, B0); PG8_BAR; PG8_SCHED;
;             PG8_LDB(B1, 1, 1); PG8_STAGE(PG8_SB(1, 0), b3, voffB);
;             PG8_BAR; PG8_WAIT_L(0); PG8_MMA(0, 1, At, B1); PG8_BAR;
.LBB0_281:
	s_add_u32 s16, s12, 0xfffc0080
	s_addc_u32 s17, s13, -1
	s_add_i32 s26, 0, 0x10000
	v_add_u32_e32 v139, s26, v137
	ds_read_b128 v[140:143], v139
	ds_read_b128 v[146:149], v139 offset:1024
	ds_read_b128 v[150:153], v139 offset:2048
	ds_read_b128 v[154:157], v139 offset:3072
	s_cmp_eq_u32 s78, 12
	s_cselect_b32 s21, s72, s17
	s_cselect_b32 s20, s76, s16
	s_cselect_b32 s17, s7, s77
	s_cselect_b32 s16, s24, s25
	s_add_i32 m0, s61, 0xc000
	ds_read_b128 v[158:161], v138
	ds_read_b128 v[162:165], v138 offset:1024
	ds_read_b128 v[166:169], v138 offset:2048
	ds_read_b128 v[170:173], v138 offset:3072
	ds_read_b128 v[174:177], v138 offset:4096
	ds_read_b128 v[178:181], v138 offset:5120
	ds_read_b128 v[182:185], v138 offset:6144
	global_load_lds_dwordx4 v132, s[12:13]
	s_add_i32 m0, s61, 0xe000
	ds_read_b128 v[196:199], v138 offset:7168
	global_load_lds_dwordx4 v134, s[12:13]
	s_waitcnt lgkmcnt(8)
	s_barrier
	s_waitcnt lgkmcnt(0)
	v_mfma_f32_16x16x32_bf16 v[120:123], v[140:143], v[158:161], v[120:123]
	v_mfma_f32_16x16x32_bf16 v[124:127], v[150:153], v[158:161], v[124:127]
	v_mfma_f32_16x16x32_bf16 v[104:107], v[140:143], v[166:169], v[104:107]
	v_mfma_f32_16x16x32_bf16 v[108:111], v[150:153], v[166:169], v[108:111]
	v_mfma_f32_16x16x32_bf16 v[88:91], v[140:143], v[174:177], v[88:91]
	v_mfma_f32_16x16x32_bf16 v[92:95], v[150:153], v[174:177], v[92:95]
	v_mfma_f32_16x16x32_bf16 v[72:75], v[140:143], v[182:185], v[72:75]
	v_mfma_f32_16x16x32_bf16 v[76:79], v[150:153], v[182:185], v[76:79]
	v_mfma_f32_16x16x32_bf16 v[120:123], v[146:149], v[162:165], v[120:123]
	v_mfma_f32_16x16x32_bf16 v[124:127], v[154:157], v[162:165], v[124:127]
	v_mfma_f32_16x16x32_bf16 v[104:107], v[146:149], v[170:173], v[104:107]
	v_mfma_f32_16x16x32_bf16 v[108:111], v[154:157], v[170:173], v[108:111]
	v_mfma_f32_16x16x32_bf16 v[88:91], v[146:149], v[178:181], v[88:91]
	v_mfma_f32_16x16x32_bf16 v[92:95], v[154:157], v[178:181], v[92:95]
	v_mfma_f32_16x16x32_bf16 v[72:75], v[146:149], v[196:199], v[72:75]
	v_mfma_f32_16x16x32_bf16 v[76:79], v[154:157], v[196:199], v[76:79]
	s_barrier
	s_add_i32 s28, 0, 0x14000
	s_add_i32 s26, s26, s35
	v_add_u32_e32 v139, s28, v137
	v_lshl_add_u64 v[186:187], s[16:17], 0, v[130:131]
	s_mov_b32 m0, s26
	ds_read_b128 v[200:203], v139
	ds_read_b128 v[204:207], v139 offset:1024
	ds_read_b128 v[214:217], v139 offset:2048
	ds_read_b128 v[218:221], v139 offset:3072
	global_load_lds_dwordx4 v[186:187], off
	s_add_i32 m0, s26, 0x2000
	v_lshl_add_u64 v[188:189], s[16:17], 0, v[128:129]
	global_load_lds_dwordx4 v[188:189], off
	s_barrier
	s_waitcnt lgkmcnt(0)
	v_mfma_f32_16x16x32_bf16 v[112:115], v[200:203], v[158:161], v[112:115]
	v_mfma_f32_16x16x32_bf16 v[116:119], v[214:217], v[158:161], v[116:119]
	v_mfma_f32_16x16x32_bf16 v[96:99], v[200:203], v[166:169], v[96:99]
	v_mfma_f32_16x16x32_bf16 v[100:103], v[214:217], v[166:169], v[100:103]
	v_mfma_f32_16x16x32_bf16 v[80:83], v[200:203], v[174:177], v[80:83]
	v_mfma_f32_16x16x32_bf16 v[84:87], v[214:217], v[174:177], v[84:87]
	v_mfma_f32_16x16x32_bf16 v[64:67], v[200:203], v[182:185], v[64:67]
	v_mfma_f32_16x16x32_bf16 v[68:71], v[214:217], v[182:185], v[68:71]
	v_mfma_f32_16x16x32_bf16 v[112:115], v[204:207], v[162:165], v[112:115]
	v_mfma_f32_16x16x32_bf16 v[116:119], v[218:221], v[162:165], v[116:119]
	v_mfma_f32_16x16x32_bf16 v[96:99], v[204:207], v[170:173], v[96:99]
	v_mfma_f32_16x16x32_bf16 v[100:103], v[218:221], v[170:173], v[100:103]
	v_mfma_f32_16x16x32_bf16 v[80:83], v[204:207], v[178:181], v[80:83]
	v_mfma_f32_16x16x32_bf16 v[84:87], v[218:221], v[178:181], v[84:87]
	v_mfma_f32_16x16x32_bf16 v[64:67], v[204:207], v[196:199], v[64:67]
	v_mfma_f32_16x16x32_bf16 v[68:71], v[218:221], v[196:199], v[68:71]
	s_mov_b32 m0, s61
	v_lshl_add_u64 v[192:193], s[20:21], 0, v[130:131]
	s_barrier
	ds_read_b128 v[158:161], v138 offset:16384
	ds_read_b128 v[162:165], v138 offset:17408
	ds_read_b128 v[166:169], v138 offset:18432
	ds_read_b128 v[170:173], v138 offset:19456
	ds_read_b128 v[174:177], v138 offset:20480
	ds_read_b128 v[178:181], v138 offset:21504
	ds_read_b128 v[182:185], v138 offset:22528
	ds_read_b128 v[196:199], v138 offset:23552
	global_load_lds_dwordx4 v[192:193], off
	s_mov_b32 m0, s62
	v_lshl_add_u64 v[222:223], s[20:21], 0, v[128:129]
	global_load_lds_dwordx4 v[222:223], off
	s_barrier
	s_waitcnt lgkmcnt(0)
	v_mfma_f32_16x16x32_bf16 v[56:59], v[140:143], v[158:161], v[56:59]
	v_mfma_f32_16x16x32_bf16 v[60:63], v[150:153], v[158:161], v[60:63]
	v_mfma_f32_16x16x32_bf16 v[40:43], v[140:143], v[166:169], v[40:43]
	v_mfma_f32_16x16x32_bf16 v[44:47], v[150:153], v[166:169], v[44:47]
	v_mfma_f32_16x16x32_bf16 v[24:27], v[140:143], v[174:177], v[24:27]
	v_mfma_f32_16x16x32_bf16 v[28:31], v[150:153], v[174:177], v[28:31]
	v_mfma_f32_16x16x32_bf16 v[8:11], v[140:143], v[182:185], v[8:11]
	v_mfma_f32_16x16x32_bf16 v[12:15], v[150:153], v[182:185], v[12:15]
	v_mfma_f32_16x16x32_bf16 v[56:59], v[146:149], v[162:165], v[56:59]
	v_mfma_f32_16x16x32_bf16 v[60:63], v[154:157], v[162:165], v[60:63]
	v_mfma_f32_16x16x32_bf16 v[40:43], v[146:149], v[170:173], v[40:43]
	v_mfma_f32_16x16x32_bf16 v[44:47], v[154:157], v[170:173], v[44:47]
	v_mfma_f32_16x16x32_bf16 v[24:27], v[146:149], v[178:181], v[24:27]
	v_mfma_f32_16x16x32_bf16 v[28:31], v[154:157], v[178:181], v[28:31]
	v_mfma_f32_16x16x32_bf16 v[8:11], v[146:149], v[196:199], v[8:11]
	v_mfma_f32_16x16x32_bf16 v[12:15], v[154:157], v[196:199], v[12:15]
	s_barrier
	s_add_u32 s26, s16, 0x40000
	s_addc_u32 s27, s17, 0
	s_add_i32 s28, s28, s35
	s_mov_b32 m0, s28
	s_nop 0
	global_load_lds_dwordx4 v130, s[26:27]
	s_add_i32 m0, s28, 0x2000
	s_nop 0
	global_load_lds_dwordx4 v128, s[26:27]
	s_waitcnt vmcnt(6)
	s_barrier
; #define PG8_STAGE(bufoff, gbase, voff) do { _Pragma("unroll") for (int _i = 0; _i < 2; ++_i) \
;         __builtin_amdgcn_global_load_lds((const unsigned*)((const char*)(gbase) + (voff)[_i]), (LAS unsigned*)(lds + (bufoff) + ldsw + _i * 8192), 16, 0, 0); } while (0)
; #define PG8_LDA(dst, b, h) do { _Pragma("unroll") for (int m = 0; m < 4; ++m) _Pragma("unroll") for (int k = 0; k < 2; ++k) dst[m][k] = *(const LAS bf16x8*)(lds + PG8_SA(b, h) + aoff + m * 2048 + k * 1024); } while (0)
; #define PG8_LDB(dst, b, h) do { _Pragma("unroll") for (int n = 0; n < 2; ++n) _Pragma("unroll") for (int k = 0; k < 2; ++k) dst[n][k] = *(const LAS bf16x8*)(lds + PG8_SB(b, h) + boff + n * 2048 + k * 1024); } while (0)
; #define PG8_MMA(ai, bj, At, Bt) do { __builtin_amdgcn_s_setprio(1); _Pragma("unroll") for (int m = 0; m < 4; ++m) _Pragma("unroll") for (int n = 0; n < 2; ++n) _Pragma("unroll") for (int k = 0; k < 2; ++k) \
;         acc[ai][bj][m][n] = __builtin_amdgcn_mfma_f32_16x16x32_bf16(Bt[n][k], At[m][k], acc[ai][bj][m][n], 0, 0, 0); __builtin_amdgcn_s_setprio(0); } while (0)
; #define PG8_WAIT_V(n) asm volatile("s_waitcnt vmcnt(" #n ")" ::: "memory")
; #define PG8_WAIT_L(n) asm volatile("s_waitcnt lgkmcnt(" #n ")" ::: "memory")
; #define PG8_BAR __builtin_amdgcn_s_barrier()
; #define PG8_SCHED __builtin_amdgcn_sched_barrier(0)
; template <class Epi>
; __device__ __forceinline__ void gemm_phase(LAS unsigned char* lds, const Gemm g, const StaticOrder& S, const Epi& E) {
;     ...
;             PG8_STAGE(PG8_SB(0, 1), b2 + hB, voffB);
;             PG8_WAIT_V(6); PG8_BAR; PG8_MMA(1, 1, At, B1); PG8_BAR;
;             PG8_LDB(B0, 1, 0); PG8_SCHED; PG8_LDA(At, 1, 0); PG8_STAGE(PG8_SA(0, 1), a2 + hA, voffA);
;             PG8_WAIT_L(8); PG8_BAR; PG8_WAIT_L(0); PG8_MMA(0, 0, At, B0); PG8_BAR; PG8_SCHED;
;             PG8_LDB(B1, 1, 1); PG8_STAGE(PG8_SB(1, 0), b3, voffB);
;             PG8_BAR; PG8_WAIT_L(0); PG8_MMA(0, 1, At, B1); PG8_BAR;
;             PG8_LDA(At, 1, 1); PG8_STAGE(PG8_SA(1, 0), a3, voffA);
;             PG8_BAR; PG8_WAIT_L(0); PG8_MMA(1, 0, At, B0); PG8_BAR; PG8_SCHED;
	v_mfma_f32_16x16x32_bf16 v[48:51], v[200:203], v[158:161], v[48:51]
	v_mfma_f32_16x16x32_bf16 v[52:55], v[214:217], v[158:161], v[52:55]
	v_mfma_f32_16x16x32_bf16 v[32:35], v[200:203], v[166:169], v[32:35]
	v_mfma_f32_16x16x32_bf16 v[36:39], v[214:217], v[166:169], v[36:39]
	v_mfma_f32_16x16x32_bf16 v[16:19], v[200:203], v[174:177], v[16:19]
	v_mfma_f32_16x16x32_bf16 v[20:23], v[214:217], v[174:177], v[20:23]
	v_mfma_f32_16x16x32_bf16 v[0:3], v[200:203], v[182:185], v[0:3]
	v_mfma_f32_16x16x32_bf16 v[4:7], v[214:217], v[182:185], v[4:7]
	v_mfma_f32_16x16x32_bf16 v[48:51], v[204:207], v[162:165], v[48:51]
	v_mfma_f32_16x16x32_bf16 v[52:55], v[218:221], v[162:165], v[52:55]
	v_mfma_f32_16x16x32_bf16 v[32:35], v[204:207], v[170:173], v[32:35]
	v_mfma_f32_16x16x32_bf16 v[36:39], v[218:221], v[170:173], v[36:39]
	v_mfma_f32_16x16x32_bf16 v[16:19], v[204:207], v[178:181], v[16:19]
	v_mfma_f32_16x16x32_bf16 v[20:23], v[218:221], v[178:181], v[20:23]
	v_mfma_f32_16x16x32_bf16 v[0:3], v[204:207], v[196:199], v[0:3]
	v_mfma_f32_16x16x32_bf16 v[4:7], v[218:221], v[196:199], v[4:7]
	s_add_i32 s26, 0, 0x18000
	v_add_u32_e32 v139, s26, v137
	s_barrier
	ds_read_b128 v[140:143], v139
	ds_read_b128 v[146:149], v139 offset:1024
	ds_read_b128 v[150:153], v139 offset:2048
	ds_read_b128 v[154:157], v139 offset:3072
	s_add_u32 s20, s20, 0x40000
	s_addc_u32 s21, s21, 0
	s_mov_b32 m0, s63
	ds_read_b128 v[158:161], v138 offset:32768
	ds_read_b128 v[162:165], v138 offset:33792
	ds_read_b128 v[166:169], v138 offset:34816
	ds_read_b128 v[170:173], v138 offset:35840
	ds_read_b128 v[174:177], v138 offset:36864
	ds_read_b128 v[178:181], v138 offset:37888
	ds_read_b128 v[182:185], v138 offset:38912
	global_load_lds_dwordx4 v130, s[20:21]
	s_mov_b32 m0, s64
	ds_read_b128 v[196:199], v138 offset:39936
	global_load_lds_dwordx4 v128, s[20:21]
	s_waitcnt lgkmcnt(8)
	s_barrier
	s_waitcnt lgkmcnt(0)
	v_mfma_f32_16x16x32_bf16 v[120:123], v[140:143], v[158:161], v[120:123]
	v_mfma_f32_16x16x32_bf16 v[124:127], v[150:153], v[158:161], v[124:127]
	v_mfma_f32_16x16x32_bf16 v[104:107], v[140:143], v[166:169], v[104:107]
	v_mfma_f32_16x16x32_bf16 v[108:111], v[150:153], v[166:169], v[108:111]
	v_mfma_f32_16x16x32_bf16 v[88:91], v[140:143], v[174:177], v[88:91]
	v_mfma_f32_16x16x32_bf16 v[92:95], v[150:153], v[174:177], v[92:95]
	v_mfma_f32_16x16x32_bf16 v[72:75], v[140:143], v[182:185], v[72:75]
	v_mfma_f32_16x16x32_bf16 v[76:79], v[150:153], v[182:185], v[76:79]
	v_mfma_f32_16x16x32_bf16 v[120:123], v[146:149], v[162:165], v[120:123]
	v_mfma_f32_16x16x32_bf16 v[124:127], v[154:157], v[162:165], v[124:127]
	v_mfma_f32_16x16x32_bf16 v[104:107], v[146:149], v[170:173], v[104:107]
	v_mfma_f32_16x16x32_bf16 v[108:111], v[154:157], v[170:173], v[108:111]
	v_mfma_f32_16x16x32_bf16 v[88:91], v[146:149], v[178:181], v[88:91]
	v_mfma_f32_16x16x32_bf16 v[92:95], v[154:157], v[178:181], v[92:95]
	v_mfma_f32_16x16x32_bf16 v[72:75], v[146:149], v[196:199], v[72:75]
	v_mfma_f32_16x16x32_bf16 v[76:79], v[154:157], v[196:199], v[76:79]
	s_barrier
	s_add_i32 s20, 0, 0x1c000
	s_add_i32 s21, s26, s35
	v_add_u32_e32 v139, s20, v137
	v_lshl_add_u64 v[186:187], v[186:187], 0, s[88:89]
	s_mov_b32 m0, s21
	ds_read_b128 v[200:203], v139
	ds_read_b128 v[204:207], v139 offset:1024
	ds_read_b128 v[214:217], v139 offset:2048
	ds_read_b128 v[218:221], v139 offset:3072
	global_load_lds_dwordx4 v[186:187], off
	s_add_i32 m0, s21, 0x2000
	v_lshl_add_u64 v[186:187], v[188:189], 0, s[88:89]
	global_load_lds_dwordx4 v[186:187], off
	s_barrier
	s_waitcnt lgkmcnt(0)
	v_mfma_f32_16x16x32_bf16 v[112:115], v[200:203], v[158:161], v[112:115]
	v_mfma_f32_16x16x32_bf16 v[116:119], v[214:217], v[158:161], v[116:119]
	v_mfma_f32_16x16x32_bf16 v[96:99], v[200:203], v[166:169], v[96:99]
	v_mfma_f32_16x16x32_bf16 v[100:103], v[214:217], v[166:169], v[100:103]
	v_mfma_f32_16x16x32_bf16 v[80:83], v[200:203], v[174:177], v[80:83]
	v_mfma_f32_16x16x32_bf16 v[84:87], v[214:217], v[174:177], v[84:87]
	v_mfma_f32_16x16x32_bf16 v[64:67], v[200:203], v[182:185], v[64:67]
	v_mfma_f32_16x16x32_bf16 v[68:71], v[214:217], v[182:185], v[68:71]
	v_mfma_f32_16x16x32_bf16 v[112:115], v[204:207], v[162:165], v[112:115]
	v_mfma_f32_16x16x32_bf16 v[116:119], v[218:221], v[162:165], v[116:119]
	v_mfma_f32_16x16x32_bf16 v[96:99], v[204:207], v[170:173], v[96:99]
	v_mfma_f32_16x16x32_bf16 v[100:103], v[218:221], v[170:173], v[100:103]
	v_mfma_f32_16x16x32_bf16 v[80:83], v[204:207], v[178:181], v[80:83]
	v_mfma_f32_16x16x32_bf16 v[84:87], v[218:221], v[178:181], v[84:87]
	v_mfma_f32_16x16x32_bf16 v[64:67], v[204:207], v[196:199], v[64:67]
	v_mfma_f32_16x16x32_bf16 v[68:71], v[218:221], v[196:199], v[68:71]
	s_mov_b32 m0, s65
	v_lshl_add_u64 v[186:187], v[192:193], 0, s[88:89]
	s_barrier
	ds_read_b128 v[158:161], v138 offset:49152
	ds_read_b128 v[162:165], v138 offset:50176
	ds_read_b128 v[166:169], v138 offset:51200
	ds_read_b128 v[170:173], v138 offset:52224
	ds_read_b128 v[174:177], v138 offset:53248
	ds_read_b128 v[178:181], v138 offset:54272
	ds_read_b128 v[182:185], v138 offset:55296
	ds_read_b128 v[196:199], v138 offset:56320
	global_load_lds_dwordx4 v[186:187], off
	s_mov_b32 m0, s68
	v_lshl_add_u64 v[186:187], v[222:223], 0, s[88:89]
	global_load_lds_dwordx4 v[186:187], off
	s_barrier
; __device__ __forceinline__ unsigned pk2(float lo, float hi) { unsigned r; asm("v_cvt_pk_bf16_f32 %0, %1, %2" : "=v"(r) : "v"(lo), "v"(hi)); return r; }
; #define PG8_STAGE(bufoff, gbase, voff) do { _Pragma("unroll") for (int _i = 0; _i < 2; ++_i) \
;         __builtin_amdgcn_global_load_lds((const unsigned*)((const char*)(gbase) + (voff)[_i]), (LAS unsigned*)(lds + (bufoff) + ldsw + _i * 8192), 16, 0, 0); } while (0)
; #define PG8_MMA(ai, bj, At, Bt) do { __builtin_amdgcn_s_setprio(1); _Pragma("unroll") for (int m = 0; m < 4; ++m) _Pragma("unroll") for (int n = 0; n < 2; ++n) _Pragma("unroll") for (int k = 0; k < 2; ++k) \
;         acc[ai][bj][m][n] = __builtin_amdgcn_mfma_f32_16x16x32_bf16(Bt[n][k], At[m][k], acc[ai][bj][m][n], 0, 0, 0); __builtin_amdgcn_s_setprio(0); } while (0)
; #define PG8_WAIT_V(n) asm volatile("s_waitcnt vmcnt(" #n ")" ::: "memory")
; #define PG8_WAIT_L(n) asm volatile("s_waitcnt lgkmcnt(" #n ")" ::: "memory")
; #define PG8_BAR __builtin_amdgcn_s_barrier()
; #define PG8_SCHED __builtin_amdgcn_sched_barrier(0)
;     static __device__ __forceinline__ float sg(float g, float u) { return (g * u) * __builtin_amdgcn_rcpf(1.f + __builtin_amdgcn_exp2f(-g)); }
; template <class Epi>
; __device__ __forceinline__ void gemm_phase(LAS unsigned char* lds, const Gemm g, const StaticOrder& S, const Epi& E) {
;     ...
;             PG8_BAR; PG8_WAIT_L(0); PG8_MMA(1, 0, At, B0); PG8_BAR; PG8_SCHED;
;             PG8_STAGE(PG8_SB(1, 1), b3 + hB, voffB);
;             PG8_WAIT_V(6); PG8_BAR; PG8_MMA(1, 1, At, B1); PG8_BAR;
;     __device__ __forceinline__ void operator()(const f32x4 (&acc)[2][2][4][2], const Unit& u, int wr, int wc, int fr, int fq) const {
; #pragma unroll
;         for (int ai = 0; ai < 2; ++ai)
; #pragma unroll
;             for (int m = 0; m < 4; ++m) {
;                 const int row = u.pm * BM + ai * HALF + wr * 64 + m * 16 + fr;
;                 const f32x4 g0 = acc[ai][0][m][0], u0 = acc[ai][0][m][1], g1 = acc[ai][1][m][0], u1 = acc[ai][1][m][1];
;                 u32x4 o; o.x = pk2(sg(g0[0], u0[0]), sg(g0[1], u0[1])); o.y = pk2(sg(g0[2], u0[2]), sg(g0[3], u0[3]));
;                 o.z = pk2(sg(g1[0], u1[0]), sg(g1[1], u1[1])); o.w = pk2(sg(g1[2], u1[2]), sg(g1[3], u1[3]));
;                 *(u32x4*)(O + (size_t)row * DFF + u.pn * 128 + wc * 32 + fq * 8) = o;
	s_waitcnt lgkmcnt(0)
	v_mfma_f32_16x16x32_bf16 v[56:59], v[140:143], v[158:161], v[56:59]
	v_mfma_f32_16x16x32_bf16 v[60:63], v[150:153], v[158:161], v[60:63]
	v_mfma_f32_16x16x32_bf16 v[40:43], v[140:143], v[166:169], v[40:43]
	v_mfma_f32_16x16x32_bf16 v[44:47], v[150:153], v[166:169], v[44:47]
	v_mfma_f32_16x16x32_bf16 v[24:27], v[140:143], v[174:177], v[24:27]
	v_mfma_f32_16x16x32_bf16 v[28:31], v[150:153], v[174:177], v[28:31]
	v_mfma_f32_16x16x32_bf16 v[8:11], v[140:143], v[182:185], v[8:11]
	v_mfma_f32_16x16x32_bf16 v[12:15], v[150:153], v[182:185], v[12:15]
	v_mfma_f32_16x16x32_bf16 v[56:59], v[146:149], v[162:165], v[56:59]
	v_mfma_f32_16x16x32_bf16 v[60:63], v[154:157], v[162:165], v[60:63]
	v_mfma_f32_16x16x32_bf16 v[40:43], v[146:149], v[170:173], v[40:43]
	v_mfma_f32_16x16x32_bf16 v[44:47], v[154:157], v[170:173], v[44:47]
	v_mfma_f32_16x16x32_bf16 v[24:27], v[146:149], v[178:181], v[24:27]
	v_mfma_f32_16x16x32_bf16 v[28:31], v[154:157], v[178:181], v[28:31]
	v_mfma_f32_16x16x32_bf16 v[8:11], v[146:149], v[196:199], v[8:11]
	v_mfma_f32_16x16x32_bf16 v[12:15], v[154:157], v[196:199], v[12:15]
	s_barrier
	s_add_u32 s16, s16, 0x40080
	s_addc_u32 s17, s17, 0
	s_add_i32 s20, s20, s35
	s_mov_b32 m0, s20
	s_nop 0
	global_load_lds_dwordx4 v130, s[16:17]
	s_add_i32 m0, s20, 0x2000
	s_nop 0
	global_load_lds_dwordx4 v128, s[16:17]
	s_waitcnt vmcnt(6)
	s_barrier
	v_mfma_f32_16x16x32_bf16 v[48:51], v[200:203], v[158:161], v[48:51]
	v_mfma_f32_16x16x32_bf16 v[52:55], v[214:217], v[158:161], v[52:55]
	v_mfma_f32_16x16x32_bf16 v[32:35], v[200:203], v[166:169], v[32:35]
	v_mfma_f32_16x16x32_bf16 v[36:39], v[214:217], v[166:169], v[36:39]
	v_mfma_f32_16x16x32_bf16 v[16:19], v[200:203], v[174:177], v[16:19]
	v_mfma_f32_16x16x32_bf16 v[20:23], v[214:217], v[174:177], v[20:23]
	v_mfma_f32_16x16x32_bf16 v[0:3], v[200:203], v[182:185], v[0:3]
	v_mfma_f32_16x16x32_bf16 v[4:7], v[214:217], v[182:185], v[4:7]
	v_mfma_f32_16x16x32_bf16 v[48:51], v[204:207], v[162:165], v[48:51]
	v_mfma_f32_16x16x32_bf16 v[52:55], v[218:221], v[162:165], v[52:55]
	v_mfma_f32_16x16x32_bf16 v[32:35], v[204:207], v[170:173], v[32:35]
	v_mfma_f32_16x16x32_bf16 v[36:39], v[218:221], v[170:173], v[36:39]
	v_mfma_f32_16x16x32_bf16 v[16:19], v[204:207], v[178:181], v[16:19]
	v_mfma_f32_16x16x32_bf16 v[20:23], v[218:221], v[178:181], v[20:23]
	v_mfma_f32_16x16x32_bf16 v[0:3], v[204:207], v[196:199], v[0:3]
	v_mfma_f32_16x16x32_bf16 v[4:7], v[218:221], v[196:199], v[4:7]
	s_add_i32 s78, s78, 2
	s_add_u32 s12, s12, 0x100
	s_addc_u32 s13, s13, 0
	s_add_u32 s25, s25, 0x100
	s_addc_u32 s77, s77, 0
	s_cmp_gt_u32 s78, 13
	s_barrier
	s_cbranch_scc0 .LBB0_281
	v_mul_f32_e32 v124, v120, v124
	v_exp_f32_e64 v120, -v120
	v_mul_f32_e32 v108, v104, v108
	v_exp_f32_e64 v104, -v104
	v_mul_f32_e32 v92, v88, v92
	v_add_f32_e32 v120, 1.0, v120
	v_rcp_f32_e32 v120, v120
	v_add_f32_e32 v104, 1.0, v104
	v_rcp_f32_e32 v104, v104
	v_exp_f32_e64 v88, -v88
	v_mul_f32_e32 v120, v124, v120
	v_mul_f32_e32 v124, v121, v125
	v_exp_f32_e64 v121, -v121
	v_mul_f32_e32 v104, v108, v104
	v_mul_f32_e32 v108, v105, v109
	v_exp_f32_e64 v105, -v105
	v_add_f32_e32 v121, 1.0, v121
	v_rcp_f32_e32 v121, v121
	v_add_f32_e32 v88, 1.0, v88
	v_rcp_f32_e32 v88, v88
	v_mul_f32_e32 v76, v72, v76
	v_exp_f32_e64 v72, -v72
	v_mul_f32_e32 v121, v124, v121
	v_cvt_pk_bf16_f32 v120, v120, v121
	v_mul_f32_e32 v121, v122, v126
	v_exp_f32_e64 v122, -v122
	v_mul_f32_e32 v116, v112, v116
	v_exp_f32_e64 v112, -v112
	v_add_f32_e32 v105, 1.0, v105
	v_rcp_f32_e32 v105, v105
	v_mul_f32_e32 v88, v92, v88
	v_mul_f32_e32 v92, v89, v93
	v_exp_f32_e64 v89, -v89
	v_add_f32_e32 v72, 1.0, v72
	v_rcp_f32_e32 v72, v72
	v_mul_f32_e32 v60, v56, v60
	v_exp_f32_e64 v56, -v56
	v_add_f32_e32 v122, 1.0, v122
	v_add_f32_e32 v112, 1.0, v112
	v_rcp_f32_e32 v122, v122
	v_rcp_f32_e32 v112, v112
	v_mul_f32_e32 v105, v108, v105
	v_add_f32_e32 v89, 1.0, v89
	v_cvt_pk_bf16_f32 v104, v104, v105
	v_mul_f32_e32 v105, v106, v110
	v_exp_f32_e64 v106, -v106
	v_mul_f32_e32 v100, v96, v100
	v_exp_f32_e64 v96, -v96
	v_rcp_f32_e32 v89, v89
	v_mul_f32_e32 v72, v76, v72
	v_mul_f32_e32 v76, v73, v77
	v_exp_f32_e64 v73, -v73
	v_add_f32_e32 v56, 1.0, v56
	v_rcp_f32_e32 v56, v56
	v_mul_f32_e32 v44, v40, v44
	v_exp_f32_e64 v40, -v40
	v_mul_f32_e32 v121, v121, v122
	v_mul_f32_e32 v122, v123, v127
	v_exp_f32_e64 v123, -v123
	v_mul_f32_e32 v112, v116, v112
	v_mul_f32_e32 v116, v113, v117
	v_exp_f32_e64 v113, -v113
	v_add_f32_e32 v106, 1.0, v106
	v_add_f32_e32 v96, 1.0, v96
	v_mul_f32_e32 v89, v92, v89
	v_add_f32_e32 v73, 1.0, v73
	v_rcp_f32_e32 v106, v106
	v_rcp_f32_e32 v96, v96
	v_cvt_pk_bf16_f32 v88, v88, v89
	v_mul_f32_e32 v89, v90, v94
	v_exp_f32_e64 v90, -v90
	v_mul_f32_e32 v84, v80, v84
	v_exp_f32_e64 v80, -v80
	v_rcp_f32_e32 v73, v73
	v_mul_f32_e32 v56, v60, v56
	v_mul_f32_e32 v60, v57, v61
	v_exp_f32_e64 v57, -v57
	v_add_f32_e32 v40, 1.0, v40
	v_rcp_f32_e32 v40, v40
	v_mul_f32_e32 v28, v24, v28
	v_exp_f32_e64 v24, -v24
	v_add_f32_e32 v123, 1.0, v123
	v_add_f32_e32 v113, 1.0, v113
	v_rcp_f32_e32 v123, v123
	v_rcp_f32_e32 v113, v113
	v_mul_f32_e32 v105, v105, v106
	v_mul_f32_e32 v106, v107, v111
	v_exp_f32_e64 v107, -v107
	v_mul_f32_e32 v96, v100, v96
	v_mul_f32_e32 v100, v97, v101
	v_exp_f32_e64 v97, -v97
	v_add_f32_e32 v90, 1.0, v90
	v_add_f32_e32 v80, 1.0, v80
	v_mul_f32_e32 v73, v76, v73
	v_add_f32_e32 v57, 1.0, v57
	v_rcp_f32_e32 v90, v90
	v_rcp_f32_e32 v80, v80
	v_cvt_pk_bf16_f32 v72, v72, v73
	v_mul_f32_e32 v73, v74, v78
	v_exp_f32_e64 v74, -v74
	v_mul_f32_e32 v68, v64, v68
	v_exp_f32_e64 v64, -v64
	v_rcp_f32_e32 v57, v57
	v_mul_f32_e32 v40, v44, v40
	v_mul_f32_e32 v44, v41, v45
; __device__ __forceinline__ unsigned pk2(float lo, float hi) { unsigned r; asm("v_cvt_pk_bf16_f32 %0, %1, %2" : "=v"(r) : "v"(lo), "v"(hi)); return r; }
;     static __device__ __forceinline__ float sg(float g, float u) { return (g * u) * __builtin_amdgcn_rcpf(1.f + __builtin_amdgcn_exp2f(-g)); }
;     __device__ __forceinline__ void operator()(const f32x4 (&acc)[2][2][4][2], const Unit& u, int wr, int wc, int fr, int fq) const {
; #pragma unroll
;         for (int ai = 0; ai < 2; ++ai)
; #pragma unroll
;             for (int m = 0; m < 4; ++m) {
;                 const int row = u.pm * BM + ai * HALF + wr * 64 + m * 16 + fr;
;                 const f32x4 g0 = acc[ai][0][m][0], u0 = acc[ai][0][m][1], g1 = acc[ai][1][m][0], u1 = acc[ai][1][m][1];
;                 u32x4 o; o.x = pk2(sg(g0[0], u0[0]), sg(g0[1], u0[1])); o.y = pk2(sg(g0[2], u0[2]), sg(g0[3], u0[3]));
;                 o.z = pk2(sg(g1[0], u1[0]), sg(g1[1], u1[1])); o.w = pk2(sg(g1[2], u1[2]), sg(g1[3], u1[3]));
;                 *(u32x4*)(O + (size_t)row * DFF + u.pn * 128 + wc * 32 + fq * 8) = o;
	v_exp_f32_e64 v41, -v41
	v_add_f32_e32 v24, 1.0, v24
	v_rcp_f32_e32 v24, v24
	v_mul_f32_e32 v12, v8, v12
	v_exp_f32_e64 v8, -v8
	v_mul_f32_e32 v122, v122, v123
	v_mul_f32_e32 v113, v116, v113
	v_cvt_pk_bf16_f32 v121, v121, v122
	v_cvt_pk_bf16_f32 v122, v112, v113
	v_exp_f32_e64 v113, -v114
	v_add_f32_e32 v107, 1.0, v107
	v_add_f32_e32 v97, 1.0, v97
	v_mul_f32_e32 v112, v114, v118
	v_exp_f32_e64 v114, -v115
	v_rcp_f32_e32 v107, v107
	v_rcp_f32_e32 v97, v97
	v_mul_f32_e32 v89, v89, v90
	v_mul_f32_e32 v90, v91, v95
	v_exp_f32_e64 v91, -v91
	v_mul_f32_e32 v80, v84, v80
	v_mul_f32_e32 v84, v81, v85
	v_exp_f32_e64 v81, -v81
	v_add_f32_e32 v74, 1.0, v74
	v_add_f32_e32 v64, 1.0, v64
	v_mul_f32_e32 v57, v60, v57
	v_add_f32_e32 v41, 1.0, v41
	v_rcp_f32_e32 v74, v74
	v_rcp_f32_e32 v64, v64
	v_cvt_pk_bf16_f32 v56, v56, v57
	v_mul_f32_e32 v57, v58, v62
	v_exp_f32_e64 v58, -v58
	v_mul_f32_e32 v52, v48, v52
	v_exp_f32_e64 v48, -v48
	v_rcp_f32_e32 v41, v41
	v_mul_f32_e32 v24, v28, v24
	v_mul_f32_e32 v28, v25, v29
	v_exp_f32_e64 v25, -v25
	v_add_f32_e32 v8, 1.0, v8
	v_rcp_f32_e32 v8, v8
	v_add_f32_e32 v113, 1.0, v113
	v_rcp_f32_e32 v113, v113
	v_add_f32_e32 v114, 1.0, v114
	v_mul_f32_e32 v106, v106, v107
	v_mul_f32_e32 v97, v100, v97
	v_add_f32_e32 v91, 1.0, v91
	v_add_f32_e32 v81, 1.0, v81
	v_rcp_f32_e32 v114, v114
	v_cvt_pk_bf16_f32 v105, v105, v106
	v_cvt_pk_bf16_f32 v106, v96, v97
	v_exp_f32_e64 v97, -v98
	v_rcp_f32_e32 v91, v91
	v_rcp_f32_e32 v81, v81
	v_mul_f32_e32 v73, v73, v74
	v_mul_f32_e32 v74, v75, v79
	v_exp_f32_e64 v75, -v75
	v_mul_f32_e32 v64, v68, v64
	v_mul_f32_e32 v68, v65, v69
	v_exp_f32_e64 v65, -v65
	v_add_f32_e32 v58, 1.0, v58
	v_add_f32_e32 v48, 1.0, v48
	v_mul_f32_e32 v41, v44, v41
	v_add_f32_e32 v25, 1.0, v25
	v_mul_f32_e32 v96, v98, v102
	v_exp_f32_e64 v98, -v99
	v_rcp_f32_e32 v58, v58
	v_rcp_f32_e32 v48, v48
	v_cvt_pk_bf16_f32 v40, v40, v41
	v_mul_f32_e32 v41, v42, v46
	v_exp_f32_e64 v42, -v42
	v_mul_f32_e32 v36, v32, v36
	v_exp_f32_e64 v32, -v32
	v_rcp_f32_e32 v25, v25
	v_mul_f32_e32 v8, v12, v8
	v_mul_f32_e32 v12, v9, v13
	v_exp_f32_e64 v9, -v9
	v_mul_f32_e32 v112, v112, v113
	v_mul_f32_e32 v113, v115, v119
	s_lshl_b32 s12, s15, 7
	v_mul_f32_e32 v113, v113, v114
	v_add_f32_e32 v97, 1.0, v97
	v_mul_f32_e32 v90, v90, v91
	v_mul_f32_e32 v81, v84, v81
	v_add_f32_e32 v75, 1.0, v75
	v_add_f32_e32 v65, 1.0, v65
	v_lshl_add_u32 v139, s71, 8, v136
	s_ashr_i32 s13, s12, 31
	v_cvt_pk_bf16_f32 v123, v112, v113
	v_mov_b64_e32 v[112:113], s[4:5]
	v_rcp_f32_e32 v97, v97
	v_add_f32_e32 v98, 1.0, v98
	v_cvt_pk_bf16_f32 v89, v89, v90
	v_cvt_pk_bf16_f32 v90, v80, v81
	v_exp_f32_e64 v81, -v82
	v_rcp_f32_e32 v75, v75
	v_rcp_f32_e32 v65, v65
	v_mul_f32_e32 v57, v57, v58
	v_mul_f32_e32 v58, v59, v63
	v_exp_f32_e64 v59, -v59
	v_mul_f32_e32 v48, v52, v48
	v_mul_f32_e32 v52, v49, v53
	v_exp_f32_e64 v49, -v49
	v_add_f32_e32 v42, 1.0, v42
	v_add_f32_e32 v32, 1.0, v32
	v_mul_f32_e32 v25, v28, v25
	v_add_f32_e32 v9, 1.0, v9
	v_mad_i64_i32 v[114:115], s[16:17], v139, s33, v[112:113]
	s_lshl_b64 s[12:13], s[12:13], 1
	v_rcp_f32_e32 v98, v98
	v_mul_f32_e32 v80, v82, v86
	v_exp_f32_e64 v82, -v83
	v_rcp_f32_e32 v42, v42
	v_rcp_f32_e32 v32, v32
	v_cvt_pk_bf16_f32 v24, v24, v25
	v_mul_f32_e32 v25, v26, v30
	v_exp_f32_e64 v26, -v26
	v_mul_f32_e32 v20, v16, v20
	v_exp_f32_e64 v16, -v16
	v_rcp_f32_e32 v9, v9
	v_lshl_add_u64 v[114:115], v[114:115], 0, s[12:13]
	v_lshl_add_u64 v[114:115], v[114:115], 0, s[66:67]
	v_lshl_add_u64 v[114:115], v[114:115], 0, v[144:145]
	v_mul_f32_e32 v96, v96, v97
	v_mul_f32_e32 v97, v99, v103
	v_add_f32_e32 v81, 1.0, v81
	v_mul_f32_e32 v74, v74, v75
	v_mul_f32_e32 v65, v68, v65
	v_add_f32_e32 v59, 1.0, v59
	v_add_f32_e32 v49, 1.0, v49
	global_store_dwordx4 v[114:115], v[120:123], off
	v_or_b32_e32 v114, 16, v139
	v_mul_f32_e32 v97, v97, v98
	v_rcp_f32_e32 v81, v81
	v_add_f32_e32 v82, 1.0, v82
	v_cvt_pk_bf16_f32 v73, v73, v74
	v_cvt_pk_bf16_f32 v74, v64, v65
	v_exp_f32_e64 v65, -v66
	v_rcp_f32_e32 v59, v59
	v_rcp_f32_e32 v49, v49
	v_mul_f32_e32 v41, v41, v42
	v_mul_f32_e32 v42, v43, v47
	v_exp_f32_e64 v43, -v43
	v_mul_f32_e32 v32, v36, v32
	v_mul_f32_e32 v36, v33, v37
	v_exp_f32_e64 v33, -v33
	v_add_f32_e32 v26, 1.0, v26
	v_add_f32_e32 v16, 1.0, v16
	v_mul_f32_e32 v9, v12, v9
	v_cvt_pk_bf16_f32 v107, v96, v97
	v_mad_i64_i32 v[96:97], s[16:17], v114, s33, v[112:113]
	v_rcp_f32_e32 v82, v82
	v_mul_f32_e32 v64, v66, v70
	v_exp_f32_e64 v66, -v67
	v_rcp_f32_e32 v26, v26
	v_rcp_f32_e32 v16, v16
	v_cvt_pk_bf16_f32 v8, v8, v9
	v_mul_f32_e32 v9, v10, v14
	v_exp_f32_e64 v10, -v10
	v_mul_f32_e32 v4, v0, v4
	v_exp_f32_e64 v0, -v0
	v_lshl_add_u64 v[96:97], v[96:97], 0, s[12:13]
	v_lshl_add_u64 v[96:97], v[96:97], 0, s[66:67]
; __device__ __forceinline__ unsigned pk2(float lo, float hi) { unsigned r; asm("v_cvt_pk_bf16_f32 %0, %1, %2" : "=v"(r) : "v"(lo), "v"(hi)); return r; }
; #define PG8_WAIT_V(n) asm volatile("s_waitcnt vmcnt(" #n ")" ::: "memory")
; #define PG8_BAR __builtin_amdgcn_s_barrier()
;     static __device__ __forceinline__ float sg(float g, float u) { return (g * u) * __builtin_amdgcn_rcpf(1.f + __builtin_amdgcn_exp2f(-g)); }
; template <class Epi>
; __device__ __forceinline__ void gemm_phase(LAS unsigned char* lds, const Gemm g, const StaticOrder& S, const Epi& E) {
;     ...
;         E(acc, cur, wr, wc, fr, fq);
;         if (!has_next) break;
; #pragma unroll
;         for (int a = 0; a < 2; ++a)
; #pragma unroll
;             for (int b = 0; b < 2; ++b)
; #pragma unroll
;                 for (int m = 0; m < 4; ++m)
; #pragma unroll
;                     for (int n = 0; n < 2; ++n) acc[a][b][m][n] = (f32x4){0.f, 0.f, 0.f, 0.f};
;         cur = nxt; cA = nA; cB = nB; ++ui;
;     }
;     PG8_WAIT_V(0);
;     if (wr == 0) PG8_BAR;
;     __device__ __forceinline__ void operator()(const f32x4 (&acc)[2][2][4][2], const Unit& u, int wr, int wc, int fr, int fq) const {
; #pragma unroll
;         for (int ai = 0; ai < 2; ++ai)
; #pragma unroll
;             for (int m = 0; m < 4; ++m) {
;                 const int row = u.pm * BM + ai * HALF + wr * 64 + m * 16 + fr;
;                 const f32x4 g0 = acc[ai][0][m][0], u0 = acc[ai][0][m][1], g1 = acc[ai][1][m][0], u1 = acc[ai][1][m][1];
;                 u32x4 o; o.x = pk2(sg(g0[0], u0[0]), sg(g0[1], u0[1])); o.y = pk2(sg(g0[2], u0[2]), sg(g0[3], u0[3]));
;                 o.z = pk2(sg(g1[0], u1[0]), sg(g1[1], u1[1])); o.w = pk2(sg(g1[2], u1[2]), sg(g1[3], u1[3]));
;                 *(u32x4*)(O + (size_t)row * DFF + u.pn * 128 + wc * 32 + fq * 8) = o;
	v_lshl_add_u64 v[96:97], v[96:97], 0, v[144:145]
	v_mul_f32_e32 v80, v80, v81
	v_mul_f32_e32 v81, v83, v87
	v_add_f32_e32 v65, 1.0, v65
	v_mul_f32_e32 v58, v58, v59
	v_mul_f32_e32 v49, v52, v49
	v_add_f32_e32 v43, 1.0, v43
	v_add_f32_e32 v33, 1.0, v33
	global_store_dwordx4 v[96:97], v[104:107], off
	v_or_b32_e32 v96, 32, v139
	v_mul_f32_e32 v81, v81, v82
	v_rcp_f32_e32 v65, v65
	v_add_f32_e32 v66, 1.0, v66
	v_cvt_pk_bf16_f32 v57, v57, v58
	v_cvt_pk_bf16_f32 v58, v48, v49
	v_exp_f32_e64 v49, -v50
	v_rcp_f32_e32 v43, v43
	v_rcp_f32_e32 v33, v33
	v_mul_f32_e32 v25, v25, v26
	v_mul_f32_e32 v26, v27, v31
	v_exp_f32_e64 v27, -v27
	v_mul_f32_e32 v16, v20, v16
	v_mul_f32_e32 v20, v17, v21
	v_exp_f32_e64 v17, -v17
	v_add_f32_e32 v10, 1.0, v10
	v_add_f32_e32 v0, 1.0, v0
	v_cvt_pk_bf16_f32 v91, v80, v81
	v_mad_i64_i32 v[80:81], s[16:17], v96, s33, v[112:113]
	v_rcp_f32_e32 v66, v66
	v_mul_f32_e32 v48, v50, v54
	v_exp_f32_e64 v50, -v51
	v_rcp_f32_e32 v10, v10
	v_rcp_f32_e32 v0, v0
	v_lshl_add_u64 v[80:81], v[80:81], 0, s[12:13]
	v_lshl_add_u64 v[80:81], v[80:81], 0, s[66:67]
	v_lshl_add_u64 v[80:81], v[80:81], 0, v[144:145]
	v_mul_f32_e32 v64, v64, v65
	v_mul_f32_e32 v65, v67, v71
	v_add_f32_e32 v49, 1.0, v49
	v_mul_f32_e32 v42, v42, v43
	v_mul_f32_e32 v33, v36, v33
	v_add_f32_e32 v27, 1.0, v27
	v_add_f32_e32 v17, 1.0, v17
	global_store_dwordx4 v[80:81], v[88:91], off
	v_or_b32_e32 v80, 48, v139
	v_mul_f32_e32 v65, v65, v66
	v_rcp_f32_e32 v49, v49
	v_add_f32_e32 v50, 1.0, v50
	v_cvt_pk_bf16_f32 v41, v41, v42
	v_cvt_pk_bf16_f32 v42, v32, v33
	v_exp_f32_e64 v33, -v34
	v_rcp_f32_e32 v27, v27
	v_rcp_f32_e32 v17, v17
	v_mul_f32_e32 v9, v9, v10
	v_mul_f32_e32 v10, v11, v15
	v_exp_f32_e64 v11, -v11
	v_mul_f32_e32 v0, v4, v0
	v_mul_f32_e32 v4, v1, v5
	v_exp_f32_e64 v1, -v1
	v_cvt_pk_bf16_f32 v75, v64, v65
	v_mad_i64_i32 v[64:65], s[16:17], v80, s33, v[112:113]
	v_rcp_f32_e32 v50, v50
	v_mul_f32_e32 v32, v34, v38
	v_exp_f32_e64 v34, -v35
	v_lshl_add_u64 v[64:65], v[64:65], 0, s[12:13]
	v_lshl_add_u64 v[64:65], v[64:65], 0, s[66:67]
	v_lshl_add_u64 v[64:65], v[64:65], 0, v[144:145]
	v_mul_f32_e32 v48, v48, v49
	v_mul_f32_e32 v49, v51, v55
	v_add_f32_e32 v33, 1.0, v33
	v_mul_f32_e32 v26, v26, v27
	v_mul_f32_e32 v17, v20, v17
	v_add_f32_e32 v11, 1.0, v11
	v_add_f32_e32 v1, 1.0, v1
	global_store_dwordx4 v[64:65], v[72:75], off
	v_add_u32_e32 v64, 0x80, v139
	v_mul_f32_e32 v49, v49, v50
	v_rcp_f32_e32 v33, v33
	v_add_f32_e32 v34, 1.0, v34
	v_cvt_pk_bf16_f32 v25, v25, v26
	v_cvt_pk_bf16_f32 v26, v16, v17
	v_exp_f32_e64 v17, -v18
	v_rcp_f32_e32 v11, v11
	v_rcp_f32_e32 v1, v1
	v_cvt_pk_bf16_f32 v59, v48, v49
	v_mad_i64_i32 v[48:49], s[16:17], v64, s33, v[112:113]
	v_rcp_f32_e32 v34, v34
	v_mul_f32_e32 v16, v18, v22
	v_exp_f32_e64 v18, -v19
	v_lshl_add_u64 v[48:49], v[48:49], 0, s[12:13]
	v_lshl_add_u64 v[48:49], v[48:49], 0, s[66:67]
	v_lshl_add_u64 v[48:49], v[48:49], 0, v[144:145]
	v_mul_f32_e32 v32, v32, v33
	v_mul_f32_e32 v33, v35, v39
	v_add_f32_e32 v17, 1.0, v17
	v_mul_f32_e32 v10, v10, v11
	v_mul_f32_e32 v1, v4, v1
	global_store_dwordx4 v[48:49], v[56:59], off
	v_add_u32_e32 v48, 0x90, v139
	v_mul_f32_e32 v33, v33, v34
	v_rcp_f32_e32 v17, v17
	v_add_f32_e32 v18, 1.0, v18
	v_cvt_pk_bf16_f32 v9, v9, v10
	v_cvt_pk_bf16_f32 v10, v0, v1
	v_exp_f32_e64 v1, -v2
	v_cvt_pk_bf16_f32 v43, v32, v33
	v_mad_i64_i32 v[32:33], s[16:17], v48, s33, v[112:113]
	v_rcp_f32_e32 v18, v18
	v_mul_f32_e32 v0, v2, v6
	v_exp_f32_e64 v2, -v3
	v_lshl_add_u64 v[32:33], v[32:33], 0, s[12:13]
	v_lshl_add_u64 v[32:33], v[32:33], 0, s[66:67]
	v_lshl_add_u64 v[32:33], v[32:33], 0, v[144:145]
	v_mul_f32_e32 v16, v16, v17
	v_mul_f32_e32 v17, v19, v23
	v_add_f32_e32 v1, 1.0, v1
	global_store_dwordx4 v[32:33], v[40:43], off
	v_add_u32_e32 v32, 0xa0, v139
	v_mul_f32_e32 v17, v17, v18
	v_rcp_f32_e32 v1, v1
	v_add_f32_e32 v2, 1.0, v2
	v_cvt_pk_bf16_f32 v27, v16, v17
	v_mad_i64_i32 v[16:17], s[16:17], v32, s33, v[112:113]
	v_rcp_f32_e32 v2, v2
	v_lshl_add_u64 v[16:17], v[16:17], 0, s[12:13]
	v_lshl_add_u64 v[16:17], v[16:17], 0, s[66:67]
	v_lshl_add_u64 v[16:17], v[16:17], 0, v[144:145]
	v_mul_f32_e32 v0, v0, v1
	v_mul_f32_e32 v1, v3, v7
	global_store_dwordx4 v[16:17], v[24:27], off
	v_add_u32_e32 v16, 0xb0, v139
	v_mul_f32_e32 v1, v1, v2
	v_cvt_pk_bf16_f32 v11, v0, v1
	v_mad_i64_i32 v[0:1], s[16:17], v16, s33, v[112:113]
	v_lshl_add_u64 v[0:1], v[0:1], 0, s[12:13]
	v_lshl_add_u64 v[0:1], v[0:1], 0, s[66:67]
	v_lshl_add_u64 v[0:1], v[0:1], 0, v[144:145]
	s_and_b64 vcc, exec, s[0:1]
	s_mov_b32 s15, s6
	s_mov_b32 s71, s70
	s_mov_b64 s[16:17], s[10:11]
	s_mov_b64 s[12:13], s[8:9]
	global_store_dwordx4 v[0:1], v[8:11], off
	s_cbranch_vccz .LBB0_278
	s_waitcnt vmcnt(0)
	s_cmpk_gt_u32 s3, 0xff
	s_cbranch_scc1 .LBB0_285
	s_barrier

; #define PG8_STAGE(bufoff, gbase, voff) do { _Pragma("unroll") for (int _i = 0; _i < 2; ++_i) \
;         __builtin_amdgcn_global_load_lds((const unsigned*)((const char*)(gbase) + (voff)[_i]), (LAS unsigned*)(lds + (bufoff) + ldsw + _i * 8192), 16, 0, 0); } while (0)
; #define PG8_LDA(dst, b, h) do { _Pragma("unroll") for (int m = 0; m < 4; ++m) _Pragma("unroll") for (int k = 0; k < 2; ++k) dst[m][k] = *(const LAS bf16x8*)(lds + PG8_SA(b, h) + aoff + m * 2048 + k * 1024); } while (0)
; #define PG8_LDB(dst, b, h) do { _Pragma("unroll") for (int n = 0; n < 2; ++n) _Pragma("unroll") for (int k = 0; k < 2; ++k) dst[n][k] = *(const LAS bf16x8*)(lds + PG8_SB(b, h) + boff + n * 2048 + k * 1024); } while (0)
; #define PG8_MMA(ai, bj, At, Bt) do { __builtin_amdgcn_s_setprio(1); _Pragma("unroll") for (int m = 0; m < 4; ++m) _Pragma("unroll") for (int n = 0; n < 2; ++n) _Pragma("unroll") for (int k = 0; k < 2; ++k) \
;         acc[ai][bj][m][n] = __builtin_amdgcn_mfma_f32_16x16x32_bf16(Bt[n][k], At[m][k], acc[ai][bj][m][n], 0, 0, 0); __builtin_amdgcn_s_setprio(0); } while (0)
; #define PG8_WAIT_L(n) asm volatile("s_waitcnt lgkmcnt(" #n ")" ::: "memory")
; #define PG8_BAR __builtin_amdgcn_s_barrier()
; #define PG8_SCHED __builtin_amdgcn_sched_barrier(0)
; template <class Epi>
; __device__ __forceinline__ void gemm_phase(LAS unsigned char* lds, const Gemm g, const StaticOrder& S, const Epi& E) {
;     ...
;             PG8_LDB(B0, 0, 0); PG8_SCHED; PG8_LDA(At, 0, 0); PG8_STAGE(PG8_SA(1, 1), a1 + hA, voffA);
;             PG8_WAIT_L(8); PG8_BAR; PG8_WAIT_L(0); PG8_MMA(0, 0, At, B0); PG8_BAR; PG8_SCHED;
;             PG8_LDB(B1, 0, 1); PG8_STAGE(PG8_SB(0, 0), b2, voffB);
;             PG8_BAR; PG8_WAIT_L(0); PG8_MMA(0, 1, At, B1); PG8_BAR;
;             PG8_LDA(At, 0, 1); PG8_STAGE(PG8_SA(0, 0), a2, voffA);
;             PG8_BAR; PG8_WAIT_L(0); PG8_MMA(1, 0, At, B0); PG8_BAR; PG8_SCHED;
.LBB0_349:
	s_add_u32 s12, s10, 0x100
	s_addc_u32 s13, s11, 0
	s_add_i32 s26, 0, 0x10000
	v_add_u32_e32 v142, s26, v139
	ds_read_b128 v[134:137], v142
	ds_read_b128 v[146:149], v142 offset:1024
	ds_read_b128 v[150:153], v142 offset:2048
	ds_read_b128 v[154:157], v142 offset:3072
	s_cmp_eq_u32 s72, 40
	s_cselect_b32 s21, s5, s13
	s_cselect_b32 s20, s4, s12
	s_cselect_b32 s17, s7, s25
	s_cselect_b32 s16, s6, s24
	s_add_i32 m0, s61, 0xc000
	ds_read_b128 v[158:161], v141
	ds_read_b128 v[162:165], v141 offset:1024
	ds_read_b128 v[166:169], v141 offset:2048
	ds_read_b128 v[170:173], v141 offset:3072
	ds_read_b128 v[174:177], v141 offset:4096
	ds_read_b128 v[178:181], v141 offset:5120
	ds_read_b128 v[182:185], v141 offset:6144
	ds_read_b128 v[196:199], v141 offset:7168
	global_load_lds_dwordx4 v130, s[10:11]
	s_add_i32 m0, s61, 0xe000
	v_lshl_add_u64 v[142:143], s[10:11], 0, v[132:133]
	global_load_lds_dwordx4 v[142:143], off
	s_waitcnt lgkmcnt(8)
	s_barrier
	s_waitcnt lgkmcnt(0)
	v_mfma_f32_16x16x32_bf16 v[124:127], v[134:137], v[158:161], v[124:127]
	v_mfma_f32_16x16x32_bf16 v[120:123], v[150:153], v[158:161], v[120:123]
	v_mfma_f32_16x16x32_bf16 v[116:119], v[134:137], v[166:169], v[116:119]
	v_mfma_f32_16x16x32_bf16 v[108:111], v[150:153], v[166:169], v[108:111]
	v_mfma_f32_16x16x32_bf16 v[100:103], v[134:137], v[174:177], v[100:103]
	v_mfma_f32_16x16x32_bf16 v[92:95], v[150:153], v[174:177], v[92:95]
	v_mfma_f32_16x16x32_bf16 v[84:87], v[134:137], v[182:185], v[84:87]
	v_mfma_f32_16x16x32_bf16 v[76:79], v[150:153], v[182:185], v[76:79]
	v_mfma_f32_16x16x32_bf16 v[124:127], v[146:149], v[162:165], v[124:127]
	v_mfma_f32_16x16x32_bf16 v[120:123], v[154:157], v[162:165], v[120:123]
	v_mfma_f32_16x16x32_bf16 v[116:119], v[146:149], v[170:173], v[116:119]
	v_mfma_f32_16x16x32_bf16 v[108:111], v[154:157], v[170:173], v[108:111]
	v_mfma_f32_16x16x32_bf16 v[100:103], v[146:149], v[178:181], v[100:103]
	v_mfma_f32_16x16x32_bf16 v[92:95], v[154:157], v[178:181], v[92:95]
	v_mfma_f32_16x16x32_bf16 v[84:87], v[146:149], v[196:199], v[84:87]
	v_mfma_f32_16x16x32_bf16 v[76:79], v[154:157], v[196:199], v[76:79]
	s_barrier
	s_add_i32 s27, 0, 0x14000
	v_add_u32_e32 v142, s27, v139
	s_add_i32 s10, s26, s35
	ds_read_b128 v[200:203], v142
	ds_read_b128 v[204:207], v142 offset:1024
	ds_read_b128 v[214:217], v142 offset:2048
	ds_read_b128 v[218:221], v142 offset:3072
	v_lshl_add_u64 v[142:143], s[16:17], 0, v[144:145]
	s_mov_b32 m0, s10
	v_lshl_add_u64 v[186:187], s[16:17], 0, v[128:129]
	global_load_lds_dwordx4 v[142:143], off
	s_add_i32 m0, s10, 0x2000
	s_nop 0
	global_load_lds_dwordx4 v[186:187], off
	s_barrier
	s_waitcnt lgkmcnt(0)
	v_mfma_f32_16x16x32_bf16 v[112:115], v[200:203], v[158:161], v[112:115]
	v_mfma_f32_16x16x32_bf16 v[104:107], v[214:217], v[158:161], v[104:107]
	v_mfma_f32_16x16x32_bf16 v[96:99], v[200:203], v[166:169], v[96:99]
	v_mfma_f32_16x16x32_bf16 v[88:91], v[214:217], v[166:169], v[88:91]
	v_mfma_f32_16x16x32_bf16 v[80:83], v[200:203], v[174:177], v[80:83]
	v_mfma_f32_16x16x32_bf16 v[72:75], v[214:217], v[174:177], v[72:75]
	v_mfma_f32_16x16x32_bf16 v[68:71], v[200:203], v[182:185], v[68:71]
	v_mfma_f32_16x16x32_bf16 v[64:67], v[214:217], v[182:185], v[64:67]
	v_mfma_f32_16x16x32_bf16 v[112:115], v[204:207], v[162:165], v[112:115]
	v_mfma_f32_16x16x32_bf16 v[104:107], v[218:221], v[162:165], v[104:107]
	v_mfma_f32_16x16x32_bf16 v[96:99], v[204:207], v[170:173], v[96:99]
	v_mfma_f32_16x16x32_bf16 v[88:91], v[218:221], v[170:173], v[88:91]
	v_mfma_f32_16x16x32_bf16 v[80:83], v[204:207], v[178:181], v[80:83]
	v_mfma_f32_16x16x32_bf16 v[72:75], v[218:221], v[178:181], v[72:75]
	v_mfma_f32_16x16x32_bf16 v[68:71], v[204:207], v[196:199], v[68:71]
	v_mfma_f32_16x16x32_bf16 v[64:67], v[218:221], v[196:199], v[64:67]
	s_mov_b32 m0, s61
	v_lshl_add_u64 v[188:189], s[20:21], 0, v[144:145]
	s_barrier
	ds_read_b128 v[158:161], v141 offset:16384
	ds_read_b128 v[162:165], v141 offset:17408
	ds_read_b128 v[166:169], v141 offset:18432
	ds_read_b128 v[170:173], v141 offset:19456
	ds_read_b128 v[174:177], v141 offset:20480
	ds_read_b128 v[178:181], v141 offset:21504
	ds_read_b128 v[182:185], v141 offset:22528
	ds_read_b128 v[196:199], v141 offset:23552
	global_load_lds_dwordx4 v[188:189], off
	s_mov_b32 m0, s62
	v_lshl_add_u64 v[192:193], s[20:21], 0, v[128:129]
	global_load_lds_dwordx4 v[192:193], off
	s_barrier
	s_waitcnt lgkmcnt(0)
	v_mfma_f32_16x16x32_bf16 v[60:63], v[134:137], v[158:161], v[60:63]
	v_mfma_f32_16x16x32_bf16 v[56:59], v[150:153], v[158:161], v[56:59]
	v_mfma_f32_16x16x32_bf16 v[52:55], v[134:137], v[166:169], v[52:55]
	v_mfma_f32_16x16x32_bf16 v[44:47], v[150:153], v[166:169], v[44:47]
	v_mfma_f32_16x16x32_bf16 v[36:39], v[134:137], v[174:177], v[36:39]
	v_mfma_f32_16x16x32_bf16 v[28:31], v[150:153], v[174:177], v[28:31]
	v_mfma_f32_16x16x32_bf16 v[20:23], v[134:137], v[182:185], v[20:23]
	v_mfma_f32_16x16x32_bf16 v[12:15], v[150:153], v[182:185], v[12:15]
	v_mfma_f32_16x16x32_bf16 v[60:63], v[146:149], v[162:165], v[60:63]
	v_mfma_f32_16x16x32_bf16 v[56:59], v[154:157], v[162:165], v[56:59]
	v_mfma_f32_16x16x32_bf16 v[52:55], v[146:149], v[170:173], v[52:55]
	v_mfma_f32_16x16x32_bf16 v[44:47], v[154:157], v[170:173], v[44:47]
	v_mfma_f32_16x16x32_bf16 v[36:39], v[146:149], v[178:181], v[36:39]
	v_mfma_f32_16x16x32_bf16 v[28:31], v[154:157], v[178:181], v[28:31]
	v_mfma_f32_16x16x32_bf16 v[20:23], v[146:149], v[196:199], v[20:23]
	v_mfma_f32_16x16x32_bf16 v[12:15], v[154:157], v[196:199], v[12:15]
	s_barrier
; #define PG8_STAGE(bufoff, gbase, voff) do { _Pragma("unroll") for (int _i = 0; _i < 2; ++_i) \
;         __builtin_amdgcn_global_load_lds((const unsigned*)((const char*)(gbase) + (voff)[_i]), (LAS unsigned*)(lds + (bufoff) + ldsw + _i * 8192), 16, 0, 0); } while (0)
; #define PG8_LDA(dst, b, h) do { _Pragma("unroll") for (int m = 0; m < 4; ++m) _Pragma("unroll") for (int k = 0; k < 2; ++k) dst[m][k] = *(const LAS bf16x8*)(lds + PG8_SA(b, h) + aoff + m * 2048 + k * 1024); } while (0)
; #define PG8_LDB(dst, b, h) do { _Pragma("unroll") for (int n = 0; n < 2; ++n) _Pragma("unroll") for (int k = 0; k < 2; ++k) dst[n][k] = *(const LAS bf16x8*)(lds + PG8_SB(b, h) + boff + n * 2048 + k * 1024); } while (0)
; #define PG8_MMA(ai, bj, At, Bt) do { __builtin_amdgcn_s_setprio(1); _Pragma("unroll") for (int m = 0; m < 4; ++m) _Pragma("unroll") for (int n = 0; n < 2; ++n) _Pragma("unroll") for (int k = 0; k < 2; ++k) \
;         acc[ai][bj][m][n] = __builtin_amdgcn_mfma_f32_16x16x32_bf16(Bt[n][k], At[m][k], acc[ai][bj][m][n], 0, 0, 0); __builtin_amdgcn_s_setprio(0); } while (0)
; #define PG8_WAIT_V(n) asm volatile("s_waitcnt vmcnt(" #n ")" ::: "memory")
; #define PG8_WAIT_L(n) asm volatile("s_waitcnt lgkmcnt(" #n ")" ::: "memory")
; #define PG8_BAR __builtin_amdgcn_s_barrier()
; #define PG8_SCHED __builtin_amdgcn_sched_barrier(0)
; template <class Epi>
; __device__ __forceinline__ void gemm_phase(LAS unsigned char* lds, const Gemm g, const StaticOrder& S, const Epi& E) {
;     ...
;             PG8_STAGE(PG8_SB(0, 1), b2 + hB, voffB);
;             PG8_WAIT_V(6); PG8_BAR; PG8_MMA(1, 1, At, B1); PG8_BAR;
;             PG8_LDB(B0, 1, 0); PG8_SCHED; PG8_LDA(At, 1, 0); PG8_STAGE(PG8_SA(0, 1), a2 + hA, voffA);
;             PG8_WAIT_L(8); PG8_BAR; PG8_WAIT_L(0); PG8_MMA(0, 0, At, B0); PG8_BAR; PG8_SCHED;
;             PG8_LDB(B1, 1, 1); PG8_STAGE(PG8_SB(1, 0), b3, voffB);
;             PG8_BAR; PG8_WAIT_L(0); PG8_MMA(0, 1, At, B1); PG8_BAR;
;             PG8_LDA(At, 1, 1); PG8_STAGE(PG8_SA(1, 0), a3, voffA);
	s_add_u32 s10, s16, 0xb0000
	s_addc_u32 s11, s17, 0
	s_add_i32 s26, s27, s35
	s_mov_b32 m0, s26
	s_nop 0
	global_load_lds_dwordx4 v144, s[10:11]
	s_add_i32 m0, s26, 0x2000
	s_nop 0
	global_load_lds_dwordx4 v128, s[10:11]
	s_waitcnt vmcnt(6)
	s_barrier
	v_mfma_f32_16x16x32_bf16 v[48:51], v[200:203], v[158:161], v[48:51]
	v_mfma_f32_16x16x32_bf16 v[40:43], v[214:217], v[158:161], v[40:43]
	v_mfma_f32_16x16x32_bf16 v[32:35], v[200:203], v[166:169], v[32:35]
	v_mfma_f32_16x16x32_bf16 v[24:27], v[214:217], v[166:169], v[24:27]
	v_mfma_f32_16x16x32_bf16 v[16:19], v[200:203], v[174:177], v[16:19]
	v_mfma_f32_16x16x32_bf16 v[8:11], v[214:217], v[174:177], v[8:11]
	v_mfma_f32_16x16x32_bf16 v[4:7], v[200:203], v[182:185], v[4:7]
	v_mfma_f32_16x16x32_bf16 v[0:3], v[214:217], v[182:185], v[0:3]
	v_mfma_f32_16x16x32_bf16 v[48:51], v[204:207], v[162:165], v[48:51]
	v_mfma_f32_16x16x32_bf16 v[40:43], v[218:221], v[162:165], v[40:43]
	v_mfma_f32_16x16x32_bf16 v[32:35], v[204:207], v[170:173], v[32:35]
	v_mfma_f32_16x16x32_bf16 v[24:27], v[218:221], v[170:173], v[24:27]
	v_mfma_f32_16x16x32_bf16 v[16:19], v[204:207], v[178:181], v[16:19]
	v_mfma_f32_16x16x32_bf16 v[8:11], v[218:221], v[178:181], v[8:11]
	v_mfma_f32_16x16x32_bf16 v[4:7], v[204:207], v[196:199], v[4:7]
	v_mfma_f32_16x16x32_bf16 v[0:3], v[218:221], v[196:199], v[0:3]
	s_add_i32 s26, 0, 0x18000
	v_add_u32_e32 v154, s26, v139
	s_barrier
	ds_read_b128 v[134:137], v154
	ds_read_b128 v[146:149], v154 offset:1024
	ds_read_b128 v[150:153], v154 offset:2048
	ds_read_b128 v[154:157], v154 offset:3072
	s_add_u32 s10, s20, 0xb0000
	s_addc_u32 s11, s21, 0
	s_mov_b32 m0, s63
	ds_read_b128 v[158:161], v141 offset:32768
	ds_read_b128 v[162:165], v141 offset:33792
	ds_read_b128 v[166:169], v141 offset:34816
	ds_read_b128 v[170:173], v141 offset:35840
	ds_read_b128 v[174:177], v141 offset:36864
	ds_read_b128 v[178:181], v141 offset:37888
	ds_read_b128 v[182:185], v141 offset:38912
	global_load_lds_dwordx4 v144, s[10:11]
	s_mov_b32 m0, s64
	ds_read_b128 v[196:199], v141 offset:39936
	global_load_lds_dwordx4 v128, s[10:11]
	s_waitcnt lgkmcnt(8)
	s_barrier
	s_waitcnt lgkmcnt(0)
	v_mfma_f32_16x16x32_bf16 v[124:127], v[134:137], v[158:161], v[124:127]
	v_mfma_f32_16x16x32_bf16 v[120:123], v[150:153], v[158:161], v[120:123]
	v_mfma_f32_16x16x32_bf16 v[116:119], v[134:137], v[166:169], v[116:119]
	v_mfma_f32_16x16x32_bf16 v[108:111], v[150:153], v[166:169], v[108:111]
	v_mfma_f32_16x16x32_bf16 v[100:103], v[134:137], v[174:177], v[100:103]
	v_mfma_f32_16x16x32_bf16 v[92:95], v[150:153], v[174:177], v[92:95]
	v_mfma_f32_16x16x32_bf16 v[84:87], v[134:137], v[182:185], v[84:87]
	v_mfma_f32_16x16x32_bf16 v[76:79], v[150:153], v[182:185], v[76:79]
	v_mfma_f32_16x16x32_bf16 v[124:127], v[146:149], v[162:165], v[124:127]
	v_mfma_f32_16x16x32_bf16 v[120:123], v[154:157], v[162:165], v[120:123]
	v_mfma_f32_16x16x32_bf16 v[116:119], v[146:149], v[170:173], v[116:119]
	v_mfma_f32_16x16x32_bf16 v[108:111], v[154:157], v[170:173], v[108:111]
	v_mfma_f32_16x16x32_bf16 v[100:103], v[146:149], v[178:181], v[100:103]
	v_mfma_f32_16x16x32_bf16 v[92:95], v[154:157], v[178:181], v[92:95]
	v_mfma_f32_16x16x32_bf16 v[84:87], v[146:149], v[196:199], v[84:87]
	v_mfma_f32_16x16x32_bf16 v[76:79], v[154:157], v[196:199], v[76:79]
	s_barrier
	s_add_i32 s20, 0, 0x1c000
	s_add_i32 s10, s26, s35
	v_add_u32_e32 v190, s20, v139
	v_lshl_add_u64 v[142:143], v[142:143], 0, s[88:89]
	s_mov_b32 m0, s10
	ds_read_b128 v[200:203], v190
	ds_read_b128 v[204:207], v190 offset:1024
	ds_read_b128 v[214:217], v190 offset:2048
	ds_read_b128 v[218:221], v190 offset:3072
	global_load_lds_dwordx4 v[142:143], off
	s_add_i32 m0, s10, 0x2000
	v_lshl_add_u64 v[142:143], v[186:187], 0, s[88:89]
	global_load_lds_dwordx4 v[142:143], off
	s_barrier
	s_waitcnt lgkmcnt(0)
	v_mfma_f32_16x16x32_bf16 v[112:115], v[200:203], v[158:161], v[112:115]
	v_mfma_f32_16x16x32_bf16 v[104:107], v[214:217], v[158:161], v[104:107]
	v_mfma_f32_16x16x32_bf16 v[96:99], v[200:203], v[166:169], v[96:99]
	v_mfma_f32_16x16x32_bf16 v[88:91], v[214:217], v[166:169], v[88:91]
	v_mfma_f32_16x16x32_bf16 v[80:83], v[200:203], v[174:177], v[80:83]
	v_mfma_f32_16x16x32_bf16 v[72:75], v[214:217], v[174:177], v[72:75]
	v_mfma_f32_16x16x32_bf16 v[68:71], v[200:203], v[182:185], v[68:71]
	v_mfma_f32_16x16x32_bf16 v[64:67], v[214:217], v[182:185], v[64:67]
	v_mfma_f32_16x16x32_bf16 v[112:115], v[204:207], v[162:165], v[112:115]
	v_mfma_f32_16x16x32_bf16 v[104:107], v[218:221], v[162:165], v[104:107]
	v_mfma_f32_16x16x32_bf16 v[96:99], v[204:207], v[170:173], v[96:99]
	v_mfma_f32_16x16x32_bf16 v[88:91], v[218:221], v[170:173], v[88:91]
	v_mfma_f32_16x16x32_bf16 v[80:83], v[204:207], v[178:181], v[80:83]
	v_mfma_f32_16x16x32_bf16 v[72:75], v[218:221], v[178:181], v[72:75]
	v_mfma_f32_16x16x32_bf16 v[68:71], v[204:207], v[196:199], v[68:71]
	v_mfma_f32_16x16x32_bf16 v[64:67], v[218:221], v[196:199], v[64:67]
	s_mov_b32 m0, s65
	v_lshl_add_u64 v[142:143], v[188:189], 0, s[88:89]
	s_barrier
	ds_read_b128 v[158:161], v141 offset:49152
	ds_read_b128 v[162:165], v141 offset:50176
	ds_read_b128 v[166:169], v141 offset:51200
	ds_read_b128 v[170:173], v141 offset:52224
	ds_read_b128 v[174:177], v141 offset:53248
	ds_read_b128 v[178:181], v141 offset:54272
	ds_read_b128 v[182:185], v141 offset:55296
	ds_read_b128 v[196:199], v141 offset:56320
	global_load_lds_dwordx4 v[142:143], off
	s_mov_b32 m0, s66
	v_lshl_add_u64 v[142:143], v[192:193], 0, s[88:89]
	global_load_lds_dwordx4 v[142:143], off
	s_barrier
; #define PG8_STAGE(bufoff, gbase, voff) do { _Pragma("unroll") for (int _i = 0; _i < 2; ++_i) \
;         __builtin_amdgcn_global_load_lds((const unsigned*)((const char*)(gbase) + (voff)[_i]), (LAS unsigned*)(lds + (bufoff) + ldsw + _i * 8192), 16, 0, 0); } while (0)
; #define PG8_MMA(ai, bj, At, Bt) do { __builtin_amdgcn_s_setprio(1); _Pragma("unroll") for (int m = 0; m < 4; ++m) _Pragma("unroll") for (int n = 0; n < 2; ++n) _Pragma("unroll") for (int k = 0; k < 2; ++k) \
;         acc[ai][bj][m][n] = __builtin_amdgcn_mfma_f32_16x16x32_bf16(Bt[n][k], At[m][k], acc[ai][bj][m][n], 0, 0, 0); __builtin_amdgcn_s_setprio(0); } while (0)
; #define PG8_WAIT_V(n) asm volatile("s_waitcnt vmcnt(" #n ")" ::: "memory")
; #define PG8_WAIT_L(n) asm volatile("s_waitcnt lgkmcnt(" #n ")" ::: "memory")
; #define PG8_BAR __builtin_amdgcn_s_barrier()
; #define PG8_SCHED __builtin_amdgcn_sched_barrier(0)
; template <class Epi>
; __device__ __forceinline__ void gemm_phase(LAS unsigned char* lds, const Gemm g, const StaticOrder& S, const Epi& E) {
;     ...
;             PG8_BAR; PG8_WAIT_L(0); PG8_MMA(1, 0, At, B0); PG8_BAR; PG8_SCHED;
;             PG8_STAGE(PG8_SB(1, 1), b3 + hB, voffB);
;             PG8_WAIT_V(6); PG8_BAR; PG8_MMA(1, 1, At, B1); PG8_BAR;
	s_waitcnt lgkmcnt(0)
	v_mfma_f32_16x16x32_bf16 v[60:63], v[134:137], v[158:161], v[60:63]
	v_mfma_f32_16x16x32_bf16 v[56:59], v[150:153], v[158:161], v[56:59]
	v_mfma_f32_16x16x32_bf16 v[52:55], v[134:137], v[166:169], v[52:55]
	v_mfma_f32_16x16x32_bf16 v[44:47], v[150:153], v[166:169], v[44:47]
	v_mfma_f32_16x16x32_bf16 v[36:39], v[134:137], v[174:177], v[36:39]
	v_mfma_f32_16x16x32_bf16 v[28:31], v[150:153], v[174:177], v[28:31]
	v_mfma_f32_16x16x32_bf16 v[20:23], v[134:137], v[182:185], v[20:23]
	v_mfma_f32_16x16x32_bf16 v[12:15], v[150:153], v[182:185], v[12:15]
	v_mfma_f32_16x16x32_bf16 v[60:63], v[146:149], v[162:165], v[60:63]
	v_mfma_f32_16x16x32_bf16 v[56:59], v[154:157], v[162:165], v[56:59]
	v_mfma_f32_16x16x32_bf16 v[52:55], v[146:149], v[170:173], v[52:55]
	v_mfma_f32_16x16x32_bf16 v[44:47], v[154:157], v[170:173], v[44:47]
	v_mfma_f32_16x16x32_bf16 v[36:39], v[146:149], v[178:181], v[36:39]
	v_mfma_f32_16x16x32_bf16 v[28:31], v[154:157], v[178:181], v[28:31]
	v_mfma_f32_16x16x32_bf16 v[20:23], v[146:149], v[196:199], v[20:23]
	v_mfma_f32_16x16x32_bf16 v[12:15], v[154:157], v[196:199], v[12:15]
	s_barrier
	s_add_u32 s10, s16, 0xb0080
	s_addc_u32 s11, s17, 0
	s_add_i32 s16, s20, s35
	s_mov_b32 m0, s16
	s_nop 0
	global_load_lds_dwordx4 v144, s[10:11]
	s_add_i32 m0, s16, 0x2000
	s_nop 0
	global_load_lds_dwordx4 v128, s[10:11]
	s_waitcnt vmcnt(6)
	s_barrier
	v_mfma_f32_16x16x32_bf16 v[48:51], v[200:203], v[158:161], v[48:51]
	v_mfma_f32_16x16x32_bf16 v[40:43], v[214:217], v[158:161], v[40:43]
	v_mfma_f32_16x16x32_bf16 v[32:35], v[200:203], v[166:169], v[32:35]
	v_mfma_f32_16x16x32_bf16 v[24:27], v[214:217], v[166:169], v[24:27]
	v_mfma_f32_16x16x32_bf16 v[16:19], v[200:203], v[174:177], v[16:19]
	v_mfma_f32_16x16x32_bf16 v[8:11], v[214:217], v[174:177], v[8:11]
	v_mfma_f32_16x16x32_bf16 v[4:7], v[200:203], v[182:185], v[4:7]
	v_mfma_f32_16x16x32_bf16 v[0:3], v[214:217], v[182:185], v[0:3]
	v_mfma_f32_16x16x32_bf16 v[48:51], v[204:207], v[162:165], v[48:51]
	v_mfma_f32_16x16x32_bf16 v[40:43], v[218:221], v[162:165], v[40:43]
	v_mfma_f32_16x16x32_bf16 v[32:35], v[204:207], v[170:173], v[32:35]
	v_mfma_f32_16x16x32_bf16 v[24:27], v[218:221], v[170:173], v[24:27]
	v_mfma_f32_16x16x32_bf16 v[16:19], v[204:207], v[178:181], v[16:19]
	v_mfma_f32_16x16x32_bf16 v[8:11], v[218:221], v[178:181], v[8:11]
	v_mfma_f32_16x16x32_bf16 v[4:7], v[204:207], v[196:199], v[4:7]
	v_mfma_f32_16x16x32_bf16 v[0:3], v[218:221], v[196:199], v[0:3]
	s_add_i32 s72, s72, 2
	s_add_u32 s24, s24, 0x100
	s_addc_u32 s25, s25, 0
	s_cmp_gt_u32 s72, 41
	s_mov_b64 s[10:11], s[12:13]
	s_barrier
	s_cbranch_scc0 .LBB0_349
; __device__ __forceinline__ unsigned pk2(float lo, float hi) { unsigned r; asm("v_cvt_pk_bf16_f32 %0, %1, %2" : "=v"(r) : "v"(lo), "v"(hi)); return r; }
; #define PG8_WAIT_V(n) asm volatile("s_waitcnt vmcnt(" #n ")" ::: "memory")
; #define PG8_BAR __builtin_amdgcn_s_barrier()
; template <class Epi>
; __device__ __forceinline__ void gemm_phase(LAS unsigned char* lds, const Gemm g, const StaticOrder& S, const Epi& E) {
;     ...
;         E(acc, cur, wr, wc, fr, fq);
;         if (!has_next) break;
; #pragma unroll
;         for (int a = 0; a < 2; ++a)
; #pragma unroll
;             for (int b = 0; b < 2; ++b)
; #pragma unroll
;                 for (int m = 0; m < 4; ++m)
; #pragma unroll
;                     for (int n = 0; n < 2; ++n) acc[a][b][m][n] = (f32x4){0.f, 0.f, 0.f, 0.f};
;         cur = nxt; cA = nA; cB = nB; ++ui;
;     }
;     PG8_WAIT_V(0);
;     if (wr == 0) PG8_BAR;
;     __device__ __forceinline__ void operator()(const f32x4 (&acc)[2][2][4][2], const Unit& u, int wr, int wc, int fr, int fq) const {
;     ...
;         const int row_t = rmap == 1 ? odd_phys_row0(u.pm, grp) : (rmap == 2 ? odd_phys_row0(u.pm % (BG * TPB), u.pm / (BG * TPB)) : u.pm * BM);
;         int c = col_t + 64 * wc + 16 * fq;
;         if (mode == 2) c = (c >> 6) * 96 + (c & 63);
; #pragma unroll
;         for (int ai = 0; ai < 2; ++ai)
; #pragma unroll
;             for (int m = 0; m < 4; ++m) {
;                 const int row = row_t + ai * HALF + wr * 64 + m * 16 + fr;
;                 bf16_t* rp = O + (size_t)row * ldc + c;
; #pragma unroll
;                 for (int bj = 0; bj < 2; ++bj) {
;                     const f32x4 v0 = acc[ai][bj][m][0], v1 = acc[ai][bj][m][1];
;                     u32x4 o; o.x = pk2(v0[0], v0[1]); o.y = pk2(v0[2], v0[3]); o.z = pk2(v1[0], v1[1]); o.w = pk2(v1[2], v1[3]);
;                     *(u32x4*)(rp + 8 * bj) = o;
;                 }
;             }
	v_lshl_add_u32 v134, s71, 8, v138
	v_cvt_pk_bf16_f32 v68, v68, v69
	v_cvt_pk_bf16_f32 v69, v70, v71
	v_cvt_pk_bf16_f32 v70, v64, v65
	v_add_u32_e32 v64, 0x80, v134
	v_lshl_or_b32 v136, s15, 8, v140
	v_ashrrev_i32_e32 v135, 31, v134
	v_cvt_pk_bf16_f32 v112, v112, v113
	v_cvt_pk_bf16_f32 v113, v114, v115
	v_cvt_pk_bf16_f32 v114, v104, v105
	v_or_b32_e32 v104, 16, v134
	v_ashrrev_i32_e32 v65, 31, v64
	v_cvt_pk_bf16_f32 v48, v48, v49
	v_cvt_pk_bf16_f32 v49, v50, v51
	v_cvt_pk_bf16_f32 v50, v40, v41
	v_add_u32_e32 v40, 0x90, v134
	v_ashrrev_i32_e32 v137, 31, v136
	v_lshlrev_b64 v[142:143], 11, v[134:135]
	v_ashrrev_i32_e32 v105, 31, v104
	v_cvt_pk_bf16_f32 v96, v96, v97
	v_cvt_pk_bf16_f32 v97, v98, v99
	v_cvt_pk_bf16_f32 v98, v88, v89
	v_or_b32_e32 v88, 32, v134
	v_lshlrev_b64 v[64:65], 11, v[64:65]
	v_ashrrev_i32_e32 v41, 31, v40
	v_cvt_pk_bf16_f32 v32, v32, v33
	v_cvt_pk_bf16_f32 v33, v34, v35
	v_cvt_pk_bf16_f32 v34, v24, v25
	v_add_u32_e32 v24, 0xa0, v134
	v_lshl_add_u64 v[142:143], s[8:9], 0, v[142:143]
	v_lshlrev_b64 v[136:137], 1, v[136:137]
	v_lshlrev_b64 v[104:105], 11, v[104:105]
	v_ashrrev_i32_e32 v89, 31, v88
	v_cvt_pk_bf16_f32 v80, v80, v81
	v_cvt_pk_bf16_f32 v81, v82, v83
	v_cvt_pk_bf16_f32 v82, v72, v73
	v_or_b32_e32 v72, 48, v134
	v_lshl_add_u64 v[64:65], s[8:9], 0, v[64:65]
	v_lshlrev_b64 v[40:41], 11, v[40:41]
	v_ashrrev_i32_e32 v25, 31, v24
	v_cvt_pk_bf16_f32 v16, v16, v17
	v_cvt_pk_bf16_f32 v17, v18, v19
	v_cvt_pk_bf16_f32 v18, v8, v9
	v_add_u32_e32 v8, 0xb0, v134
	v_lshl_add_u64 v[142:143], v[142:143], 0, v[136:137]
	v_lshl_add_u64 v[104:105], s[8:9], 0, v[104:105]
	v_lshlrev_b64 v[88:89], 11, v[88:89]
	v_ashrrev_i32_e32 v73, 31, v72
	v_lshl_add_u64 v[64:65], v[64:65], 0, v[136:137]
	v_lshl_add_u64 v[40:41], s[8:9], 0, v[40:41]
	v_lshlrev_b64 v[24:25], 11, v[24:25]
	v_ashrrev_i32_e32 v9, 31, v8
	v_cvt_pk_bf16_f32 v115, v106, v107
	global_store_dwordx4 v[142:143], v[112:115], off offset:16
	v_lshl_add_u64 v[88:89], s[8:9], 0, v[88:89]
	v_lshlrev_b64 v[72:73], 11, v[72:73]
	v_lshl_add_u64 v[112:113], v[104:105], 0, v[136:137]
	v_cvt_pk_bf16_f32 v51, v42, v43
	global_store_dwordx4 v[64:65], v[48:51], off offset:16
	v_lshl_add_u64 v[24:25], s[8:9], 0, v[24:25]
	v_lshlrev_b64 v[8:9], 11, v[8:9]
	v_lshl_add_u64 v[48:49], v[40:41], 0, v[136:137]
	v_cvt_pk_bf16_f32 v99, v90, v91
	global_store_dwordx4 v[112:113], v[96:99], off offset:16
	v_lshl_add_u64 v[72:73], s[8:9], 0, v[72:73]
	v_cvt_pk_bf16_f32 v35, v26, v27
	global_store_dwordx4 v[48:49], v[32:35], off offset:16
	v_lshl_add_u64 v[96:97], v[88:89], 0, v[136:137]
	v_lshl_add_u64 v[8:9], s[8:9], 0, v[8:9]
	v_lshl_add_u64 v[32:33], v[24:25], 0, v[136:137]
	v_cvt_pk_bf16_f32 v83, v74, v75
	global_store_dwordx4 v[96:97], v[80:83], off offset:16
	v_cvt_pk_bf16_f32 v19, v10, v11
	global_store_dwordx4 v[32:33], v[16:19], off offset:16
	s_and_b64 vcc, exec, s[0:1]
	v_lshl_add_u64 v[80:81], v[72:73], 0, v[136:137]
	v_lshl_add_u64 v[16:17], v[8:9], 0, v[136:137]
	s_mov_b32 s15, s69
	s_mov_b32 s71, s70
	s_mov_b64 s[12:13], s[6:7]
	s_mov_b64 s[10:11], s[4:5]
	v_cvt_pk_bf16_f32 v124, v124, v125
	v_cvt_pk_bf16_f32 v125, v126, v127
	v_cvt_pk_bf16_f32 v126, v120, v121
	v_cvt_pk_bf16_f32 v127, v122, v123
	global_store_dwordx4 v[142:143], v[124:127], off
	v_cvt_pk_bf16_f32 v104, v116, v117
	v_cvt_pk_bf16_f32 v105, v118, v119
	v_cvt_pk_bf16_f32 v106, v108, v109
	v_cvt_pk_bf16_f32 v107, v110, v111
	global_store_dwordx4 v[112:113], v[104:107], off
	v_cvt_pk_bf16_f32 v88, v100, v101
	v_cvt_pk_bf16_f32 v89, v102, v103
	v_cvt_pk_bf16_f32 v90, v92, v93
	v_cvt_pk_bf16_f32 v91, v94, v95
	global_store_dwordx4 v[96:97], v[88:91], off
	v_cvt_pk_bf16_f32 v72, v84, v85
	v_cvt_pk_bf16_f32 v73, v86, v87
	v_cvt_pk_bf16_f32 v74, v76, v77
	v_cvt_pk_bf16_f32 v75, v78, v79
	global_store_dwordx4 v[80:81], v[72:75], off
	v_cvt_pk_bf16_f32 v71, v66, v67
	global_store_dwordx4 v[80:81], v[68:71], off offset:16
	v_cvt_pk_bf16_f32 v60, v60, v61
	v_cvt_pk_bf16_f32 v61, v62, v63
	v_cvt_pk_bf16_f32 v62, v56, v57
	v_cvt_pk_bf16_f32 v63, v58, v59
	global_store_dwordx4 v[64:65], v[60:63], off
	v_cvt_pk_bf16_f32 v40, v52, v53
	v_cvt_pk_bf16_f32 v41, v54, v55
	v_cvt_pk_bf16_f32 v42, v44, v45
	v_cvt_pk_bf16_f32 v43, v46, v47
	global_store_dwordx4 v[48:49], v[40:43], off
	v_cvt_pk_bf16_f32 v24, v36, v37
	v_cvt_pk_bf16_f32 v25, v38, v39
	v_cvt_pk_bf16_f32 v26, v28, v29
	v_cvt_pk_bf16_f32 v27, v30, v31
	global_store_dwordx4 v[32:33], v[24:27], off
	v_cvt_pk_bf16_f32 v8, v20, v21
	v_cvt_pk_bf16_f32 v9, v22, v23
	v_cvt_pk_bf16_f32 v10, v12, v13
	v_cvt_pk_bf16_f32 v11, v14, v15
	global_store_dwordx4 v[16:17], v[8:11], off
	v_cvt_pk_bf16_f32 v4, v4, v5
	v_cvt_pk_bf16_f32 v5, v6, v7
	v_cvt_pk_bf16_f32 v6, v0, v1
	v_cvt_pk_bf16_f32 v7, v2, v3
	global_store_dwordx4 v[16:17], v[4:7], off offset:16
	s_cbranch_vccz .LBB0_342
	s_waitcnt vmcnt(0)
	s_cmpk_gt_u32 s3, 0xff
	s_cbranch_scc1 .LBB0_353
	s_barrier

; #define PG8_STAGE(bufoff, gbase, voff) do { _Pragma("unroll") for (int _i = 0; _i < 2; ++_i) \
;         __builtin_amdgcn_global_load_lds((const unsigned*)((const char*)(gbase) + (voff)[_i]), (LAS unsigned*)(lds + (bufoff) + ldsw + _i * 8192), 16, 0, 0); } while (0)
; #define PG8_LDA(dst, b, h) do { _Pragma("unroll") for (int m = 0; m < 4; ++m) _Pragma("unroll") for (int k = 0; k < 2; ++k) dst[m][k] = *(const LAS bf16x8*)(lds + PG8_SA(b, h) + aoff + m * 2048 + k * 1024); } while (0)
; #define PG8_LDB(dst, b, h) do { _Pragma("unroll") for (int n = 0; n < 2; ++n) _Pragma("unroll") for (int k = 0; k < 2; ++k) dst[n][k] = *(const LAS bf16x8*)(lds + PG8_SB(b, h) + boff + n * 2048 + k * 1024); } while (0)
; #define PG8_MMA(ai, bj, At, Bt) do { __builtin_amdgcn_s_setprio(1); _Pragma("unroll") for (int m = 0; m < 4; ++m) _Pragma("unroll") for (int n = 0; n < 2; ++n) _Pragma("unroll") for (int k = 0; k < 2; ++k) \
;         acc[ai][bj][m][n] = __builtin_amdgcn_mfma_f32_16x16x32_bf16(Bt[n][k], At[m][k], acc[ai][bj][m][n], 0, 0, 0); __builtin_amdgcn_s_setprio(0); } while (0)
; #define PG8_WAIT_L(n) asm volatile("s_waitcnt lgkmcnt(" #n ")" ::: "memory")
; #define PG8_BAR __builtin_amdgcn_s_barrier()
; #define PG8_SCHED __builtin_amdgcn_sched_barrier(0)
; template <class Epi>
; __device__ __forceinline__ void gemm_phase(LAS unsigned char* lds, const Gemm g, const StaticOrder& S, const Epi& E) {
;     ...
;             PG8_LDB(B0, 0, 0); PG8_SCHED; PG8_LDA(At, 0, 0); PG8_STAGE(PG8_SA(1, 1), a1 + hA, voffA);
;             PG8_WAIT_L(8); PG8_BAR; PG8_WAIT_L(0); PG8_MMA(0, 0, At, B0); PG8_BAR; PG8_SCHED;
;             PG8_LDB(B1, 0, 1); PG8_STAGE(PG8_SB(0, 0), b2, voffB);
;             PG8_BAR; PG8_WAIT_L(0); PG8_MMA(0, 1, At, B1); PG8_BAR;
;             PG8_LDA(At, 0, 1); PG8_STAGE(PG8_SA(0, 0), a2, voffA);
;             PG8_BAR; PG8_WAIT_L(0); PG8_MMA(1, 0, At, B0); PG8_BAR; PG8_SCHED;
.LBB0_499:
	s_add_u32 s26, s4, 0xfffc0080
	s_addc_u32 s27, s5, -1
	s_add_i32 s28, 0, 0x10000
	v_add_u32_e32 v146, s28, v149
	ds_read_b128 v[136:139], v146
	ds_read_b128 v[140:143], v146 offset:1024
	ds_read_b128 v[158:161], v146 offset:2048
	ds_read_b128 v[162:165], v146 offset:3072
	s_cmp_eq_u32 s84, 12
	s_cselect_b32 s65, s21, s27
	s_cselect_b32 s64, s20, s26
	s_cselect_b32 s35, s15, s25
	s_cselect_b32 s34, s17, s24
	s_add_i32 m0, s66, 0xc000
	ds_read_b128 v[166:169], v154
	ds_read_b128 v[170:173], v154 offset:1024
	ds_read_b128 v[174:177], v154 offset:2048
	ds_read_b128 v[178:181], v154 offset:3072
	ds_read_b128 v[182:185], v154 offset:4096
	ds_read_b128 v[196:199], v154 offset:5120
	ds_read_b128 v[200:203], v154 offset:6144
	ds_read_b128 v[204:207], v154 offset:7168
	global_load_lds_dwordx4 v132, s[4:5]
	s_add_i32 m0, s66, 0xe000
	v_lshl_add_u64 v[146:147], s[4:5], 0, v[134:135]
	global_load_lds_dwordx4 v[146:147], off
	s_waitcnt lgkmcnt(8)
	s_barrier
	s_waitcnt lgkmcnt(0)
	v_mfma_f32_16x16x32_bf16 v[124:127], v[136:139], v[166:169], v[124:127]
	v_mfma_f32_16x16x32_bf16 v[120:123], v[158:161], v[166:169], v[120:123]
	v_mfma_f32_16x16x32_bf16 v[116:119], v[136:139], v[174:177], v[116:119]
	v_mfma_f32_16x16x32_bf16 v[108:111], v[158:161], v[174:177], v[108:111]
	v_mfma_f32_16x16x32_bf16 v[100:103], v[136:139], v[182:185], v[100:103]
	v_mfma_f32_16x16x32_bf16 v[92:95], v[158:161], v[182:185], v[92:95]
	v_mfma_f32_16x16x32_bf16 v[84:87], v[136:139], v[200:203], v[84:87]
	v_mfma_f32_16x16x32_bf16 v[76:79], v[158:161], v[200:203], v[76:79]
	v_mfma_f32_16x16x32_bf16 v[124:127], v[140:143], v[170:173], v[124:127]
	v_mfma_f32_16x16x32_bf16 v[120:123], v[162:165], v[170:173], v[120:123]
	v_mfma_f32_16x16x32_bf16 v[116:119], v[140:143], v[178:181], v[116:119]
	v_mfma_f32_16x16x32_bf16 v[108:111], v[162:165], v[178:181], v[108:111]
	v_mfma_f32_16x16x32_bf16 v[100:103], v[140:143], v[196:199], v[100:103]
	v_mfma_f32_16x16x32_bf16 v[92:95], v[162:165], v[196:199], v[92:95]
	v_mfma_f32_16x16x32_bf16 v[84:87], v[140:143], v[204:207], v[84:87]
	v_mfma_f32_16x16x32_bf16 v[76:79], v[162:165], v[204:207], v[76:79]
	s_barrier
	s_add_i32 s29, 0, 0x14000
	v_add_u32_e32 v146, s29, v149
	s_add_i32 s26, s28, s71
	ds_read_b128 v[216:219], v146
	ds_read_b128 v[220:223], v146 offset:1024
	ds_read_b128 v[224:227], v146 offset:2048
	ds_read_b128 v[228:231], v146 offset:3072
	v_lshl_add_u64 v[146:147], s[34:35], 0, v[128:129]
	s_mov_b32 m0, s26
	v_lshl_add_u64 v[186:187], s[34:35], 0, v[130:131]
	global_load_lds_dwordx4 v[146:147], off
	s_add_i32 m0, s26, 0x2000
	s_nop 0
	global_load_lds_dwordx4 v[186:187], off
	s_barrier
	s_waitcnt lgkmcnt(0)
	v_mfma_f32_16x16x32_bf16 v[112:115], v[216:219], v[166:169], v[112:115]
	v_mfma_f32_16x16x32_bf16 v[104:107], v[224:227], v[166:169], v[104:107]
	v_mfma_f32_16x16x32_bf16 v[96:99], v[216:219], v[174:177], v[96:99]
	v_mfma_f32_16x16x32_bf16 v[88:91], v[224:227], v[174:177], v[88:91]
	v_mfma_f32_16x16x32_bf16 v[80:83], v[216:219], v[182:185], v[80:83]
	v_mfma_f32_16x16x32_bf16 v[72:75], v[224:227], v[182:185], v[72:75]
	v_mfma_f32_16x16x32_bf16 v[68:71], v[216:219], v[200:203], v[68:71]
	v_mfma_f32_16x16x32_bf16 v[64:67], v[224:227], v[200:203], v[64:67]
	v_mfma_f32_16x16x32_bf16 v[112:115], v[220:223], v[170:173], v[112:115]
	v_mfma_f32_16x16x32_bf16 v[104:107], v[228:231], v[170:173], v[104:107]
	v_mfma_f32_16x16x32_bf16 v[96:99], v[220:223], v[178:181], v[96:99]
	v_mfma_f32_16x16x32_bf16 v[88:91], v[228:231], v[178:181], v[88:91]
	v_mfma_f32_16x16x32_bf16 v[80:83], v[220:223], v[196:199], v[80:83]
	v_mfma_f32_16x16x32_bf16 v[72:75], v[228:231], v[196:199], v[72:75]
	v_mfma_f32_16x16x32_bf16 v[68:71], v[220:223], v[204:207], v[68:71]
	v_mfma_f32_16x16x32_bf16 v[64:67], v[228:231], v[204:207], v[64:67]
	s_mov_b32 m0, s66
	v_lshl_add_u64 v[188:189], s[64:65], 0, v[128:129]
	s_barrier
	ds_read_b128 v[166:169], v154 offset:16384
	ds_read_b128 v[170:173], v154 offset:17408
	ds_read_b128 v[174:177], v154 offset:18432
	ds_read_b128 v[178:181], v154 offset:19456
	ds_read_b128 v[182:185], v154 offset:20480
	ds_read_b128 v[196:199], v154 offset:21504
	ds_read_b128 v[200:203], v154 offset:22528
	ds_read_b128 v[204:207], v154 offset:23552
	global_load_lds_dwordx4 v[188:189], off
	s_mov_b32 m0, s72
	v_lshl_add_u64 v[192:193], s[64:65], 0, v[130:131]
	global_load_lds_dwordx4 v[192:193], off
	s_barrier
	s_waitcnt lgkmcnt(0)
	v_mfma_f32_16x16x32_bf16 v[60:63], v[136:139], v[166:169], v[60:63]
	v_mfma_f32_16x16x32_bf16 v[56:59], v[158:161], v[166:169], v[56:59]
	v_mfma_f32_16x16x32_bf16 v[52:55], v[136:139], v[174:177], v[52:55]
	v_mfma_f32_16x16x32_bf16 v[44:47], v[158:161], v[174:177], v[44:47]
	v_mfma_f32_16x16x32_bf16 v[36:39], v[136:139], v[182:185], v[36:39]
	v_mfma_f32_16x16x32_bf16 v[28:31], v[158:161], v[182:185], v[28:31]
	v_mfma_f32_16x16x32_bf16 v[20:23], v[136:139], v[200:203], v[20:23]
	v_mfma_f32_16x16x32_bf16 v[12:15], v[158:161], v[200:203], v[12:15]
	v_mfma_f32_16x16x32_bf16 v[60:63], v[140:143], v[170:173], v[60:63]
	v_mfma_f32_16x16x32_bf16 v[56:59], v[162:165], v[170:173], v[56:59]
	v_mfma_f32_16x16x32_bf16 v[52:55], v[140:143], v[178:181], v[52:55]
	v_mfma_f32_16x16x32_bf16 v[44:47], v[162:165], v[178:181], v[44:47]
	v_mfma_f32_16x16x32_bf16 v[36:39], v[140:143], v[196:199], v[36:39]
	v_mfma_f32_16x16x32_bf16 v[28:31], v[162:165], v[196:199], v[28:31]
	v_mfma_f32_16x16x32_bf16 v[20:23], v[140:143], v[204:207], v[20:23]
	v_mfma_f32_16x16x32_bf16 v[12:15], v[162:165], v[204:207], v[12:15]
	s_barrier
; #define PG8_STAGE(bufoff, gbase, voff) do { _Pragma("unroll") for (int _i = 0; _i < 2; ++_i) \
;         __builtin_amdgcn_global_load_lds((const unsigned*)((const char*)(gbase) + (voff)[_i]), (LAS unsigned*)(lds + (bufoff) + ldsw + _i * 8192), 16, 0, 0); } while (0)
; #define PG8_LDA(dst, b, h) do { _Pragma("unroll") for (int m = 0; m < 4; ++m) _Pragma("unroll") for (int k = 0; k < 2; ++k) dst[m][k] = *(const LAS bf16x8*)(lds + PG8_SA(b, h) + aoff + m * 2048 + k * 1024); } while (0)
; #define PG8_LDB(dst, b, h) do { _Pragma("unroll") for (int n = 0; n < 2; ++n) _Pragma("unroll") for (int k = 0; k < 2; ++k) dst[n][k] = *(const LAS bf16x8*)(lds + PG8_SB(b, h) + boff + n * 2048 + k * 1024); } while (0)
; #define PG8_MMA(ai, bj, At, Bt) do { __builtin_amdgcn_s_setprio(1); _Pragma("unroll") for (int m = 0; m < 4; ++m) _Pragma("unroll") for (int n = 0; n < 2; ++n) _Pragma("unroll") for (int k = 0; k < 2; ++k) \
;         acc[ai][bj][m][n] = __builtin_amdgcn_mfma_f32_16x16x32_bf16(Bt[n][k], At[m][k], acc[ai][bj][m][n], 0, 0, 0); __builtin_amdgcn_s_setprio(0); } while (0)
; #define PG8_WAIT_V(n) asm volatile("s_waitcnt vmcnt(" #n ")" ::: "memory")
; #define PG8_WAIT_L(n) asm volatile("s_waitcnt lgkmcnt(" #n ")" ::: "memory")
; #define PG8_BAR __builtin_amdgcn_s_barrier()
; #define PG8_SCHED __builtin_amdgcn_sched_barrier(0)
; template <class Epi>
; __device__ __forceinline__ void gemm_phase(LAS unsigned char* lds, const Gemm g, const StaticOrder& S, const Epi& E) {
;     ...
;             PG8_STAGE(PG8_SB(0, 1), b2 + hB, voffB);
;             PG8_WAIT_V(6); PG8_BAR; PG8_MMA(1, 1, At, B1); PG8_BAR;
;             PG8_LDB(B0, 1, 0); PG8_SCHED; PG8_LDA(At, 1, 0); PG8_STAGE(PG8_SA(0, 1), a2 + hA, voffA);
;             PG8_WAIT_L(8); PG8_BAR; PG8_WAIT_L(0); PG8_MMA(0, 0, At, B0); PG8_BAR; PG8_SCHED;
;             PG8_LDB(B1, 1, 1); PG8_STAGE(PG8_SB(1, 0), b3, voffB);
;             PG8_BAR; PG8_WAIT_L(0); PG8_MMA(0, 1, At, B1); PG8_BAR;
;             PG8_LDA(At, 1, 1); PG8_STAGE(PG8_SA(1, 0), a3, voffA);
	s_add_u32 s26, s34, 0x40000
	s_addc_u32 s27, s35, 0
	s_add_i32 s28, s29, s71
	s_mov_b32 m0, s28
	s_nop 0
	global_load_lds_dwordx4 v128, s[26:27]
	s_add_i32 m0, s28, 0x2000
	s_nop 0
	global_load_lds_dwordx4 v130, s[26:27]
	s_waitcnt vmcnt(6)
	s_barrier
	v_mfma_f32_16x16x32_bf16 v[48:51], v[216:219], v[166:169], v[48:51]
	v_mfma_f32_16x16x32_bf16 v[40:43], v[224:227], v[166:169], v[40:43]
	v_mfma_f32_16x16x32_bf16 v[32:35], v[216:219], v[174:177], v[32:35]
	v_mfma_f32_16x16x32_bf16 v[24:27], v[224:227], v[174:177], v[24:27]
	v_mfma_f32_16x16x32_bf16 v[16:19], v[216:219], v[182:185], v[16:19]
	v_mfma_f32_16x16x32_bf16 v[8:11], v[224:227], v[182:185], v[8:11]
	v_mfma_f32_16x16x32_bf16 v[4:7], v[216:219], v[200:203], v[4:7]
	v_mfma_f32_16x16x32_bf16 v[0:3], v[224:227], v[200:203], v[0:3]
	v_mfma_f32_16x16x32_bf16 v[48:51], v[220:223], v[170:173], v[48:51]
	v_mfma_f32_16x16x32_bf16 v[40:43], v[228:231], v[170:173], v[40:43]
	v_mfma_f32_16x16x32_bf16 v[32:35], v[220:223], v[178:181], v[32:35]
	v_mfma_f32_16x16x32_bf16 v[24:27], v[228:231], v[178:181], v[24:27]
	v_mfma_f32_16x16x32_bf16 v[16:19], v[220:223], v[196:199], v[16:19]
	v_mfma_f32_16x16x32_bf16 v[8:11], v[228:231], v[196:199], v[8:11]
	v_mfma_f32_16x16x32_bf16 v[4:7], v[220:223], v[204:207], v[4:7]
	v_mfma_f32_16x16x32_bf16 v[0:3], v[228:231], v[204:207], v[0:3]
	s_add_i32 s28, 0, 0x18000
	v_add_u32_e32 v157, s28, v149
	s_barrier
	ds_read_b128 v[136:139], v157
	ds_read_b128 v[140:143], v157 offset:1024
	ds_read_b128 v[158:161], v157 offset:2048
	ds_read_b128 v[162:165], v157 offset:3072
	s_add_u32 s26, s64, 0x40000
	s_addc_u32 s27, s65, 0
	s_mov_b32 m0, s76
	ds_read_b128 v[166:169], v154 offset:32768
	ds_read_b128 v[170:173], v154 offset:33792
	ds_read_b128 v[174:177], v154 offset:34816
	ds_read_b128 v[178:181], v154 offset:35840
	ds_read_b128 v[182:185], v154 offset:36864
	ds_read_b128 v[196:199], v154 offset:37888
	ds_read_b128 v[200:203], v154 offset:38912
	global_load_lds_dwordx4 v128, s[26:27]
	s_mov_b32 m0, s77
	ds_read_b128 v[204:207], v154 offset:39936
	global_load_lds_dwordx4 v130, s[26:27]
	s_waitcnt lgkmcnt(8)
	s_barrier
	s_waitcnt lgkmcnt(0)
	v_mfma_f32_16x16x32_bf16 v[124:127], v[136:139], v[166:169], v[124:127]
	v_mfma_f32_16x16x32_bf16 v[120:123], v[158:161], v[166:169], v[120:123]
	v_mfma_f32_16x16x32_bf16 v[116:119], v[136:139], v[174:177], v[116:119]
	v_mfma_f32_16x16x32_bf16 v[108:111], v[158:161], v[174:177], v[108:111]
	v_mfma_f32_16x16x32_bf16 v[100:103], v[136:139], v[182:185], v[100:103]
	v_mfma_f32_16x16x32_bf16 v[92:95], v[158:161], v[182:185], v[92:95]
	v_mfma_f32_16x16x32_bf16 v[84:87], v[136:139], v[200:203], v[84:87]
	v_mfma_f32_16x16x32_bf16 v[76:79], v[158:161], v[200:203], v[76:79]
	v_mfma_f32_16x16x32_bf16 v[124:127], v[140:143], v[170:173], v[124:127]
	v_mfma_f32_16x16x32_bf16 v[120:123], v[162:165], v[170:173], v[120:123]
	v_mfma_f32_16x16x32_bf16 v[116:119], v[140:143], v[178:181], v[116:119]
	v_mfma_f32_16x16x32_bf16 v[108:111], v[162:165], v[178:181], v[108:111]
	v_mfma_f32_16x16x32_bf16 v[100:103], v[140:143], v[196:199], v[100:103]
	v_mfma_f32_16x16x32_bf16 v[92:95], v[162:165], v[196:199], v[92:95]
	v_mfma_f32_16x16x32_bf16 v[84:87], v[140:143], v[204:207], v[84:87]
	v_mfma_f32_16x16x32_bf16 v[76:79], v[162:165], v[204:207], v[76:79]
	s_barrier
	s_add_i32 s29, 0, 0x1c000
	s_add_i32 s26, s28, s71
	v_add_u32_e32 v157, s29, v149
	v_lshl_add_u64 v[146:147], v[146:147], 0, s[88:89]
	s_mov_b32 m0, s26
	ds_read_b128 v[216:219], v157
	ds_read_b128 v[220:223], v157 offset:1024
	ds_read_b128 v[224:227], v157 offset:2048
	ds_read_b128 v[228:231], v157 offset:3072
	global_load_lds_dwordx4 v[146:147], off
	s_add_i32 m0, s26, 0x2000
	v_lshl_add_u64 v[146:147], v[186:187], 0, s[88:89]
	global_load_lds_dwordx4 v[146:147], off
	s_barrier
	s_waitcnt lgkmcnt(0)
	v_mfma_f32_16x16x32_bf16 v[112:115], v[216:219], v[166:169], v[112:115]
	v_mfma_f32_16x16x32_bf16 v[104:107], v[224:227], v[166:169], v[104:107]
	v_mfma_f32_16x16x32_bf16 v[96:99], v[216:219], v[174:177], v[96:99]
	v_mfma_f32_16x16x32_bf16 v[88:91], v[224:227], v[174:177], v[88:91]
	v_mfma_f32_16x16x32_bf16 v[80:83], v[216:219], v[182:185], v[80:83]
	v_mfma_f32_16x16x32_bf16 v[72:75], v[224:227], v[182:185], v[72:75]
	v_mfma_f32_16x16x32_bf16 v[68:71], v[216:219], v[200:203], v[68:71]
	v_mfma_f32_16x16x32_bf16 v[64:67], v[224:227], v[200:203], v[64:67]
	v_mfma_f32_16x16x32_bf16 v[112:115], v[220:223], v[170:173], v[112:115]
	v_mfma_f32_16x16x32_bf16 v[104:107], v[228:231], v[170:173], v[104:107]
	v_mfma_f32_16x16x32_bf16 v[96:99], v[220:223], v[178:181], v[96:99]
	v_mfma_f32_16x16x32_bf16 v[88:91], v[228:231], v[178:181], v[88:91]
	v_mfma_f32_16x16x32_bf16 v[80:83], v[220:223], v[196:199], v[80:83]
	v_mfma_f32_16x16x32_bf16 v[72:75], v[228:231], v[196:199], v[72:75]
	v_mfma_f32_16x16x32_bf16 v[68:71], v[220:223], v[204:207], v[68:71]
	v_mfma_f32_16x16x32_bf16 v[64:67], v[228:231], v[204:207], v[64:67]
	s_mov_b32 m0, s78
	v_lshl_add_u64 v[146:147], v[188:189], 0, s[88:89]
	s_barrier
	ds_read_b128 v[166:169], v154 offset:49152
	ds_read_b128 v[170:173], v154 offset:50176
	ds_read_b128 v[174:177], v154 offset:51200
	ds_read_b128 v[178:181], v154 offset:52224
	ds_read_b128 v[182:185], v154 offset:53248
	ds_read_b128 v[196:199], v154 offset:54272
	ds_read_b128 v[200:203], v154 offset:55296
	ds_read_b128 v[204:207], v154 offset:56320
	global_load_lds_dwordx4 v[146:147], off
	s_mov_b32 m0, s79
	v_lshl_add_u64 v[146:147], v[192:193], 0, s[88:89]
	global_load_lds_dwordx4 v[146:147], off
	s_barrier
; #define LAS __attribute__((address_space(3)))
; __device__ __forceinline__ unsigned pk2(float lo, float hi) { unsigned r; asm("v_cvt_pk_bf16_f32 %0, %1, %2" : "=v"(r) : "v"(lo), "v"(hi)); return r; }
; #define PG8_STAGE(bufoff, gbase, voff) do { _Pragma("unroll") for (int _i = 0; _i < 2; ++_i) \
;         __builtin_amdgcn_global_load_lds((const unsigned*)((const char*)(gbase) + (voff)[_i]), (LAS unsigned*)(lds + (bufoff) + ldsw + _i * 8192), 16, 0, 0); } while (0)
; template <class Epi>
; __device__ __forceinline__ void gemm_phase(LAS unsigned char* lds, const Gemm g, const StaticOrder& S, const Epi& E) {
;     ...
;             PG8_BAR; PG8_WAIT_L(0); PG8_MMA(1, 0, At, B0); PG8_BAR; PG8_SCHED;
;             PG8_STAGE(PG8_SB(1, 1), b3 + hB, voffB);
;             PG8_WAIT_V(6); PG8_BAR; PG8_MMA(1, 1, At, B1); PG8_BAR;
;     __device__ __forceinline__ void operator()(const f32x4 (&acc)[2][2][4][2], const Unit& u, int wr, int wc, int fr, int fq) const {
;         const int col_t = u.pn * BM;
;         if (mode != 0 && col_t >= vt0) {
;             const int bl = u.pm / TPB, key0 = (u.pm - bl * TPB) * 256;
;             LAS bf16_t* sc = (LAS bf16_t*)(trs + (wr * 4 + wc) * 2304);
;             const int lane = fq * 16 + fr;
; #pragma unroll
;             for (int ai = 0; ai < 2; ++ai)
; #pragma unroll
;                 for (int bj = 0; bj < 2; ++bj)
; #pragma unroll
;                     for (int n = 0; n < 2; ++n) {
; #pragma unroll
;                         for (int m = 0; m < 4; ++m) {
;                             const f32x4 v = acc[ai][bj][m][n];
;                             const unsigned p0 = pk2(v[0], v[1]), p1 = pk2(v[2], v[3]);
;                             LAS bf16_t* w = sc + (4 * fq) * 72 + 16 * m + fr;
;                             w[0] = (bf16_t)(p0 & 0xffffu); w[72] = (bf16_t)(p0 >> 16); w[144] = (bf16_t)(p1 & 0xffffu); w[216] = (bf16_t)(p1 >> 16);
;                         }
; #pragma unroll
;                         for (int j = 0; j < 2; ++j) {
;                             const int ch = lane + 64 * j, fi = ch >> 3, seg = ch & 7;
;                             const u32x4 o = *(const LAS u32x4*)(sc + fi * 72 + 8 * seg);
;                             const int f = col_t - vt0 + 64 * wc + 16 * (fi >> 2) + 8 * bj + 4 * n + (fi & 3);
;                             *(u32x4*)(Vt + ((size_t)bl * vtnf + f) * KEYS + key0 + ai * HALF + wr * 64 + 8 * seg) = o;
	s_waitcnt lgkmcnt(0)
	v_mfma_f32_16x16x32_bf16 v[60:63], v[136:139], v[166:169], v[60:63]
	v_mfma_f32_16x16x32_bf16 v[56:59], v[158:161], v[166:169], v[56:59]
	v_mfma_f32_16x16x32_bf16 v[52:55], v[136:139], v[174:177], v[52:55]
	v_mfma_f32_16x16x32_bf16 v[44:47], v[158:161], v[174:177], v[44:47]
	v_mfma_f32_16x16x32_bf16 v[36:39], v[136:139], v[182:185], v[36:39]
	v_mfma_f32_16x16x32_bf16 v[28:31], v[158:161], v[182:185], v[28:31]
	v_mfma_f32_16x16x32_bf16 v[20:23], v[136:139], v[200:203], v[20:23]
	v_mfma_f32_16x16x32_bf16 v[12:15], v[158:161], v[200:203], v[12:15]
	v_mfma_f32_16x16x32_bf16 v[60:63], v[140:143], v[170:173], v[60:63]
	v_mfma_f32_16x16x32_bf16 v[56:59], v[162:165], v[170:173], v[56:59]
	v_mfma_f32_16x16x32_bf16 v[52:55], v[140:143], v[178:181], v[52:55]
	v_mfma_f32_16x16x32_bf16 v[44:47], v[162:165], v[178:181], v[44:47]
	v_mfma_f32_16x16x32_bf16 v[36:39], v[140:143], v[196:199], v[36:39]
	v_mfma_f32_16x16x32_bf16 v[28:31], v[162:165], v[196:199], v[28:31]
	v_mfma_f32_16x16x32_bf16 v[20:23], v[140:143], v[204:207], v[20:23]
	v_mfma_f32_16x16x32_bf16 v[12:15], v[162:165], v[204:207], v[12:15]
	s_barrier
	s_add_u32 s26, s34, 0x40080
	s_addc_u32 s27, s35, 0
	s_add_i32 s28, s29, s71
	s_mov_b32 m0, s28
	s_nop 0
	global_load_lds_dwordx4 v128, s[26:27]
	s_add_i32 m0, s28, 0x2000
	s_nop 0
	global_load_lds_dwordx4 v130, s[26:27]
	s_waitcnt vmcnt(6)
	s_barrier
	v_mfma_f32_16x16x32_bf16 v[48:51], v[216:219], v[166:169], v[48:51]
	v_mfma_f32_16x16x32_bf16 v[40:43], v[224:227], v[166:169], v[40:43]
	v_mfma_f32_16x16x32_bf16 v[32:35], v[216:219], v[174:177], v[32:35]
	v_mfma_f32_16x16x32_bf16 v[24:27], v[224:227], v[174:177], v[24:27]
	v_mfma_f32_16x16x32_bf16 v[16:19], v[216:219], v[182:185], v[16:19]
	v_mfma_f32_16x16x32_bf16 v[8:11], v[224:227], v[182:185], v[8:11]
	v_mfma_f32_16x16x32_bf16 v[4:7], v[216:219], v[200:203], v[4:7]
	v_mfma_f32_16x16x32_bf16 v[0:3], v[224:227], v[200:203], v[0:3]
	v_mfma_f32_16x16x32_bf16 v[48:51], v[220:223], v[170:173], v[48:51]
	v_mfma_f32_16x16x32_bf16 v[40:43], v[228:231], v[170:173], v[40:43]
	v_mfma_f32_16x16x32_bf16 v[32:35], v[220:223], v[178:181], v[32:35]
	v_mfma_f32_16x16x32_bf16 v[24:27], v[228:231], v[178:181], v[24:27]
	v_mfma_f32_16x16x32_bf16 v[16:19], v[220:223], v[196:199], v[16:19]
	v_mfma_f32_16x16x32_bf16 v[8:11], v[228:231], v[196:199], v[8:11]
	v_mfma_f32_16x16x32_bf16 v[4:7], v[220:223], v[204:207], v[4:7]
	v_mfma_f32_16x16x32_bf16 v[0:3], v[228:231], v[204:207], v[0:3]
	s_add_i32 s84, s84, 2
	s_add_u32 s4, s4, 0x100
	s_addc_u32 s5, s5, 0
	s_add_u32 s24, s24, 0x100
	s_addc_u32 s25, s25, 0
	s_cmp_gt_u32 s84, 13
	s_barrier
	s_cbranch_scc0 .LBB0_499
	s_lshl_b32 s15, s3, 8
	s_cmp_lt_i32 s3, 11
	s_mov_b64 s[4:5], -1
	s_cbranch_scc1 .LBB0_502
	s_mul_hi_i32 s3, s80, 0x3e0f83e1
	s_lshr_b32 s4, s3, 31
	s_ashr_i32 s3, s3, 3
	s_add_i32 s4, s3, s4
	v_cvt_pk_bf16_f32 v136, v124, v125
	s_mul_i32 s3, s4, 0xffffffdf
	v_cvt_pk_bf16_f32 v137, v126, v127
	ds_write_b16 v151, v136
	ds_write_b16_d16_hi v151, v136 offset:144
	ds_write_b16 v151, v137 offset:288
	ds_write_b16_d16_hi v151, v137 offset:432
	v_cvt_pk_bf16_f32 v136, v116, v117
	s_add_i32 s3, s3, s80
	v_cvt_pk_bf16_f32 v137, v118, v119
	ds_write_b16 v151, v136 offset:32
	ds_write_b16_d16_hi v151, v136 offset:176
	ds_write_b16 v151, v137 offset:320
	ds_write_b16_d16_hi v151, v137 offset:464
	v_cvt_pk_bf16_f32 v136, v100, v101
	s_lshl_b32 s24, s3, 8
	s_or_b32 s3, s15, s81
	v_cvt_pk_bf16_f32 v137, v102, v103
	ds_write_b16 v151, v136 offset:64
	ds_write_b16_d16_hi v151, v136 offset:208
	ds_write_b16 v151, v137 offset:352
	ds_write_b16_d16_hi v151, v137 offset:496
	v_cvt_pk_bf16_f32 v136, v84, v85
	s_ashr_i32 s5, s4, 31
	v_cvt_pk_bf16_f32 v137, v86, v87
	ds_write_b16 v151, v136 offset:96
	ds_write_b16_d16_hi v151, v136 offset:240
	ds_write_b16 v151, v137 offset:384
	ds_write_b16_d16_hi v151, v137 offset:528
	v_add_u32_e32 v136, s3, v152
	s_lshl_b64 s[4:5], s[4:5], 10
	v_ashrrev_i32_e32 v137, 31, v136
	v_lshl_add_u64 v[136:137], s[4:5], 0, v[136:137]
	v_mov_b64_e32 v[162:163], s[10:11]
	s_ashr_i32 s25, s24, 31
	ds_read_b128 v[138:141], v155
	v_mad_u64_u32 v[142:143], s[26:27], v136, s91, v[162:163]
	v_mad_i32_i24 v143, v137, s91, v143
	s_lshl_b64 s[34:35], s[24:25], 1
	v_lshl_add_u64 v[136:137], v[142:143], 0, s[34:35]
	v_lshl_add_u64 v[136:137], v[136:137], 0, s[12:13]
	v_lshl_add_u64 v[136:137], v[136:137], 0, v[144:145]
	s_waitcnt lgkmcnt(0)
	global_store_dwordx4 v[136:137], v[138:141], off
	ds_read_b128 v[140:143], v156
	s_or_b32 s17, s3, 4
	v_add_u32_e32 v138, s3, v153
	v_ashrrev_i32_e32 v139, 31, v138
	v_lshl_add_u64 v[138:139], s[4:5], 0, v[138:139]
	v_mad_u64_u32 v[146:147], s[24:25], v138, s91, v[162:163]
	v_mad_i32_i24 v147, v139, s91, v147
	v_lshl_add_u64 v[138:139], v[146:147], 0, s[34:35]
	v_lshl_add_u64 v[138:139], v[138:139], 0, s[12:13]
	v_lshl_add_u64 v[138:139], v[138:139], 0, v[144:145]
	s_waitcnt lgkmcnt(0)
; #define LAS __attribute__((address_space(3)))
; __device__ __forceinline__ unsigned pk2(float lo, float hi) { unsigned r; asm("v_cvt_pk_bf16_f32 %0, %1, %2" : "=v"(r) : "v"(lo), "v"(hi)); return r; }
;     __device__ __forceinline__ void operator()(const f32x4 (&acc)[2][2][4][2], const Unit& u, int wr, int wc, int fr, int fq) const {
;     ...
;             for (int ai = 0; ai < 2; ++ai)
; #pragma unroll
;                 for (int bj = 0; bj < 2; ++bj)
; #pragma unroll
;                     for (int n = 0; n < 2; ++n) {
; #pragma unroll
;                         for (int m = 0; m < 4; ++m) {
;                             const f32x4 v = acc[ai][bj][m][n];
;                             const unsigned p0 = pk2(v[0], v[1]), p1 = pk2(v[2], v[3]);
;                             LAS bf16_t* w = sc + (4 * fq) * 72 + 16 * m + fr;
;                             w[0] = (bf16_t)(p0 & 0xffffu); w[72] = (bf16_t)(p0 >> 16); w[144] = (bf16_t)(p1 & 0xffffu); w[216] = (bf16_t)(p1 >> 16);
;                         }
; #pragma unroll
;                         for (int j = 0; j < 2; ++j) {
;                             const int ch = lane + 64 * j, fi = ch >> 3, seg = ch & 7;
;                             const u32x4 o = *(const LAS u32x4*)(sc + fi * 72 + 8 * seg);
;                             const int f = col_t - vt0 + 64 * wc + 16 * (fi >> 2) + 8 * bj + 4 * n + (fi & 3);
;                             *(u32x4*)(Vt + ((size_t)bl * vtnf + f) * KEYS + key0 + ai * HALF + wr * 64 + 8 * seg) = o;
	global_store_dwordx4 v[138:139], v[140:143], off
	v_cvt_pk_bf16_f32 v157, v104, v105
	s_nop 1
	v_cvt_pk_bf16_f32 v140, v120, v121
	v_cvt_pk_bf16_f32 v141, v122, v123
	ds_write_b16 v151, v140
	ds_write_b16_d16_hi v151, v140 offset:144
	ds_write_b16 v151, v141 offset:288
	ds_write_b16_d16_hi v151, v141 offset:432
	v_cvt_pk_bf16_f32 v140, v108, v109
	v_cvt_pk_bf16_f32 v141, v110, v111
	ds_write_b16 v151, v140 offset:32
	ds_write_b16_d16_hi v151, v140 offset:176
	ds_write_b16 v151, v141 offset:320
	ds_write_b16_d16_hi v151, v141 offset:464
	v_cvt_pk_bf16_f32 v140, v92, v93
	v_cvt_pk_bf16_f32 v141, v94, v95
	ds_write_b16 v151, v140 offset:64
	ds_write_b16_d16_hi v151, v140 offset:208
	ds_write_b16 v151, v141 offset:352
	ds_write_b16_d16_hi v151, v141 offset:496
	v_cvt_pk_bf16_f32 v140, v76, v77
	v_cvt_pk_bf16_f32 v141, v78, v79
	ds_write_b16 v151, v140 offset:96
	ds_write_b16_d16_hi v151, v140 offset:240
	ds_write_b16 v151, v141 offset:384
	ds_write_b16_d16_hi v151, v141 offset:528
	v_add_u32_e32 v140, s17, v152
	v_ashrrev_i32_e32 v141, 31, v140
	v_lshl_add_u64 v[140:141], s[4:5], 0, v[140:141]
	ds_read_b128 v[158:161], v155
	v_mad_u64_u32 v[142:143], s[24:25], v140, s91, v[162:163]
	v_mad_i32_i24 v143, v141, s91, v143
	v_lshl_add_u64 v[140:141], v[142:143], 0, s[34:35]
	v_add_u32_e32 v142, s17, v153
	v_lshl_add_u64 v[140:141], v[140:141], 0, s[12:13]
	v_ashrrev_i32_e32 v143, 31, v142
	v_lshl_add_u64 v[140:141], v[140:141], 0, v[144:145]
	v_lshl_add_u64 v[142:143], s[4:5], 0, v[142:143]
	s_waitcnt lgkmcnt(0)
	global_store_dwordx4 v[140:141], v[158:161], off
	ds_read_b128 v[158:161], v156
	v_mad_u64_u32 v[146:147], s[24:25], v142, s91, v[162:163]
	v_mad_i32_i24 v147, v143, s91, v147
	v_lshl_add_u64 v[142:143], v[146:147], 0, s[34:35]
	v_lshl_add_u64 v[142:143], v[142:143], 0, s[12:13]
	v_lshl_add_u64 v[142:143], v[142:143], 0, v[144:145]
	v_cvt_pk_bf16_f32 v146, v112, v113
	s_waitcnt lgkmcnt(0)
	global_store_dwordx4 v[142:143], v[158:161], off
	v_cvt_pk_bf16_f32 v147, v114, v115
	ds_write_b16 v151, v146
	ds_write_b16_d16_hi v151, v146 offset:144
	ds_write_b16 v151, v147 offset:288
	ds_write_b16_d16_hi v151, v147 offset:432
	v_cvt_pk_bf16_f32 v146, v96, v97
	v_cvt_pk_bf16_f32 v147, v98, v99
	ds_write_b16 v151, v146 offset:32
	ds_write_b16_d16_hi v151, v146 offset:176
	ds_write_b16 v151, v147 offset:320
	ds_write_b16_d16_hi v151, v147 offset:464
	v_cvt_pk_bf16_f32 v146, v80, v81
	s_or_b32 s17, s3, 8
	v_cvt_pk_bf16_f32 v147, v82, v83
	ds_write_b16 v151, v146 offset:64
	ds_write_b16_d16_hi v151, v146 offset:208
	ds_write_b16 v151, v147 offset:352
	ds_write_b16_d16_hi v151, v147 offset:496
	v_cvt_pk_bf16_f32 v146, v68, v69
	v_cvt_pk_bf16_f32 v147, v70, v71
	ds_write_b16 v151, v146 offset:96
	ds_write_b16_d16_hi v151, v146 offset:240
	ds_write_b16 v151, v147 offset:384
	ds_write_b16_d16_hi v151, v147 offset:528
	v_add_u32_e32 v146, s17, v152
	v_ashrrev_i32_e32 v147, 31, v146
	v_lshl_add_u64 v[146:147], s[4:5], 0, v[146:147]
	ds_read_b128 v[158:161], v155
	v_mad_u64_u32 v[164:165], s[24:25], v146, s91, v[162:163]
	v_mad_i32_i24 v165, v147, s91, v165
	v_lshl_add_u64 v[146:147], v[164:165], 0, s[34:35]
	v_add_u32_e32 v164, s17, v153
	v_lshl_add_u64 v[146:147], v[146:147], 0, s[12:13]
	v_ashrrev_i32_e32 v165, 31, v164
	v_lshl_add_u64 v[146:147], v[146:147], 0, v[144:145]
	v_lshl_add_u64 v[164:165], s[4:5], 0, v[164:165]
	s_waitcnt lgkmcnt(0)
	global_store_dwordx4 v[146:147], v[158:161], off
	ds_read_b128 v[158:161], v156
	v_mad_u64_u32 v[166:167], s[24:25], v164, s91, v[162:163]
	v_mad_i32_i24 v167, v165, s91, v167
	v_lshl_add_u64 v[164:165], v[166:167], 0, s[34:35]
	v_lshl_add_u64 v[164:165], v[164:165], 0, s[12:13]
	v_lshl_add_u64 v[164:165], v[164:165], 0, v[144:145]
	s_waitcnt lgkmcnt(0)
	global_store_dwordx4 v[164:165], v[158:161], off
	s_or_b32 s3, s3, 12
	v_add_u32_e32 v166, s3, v152
	v_cvt_pk_bf16_f32 v158, v106, v107
	ds_write_b16 v151, v157
	ds_write_b16_d16_hi v151, v157 offset:144
	ds_write_b16 v151, v158 offset:288
	ds_write_b16_d16_hi v151, v158 offset:432
	v_cvt_pk_bf16_f32 v157, v88, v89
	v_cvt_pk_bf16_f32 v158, v90, v91
	ds_write_b16 v151, v157 offset:32
	ds_write_b16_d16_hi v151, v157 offset:176
	ds_write_b16 v151, v158 offset:320
	ds_write_b16_d16_hi v151, v158 offset:464
	v_cvt_pk_bf16_f32 v157, v72, v73
	v_cvt_pk_bf16_f32 v158, v74, v75
	ds_write_b16 v151, v157 offset:64
	ds_write_b16_d16_hi v151, v157 offset:208
	ds_write_b16 v151, v158 offset:352
	ds_write_b16_d16_hi v151, v158 offset:496
	v_cvt_pk_bf16_f32 v157, v64, v65
	v_ashrrev_i32_e32 v167, 31, v166
	v_cvt_pk_bf16_f32 v158, v66, v67
	ds_write_b16 v151, v157 offset:96
	ds_write_b16_d16_hi v151, v157 offset:240
	ds_write_b16 v151, v158 offset:384
	ds_write_b16_d16_hi v151, v158 offset:528
	v_lshl_add_u64 v[166:167], s[4:5], 0, v[166:167]
	ds_read_b128 v[158:161], v155
	v_mad_u64_u32 v[168:169], s[24:25], v166, s91, v[162:163]
	v_mad_i32_i24 v169, v167, s91, v169
	v_lshl_add_u64 v[166:167], v[168:169], 0, s[34:35]
	v_add_u32_e32 v168, s3, v153
	v_lshl_add_u64 v[166:167], v[166:167], 0, s[12:13]
	v_ashrrev_i32_e32 v169, 31, v168
	v_lshl_add_u64 v[166:167], v[166:167], 0, v[144:145]
	v_lshl_add_u64 v[168:169], s[4:5], 0, v[168:169]
	s_waitcnt lgkmcnt(0)
; #define LAS __attribute__((address_space(3)))
; __device__ __forceinline__ unsigned pk2(float lo, float hi) { unsigned r; asm("v_cvt_pk_bf16_f32 %0, %1, %2" : "=v"(r) : "v"(lo), "v"(hi)); return r; }
;     __device__ __forceinline__ void operator()(const f32x4 (&acc)[2][2][4][2], const Unit& u, int wr, int wc, int fr, int fq) const {
;     ...
;             for (int ai = 0; ai < 2; ++ai)
; #pragma unroll
;                 for (int bj = 0; bj < 2; ++bj)
; #pragma unroll
;                     for (int n = 0; n < 2; ++n) {
; #pragma unroll
;                         for (int m = 0; m < 4; ++m) {
;                             const f32x4 v = acc[ai][bj][m][n];
;                             const unsigned p0 = pk2(v[0], v[1]), p1 = pk2(v[2], v[3]);
;                             LAS bf16_t* w = sc + (4 * fq) * 72 + 16 * m + fr;
;                             w[0] = (bf16_t)(p0 & 0xffffu); w[72] = (bf16_t)(p0 >> 16); w[144] = (bf16_t)(p1 & 0xffffu); w[216] = (bf16_t)(p1 >> 16);
;                         }
; #pragma unroll
;                         for (int j = 0; j < 2; ++j) {
;                             const int ch = lane + 64 * j, fi = ch >> 3, seg = ch & 7;
;                             const u32x4 o = *(const LAS u32x4*)(sc + fi * 72 + 8 * seg);
;                             const int f = col_t - vt0 + 64 * wc + 16 * (fi >> 2) + 8 * bj + 4 * n + (fi & 3);
;                             *(u32x4*)(Vt + ((size_t)bl * vtnf + f) * KEYS + key0 + ai * HALF + wr * 64 + 8 * seg) = o;
	global_store_dwordx4 v[166:167], v[158:161], off
	ds_read_b128 v[158:161], v156
	v_mad_u64_u32 v[162:163], s[4:5], v168, s91, v[162:163]
	v_mad_i32_i24 v163, v169, s91, v163
	v_lshl_add_u64 v[162:163], v[162:163], 0, s[34:35]
	v_lshl_add_u64 v[162:163], v[162:163], 0, s[12:13]
	v_lshl_add_u64 v[162:163], v[162:163], 0, v[144:145]
	v_cvt_pk_bf16_f32 v157, v60, v61
	s_waitcnt lgkmcnt(0)
	global_store_dwordx4 v[162:163], v[158:161], off
	s_mov_b64 s[4:5], 0
	s_nop 0
	v_cvt_pk_bf16_f32 v158, v62, v63
	ds_write_b16 v151, v157
	ds_write_b16_d16_hi v151, v157 offset:144
	ds_write_b16 v151, v158 offset:288
	ds_write_b16_d16_hi v151, v158 offset:432
	v_cvt_pk_bf16_f32 v157, v52, v53
	v_cvt_pk_bf16_f32 v158, v54, v55
	ds_write_b16 v151, v157 offset:32
	ds_write_b16_d16_hi v151, v157 offset:176
	ds_write_b16 v151, v158 offset:320
	ds_write_b16_d16_hi v151, v158 offset:464
	v_cvt_pk_bf16_f32 v157, v36, v37
	v_cvt_pk_bf16_f32 v158, v38, v39
	ds_write_b16 v151, v157 offset:64
	ds_write_b16_d16_hi v151, v157 offset:208
	ds_write_b16 v151, v158 offset:352
	ds_write_b16_d16_hi v151, v158 offset:496
	v_cvt_pk_bf16_f32 v157, v20, v21
	v_cvt_pk_bf16_f32 v158, v22, v23
	ds_write_b16 v151, v157 offset:96
	ds_write_b16_d16_hi v151, v157 offset:240
	ds_write_b16 v151, v158 offset:384
	ds_write_b16_d16_hi v151, v158 offset:528
	ds_read_b128 v[158:161], v155
	s_waitcnt lgkmcnt(0)
	global_store_dwordx4 v[136:137], v[158:161], off offset:256
	ds_read_b128 v[158:161], v156
	v_cvt_pk_bf16_f32 v136, v56, v57
	v_cvt_pk_bf16_f32 v137, v58, v59
	s_waitcnt lgkmcnt(0)
	global_store_dwordx4 v[138:139], v[158:161], off offset:256
	ds_write_b16 v151, v136
	ds_write_b16_d16_hi v151, v136 offset:144
	ds_write_b16 v151, v137 offset:288
	ds_write_b16_d16_hi v151, v137 offset:432
	v_cvt_pk_bf16_f32 v136, v44, v45
	v_cvt_pk_bf16_f32 v137, v46, v47
	ds_write_b16 v151, v136 offset:32
	ds_write_b16_d16_hi v151, v136 offset:176
	ds_write_b16 v151, v137 offset:320
	ds_write_b16_d16_hi v151, v137 offset:464
	v_cvt_pk_bf16_f32 v136, v28, v29
	v_cvt_pk_bf16_f32 v137, v30, v31
	ds_write_b16 v151, v136 offset:64
	ds_write_b16_d16_hi v151, v136 offset:208
	ds_write_b16 v151, v137 offset:352
	ds_write_b16_d16_hi v151, v137 offset:496
	v_cvt_pk_bf16_f32 v136, v12, v13
	v_cvt_pk_bf16_f32 v137, v14, v15
	ds_write_b16 v151, v136 offset:96
	ds_write_b16_d16_hi v151, v136 offset:240
	ds_write_b16 v151, v137 offset:384
	ds_write_b16_d16_hi v151, v137 offset:528
	ds_read_b128 v[136:139], v155
	s_waitcnt lgkmcnt(0)
	global_store_dwordx4 v[140:141], v[136:139], off offset:256
	ds_read_b128 v[136:139], v156
	s_waitcnt lgkmcnt(0)
	global_store_dwordx4 v[142:143], v[136:139], off offset:256
	s_nop 1
	v_cvt_pk_bf16_f32 v136, v48, v49
	v_cvt_pk_bf16_f32 v137, v50, v51
	ds_write_b16 v151, v136
	ds_write_b16_d16_hi v151, v136 offset:144
	ds_write_b16 v151, v137 offset:288
	ds_write_b16_d16_hi v151, v137 offset:432
	v_cvt_pk_bf16_f32 v136, v32, v33
	v_cvt_pk_bf16_f32 v137, v34, v35
	ds_write_b16 v151, v136 offset:32
	ds_write_b16_d16_hi v151, v136 offset:176
	ds_write_b16 v151, v137 offset:320
	ds_write_b16_d16_hi v151, v137 offset:464
	v_cvt_pk_bf16_f32 v136, v16, v17
	v_cvt_pk_bf16_f32 v137, v18, v19
	ds_write_b16 v151, v136 offset:64
	ds_write_b16_d16_hi v151, v136 offset:208
	ds_write_b16 v151, v137 offset:352
	ds_write_b16_d16_hi v151, v137 offset:496
	v_cvt_pk_bf16_f32 v136, v4, v5
	v_cvt_pk_bf16_f32 v137, v6, v7
	ds_write_b16 v151, v136 offset:96
	ds_write_b16_d16_hi v151, v136 offset:240
	ds_write_b16 v151, v137 offset:384
	ds_write_b16_d16_hi v151, v137 offset:528
	ds_read_b128 v[136:139], v155
	s_waitcnt lgkmcnt(0)
	global_store_dwordx4 v[146:147], v[136:139], off offset:256
	ds_read_b128 v[136:139], v156
	s_waitcnt lgkmcnt(0)
	global_store_dwordx4 v[164:165], v[136:139], off offset:256
	s_nop 1
	v_cvt_pk_bf16_f32 v136, v40, v41
	v_cvt_pk_bf16_f32 v137, v42, v43
	ds_write_b16 v151, v136
	ds_write_b16_d16_hi v151, v136 offset:144
	ds_write_b16 v151, v137 offset:288
	ds_write_b16_d16_hi v151, v137 offset:432
	v_cvt_pk_bf16_f32 v136, v24, v25
	v_cvt_pk_bf16_f32 v137, v26, v27
	ds_write_b16 v151, v136 offset:32
	ds_write_b16_d16_hi v151, v136 offset:176
	ds_write_b16 v151, v137 offset:320
	ds_write_b16_d16_hi v151, v137 offset:464
	v_cvt_pk_bf16_f32 v136, v8, v9
	v_cvt_pk_bf16_f32 v137, v10, v11
	ds_write_b16 v151, v136 offset:64
	ds_write_b16_d16_hi v151, v136 offset:208
	ds_write_b16 v151, v137 offset:352
	ds_write_b16_d16_hi v151, v137 offset:496
	v_cvt_pk_bf16_f32 v136, v0, v1
	v_cvt_pk_bf16_f32 v137, v2, v3
	ds_write_b16 v151, v136 offset:96
	ds_write_b16_d16_hi v151, v136 offset:240
	ds_write_b16 v151, v137 offset:384
	ds_write_b16_d16_hi v151, v137 offset:528
	ds_read_b128 v[136:139], v155
	s_waitcnt lgkmcnt(0)
	global_store_dwordx4 v[166:167], v[136:139], off offset:256
	ds_read_b128 v[136:139], v156
	s_waitcnt lgkmcnt(0)
	global_store_dwordx4 v[162:163], v[136:139], off offset:256

; #define PG8_STAGE(bufoff, gbase, voff) do { _Pragma("unroll") for (int _i = 0; _i < 2; ++_i) \
;         __builtin_amdgcn_global_load_lds((const unsigned*)((const char*)(gbase) + (voff)[_i]), (LAS unsigned*)(lds + (bufoff) + ldsw + _i * 8192), 16, 0, 0); } while (0)
; #define PG8_LDA(dst, b, h) do { _Pragma("unroll") for (int m = 0; m < 4; ++m) _Pragma("unroll") for (int k = 0; k < 2; ++k) dst[m][k] = *(const LAS bf16x8*)(lds + PG8_SA(b, h) + aoff + m * 2048 + k * 1024); } while (0)
; #define PG8_LDB(dst, b, h) do { _Pragma("unroll") for (int n = 0; n < 2; ++n) _Pragma("unroll") for (int k = 0; k < 2; ++k) dst[n][k] = *(const LAS bf16x8*)(lds + PG8_SB(b, h) + boff + n * 2048 + k * 1024); } while (0)
; #define PG8_MMA(ai, bj, At, Bt) do { __builtin_amdgcn_s_setprio(1); _Pragma("unroll") for (int m = 0; m < 4; ++m) _Pragma("unroll") for (int n = 0; n < 2; ++n) _Pragma("unroll") for (int k = 0; k < 2; ++k) \
;         acc[ai][bj][m][n] = __builtin_amdgcn_mfma_f32_16x16x32_bf16(Bt[n][k], At[m][k], acc[ai][bj][m][n], 0, 0, 0); __builtin_amdgcn_s_setprio(0); } while (0)
; #define PG8_WAIT_L(n) asm volatile("s_waitcnt lgkmcnt(" #n ")" ::: "memory")
; #define PG8_BAR __builtin_amdgcn_s_barrier()
; #define PG8_SCHED __builtin_amdgcn_sched_barrier(0)
; template <class Epi>
; __device__ __forceinline__ void gemm_phase(LAS unsigned char* lds, const Gemm g, const StaticOrder& S, const Epi& E) {
;     ...
;             PG8_LDB(B0, 0, 0); PG8_SCHED; PG8_LDA(At, 0, 0); PG8_STAGE(PG8_SA(1, 1), a1 + hA, voffA);
;             PG8_WAIT_L(8); PG8_BAR; PG8_WAIT_L(0); PG8_MMA(0, 0, At, B0); PG8_BAR; PG8_SCHED;
;             PG8_LDB(B1, 0, 1); PG8_STAGE(PG8_SB(0, 0), b2, voffB);
;             PG8_BAR; PG8_WAIT_L(0); PG8_MMA(0, 1, At, B1); PG8_BAR;
;             PG8_LDA(At, 0, 1); PG8_STAGE(PG8_SA(0, 0), a2, voffA);
;             PG8_BAR; PG8_WAIT_L(0); PG8_MMA(1, 0, At, B0); PG8_BAR; PG8_SCHED;
.LBB0_655:
	s_add_u32 s12, s10, 0x100
	s_addc_u32 s13, s11, 0
	s_add_i32 s26, 0, 0x10000
	v_add_u32_e32 v156, s26, v143
	ds_read_b128 v[138:141], v156
	ds_read_b128 v[148:151], v156 offset:1024
	ds_read_b128 v[152:155], v156 offset:2048
	ds_read_b128 v[156:159], v156 offset:3072
	s_cmp_eq_u32 s78, 2
	s_cselect_b32 s21, s5, s13
	s_cselect_b32 s20, s4, s12
	s_cselect_b32 s17, s7, s25
	s_cselect_b32 s16, s6, s24
	s_add_i32 m0, s64, 0xc000
	ds_read_b128 v[160:163], v147
	ds_read_b128 v[164:167], v147 offset:1024
	ds_read_b128 v[168:171], v147 offset:2048
	ds_read_b128 v[172:175], v147 offset:3072
	ds_read_b128 v[176:179], v147 offset:4096
	ds_read_b128 v[180:183], v147 offset:5120
	ds_read_b128 v[196:199], v147 offset:6144
	ds_read_b128 v[200:203], v147 offset:7168
	global_load_lds_dwordx4 v134, s[10:11]
	s_add_i32 m0, s64, 0xe000
	v_lshl_add_u64 v[184:185], s[10:11], 0, v[136:137]
	global_load_lds_dwordx4 v[184:185], off
	s_waitcnt lgkmcnt(8)
	s_barrier
	s_waitcnt lgkmcnt(0)
	v_mfma_f32_16x16x32_bf16 v[124:127], v[138:141], v[160:163], v[124:127]
	v_mfma_f32_16x16x32_bf16 v[120:123], v[152:155], v[160:163], v[120:123]
	v_mfma_f32_16x16x32_bf16 v[116:119], v[138:141], v[168:171], v[116:119]
	v_mfma_f32_16x16x32_bf16 v[108:111], v[152:155], v[168:171], v[108:111]
	v_mfma_f32_16x16x32_bf16 v[100:103], v[138:141], v[176:179], v[100:103]
	v_mfma_f32_16x16x32_bf16 v[92:95], v[152:155], v[176:179], v[92:95]
	v_mfma_f32_16x16x32_bf16 v[84:87], v[138:141], v[196:199], v[84:87]
	v_mfma_f32_16x16x32_bf16 v[76:79], v[152:155], v[196:199], v[76:79]
	v_mfma_f32_16x16x32_bf16 v[124:127], v[148:151], v[164:167], v[124:127]
	v_mfma_f32_16x16x32_bf16 v[120:123], v[156:159], v[164:167], v[120:123]
	v_mfma_f32_16x16x32_bf16 v[116:119], v[148:151], v[172:175], v[116:119]
	v_mfma_f32_16x16x32_bf16 v[108:111], v[156:159], v[172:175], v[108:111]
	v_mfma_f32_16x16x32_bf16 v[100:103], v[148:151], v[180:183], v[100:103]
	v_mfma_f32_16x16x32_bf16 v[92:95], v[156:159], v[180:183], v[92:95]
	v_mfma_f32_16x16x32_bf16 v[84:87], v[148:151], v[200:203], v[84:87]
	v_mfma_f32_16x16x32_bf16 v[76:79], v[156:159], v[200:203], v[76:79]
	s_barrier
	s_add_i32 s27, 0, 0x14000
	v_add_u32_e32 v184, s27, v143
	s_add_i32 s10, s26, s63
	ds_read_b128 v[204:207], v184
	ds_read_b128 v[216:219], v184 offset:1024
	ds_read_b128 v[220:223], v184 offset:2048
	ds_read_b128 v[224:227], v184 offset:3072
	v_lshl_add_u64 v[184:185], s[16:17], 0, v[144:145]
	s_mov_b32 m0, s10
	v_lshl_add_u64 v[186:187], s[16:17], 0, v[132:133]
	global_load_lds_dwordx4 v[184:185], off
	s_add_i32 m0, s10, 0x2000
	s_nop 0
	global_load_lds_dwordx4 v[186:187], off
	s_barrier
	s_waitcnt lgkmcnt(0)
	v_mfma_f32_16x16x32_bf16 v[112:115], v[204:207], v[160:163], v[112:115]
	v_mfma_f32_16x16x32_bf16 v[104:107], v[220:223], v[160:163], v[104:107]
	v_mfma_f32_16x16x32_bf16 v[96:99], v[204:207], v[168:171], v[96:99]
	v_mfma_f32_16x16x32_bf16 v[88:91], v[220:223], v[168:171], v[88:91]
	v_mfma_f32_16x16x32_bf16 v[80:83], v[204:207], v[176:179], v[80:83]
	v_mfma_f32_16x16x32_bf16 v[72:75], v[220:223], v[176:179], v[72:75]
	v_mfma_f32_16x16x32_bf16 v[68:71], v[204:207], v[196:199], v[68:71]
	v_mfma_f32_16x16x32_bf16 v[64:67], v[220:223], v[196:199], v[64:67]
	v_mfma_f32_16x16x32_bf16 v[112:115], v[216:219], v[164:167], v[112:115]
	v_mfma_f32_16x16x32_bf16 v[104:107], v[224:227], v[164:167], v[104:107]
	v_mfma_f32_16x16x32_bf16 v[96:99], v[216:219], v[172:175], v[96:99]
	v_mfma_f32_16x16x32_bf16 v[88:91], v[224:227], v[172:175], v[88:91]
	v_mfma_f32_16x16x32_bf16 v[80:83], v[216:219], v[180:183], v[80:83]
	v_mfma_f32_16x16x32_bf16 v[72:75], v[224:227], v[180:183], v[72:75]
	v_mfma_f32_16x16x32_bf16 v[68:71], v[216:219], v[200:203], v[68:71]
	v_mfma_f32_16x16x32_bf16 v[64:67], v[224:227], v[200:203], v[64:67]
	s_mov_b32 m0, s64
	v_lshl_add_u64 v[188:189], s[20:21], 0, v[128:129]
	s_barrier
	ds_read_b128 v[160:163], v147 offset:16384
	ds_read_b128 v[164:167], v147 offset:17408
	ds_read_b128 v[168:171], v147 offset:18432
	ds_read_b128 v[172:175], v147 offset:19456
	ds_read_b128 v[176:179], v147 offset:20480
	ds_read_b128 v[180:183], v147 offset:21504
	ds_read_b128 v[196:199], v147 offset:22528
	ds_read_b128 v[200:203], v147 offset:23552
	global_load_lds_dwordx4 v[188:189], off
	s_mov_b32 m0, s65
	v_lshl_add_u64 v[192:193], s[20:21], 0, v[130:131]
	global_load_lds_dwordx4 v[192:193], off
	s_barrier
	s_waitcnt lgkmcnt(0)
	v_mfma_f32_16x16x32_bf16 v[60:63], v[138:141], v[160:163], v[60:63]
	v_mfma_f32_16x16x32_bf16 v[56:59], v[152:155], v[160:163], v[56:59]
	v_mfma_f32_16x16x32_bf16 v[52:55], v[138:141], v[168:171], v[52:55]
	v_mfma_f32_16x16x32_bf16 v[44:47], v[152:155], v[168:171], v[44:47]
	v_mfma_f32_16x16x32_bf16 v[36:39], v[138:141], v[176:179], v[36:39]
	v_mfma_f32_16x16x32_bf16 v[28:31], v[152:155], v[176:179], v[28:31]
	v_mfma_f32_16x16x32_bf16 v[20:23], v[138:141], v[196:199], v[20:23]
	v_mfma_f32_16x16x32_bf16 v[12:15], v[152:155], v[196:199], v[12:15]
	v_mfma_f32_16x16x32_bf16 v[60:63], v[148:151], v[164:167], v[60:63]
	v_mfma_f32_16x16x32_bf16 v[56:59], v[156:159], v[164:167], v[56:59]
	v_mfma_f32_16x16x32_bf16 v[52:55], v[148:151], v[172:175], v[52:55]
	v_mfma_f32_16x16x32_bf16 v[44:47], v[156:159], v[172:175], v[44:47]
	v_mfma_f32_16x16x32_bf16 v[36:39], v[148:151], v[180:183], v[36:39]
	v_mfma_f32_16x16x32_bf16 v[28:31], v[156:159], v[180:183], v[28:31]
	v_mfma_f32_16x16x32_bf16 v[20:23], v[148:151], v[200:203], v[20:23]
	v_mfma_f32_16x16x32_bf16 v[12:15], v[156:159], v[200:203], v[12:15]
	s_barrier
; #define PG8_STAGE(bufoff, gbase, voff) do { _Pragma("unroll") for (int _i = 0; _i < 2; ++_i) \
;         __builtin_amdgcn_global_load_lds((const unsigned*)((const char*)(gbase) + (voff)[_i]), (LAS unsigned*)(lds + (bufoff) + ldsw + _i * 8192), 16, 0, 0); } while (0)
; #define PG8_LDA(dst, b, h) do { _Pragma("unroll") for (int m = 0; m < 4; ++m) _Pragma("unroll") for (int k = 0; k < 2; ++k) dst[m][k] = *(const LAS bf16x8*)(lds + PG8_SA(b, h) + aoff + m * 2048 + k * 1024); } while (0)
; #define PG8_LDB(dst, b, h) do { _Pragma("unroll") for (int n = 0; n < 2; ++n) _Pragma("unroll") for (int k = 0; k < 2; ++k) dst[n][k] = *(const LAS bf16x8*)(lds + PG8_SB(b, h) + boff + n * 2048 + k * 1024); } while (0)
; #define PG8_MMA(ai, bj, At, Bt) do { __builtin_amdgcn_s_setprio(1); _Pragma("unroll") for (int m = 0; m < 4; ++m) _Pragma("unroll") for (int n = 0; n < 2; ++n) _Pragma("unroll") for (int k = 0; k < 2; ++k) \
;         acc[ai][bj][m][n] = __builtin_amdgcn_mfma_f32_16x16x32_bf16(Bt[n][k], At[m][k], acc[ai][bj][m][n], 0, 0, 0); __builtin_amdgcn_s_setprio(0); } while (0)
; #define PG8_WAIT_V(n) asm volatile("s_waitcnt vmcnt(" #n ")" ::: "memory")
; #define PG8_WAIT_L(n) asm volatile("s_waitcnt lgkmcnt(" #n ")" ::: "memory")
; #define PG8_BAR __builtin_amdgcn_s_barrier()
; #define PG8_SCHED __builtin_amdgcn_sched_barrier(0)
; template <class Epi>
; __device__ __forceinline__ void gemm_phase(LAS unsigned char* lds, const Gemm g, const StaticOrder& S, const Epi& E) {
;     ...
;             PG8_STAGE(PG8_SB(0, 1), b2 + hB, voffB);
;             PG8_WAIT_V(6); PG8_BAR; PG8_MMA(1, 1, At, B1); PG8_BAR;
;             PG8_LDB(B0, 1, 0); PG8_SCHED; PG8_LDA(At, 1, 0); PG8_STAGE(PG8_SA(0, 1), a2 + hA, voffA);
;             PG8_WAIT_L(8); PG8_BAR; PG8_WAIT_L(0); PG8_MMA(0, 0, At, B0); PG8_BAR; PG8_SCHED;
;             PG8_LDB(B1, 1, 1); PG8_STAGE(PG8_SB(1, 0), b3, voffB);
;             PG8_BAR; PG8_WAIT_L(0); PG8_MMA(0, 1, At, B1); PG8_BAR;
;             PG8_LDA(At, 1, 1); PG8_STAGE(PG8_SA(1, 0), a3, voffA);
	s_add_u32 s10, s16, 0x18000
	s_addc_u32 s11, s17, 0
	s_add_i32 s26, s27, s63
	s_mov_b32 m0, s26
	s_nop 0
	global_load_lds_dwordx4 v144, s[10:11]
	s_add_i32 m0, s26, 0x2000
	s_nop 0
	global_load_lds_dwordx4 v132, s[10:11]
	s_waitcnt vmcnt(6)
	s_barrier
	v_mfma_f32_16x16x32_bf16 v[48:51], v[204:207], v[160:163], v[48:51]
	v_mfma_f32_16x16x32_bf16 v[40:43], v[220:223], v[160:163], v[40:43]
	v_mfma_f32_16x16x32_bf16 v[32:35], v[204:207], v[168:171], v[32:35]
	v_mfma_f32_16x16x32_bf16 v[24:27], v[220:223], v[168:171], v[24:27]
	v_mfma_f32_16x16x32_bf16 v[16:19], v[204:207], v[176:179], v[16:19]
	v_mfma_f32_16x16x32_bf16 v[8:11], v[220:223], v[176:179], v[8:11]
	v_mfma_f32_16x16x32_bf16 v[4:7], v[204:207], v[196:199], v[4:7]
	v_mfma_f32_16x16x32_bf16 v[0:3], v[220:223], v[196:199], v[0:3]
	v_mfma_f32_16x16x32_bf16 v[48:51], v[216:219], v[164:167], v[48:51]
	v_mfma_f32_16x16x32_bf16 v[40:43], v[224:227], v[164:167], v[40:43]
	v_mfma_f32_16x16x32_bf16 v[32:35], v[216:219], v[172:175], v[32:35]
	v_mfma_f32_16x16x32_bf16 v[24:27], v[224:227], v[172:175], v[24:27]
	v_mfma_f32_16x16x32_bf16 v[16:19], v[216:219], v[180:183], v[16:19]
	v_mfma_f32_16x16x32_bf16 v[8:11], v[224:227], v[180:183], v[8:11]
	v_mfma_f32_16x16x32_bf16 v[4:7], v[216:219], v[200:203], v[4:7]
	v_mfma_f32_16x16x32_bf16 v[0:3], v[224:227], v[200:203], v[0:3]
	s_add_i32 s26, 0, 0x18000
	v_add_u32_e32 v156, s26, v143
	s_barrier
	ds_read_b128 v[138:141], v156
	ds_read_b128 v[148:151], v156 offset:1024
	ds_read_b128 v[152:155], v156 offset:2048
	ds_read_b128 v[156:159], v156 offset:3072
	s_add_u32 s10, s20, 0xb0000
	s_addc_u32 s11, s21, 0
	s_mov_b32 m0, s66
	ds_read_b128 v[160:163], v147 offset:32768
	ds_read_b128 v[164:167], v147 offset:33792
	ds_read_b128 v[168:171], v147 offset:34816
	ds_read_b128 v[172:175], v147 offset:35840
	ds_read_b128 v[176:179], v147 offset:36864
	ds_read_b128 v[180:183], v147 offset:37888
	ds_read_b128 v[196:199], v147 offset:38912
	global_load_lds_dwordx4 v128, s[10:11]
	s_mov_b32 m0, s68
	ds_read_b128 v[200:203], v147 offset:39936
	global_load_lds_dwordx4 v130, s[10:11]
	s_waitcnt lgkmcnt(8)
	s_barrier
	s_waitcnt lgkmcnt(0)
	v_mfma_f32_16x16x32_bf16 v[124:127], v[138:141], v[160:163], v[124:127]
	v_mfma_f32_16x16x32_bf16 v[120:123], v[152:155], v[160:163], v[120:123]
	v_mfma_f32_16x16x32_bf16 v[116:119], v[138:141], v[168:171], v[116:119]
	v_mfma_f32_16x16x32_bf16 v[108:111], v[152:155], v[168:171], v[108:111]
	v_mfma_f32_16x16x32_bf16 v[100:103], v[138:141], v[176:179], v[100:103]
	v_mfma_f32_16x16x32_bf16 v[92:95], v[152:155], v[176:179], v[92:95]
	v_mfma_f32_16x16x32_bf16 v[84:87], v[138:141], v[196:199], v[84:87]
	v_mfma_f32_16x16x32_bf16 v[76:79], v[152:155], v[196:199], v[76:79]
	v_mfma_f32_16x16x32_bf16 v[124:127], v[148:151], v[164:167], v[124:127]
	v_mfma_f32_16x16x32_bf16 v[120:123], v[156:159], v[164:167], v[120:123]
	v_mfma_f32_16x16x32_bf16 v[116:119], v[148:151], v[172:175], v[116:119]
	v_mfma_f32_16x16x32_bf16 v[108:111], v[156:159], v[172:175], v[108:111]
	v_mfma_f32_16x16x32_bf16 v[100:103], v[148:151], v[180:183], v[100:103]
	v_mfma_f32_16x16x32_bf16 v[92:95], v[156:159], v[180:183], v[92:95]
	v_mfma_f32_16x16x32_bf16 v[84:87], v[148:151], v[200:203], v[84:87]
	v_mfma_f32_16x16x32_bf16 v[76:79], v[156:159], v[200:203], v[76:79]
	s_barrier
	s_add_i32 s20, 0, 0x1c000
	s_add_i32 s10, s26, s63
	v_add_u32_e32 v190, s20, v143
	v_lshl_add_u64 v[184:185], v[184:185], 0, s[88:89]
	s_mov_b32 m0, s10
	ds_read_b128 v[204:207], v190
	ds_read_b128 v[216:219], v190 offset:1024
	ds_read_b128 v[220:223], v190 offset:2048
	ds_read_b128 v[224:227], v190 offset:3072
	global_load_lds_dwordx4 v[184:185], off
	s_add_i32 m0, s10, 0x2000
	v_lshl_add_u64 v[184:185], v[186:187], 0, s[88:89]
	global_load_lds_dwordx4 v[184:185], off
	s_barrier
	s_waitcnt lgkmcnt(0)
	v_mfma_f32_16x16x32_bf16 v[112:115], v[204:207], v[160:163], v[112:115]
	v_mfma_f32_16x16x32_bf16 v[104:107], v[220:223], v[160:163], v[104:107]
	v_mfma_f32_16x16x32_bf16 v[96:99], v[204:207], v[168:171], v[96:99]
	v_mfma_f32_16x16x32_bf16 v[88:91], v[220:223], v[168:171], v[88:91]
	v_mfma_f32_16x16x32_bf16 v[80:83], v[204:207], v[176:179], v[80:83]
	v_mfma_f32_16x16x32_bf16 v[72:75], v[220:223], v[176:179], v[72:75]
	v_mfma_f32_16x16x32_bf16 v[68:71], v[204:207], v[196:199], v[68:71]
	v_mfma_f32_16x16x32_bf16 v[64:67], v[220:223], v[196:199], v[64:67]
	v_mfma_f32_16x16x32_bf16 v[112:115], v[216:219], v[164:167], v[112:115]
	v_mfma_f32_16x16x32_bf16 v[104:107], v[224:227], v[164:167], v[104:107]
	v_mfma_f32_16x16x32_bf16 v[96:99], v[216:219], v[172:175], v[96:99]
	v_mfma_f32_16x16x32_bf16 v[88:91], v[224:227], v[172:175], v[88:91]
	v_mfma_f32_16x16x32_bf16 v[80:83], v[216:219], v[180:183], v[80:83]
	v_mfma_f32_16x16x32_bf16 v[72:75], v[224:227], v[180:183], v[72:75]
	v_mfma_f32_16x16x32_bf16 v[68:71], v[216:219], v[200:203], v[68:71]
	v_mfma_f32_16x16x32_bf16 v[64:67], v[224:227], v[200:203], v[64:67]
	s_mov_b32 m0, s69
	v_lshl_add_u64 v[184:185], v[188:189], 0, s[88:89]
	s_barrier
	ds_read_b128 v[160:163], v147 offset:49152
	ds_read_b128 v[164:167], v147 offset:50176
	ds_read_b128 v[168:171], v147 offset:51200
	ds_read_b128 v[172:175], v147 offset:52224
	ds_read_b128 v[176:179], v147 offset:53248
	ds_read_b128 v[180:183], v147 offset:54272
	ds_read_b128 v[196:199], v147 offset:55296
	ds_read_b128 v[200:203], v147 offset:56320
	global_load_lds_dwordx4 v[184:185], off
	s_mov_b32 m0, s70
	v_lshl_add_u64 v[184:185], v[192:193], 0, s[88:89]
	global_load_lds_dwordx4 v[184:185], off
	s_barrier
; #define PG8_STAGE(bufoff, gbase, voff) do { _Pragma("unroll") for (int _i = 0; _i < 2; ++_i) \
;         __builtin_amdgcn_global_load_lds((const unsigned*)((const char*)(gbase) + (voff)[_i]), (LAS unsigned*)(lds + (bufoff) + ldsw + _i * 8192), 16, 0, 0); } while (0)
; #define PG8_MMA(ai, bj, At, Bt) do { __builtin_amdgcn_s_setprio(1); _Pragma("unroll") for (int m = 0; m < 4; ++m) _Pragma("unroll") for (int n = 0; n < 2; ++n) _Pragma("unroll") for (int k = 0; k < 2; ++k) \
;         acc[ai][bj][m][n] = __builtin_amdgcn_mfma_f32_16x16x32_bf16(Bt[n][k], At[m][k], acc[ai][bj][m][n], 0, 0, 0); __builtin_amdgcn_s_setprio(0); } while (0)
; #define PG8_WAIT_V(n) asm volatile("s_waitcnt vmcnt(" #n ")" ::: "memory")
; #define PG8_WAIT_L(n) asm volatile("s_waitcnt lgkmcnt(" #n ")" ::: "memory")
; #define PG8_BAR __builtin_amdgcn_s_barrier()
; #define PG8_SCHED __builtin_amdgcn_sched_barrier(0)
; template <class Epi>
; __device__ __forceinline__ void gemm_phase(LAS unsigned char* lds, const Gemm g, const StaticOrder& S, const Epi& E) {
;     ...
;             PG8_BAR; PG8_WAIT_L(0); PG8_MMA(1, 0, At, B0); PG8_BAR; PG8_SCHED;
;             PG8_STAGE(PG8_SB(1, 1), b3 + hB, voffB);
;             PG8_WAIT_V(6); PG8_BAR; PG8_MMA(1, 1, At, B1); PG8_BAR;
	s_waitcnt lgkmcnt(0)
	v_mfma_f32_16x16x32_bf16 v[60:63], v[138:141], v[160:163], v[60:63]
	v_mfma_f32_16x16x32_bf16 v[56:59], v[152:155], v[160:163], v[56:59]
	v_mfma_f32_16x16x32_bf16 v[52:55], v[138:141], v[168:171], v[52:55]
	v_mfma_f32_16x16x32_bf16 v[44:47], v[152:155], v[168:171], v[44:47]
	v_mfma_f32_16x16x32_bf16 v[36:39], v[138:141], v[176:179], v[36:39]
	v_mfma_f32_16x16x32_bf16 v[28:31], v[152:155], v[176:179], v[28:31]
	v_mfma_f32_16x16x32_bf16 v[20:23], v[138:141], v[196:199], v[20:23]
	v_mfma_f32_16x16x32_bf16 v[12:15], v[152:155], v[196:199], v[12:15]
	v_mfma_f32_16x16x32_bf16 v[60:63], v[148:151], v[164:167], v[60:63]
	v_mfma_f32_16x16x32_bf16 v[56:59], v[156:159], v[164:167], v[56:59]
	v_mfma_f32_16x16x32_bf16 v[52:55], v[148:151], v[172:175], v[52:55]
	v_mfma_f32_16x16x32_bf16 v[44:47], v[156:159], v[172:175], v[44:47]
	v_mfma_f32_16x16x32_bf16 v[36:39], v[148:151], v[180:183], v[36:39]
	v_mfma_f32_16x16x32_bf16 v[28:31], v[156:159], v[180:183], v[28:31]
	v_mfma_f32_16x16x32_bf16 v[20:23], v[148:151], v[200:203], v[20:23]
	v_mfma_f32_16x16x32_bf16 v[12:15], v[156:159], v[200:203], v[12:15]
	s_barrier
	s_add_u32 s10, s16, 0x18080
	s_addc_u32 s11, s17, 0
	s_add_i32 s16, s20, s63
	s_mov_b32 m0, s16
	s_nop 0
	global_load_lds_dwordx4 v144, s[10:11]
	s_add_i32 m0, s16, 0x2000
	s_nop 0
	global_load_lds_dwordx4 v132, s[10:11]
	s_waitcnt vmcnt(6)
	s_barrier
	v_mfma_f32_16x16x32_bf16 v[48:51], v[204:207], v[160:163], v[48:51]
	v_mfma_f32_16x16x32_bf16 v[40:43], v[220:223], v[160:163], v[40:43]
	v_mfma_f32_16x16x32_bf16 v[32:35], v[204:207], v[168:171], v[32:35]
	v_mfma_f32_16x16x32_bf16 v[24:27], v[220:223], v[168:171], v[24:27]
	v_mfma_f32_16x16x32_bf16 v[16:19], v[204:207], v[176:179], v[16:19]
	v_mfma_f32_16x16x32_bf16 v[8:11], v[220:223], v[176:179], v[8:11]
	v_mfma_f32_16x16x32_bf16 v[4:7], v[204:207], v[196:199], v[4:7]
	v_mfma_f32_16x16x32_bf16 v[0:3], v[220:223], v[196:199], v[0:3]
	v_mfma_f32_16x16x32_bf16 v[48:51], v[216:219], v[164:167], v[48:51]
	v_mfma_f32_16x16x32_bf16 v[40:43], v[224:227], v[164:167], v[40:43]
	v_mfma_f32_16x16x32_bf16 v[32:35], v[216:219], v[172:175], v[32:35]
	v_mfma_f32_16x16x32_bf16 v[24:27], v[224:227], v[172:175], v[24:27]
	v_mfma_f32_16x16x32_bf16 v[16:19], v[216:219], v[180:183], v[16:19]
	v_mfma_f32_16x16x32_bf16 v[8:11], v[224:227], v[180:183], v[8:11]
	v_mfma_f32_16x16x32_bf16 v[4:7], v[216:219], v[200:203], v[4:7]
	v_mfma_f32_16x16x32_bf16 v[0:3], v[224:227], v[200:203], v[0:3]
	s_add_i32 s78, s78, 2
	s_add_u32 s24, s24, 0x100
	s_addc_u32 s25, s25, 0
	s_cmp_gt_u32 s78, 3
	s_mov_b64 s[10:11], s[12:13]
	s_barrier
	s_cbranch_scc0 .LBB0_655
; __device__ __forceinline__ unsigned pk2(float lo, float hi) { unsigned r; asm("v_cvt_pk_bf16_f32 %0, %1, %2" : "=v"(r) : "v"(lo), "v"(hi)); return r; }
; #define PG8_WAIT_V(n) asm volatile("s_waitcnt vmcnt(" #n ")" ::: "memory")
; #define PG8_BAR __builtin_amdgcn_s_barrier()
; template <class Epi>
; __device__ __forceinline__ void gemm_phase(LAS unsigned char* lds, const Gemm g, const StaticOrder& S, const Epi& E) {
;     ...
;         E(acc, cur, wr, wc, fr, fq);
;         if (!has_next) break;
; #pragma unroll
;         for (int a = 0; a < 2; ++a)
; #pragma unroll
;             for (int b = 0; b < 2; ++b)
; #pragma unroll
;                 for (int m = 0; m < 4; ++m)
; #pragma unroll
;                     for (int n = 0; n < 2; ++n) acc[a][b][m][n] = (f32x4){0.f, 0.f, 0.f, 0.f};
;         cur = nxt; cA = nA; cB = nB; ++ui;
;     }
;     PG8_WAIT_V(0);
;     if (wr == 0) PG8_BAR;
;     __device__ __forceinline__ void operator()(const f32x4 (&acc)[2][2][4][2], const Unit& u, int wr, int wc, int fr, int fq) const {
;     ...
;         const int row_t = rmap == 1 ? odd_phys_row0(u.pm, grp) : (rmap == 2 ? odd_phys_row0(u.pm % (BG * TPB), u.pm / (BG * TPB)) : u.pm * BM);
;         int c = col_t + 64 * wc + 16 * fq;
;         if (mode == 2) c = (c >> 6) * 96 + (c & 63);
; #pragma unroll
;         for (int ai = 0; ai < 2; ++ai)
; #pragma unroll
;             for (int m = 0; m < 4; ++m) {
;                 const int row = row_t + ai * HALF + wr * 64 + m * 16 + fr;
;                 bf16_t* rp = O + (size_t)row * ldc + c;
; #pragma unroll
;                 for (int bj = 0; bj < 2; ++bj) {
;                     const f32x4 v0 = acc[ai][bj][m][0], v1 = acc[ai][bj][m][1];
;                     u32x4 o; o.x = pk2(v0[0], v0[1]); o.y = pk2(v0[2], v0[3]); o.z = pk2(v1[0], v1[1]); o.w = pk2(v1[2], v1[3]);
;                     *(u32x4*)(rp + 8 * bj) = o;
;                 }
;             }
	v_lshl_or_b32 v140, s15, 8, v146
	v_lshl_add_u32 v150, s77, 8, v142
	v_ashrrev_i32_e32 v141, 31, v140
	v_mov_b64_e32 v[138:139], s[8:9]
	v_cvt_pk_bf16_f32 v68, v68, v69
	v_cvt_pk_bf16_f32 v69, v70, v71
	v_cvt_pk_bf16_f32 v70, v64, v65
	v_add_u32_e32 v64, 0x80, v150
	v_mad_i64_i32 v[148:149], s[10:11], v150, s90, v[138:139]
	v_lshlrev_b64 v[140:141], 1, v[140:141]
	v_cvt_pk_bf16_f32 v112, v112, v113
	v_cvt_pk_bf16_f32 v113, v114, v115
	v_cvt_pk_bf16_f32 v114, v104, v105
	v_or_b32_e32 v104, 16, v150
	v_mad_i64_i32 v[64:65], s[10:11], v64, s90, v[138:139]
	v_cvt_pk_bf16_f32 v48, v48, v49
	v_cvt_pk_bf16_f32 v49, v50, v51
	v_cvt_pk_bf16_f32 v50, v40, v41
	v_add_u32_e32 v40, 0x90, v150
	v_lshl_add_u64 v[148:149], v[148:149], 0, v[140:141]
	v_mad_i64_i32 v[104:105], s[10:11], v104, s90, v[138:139]
	v_cvt_pk_bf16_f32 v96, v96, v97
	v_cvt_pk_bf16_f32 v97, v98, v99
	v_cvt_pk_bf16_f32 v98, v88, v89
	v_or_b32_e32 v88, 32, v150
	v_lshl_add_u64 v[64:65], v[64:65], 0, v[140:141]
	v_mad_i64_i32 v[40:41], s[10:11], v40, s90, v[138:139]
	v_cvt_pk_bf16_f32 v32, v32, v33
	v_cvt_pk_bf16_f32 v33, v34, v35
	v_cvt_pk_bf16_f32 v34, v24, v25
	v_add_u32_e32 v24, 0xa0, v150
	v_cvt_pk_bf16_f32 v115, v106, v107
	global_store_dwordx4 v[148:149], v[112:115], off offset:16
	v_mad_i64_i32 v[88:89], s[10:11], v88, s90, v[138:139]
	s_nop 0
	v_lshl_add_u64 v[112:113], v[104:105], 0, v[140:141]
	v_cvt_pk_bf16_f32 v80, v80, v81
	v_cvt_pk_bf16_f32 v81, v82, v83
	v_cvt_pk_bf16_f32 v82, v72, v73
	v_or_b32_e32 v72, 48, v150
	v_cvt_pk_bf16_f32 v51, v42, v43
	global_store_dwordx4 v[64:65], v[48:51], off offset:16
	v_mad_i64_i32 v[24:25], s[10:11], v24, s90, v[138:139]
	s_nop 0
	v_lshl_add_u64 v[48:49], v[40:41], 0, v[140:141]
	v_cvt_pk_bf16_f32 v16, v16, v17
	v_cvt_pk_bf16_f32 v17, v18, v19
	v_cvt_pk_bf16_f32 v18, v8, v9
	v_add_u32_e32 v8, 0xb0, v150
	v_cvt_pk_bf16_f32 v99, v90, v91
	global_store_dwordx4 v[112:113], v[96:99], off offset:16
	v_mad_i64_i32 v[72:73], s[10:11], v72, s90, v[138:139]
	s_nop 0
	v_lshl_add_u64 v[96:97], v[88:89], 0, v[140:141]
	v_cvt_pk_bf16_f32 v35, v26, v27
	global_store_dwordx4 v[48:49], v[32:35], off offset:16
	v_mad_i64_i32 v[8:9], s[10:11], v8, s90, v[138:139]
	s_nop 0
	v_lshl_add_u64 v[32:33], v[24:25], 0, v[140:141]
	v_cvt_pk_bf16_f32 v83, v74, v75
	global_store_dwordx4 v[96:97], v[80:83], off offset:16
	v_cvt_pk_bf16_f32 v19, v10, v11
	global_store_dwordx4 v[32:33], v[16:19], off offset:16
	s_and_b64 vcc, exec, s[0:1]
	v_lshl_add_u64 v[80:81], v[72:73], 0, v[140:141]
	v_lshl_add_u64 v[16:17], v[8:9], 0, v[140:141]
	s_mov_b32 s15, s72
	s_mov_b32 s77, s76
	s_mov_b64 s[12:13], s[6:7]
	s_mov_b64 s[10:11], s[4:5]
	v_cvt_pk_bf16_f32 v124, v124, v125
	v_cvt_pk_bf16_f32 v125, v126, v127
	v_cvt_pk_bf16_f32 v126, v120, v121
	v_cvt_pk_bf16_f32 v127, v122, v123
	global_store_dwordx4 v[148:149], v[124:127], off
	v_cvt_pk_bf16_f32 v104, v116, v117
	v_cvt_pk_bf16_f32 v105, v118, v119
	v_cvt_pk_bf16_f32 v106, v108, v109
	v_cvt_pk_bf16_f32 v107, v110, v111
	global_store_dwordx4 v[112:113], v[104:107], off
	v_cvt_pk_bf16_f32 v88, v100, v101
	v_cvt_pk_bf16_f32 v89, v102, v103
	v_cvt_pk_bf16_f32 v90, v92, v93
	v_cvt_pk_bf16_f32 v91, v94, v95
	global_store_dwordx4 v[96:97], v[88:91], off
	v_cvt_pk_bf16_f32 v72, v84, v85
	v_cvt_pk_bf16_f32 v73, v86, v87
	v_cvt_pk_bf16_f32 v74, v76, v77
	v_cvt_pk_bf16_f32 v75, v78, v79
	global_store_dwordx4 v[80:81], v[72:75], off
	v_cvt_pk_bf16_f32 v71, v66, v67
	global_store_dwordx4 v[80:81], v[68:71], off offset:16
	v_cvt_pk_bf16_f32 v60, v60, v61
	v_cvt_pk_bf16_f32 v61, v62, v63
	v_cvt_pk_bf16_f32 v62, v56, v57
	v_cvt_pk_bf16_f32 v63, v58, v59
	global_store_dwordx4 v[64:65], v[60:63], off
	v_cvt_pk_bf16_f32 v40, v52, v53
	v_cvt_pk_bf16_f32 v41, v54, v55
	v_cvt_pk_bf16_f32 v42, v44, v45
	v_cvt_pk_bf16_f32 v43, v46, v47
	global_store_dwordx4 v[48:49], v[40:43], off
	v_cvt_pk_bf16_f32 v24, v36, v37
	v_cvt_pk_bf16_f32 v25, v38, v39
	v_cvt_pk_bf16_f32 v26, v28, v29
	v_cvt_pk_bf16_f32 v27, v30, v31
	global_store_dwordx4 v[32:33], v[24:27], off
	v_cvt_pk_bf16_f32 v8, v20, v21
	v_cvt_pk_bf16_f32 v9, v22, v23
	v_cvt_pk_bf16_f32 v10, v12, v13
	v_cvt_pk_bf16_f32 v11, v14, v15
	global_store_dwordx4 v[16:17], v[8:11], off
	v_cvt_pk_bf16_f32 v4, v4, v5
	v_cvt_pk_bf16_f32 v5, v6, v7
	v_cvt_pk_bf16_f32 v6, v0, v1
	v_cvt_pk_bf16_f32 v7, v2, v3
	global_store_dwordx4 v[16:17], v[4:7], off offset:16
	s_cbranch_vccz .LBB0_644
	s_waitcnt vmcnt(0)
	s_cmpk_gt_u32 s14, 0xff
	s_cbranch_scc1 .LBB0_659
	s_barrier

; #define PG8_STAGE(bufoff, gbase, voff) do { _Pragma("unroll") for (int _i = 0; _i < 2; ++_i) \
;         __builtin_amdgcn_global_load_lds((const unsigned*)((const char*)(gbase) + (voff)[_i]), (LAS unsigned*)(lds + (bufoff) + ldsw + _i * 8192), 16, 0, 0); } while (0)
; #define PG8_LDA(dst, b, h) do { _Pragma("unroll") for (int m = 0; m < 4; ++m) _Pragma("unroll") for (int k = 0; k < 2; ++k) dst[m][k] = *(const LAS bf16x8*)(lds + PG8_SA(b, h) + aoff + m * 2048 + k * 1024); } while (0)
; #define PG8_LDB(dst, b, h) do { _Pragma("unroll") for (int n = 0; n < 2; ++n) _Pragma("unroll") for (int k = 0; k < 2; ++k) dst[n][k] = *(const LAS bf16x8*)(lds + PG8_SB(b, h) + boff + n * 2048 + k * 1024); } while (0)
; #define PG8_MMA(ai, bj, At, Bt) do { __builtin_amdgcn_s_setprio(1); _Pragma("unroll") for (int m = 0; m < 4; ++m) _Pragma("unroll") for (int n = 0; n < 2; ++n) _Pragma("unroll") for (int k = 0; k < 2; ++k) \
;         acc[ai][bj][m][n] = __builtin_amdgcn_mfma_f32_16x16x32_bf16(Bt[n][k], At[m][k], acc[ai][bj][m][n], 0, 0, 0); __builtin_amdgcn_s_setprio(0); } while (0)
; #define PG8_WAIT_L(n) asm volatile("s_waitcnt lgkmcnt(" #n ")" ::: "memory")
; template <class Epi>
; __device__ __forceinline__ void gemm_phase(LAS unsigned char* lds, const Gemm g, const StaticOrder& S, const Epi& E) {
;     ...
;     for (;;) {
;         const bool has_next = S.next(ui + 1, nxt);
;         const char* nA = has_next ? g.arow(nxt.pm) : cA; const char* nB = has_next ? (const char*)g.Bt + (size_t)nxt.pn * tB : cB;
;         for (int t = 0; t < nt; t += 2) {
;             const bool last = (t == nt - 2);
;             const char* a1 = cA + (size_t)(t + 1) * kstep;
;             const char* a2 = last ? nA : cA + (size_t)(t + 2) * kstep; const char* b2 = last ? nB : cB + (size_t)(t + 2) * kstep;
;             const char* a3 = a2 + kstep; const char* b3 = b2 + kstep;
;             PG8_LDB(B0, 0, 0); PG8_SCHED; PG8_LDA(At, 0, 0); PG8_STAGE(PG8_SA(1, 1), a1 + hA, voffA);
;             PG8_WAIT_L(8); PG8_BAR; PG8_WAIT_L(0); PG8_MMA(0, 0, At, B0); PG8_BAR; PG8_SCHED;
;             PG8_LDB(B1, 0, 1); PG8_STAGE(PG8_SB(0, 0), b2, voffB);
;             PG8_BAR; PG8_WAIT_L(0); PG8_MMA(0, 1, At, B1); PG8_BAR;
;             PG8_LDA(At, 0, 1); PG8_STAGE(PG8_SA(0, 0), a2, voffA);
;             PG8_BAR; PG8_WAIT_L(0); PG8_MMA(1, 0, At, B0); PG8_BAR; PG8_SCHED;
.LBB0_670:
	s_add_u32 s28, s82, s25
	s_addc_u32 s29, s83, 0
	s_add_u32 s30, s28, 0x100
	s_addc_u32 s31, s29, 0
	s_and_b64 s[26:27], s[34:35], exec
	s_cselect_b32 s93, s17, s31
	s_cselect_b32 s92, s16, s30
	s_add_u32 s25, s64, s25
	s_addc_u32 s26, s65, 0
	s_add_u32 s25, s25, 0x100
	s_addc_u32 s30, s26, 0
	s_add_i32 s31, 0, 0x10000
	s_and_b64 s[26:27], s[34:35], exec
	s_cselect_b32 vcc_hi, s13, s30
	s_cselect_b32 vcc_lo, s24, s25
	s_add_u32 s76, s28, 0xb0080
	s_addc_u32 s77, s29, 0
	s_add_i32 s39, s31, s63
	s_add_i32 m0, s40, 0xc000
	s_add_i32 s68, s40, 0xe000
	s_add_i32 s29, 0, 0x14000
	s_add_i32 s37, s39, 0x2000
	s_add_u32 s86, vcc_lo, 0x10000
	v_add_u32_e32 v146, s31, v150
	s_addc_u32 s87, vcc_hi, 0
	s_add_i32 s30, s29, s63
	ds_read_b128 v[136:139], v146
	ds_read_b128 v[140:143], v146 offset:1024
	ds_read_b128 v[158:161], v146 offset:2048
	ds_read_b128 v[162:165], v146 offset:3072
	s_add_i32 s38, s30, 0x2000
	s_add_i32 s27, 0, 0x18000
	s_add_u32 s84, s92, 0xb0000
	s_addc_u32 s85, s93, 0
	s_add_i32 s25, s27, s63
	s_add_i32 s26, 0, 0x1c000
	s_add_i32 s28, s25, 0x2000
	s_add_u32 s34, vcc_lo, 0x10080
	s_addc_u32 s35, vcc_hi, 0
	s_add_i32 s31, s26, s63
	s_add_i32 s36, s31, 0x2000
	ds_read_b128 v[166:169], v154
	ds_read_b128 v[170:173], v154 offset:1024
	ds_read_b128 v[174:177], v154 offset:2048
	ds_read_b128 v[178:181], v154 offset:3072
	ds_read_b128 v[182:185], v154 offset:4096
	ds_read_b128 v[196:199], v154 offset:5120
	ds_read_b128 v[200:203], v154 offset:6144
	ds_read_b128 v[204:207], v154 offset:7168
	global_load_lds_dwordx4 v134, s[76:77]
	s_mov_b32 m0, s68
	v_lshl_add_u64 v[146:147], s[76:77], 0, v[130:131]
	global_load_lds_dwordx4 v[146:147], off
	s_waitcnt lgkmcnt(8)
	s_barrier
	s_waitcnt lgkmcnt(0)
	v_mfma_f32_16x16x32_bf16 v[124:127], v[136:139], v[166:169], v[124:127]
	v_mfma_f32_16x16x32_bf16 v[120:123], v[158:161], v[166:169], v[120:123]
	v_mfma_f32_16x16x32_bf16 v[116:119], v[136:139], v[174:177], v[116:119]
	v_mfma_f32_16x16x32_bf16 v[108:111], v[158:161], v[174:177], v[108:111]
	v_mfma_f32_16x16x32_bf16 v[100:103], v[136:139], v[182:185], v[100:103]
	v_mfma_f32_16x16x32_bf16 v[92:95], v[158:161], v[182:185], v[92:95]
	v_mfma_f32_16x16x32_bf16 v[84:87], v[136:139], v[200:203], v[84:87]
	v_mfma_f32_16x16x32_bf16 v[76:79], v[158:161], v[200:203], v[76:79]
	v_mfma_f32_16x16x32_bf16 v[124:127], v[140:143], v[170:173], v[124:127]
	v_mfma_f32_16x16x32_bf16 v[120:123], v[162:165], v[170:173], v[120:123]
	v_mfma_f32_16x16x32_bf16 v[116:119], v[140:143], v[178:181], v[116:119]
	v_mfma_f32_16x16x32_bf16 v[108:111], v[162:165], v[178:181], v[108:111]
	v_mfma_f32_16x16x32_bf16 v[100:103], v[140:143], v[196:199], v[100:103]
	v_mfma_f32_16x16x32_bf16 v[92:95], v[162:165], v[196:199], v[92:95]
	v_mfma_f32_16x16x32_bf16 v[84:87], v[140:143], v[204:207], v[84:87]
	v_mfma_f32_16x16x32_bf16 v[76:79], v[162:165], v[204:207], v[76:79]
	s_barrier
	v_add_u32_e32 v146, s29, v150
	s_mov_b32 m0, s39
	ds_read_b128 v[216:219], v146
	ds_read_b128 v[220:223], v146 offset:1024
	ds_read_b128 v[224:227], v146 offset:2048
	ds_read_b128 v[228:231], v146 offset:3072
	v_lshl_add_u64 v[146:147], vcc, 0, v[132:133]
	global_load_lds_dwordx4 v[146:147], off
	s_mov_b32 m0, s37
	v_lshl_add_u64 v[186:187], vcc, 0, v[128:129]
	global_load_lds_dwordx4 v[186:187], off
	s_barrier
	s_waitcnt lgkmcnt(0)
	v_mfma_f32_16x16x32_bf16 v[112:115], v[216:219], v[166:169], v[112:115]
	v_mfma_f32_16x16x32_bf16 v[104:107], v[224:227], v[166:169], v[104:107]
	v_mfma_f32_16x16x32_bf16 v[96:99], v[216:219], v[174:177], v[96:99]
	v_mfma_f32_16x16x32_bf16 v[88:91], v[224:227], v[174:177], v[88:91]
	v_mfma_f32_16x16x32_bf16 v[80:83], v[216:219], v[182:185], v[80:83]
	v_mfma_f32_16x16x32_bf16 v[72:75], v[224:227], v[182:185], v[72:75]
	v_mfma_f32_16x16x32_bf16 v[68:71], v[216:219], v[200:203], v[68:71]
	v_mfma_f32_16x16x32_bf16 v[64:67], v[224:227], v[200:203], v[64:67]
	v_mfma_f32_16x16x32_bf16 v[112:115], v[220:223], v[170:173], v[112:115]
	v_mfma_f32_16x16x32_bf16 v[104:107], v[228:231], v[170:173], v[104:107]
	v_mfma_f32_16x16x32_bf16 v[96:99], v[220:223], v[178:181], v[96:99]
	v_mfma_f32_16x16x32_bf16 v[88:91], v[228:231], v[178:181], v[88:91]
	v_mfma_f32_16x16x32_bf16 v[80:83], v[220:223], v[196:199], v[80:83]
	v_mfma_f32_16x16x32_bf16 v[72:75], v[228:231], v[196:199], v[72:75]
	v_mfma_f32_16x16x32_bf16 v[68:71], v[220:223], v[204:207], v[68:71]
	v_mfma_f32_16x16x32_bf16 v[64:67], v[228:231], v[204:207], v[64:67]
	s_mov_b32 m0, s40
	v_lshl_add_u64 v[188:189], s[92:93], 0, v[134:135]
	s_barrier
	ds_read_b128 v[166:169], v154 offset:16384
	ds_read_b128 v[170:173], v154 offset:17408
	ds_read_b128 v[174:177], v154 offset:18432
	ds_read_b128 v[178:181], v154 offset:19456
	ds_read_b128 v[182:185], v154 offset:20480
	ds_read_b128 v[196:199], v154 offset:21504
	ds_read_b128 v[200:203], v154 offset:22528
	ds_read_b128 v[204:207], v154 offset:23552
	global_load_lds_dwordx4 v[188:189], off
	s_mov_b32 m0, s69
	v_lshl_add_u64 v[192:193], s[92:93], 0, v[130:131]
	global_load_lds_dwordx4 v[192:193], off
	s_barrier
	s_waitcnt lgkmcnt(0)
	v_mfma_f32_16x16x32_bf16 v[60:63], v[136:139], v[166:169], v[60:63]
	v_mfma_f32_16x16x32_bf16 v[56:59], v[158:161], v[166:169], v[56:59]
	v_mfma_f32_16x16x32_bf16 v[52:55], v[136:139], v[174:177], v[52:55]
	v_mfma_f32_16x16x32_bf16 v[44:47], v[158:161], v[174:177], v[44:47]
	v_mfma_f32_16x16x32_bf16 v[36:39], v[136:139], v[182:185], v[36:39]
	v_mfma_f32_16x16x32_bf16 v[28:31], v[158:161], v[182:185], v[28:31]
	v_mfma_f32_16x16x32_bf16 v[20:23], v[136:139], v[200:203], v[20:23]
	v_mfma_f32_16x16x32_bf16 v[12:15], v[158:161], v[200:203], v[12:15]
	v_mfma_f32_16x16x32_bf16 v[60:63], v[140:143], v[170:173], v[60:63]
	v_mfma_f32_16x16x32_bf16 v[56:59], v[162:165], v[170:173], v[56:59]
	v_mfma_f32_16x16x32_bf16 v[52:55], v[140:143], v[178:181], v[52:55]
	v_mfma_f32_16x16x32_bf16 v[44:47], v[162:165], v[178:181], v[44:47]
	v_mfma_f32_16x16x32_bf16 v[36:39], v[140:143], v[196:199], v[36:39]
	v_mfma_f32_16x16x32_bf16 v[28:31], v[162:165], v[196:199], v[28:31]
	v_mfma_f32_16x16x32_bf16 v[20:23], v[140:143], v[204:207], v[20:23]
	v_mfma_f32_16x16x32_bf16 v[12:15], v[162:165], v[204:207], v[12:15]
	s_barrier
; #define PG8_STAGE(bufoff, gbase, voff) do { _Pragma("unroll") for (int _i = 0; _i < 2; ++_i) \
;         __builtin_amdgcn_global_load_lds((const unsigned*)((const char*)(gbase) + (voff)[_i]), (LAS unsigned*)(lds + (bufoff) + ldsw + _i * 8192), 16, 0, 0); } while (0)
; #define PG8_LDA(dst, b, h) do { _Pragma("unroll") for (int m = 0; m < 4; ++m) _Pragma("unroll") for (int k = 0; k < 2; ++k) dst[m][k] = *(const LAS bf16x8*)(lds + PG8_SA(b, h) + aoff + m * 2048 + k * 1024); } while (0)
; #define PG8_LDB(dst, b, h) do { _Pragma("unroll") for (int n = 0; n < 2; ++n) _Pragma("unroll") for (int k = 0; k < 2; ++k) dst[n][k] = *(const LAS bf16x8*)(lds + PG8_SB(b, h) + boff + n * 2048 + k * 1024); } while (0)
; #define PG8_MMA(ai, bj, At, Bt) do { __builtin_amdgcn_s_setprio(1); _Pragma("unroll") for (int m = 0; m < 4; ++m) _Pragma("unroll") for (int n = 0; n < 2; ++n) _Pragma("unroll") for (int k = 0; k < 2; ++k) \
;         acc[ai][bj][m][n] = __builtin_amdgcn_mfma_f32_16x16x32_bf16(Bt[n][k], At[m][k], acc[ai][bj][m][n], 0, 0, 0); __builtin_amdgcn_s_setprio(0); } while (0)
; #define PG8_WAIT_V(n) asm volatile("s_waitcnt vmcnt(" #n ")" ::: "memory")
; #define PG8_WAIT_L(n) asm volatile("s_waitcnt lgkmcnt(" #n ")" ::: "memory")
; #define PG8_BAR __builtin_amdgcn_s_barrier()
; #define PG8_SCHED __builtin_amdgcn_sched_barrier(0)
; template <class Epi>
; __device__ __forceinline__ void gemm_phase(LAS unsigned char* lds, const Gemm g, const StaticOrder& S, const Epi& E) {
;     ...
;             PG8_STAGE(PG8_SB(0, 1), b2 + hB, voffB);
;             PG8_WAIT_V(6); PG8_BAR; PG8_MMA(1, 1, At, B1); PG8_BAR;
;             PG8_LDB(B0, 1, 0); PG8_SCHED; PG8_LDA(At, 1, 0); PG8_STAGE(PG8_SA(0, 1), a2 + hA, voffA);
;             PG8_WAIT_L(8); PG8_BAR; PG8_WAIT_L(0); PG8_MMA(0, 0, At, B0); PG8_BAR; PG8_SCHED;
;             PG8_LDB(B1, 1, 1); PG8_STAGE(PG8_SB(1, 0), b3, voffB);
;             PG8_BAR; PG8_WAIT_L(0); PG8_MMA(0, 1, At, B1); PG8_BAR;
;             PG8_LDA(At, 1, 1); PG8_STAGE(PG8_SA(1, 0), a3, voffA);
	s_mov_b32 m0, s30
	s_nop 0
	global_load_lds_dwordx4 v132, s[86:87]
	s_mov_b32 m0, s38
	s_nop 0
	global_load_lds_dwordx4 v128, s[86:87]
	s_waitcnt vmcnt(6)
	s_barrier
	v_mfma_f32_16x16x32_bf16 v[48:51], v[216:219], v[166:169], v[48:51]
	v_mfma_f32_16x16x32_bf16 v[40:43], v[224:227], v[166:169], v[40:43]
	v_mfma_f32_16x16x32_bf16 v[32:35], v[216:219], v[174:177], v[32:35]
	v_mfma_f32_16x16x32_bf16 v[24:27], v[224:227], v[174:177], v[24:27]
	v_mfma_f32_16x16x32_bf16 v[16:19], v[216:219], v[182:185], v[16:19]
	v_mfma_f32_16x16x32_bf16 v[8:11], v[224:227], v[182:185], v[8:11]
	v_mfma_f32_16x16x32_bf16 v[4:7], v[216:219], v[200:203], v[4:7]
	v_mfma_f32_16x16x32_bf16 v[0:3], v[224:227], v[200:203], v[0:3]
	v_mfma_f32_16x16x32_bf16 v[48:51], v[220:223], v[170:173], v[48:51]
	v_mfma_f32_16x16x32_bf16 v[40:43], v[228:231], v[170:173], v[40:43]
	v_mfma_f32_16x16x32_bf16 v[32:35], v[220:223], v[178:181], v[32:35]
	v_mfma_f32_16x16x32_bf16 v[24:27], v[228:231], v[178:181], v[24:27]
	v_mfma_f32_16x16x32_bf16 v[16:19], v[220:223], v[196:199], v[16:19]
	v_mfma_f32_16x16x32_bf16 v[8:11], v[228:231], v[196:199], v[8:11]
	v_mfma_f32_16x16x32_bf16 v[4:7], v[220:223], v[204:207], v[4:7]
	v_mfma_f32_16x16x32_bf16 v[0:3], v[228:231], v[204:207], v[0:3]
	v_add_u32_e32 v157, s27, v150
	s_barrier
	ds_read_b128 v[136:139], v157
	ds_read_b128 v[140:143], v157 offset:1024
	ds_read_b128 v[158:161], v157 offset:2048
	ds_read_b128 v[162:165], v157 offset:3072
	s_mov_b32 m0, s70
	ds_read_b128 v[166:169], v154 offset:32768
	ds_read_b128 v[170:173], v154 offset:33792
	ds_read_b128 v[174:177], v154 offset:34816
	ds_read_b128 v[178:181], v154 offset:35840
	ds_read_b128 v[182:185], v154 offset:36864
	ds_read_b128 v[196:199], v154 offset:37888
	ds_read_b128 v[200:203], v154 offset:38912
	global_load_lds_dwordx4 v134, s[84:85]
	s_mov_b32 m0, s71
	ds_read_b128 v[204:207], v154 offset:39936
	global_load_lds_dwordx4 v130, s[84:85]
	s_waitcnt lgkmcnt(8)
	s_barrier
	s_waitcnt lgkmcnt(0)
	v_mfma_f32_16x16x32_bf16 v[124:127], v[136:139], v[166:169], v[124:127]
	v_mfma_f32_16x16x32_bf16 v[120:123], v[158:161], v[166:169], v[120:123]
	v_mfma_f32_16x16x32_bf16 v[116:119], v[136:139], v[174:177], v[116:119]
	v_mfma_f32_16x16x32_bf16 v[108:111], v[158:161], v[174:177], v[108:111]
	v_mfma_f32_16x16x32_bf16 v[100:103], v[136:139], v[182:185], v[100:103]
	v_mfma_f32_16x16x32_bf16 v[92:95], v[158:161], v[182:185], v[92:95]
	v_mfma_f32_16x16x32_bf16 v[84:87], v[136:139], v[200:203], v[84:87]
	v_mfma_f32_16x16x32_bf16 v[76:79], v[158:161], v[200:203], v[76:79]
	v_mfma_f32_16x16x32_bf16 v[124:127], v[140:143], v[170:173], v[124:127]
	v_mfma_f32_16x16x32_bf16 v[120:123], v[162:165], v[170:173], v[120:123]
	v_mfma_f32_16x16x32_bf16 v[116:119], v[140:143], v[178:181], v[116:119]
	v_mfma_f32_16x16x32_bf16 v[108:111], v[162:165], v[178:181], v[108:111]
	v_mfma_f32_16x16x32_bf16 v[100:103], v[140:143], v[196:199], v[100:103]
	v_mfma_f32_16x16x32_bf16 v[92:95], v[162:165], v[196:199], v[92:95]
	v_mfma_f32_16x16x32_bf16 v[84:87], v[140:143], v[204:207], v[84:87]
	v_mfma_f32_16x16x32_bf16 v[76:79], v[162:165], v[204:207], v[76:79]
	s_barrier
	s_mov_b32 m0, s25
	v_add_u32_e32 v157, s26, v150
	v_lshl_add_u64 v[146:147], v[146:147], 0, s[88:89]
	ds_read_b128 v[216:219], v157
	ds_read_b128 v[220:223], v157 offset:1024
	ds_read_b128 v[224:227], v157 offset:2048
	ds_read_b128 v[228:231], v157 offset:3072
	global_load_lds_dwordx4 v[146:147], off
	s_mov_b32 m0, s28
	v_lshl_add_u64 v[146:147], v[186:187], 0, s[88:89]
	global_load_lds_dwordx4 v[146:147], off
	s_barrier
	s_waitcnt lgkmcnt(0)
	v_mfma_f32_16x16x32_bf16 v[112:115], v[216:219], v[166:169], v[112:115]
	v_mfma_f32_16x16x32_bf16 v[104:107], v[224:227], v[166:169], v[104:107]
	v_mfma_f32_16x16x32_bf16 v[96:99], v[216:219], v[174:177], v[96:99]
	v_mfma_f32_16x16x32_bf16 v[88:91], v[224:227], v[174:177], v[88:91]
	v_mfma_f32_16x16x32_bf16 v[80:83], v[216:219], v[182:185], v[80:83]
	v_mfma_f32_16x16x32_bf16 v[72:75], v[224:227], v[182:185], v[72:75]
	v_mfma_f32_16x16x32_bf16 v[68:71], v[216:219], v[200:203], v[68:71]
	v_mfma_f32_16x16x32_bf16 v[64:67], v[224:227], v[200:203], v[64:67]
	v_mfma_f32_16x16x32_bf16 v[112:115], v[220:223], v[170:173], v[112:115]
	v_mfma_f32_16x16x32_bf16 v[104:107], v[228:231], v[170:173], v[104:107]
	v_mfma_f32_16x16x32_bf16 v[96:99], v[220:223], v[178:181], v[96:99]
	v_mfma_f32_16x16x32_bf16 v[88:91], v[228:231], v[178:181], v[88:91]
	v_mfma_f32_16x16x32_bf16 v[80:83], v[220:223], v[196:199], v[80:83]
	v_mfma_f32_16x16x32_bf16 v[72:75], v[228:231], v[196:199], v[72:75]
	v_mfma_f32_16x16x32_bf16 v[68:71], v[220:223], v[204:207], v[68:71]
	v_mfma_f32_16x16x32_bf16 v[64:67], v[228:231], v[204:207], v[64:67]
	s_mov_b32 m0, s72
	v_lshl_add_u64 v[146:147], v[188:189], 0, s[88:89]
	s_barrier
	ds_read_b128 v[166:169], v154 offset:49152
	ds_read_b128 v[170:173], v154 offset:50176
	ds_read_b128 v[174:177], v154 offset:51200
	ds_read_b128 v[178:181], v154 offset:52224
	ds_read_b128 v[182:185], v154 offset:53248
	ds_read_b128 v[196:199], v154 offset:54272
	ds_read_b128 v[200:203], v154 offset:55296
	ds_read_b128 v[204:207], v154 offset:56320
	global_load_lds_dwordx4 v[146:147], off
	s_mov_b32 m0, s78
	v_lshl_add_u64 v[146:147], v[192:193], 0, s[88:89]
	global_load_lds_dwordx4 v[146:147], off
	s_barrier
; #define LAS __attribute__((address_space(3)))
; __device__ __forceinline__ unsigned pk2(float lo, float hi) { unsigned r; asm("v_cvt_pk_bf16_f32 %0, %1, %2" : "=v"(r) : "v"(lo), "v"(hi)); return r; }
; #define PG8_STAGE(bufoff, gbase, voff) do { _Pragma("unroll") for (int _i = 0; _i < 2; ++_i) \
;         __builtin_amdgcn_global_load_lds((const unsigned*)((const char*)(gbase) + (voff)[_i]), (LAS unsigned*)(lds + (bufoff) + ldsw + _i * 8192), 16, 0, 0); } while (0)
; template <class Epi>
; __device__ __forceinline__ void gemm_phase(LAS unsigned char* lds, const Gemm g, const StaticOrder& S, const Epi& E) {
;     ...
;             PG8_BAR; PG8_WAIT_L(0); PG8_MMA(1, 0, At, B0); PG8_BAR; PG8_SCHED;
;             PG8_STAGE(PG8_SB(1, 1), b3 + hB, voffB);
;             PG8_WAIT_V(6); PG8_BAR; PG8_MMA(1, 1, At, B1); PG8_BAR;
;     __device__ __forceinline__ void operator()(const f32x4 (&acc)[2][2][4][2], const Unit& u, int wr, int wc, int fr, int fq) const {
;         const int col_t = u.pn * BM;
;         if (mode != 0 && col_t >= vt0) {
;             const int bl = u.pm / TPB, key0 = (u.pm - bl * TPB) * 256;
;             LAS bf16_t* sc = (LAS bf16_t*)(trs + (wr * 4 + wc) * 2304);
;             const int lane = fq * 16 + fr;
; #pragma unroll
;             for (int ai = 0; ai < 2; ++ai)
; #pragma unroll
;                 for (int bj = 0; bj < 2; ++bj)
; #pragma unroll
;                     for (int n = 0; n < 2; ++n) {
; #pragma unroll
;                         for (int m = 0; m < 4; ++m) {
;                             const f32x4 v = acc[ai][bj][m][n];
;                             const unsigned p0 = pk2(v[0], v[1]), p1 = pk2(v[2], v[3]);
;                             LAS bf16_t* w = sc + (4 * fq) * 72 + 16 * m + fr;
;                             w[0] = (bf16_t)(p0 & 0xffffu); w[72] = (bf16_t)(p0 >> 16); w[144] = (bf16_t)(p1 & 0xffffu); w[216] = (bf16_t)(p1 >> 16);
;                         }
; #pragma unroll
;                         for (int j = 0; j < 2; ++j) {
;                             const int ch = lane + 64 * j, fi = ch >> 3, seg = ch & 7;
;                             const u32x4 o = *(const LAS u32x4*)(sc + fi * 72 + 8 * seg);
;                             const int f = col_t - vt0 + 64 * wc + 16 * (fi >> 2) + 8 * bj + 4 * n + (fi & 3);
;                             *(u32x4*)(Vt + ((size_t)bl * vtnf + f) * KEYS + key0 + ai * HALF + wr * 64 + 8 * seg) = o;
	s_waitcnt lgkmcnt(0)
	v_mfma_f32_16x16x32_bf16 v[60:63], v[136:139], v[166:169], v[60:63]
	v_mfma_f32_16x16x32_bf16 v[56:59], v[158:161], v[166:169], v[56:59]
	v_mfma_f32_16x16x32_bf16 v[52:55], v[136:139], v[174:177], v[52:55]
	v_mfma_f32_16x16x32_bf16 v[44:47], v[158:161], v[174:177], v[44:47]
	v_mfma_f32_16x16x32_bf16 v[36:39], v[136:139], v[182:185], v[36:39]
	v_mfma_f32_16x16x32_bf16 v[28:31], v[158:161], v[182:185], v[28:31]
	v_mfma_f32_16x16x32_bf16 v[20:23], v[136:139], v[200:203], v[20:23]
	v_mfma_f32_16x16x32_bf16 v[12:15], v[158:161], v[200:203], v[12:15]
	v_mfma_f32_16x16x32_bf16 v[60:63], v[140:143], v[170:173], v[60:63]
	v_mfma_f32_16x16x32_bf16 v[56:59], v[162:165], v[170:173], v[56:59]
	v_mfma_f32_16x16x32_bf16 v[52:55], v[140:143], v[178:181], v[52:55]
	v_mfma_f32_16x16x32_bf16 v[44:47], v[162:165], v[178:181], v[44:47]
	v_mfma_f32_16x16x32_bf16 v[36:39], v[140:143], v[196:199], v[36:39]
	v_mfma_f32_16x16x32_bf16 v[28:31], v[162:165], v[196:199], v[28:31]
	v_mfma_f32_16x16x32_bf16 v[20:23], v[140:143], v[204:207], v[20:23]
	v_mfma_f32_16x16x32_bf16 v[12:15], v[162:165], v[204:207], v[12:15]
	s_barrier
	s_mov_b32 m0, s31
	s_nop 0
	global_load_lds_dwordx4 v132, s[34:35]
	s_mov_b32 m0, s36
	s_nop 0
	global_load_lds_dwordx4 v128, s[34:35]
	s_waitcnt vmcnt(6)
	s_barrier
	v_mfma_f32_16x16x32_bf16 v[48:51], v[216:219], v[166:169], v[48:51]
	v_mfma_f32_16x16x32_bf16 v[40:43], v[224:227], v[166:169], v[40:43]
	v_mfma_f32_16x16x32_bf16 v[32:35], v[216:219], v[174:177], v[32:35]
	v_mfma_f32_16x16x32_bf16 v[24:27], v[224:227], v[174:177], v[24:27]
	v_mfma_f32_16x16x32_bf16 v[16:19], v[216:219], v[182:185], v[16:19]
	v_mfma_f32_16x16x32_bf16 v[8:11], v[224:227], v[182:185], v[8:11]
	v_mfma_f32_16x16x32_bf16 v[4:7], v[216:219], v[200:203], v[4:7]
	v_mfma_f32_16x16x32_bf16 v[0:3], v[224:227], v[200:203], v[0:3]
	v_mfma_f32_16x16x32_bf16 v[48:51], v[220:223], v[170:173], v[48:51]
	v_mfma_f32_16x16x32_bf16 v[40:43], v[228:231], v[170:173], v[40:43]
	v_mfma_f32_16x16x32_bf16 v[32:35], v[220:223], v[178:181], v[32:35]
	v_mfma_f32_16x16x32_bf16 v[24:27], v[228:231], v[178:181], v[24:27]
	v_mfma_f32_16x16x32_bf16 v[16:19], v[220:223], v[196:199], v[16:19]
	v_mfma_f32_16x16x32_bf16 v[8:11], v[228:231], v[196:199], v[8:11]
	v_mfma_f32_16x16x32_bf16 v[4:7], v[220:223], v[204:207], v[4:7]
	v_mfma_f32_16x16x32_bf16 v[0:3], v[228:231], v[204:207], v[0:3]
	s_movk_i32 s25, 0x100
	s_andn2_b64 vcc, exec, s[4:5]
	s_mov_b64 s[34:35], -1
	s_mov_b64 s[4:5], 0
	s_barrier
	s_cbranch_vccz .LBB0_670
	s_lshl_b32 s13, s15, 8
	s_cmp_lt_i32 s15, 2
	s_mov_b64 s[4:5], -1
	s_cbranch_scc1 .LBB0_673
	s_mul_hi_i32 s4, s81, 0x3e0f83e1
	s_lshr_b32 s5, s4, 31
	s_ashr_i32 s4, s4, 3
	v_cvt_pk_bf16_f32 v136, v124, v125
	s_add_i32 s4, s4, s5
	v_cvt_pk_bf16_f32 v137, v126, v127
	ds_write_b16 v151, v136
	ds_write_b16_d16_hi v151, v136 offset:144
	ds_write_b16 v151, v137 offset:288
	ds_write_b16_d16_hi v151, v137 offset:432
	v_cvt_pk_bf16_f32 v136, v116, v117
	s_mul_i32 s5, s4, 0xffffffdf
	v_cvt_pk_bf16_f32 v137, v118, v119
	ds_write_b16 v151, v136 offset:32
	ds_write_b16_d16_hi v151, v136 offset:176
	ds_write_b16 v151, v137 offset:320
	ds_write_b16_d16_hi v151, v137 offset:464
	v_cvt_pk_bf16_f32 v136, v100, v101
	s_add_i32 s5, s5, s81
	s_or_b32 s15, s13, s79
	v_cvt_pk_bf16_f32 v137, v102, v103
	ds_write_b16 v151, v136 offset:64
	ds_write_b16_d16_hi v151, v136 offset:208
	ds_write_b16 v151, v137 offset:352
	ds_write_b16_d16_hi v151, v137 offset:496
	v_cvt_pk_bf16_f32 v136, v84, v85
	s_lshl_b32 s24, s5, 8
	s_ashr_i32 s5, s4, 31
	v_cvt_pk_bf16_f32 v137, v86, v87
	ds_write_b16 v151, v136 offset:96
	ds_write_b16_d16_hi v151, v136 offset:240
	ds_write_b16 v151, v137 offset:384
	ds_write_b16_d16_hi v151, v137 offset:528
	v_add_u32_e32 v136, s15, v152
	s_lshl_b64 s[4:5], s[4:5], 9
	v_ashrrev_i32_e32 v137, 31, v136
	v_lshl_add_u64 v[136:137], s[4:5], 0, v[136:137]
	v_mov_b64_e32 v[162:163], s[8:9]
	s_ashr_i32 s25, s24, 31
	ds_read_b128 v[138:141], v155
	v_mad_u64_u32 v[142:143], s[26:27], v136, s91, v[162:163]
	v_mad_i32_i24 v143, v137, s91, v143
	s_lshl_b64 s[34:35], s[24:25], 1
	v_lshl_add_u64 v[136:137], v[142:143], 0, s[34:35]
	v_lshl_add_u64 v[136:137], v[136:137], 0, s[10:11]
	v_lshl_add_u64 v[136:137], v[136:137], 0, v[144:145]
	s_waitcnt lgkmcnt(0)
	global_store_dwordx4 v[136:137], v[138:141], off
	ds_read_b128 v[140:143], v156
	s_or_b32 s26, s15, 4
	v_add_u32_e32 v138, s15, v153
	v_ashrrev_i32_e32 v139, 31, v138
	v_lshl_add_u64 v[138:139], s[4:5], 0, v[138:139]
	v_mad_u64_u32 v[146:147], s[24:25], v138, s91, v[162:163]
	v_mad_i32_i24 v147, v139, s91, v147
	v_lshl_add_u64 v[138:139], v[146:147], 0, s[34:35]
	v_lshl_add_u64 v[138:139], v[138:139], 0, s[10:11]
	v_lshl_add_u64 v[138:139], v[138:139], 0, v[144:145]
	s_waitcnt lgkmcnt(0)
	global_store_dwordx4 v[138:139], v[140:143], off
	v_cvt_pk_bf16_f32 v157, v104, v105
	s_nop 1
	v_cvt_pk_bf16_f32 v140, v120, v121
	v_cvt_pk_bf16_f32 v141, v122, v123
	ds_write_b16 v151, v140
	ds_write_b16_d16_hi v151, v140 offset:144
	ds_write_b16 v151, v141 offset:288
	ds_write_b16_d16_hi v151, v141 offset:432
	v_cvt_pk_bf16_f32 v140, v108, v109
	v_cvt_pk_bf16_f32 v141, v110, v111
	ds_write_b16 v151, v140 offset:32
	ds_write_b16_d16_hi v151, v140 offset:176
	ds_write_b16 v151, v141 offset:320
	ds_write_b16_d16_hi v151, v141 offset:464
	v_cvt_pk_bf16_f32 v140, v92, v93
	v_cvt_pk_bf16_f32 v141, v94, v95
	ds_write_b16 v151, v140 offset:64
	ds_write_b16_d16_hi v151, v140 offset:208
	ds_write_b16 v151, v141 offset:352
	ds_write_b16_d16_hi v151, v141 offset:496
	v_cvt_pk_bf16_f32 v140, v76, v77
	v_cvt_pk_bf16_f32 v141, v78, v79
	ds_write_b16 v151, v140 offset:96
	ds_write_b16_d16_hi v151, v140 offset:240
	ds_write_b16 v151, v141 offset:384
	ds_write_b16_d16_hi v151, v141 offset:528
	v_add_u32_e32 v140, s26, v152
	v_ashrrev_i32_e32 v141, 31, v140
	v_lshl_add_u64 v[140:141], s[4:5], 0, v[140:141]
	ds_read_b128 v[158:161], v155
	v_mad_u64_u32 v[142:143], s[24:25], v140, s91, v[162:163]
	v_mad_i32_i24 v143, v141, s91, v143
	v_lshl_add_u64 v[140:141], v[142:143], 0, s[34:35]
	v_add_u32_e32 v142, s26, v153
	v_lshl_add_u64 v[140:141], v[140:141], 0, s[10:11]
	v_ashrrev_i32_e32 v143, 31, v142
	v_lshl_add_u64 v[140:141], v[140:141], 0, v[144:145]
	v_lshl_add_u64 v[142:143], s[4:5], 0, v[142:143]
	s_waitcnt lgkmcnt(0)
; #define LAS __attribute__((address_space(3)))
; __device__ __forceinline__ unsigned pk2(float lo, float hi) { unsigned r; asm("v_cvt_pk_bf16_f32 %0, %1, %2" : "=v"(r) : "v"(lo), "v"(hi)); return r; }
;     __device__ __forceinline__ void operator()(const f32x4 (&acc)[2][2][4][2], const Unit& u, int wr, int wc, int fr, int fq) const {
;     ...
;             for (int ai = 0; ai < 2; ++ai)
; #pragma unroll
;                 for (int bj = 0; bj < 2; ++bj)
; #pragma unroll
;                     for (int n = 0; n < 2; ++n) {
; #pragma unroll
;                         for (int m = 0; m < 4; ++m) {
;                             const f32x4 v = acc[ai][bj][m][n];
;                             const unsigned p0 = pk2(v[0], v[1]), p1 = pk2(v[2], v[3]);
;                             LAS bf16_t* w = sc + (4 * fq) * 72 + 16 * m + fr;
;                             w[0] = (bf16_t)(p0 & 0xffffu); w[72] = (bf16_t)(p0 >> 16); w[144] = (bf16_t)(p1 & 0xffffu); w[216] = (bf16_t)(p1 >> 16);
;                         }
; #pragma unroll
;                         for (int j = 0; j < 2; ++j) {
;                             const int ch = lane + 64 * j, fi = ch >> 3, seg = ch & 7;
;                             const u32x4 o = *(const LAS u32x4*)(sc + fi * 72 + 8 * seg);
;                             const int f = col_t - vt0 + 64 * wc + 16 * (fi >> 2) + 8 * bj + 4 * n + (fi & 3);
;                             *(u32x4*)(Vt + ((size_t)bl * vtnf + f) * KEYS + key0 + ai * HALF + wr * 64 + 8 * seg) = o;
	global_store_dwordx4 v[140:141], v[158:161], off
	ds_read_b128 v[158:161], v156
	v_mad_u64_u32 v[146:147], s[24:25], v142, s91, v[162:163]
	v_mad_i32_i24 v147, v143, s91, v147
	v_lshl_add_u64 v[142:143], v[146:147], 0, s[34:35]
	v_lshl_add_u64 v[142:143], v[142:143], 0, s[10:11]
	v_lshl_add_u64 v[142:143], v[142:143], 0, v[144:145]
	v_cvt_pk_bf16_f32 v146, v112, v113
	s_waitcnt lgkmcnt(0)
	global_store_dwordx4 v[142:143], v[158:161], off
	v_cvt_pk_bf16_f32 v147, v114, v115
	ds_write_b16 v151, v146
	ds_write_b16_d16_hi v151, v146 offset:144
	ds_write_b16 v151, v147 offset:288
	ds_write_b16_d16_hi v151, v147 offset:432
	v_cvt_pk_bf16_f32 v146, v96, v97
	v_cvt_pk_bf16_f32 v147, v98, v99
	ds_write_b16 v151, v146 offset:32
	ds_write_b16_d16_hi v151, v146 offset:176
	ds_write_b16 v151, v147 offset:320
	ds_write_b16_d16_hi v151, v147 offset:464
	v_cvt_pk_bf16_f32 v146, v80, v81
	s_or_b32 s26, s15, 8
	v_cvt_pk_bf16_f32 v147, v82, v83
	ds_write_b16 v151, v146 offset:64
	ds_write_b16_d16_hi v151, v146 offset:208
	ds_write_b16 v151, v147 offset:352
	ds_write_b16_d16_hi v151, v147 offset:496
	v_cvt_pk_bf16_f32 v146, v68, v69
	v_cvt_pk_bf16_f32 v147, v70, v71
	ds_write_b16 v151, v146 offset:96
	ds_write_b16_d16_hi v151, v146 offset:240
	ds_write_b16 v151, v147 offset:384
	ds_write_b16_d16_hi v151, v147 offset:528
	v_add_u32_e32 v146, s26, v152
	v_ashrrev_i32_e32 v147, 31, v146
	v_lshl_add_u64 v[146:147], s[4:5], 0, v[146:147]
	ds_read_b128 v[158:161], v155
	v_mad_u64_u32 v[164:165], s[24:25], v146, s91, v[162:163]
	v_mad_i32_i24 v165, v147, s91, v165
	v_lshl_add_u64 v[146:147], v[164:165], 0, s[34:35]
	v_add_u32_e32 v164, s26, v153
	v_lshl_add_u64 v[146:147], v[146:147], 0, s[10:11]
	v_ashrrev_i32_e32 v165, 31, v164
	v_lshl_add_u64 v[146:147], v[146:147], 0, v[144:145]
	v_lshl_add_u64 v[164:165], s[4:5], 0, v[164:165]
	s_waitcnt lgkmcnt(0)
	global_store_dwordx4 v[146:147], v[158:161], off
	ds_read_b128 v[158:161], v156
	v_mad_u64_u32 v[166:167], s[24:25], v164, s91, v[162:163]
	v_mad_i32_i24 v167, v165, s91, v167
	v_lshl_add_u64 v[164:165], v[166:167], 0, s[34:35]
	v_lshl_add_u64 v[164:165], v[164:165], 0, s[10:11]
	v_lshl_add_u64 v[164:165], v[164:165], 0, v[144:145]
	s_waitcnt lgkmcnt(0)
	global_store_dwordx4 v[164:165], v[158:161], off
	s_or_b32 s15, s15, 12
	v_add_u32_e32 v166, s15, v152
	v_cvt_pk_bf16_f32 v158, v106, v107
	ds_write_b16 v151, v157
	ds_write_b16_d16_hi v151, v157 offset:144
	ds_write_b16 v151, v158 offset:288
	ds_write_b16_d16_hi v151, v158 offset:432
	v_cvt_pk_bf16_f32 v157, v88, v89
	v_cvt_pk_bf16_f32 v158, v90, v91
	ds_write_b16 v151, v157 offset:32
	ds_write_b16_d16_hi v151, v157 offset:176
	ds_write_b16 v151, v158 offset:320
	ds_write_b16_d16_hi v151, v158 offset:464
	v_cvt_pk_bf16_f32 v157, v72, v73
	v_cvt_pk_bf16_f32 v158, v74, v75
	ds_write_b16 v151, v157 offset:64
	ds_write_b16_d16_hi v151, v157 offset:208
	ds_write_b16 v151, v158 offset:352
	ds_write_b16_d16_hi v151, v158 offset:496
	v_cvt_pk_bf16_f32 v157, v64, v65
	v_ashrrev_i32_e32 v167, 31, v166
	v_cvt_pk_bf16_f32 v158, v66, v67
	ds_write_b16 v151, v157 offset:96
	ds_write_b16_d16_hi v151, v157 offset:240
	ds_write_b16 v151, v158 offset:384
	ds_write_b16_d16_hi v151, v158 offset:528
	v_lshl_add_u64 v[166:167], s[4:5], 0, v[166:167]
	ds_read_b128 v[158:161], v155
	v_mad_u64_u32 v[168:169], s[24:25], v166, s91, v[162:163]
	v_mad_i32_i24 v169, v167, s91, v169
	v_lshl_add_u64 v[166:167], v[168:169], 0, s[34:35]
	v_add_u32_e32 v168, s15, v153
	v_lshl_add_u64 v[166:167], v[166:167], 0, s[10:11]
	v_ashrrev_i32_e32 v169, 31, v168
	v_lshl_add_u64 v[166:167], v[166:167], 0, v[144:145]
	v_lshl_add_u64 v[168:169], s[4:5], 0, v[168:169]
	s_waitcnt lgkmcnt(0)
	global_store_dwordx4 v[166:167], v[158:161], off
	ds_read_b128 v[158:161], v156
	v_mad_u64_u32 v[162:163], s[4:5], v168, s91, v[162:163]
	v_mad_i32_i24 v163, v169, s91, v163
	v_lshl_add_u64 v[162:163], v[162:163], 0, s[34:35]
	v_lshl_add_u64 v[162:163], v[162:163], 0, s[10:11]
	v_lshl_add_u64 v[162:163], v[162:163], 0, v[144:145]
	v_cvt_pk_bf16_f32 v157, v60, v61
	s_waitcnt lgkmcnt(0)
; #define LAS __attribute__((address_space(3)))
; __device__ __forceinline__ unsigned pk2(float lo, float hi) { unsigned r; asm("v_cvt_pk_bf16_f32 %0, %1, %2" : "=v"(r) : "v"(lo), "v"(hi)); return r; }
;     __device__ __forceinline__ void operator()(const f32x4 (&acc)[2][2][4][2], const Unit& u, int wr, int wc, int fr, int fq) const {
;     ...
;             for (int ai = 0; ai < 2; ++ai)
; #pragma unroll
;                 for (int bj = 0; bj < 2; ++bj)
; #pragma unroll
;                     for (int n = 0; n < 2; ++n) {
; #pragma unroll
;                         for (int m = 0; m < 4; ++m) {
;                             const f32x4 v = acc[ai][bj][m][n];
;                             const unsigned p0 = pk2(v[0], v[1]), p1 = pk2(v[2], v[3]);
;                             LAS bf16_t* w = sc + (4 * fq) * 72 + 16 * m + fr;
;                             w[0] = (bf16_t)(p0 & 0xffffu); w[72] = (bf16_t)(p0 >> 16); w[144] = (bf16_t)(p1 & 0xffffu); w[216] = (bf16_t)(p1 >> 16);
;                         }
; #pragma unroll
;                         for (int j = 0; j < 2; ++j) {
;                             const int ch = lane + 64 * j, fi = ch >> 3, seg = ch & 7;
;                             const u32x4 o = *(const LAS u32x4*)(sc + fi * 72 + 8 * seg);
;                             const int f = col_t - vt0 + 64 * wc + 16 * (fi >> 2) + 8 * bj + 4 * n + (fi & 3);
;                             *(u32x4*)(Vt + ((size_t)bl * vtnf + f) * KEYS + key0 + ai * HALF + wr * 64 + 8 * seg) = o;
	global_store_dwordx4 v[162:163], v[158:161], off
	s_mov_b64 s[4:5], 0
	s_nop 0
	v_cvt_pk_bf16_f32 v158, v62, v63
	ds_write_b16 v151, v157
	ds_write_b16_d16_hi v151, v157 offset:144
	ds_write_b16 v151, v158 offset:288
	ds_write_b16_d16_hi v151, v158 offset:432
	v_cvt_pk_bf16_f32 v157, v52, v53
	v_cvt_pk_bf16_f32 v158, v54, v55
	ds_write_b16 v151, v157 offset:32
	ds_write_b16_d16_hi v151, v157 offset:176
	ds_write_b16 v151, v158 offset:320
	ds_write_b16_d16_hi v151, v158 offset:464
	v_cvt_pk_bf16_f32 v157, v36, v37
	v_cvt_pk_bf16_f32 v158, v38, v39
	ds_write_b16 v151, v157 offset:64
	ds_write_b16_d16_hi v151, v157 offset:208
	ds_write_b16 v151, v158 offset:352
	ds_write_b16_d16_hi v151, v158 offset:496
	v_cvt_pk_bf16_f32 v157, v20, v21
	v_cvt_pk_bf16_f32 v158, v22, v23
	ds_write_b16 v151, v157 offset:96
	ds_write_b16_d16_hi v151, v157 offset:240
	ds_write_b16 v151, v158 offset:384
	ds_write_b16_d16_hi v151, v158 offset:528
	ds_read_b128 v[158:161], v155
	s_waitcnt lgkmcnt(0)
	global_store_dwordx4 v[136:137], v[158:161], off offset:256
	ds_read_b128 v[158:161], v156
	v_cvt_pk_bf16_f32 v136, v56, v57
	v_cvt_pk_bf16_f32 v137, v58, v59
	s_waitcnt lgkmcnt(0)
	global_store_dwordx4 v[138:139], v[158:161], off offset:256
	ds_write_b16 v151, v136
	ds_write_b16_d16_hi v151, v136 offset:144
	ds_write_b16 v151, v137 offset:288
	ds_write_b16_d16_hi v151, v137 offset:432
	v_cvt_pk_bf16_f32 v136, v44, v45
	v_cvt_pk_bf16_f32 v137, v46, v47
	ds_write_b16 v151, v136 offset:32
	ds_write_b16_d16_hi v151, v136 offset:176
	ds_write_b16 v151, v137 offset:320
	ds_write_b16_d16_hi v151, v137 offset:464
	v_cvt_pk_bf16_f32 v136, v28, v29
	v_cvt_pk_bf16_f32 v137, v30, v31
	ds_write_b16 v151, v136 offset:64
	ds_write_b16_d16_hi v151, v136 offset:208
	ds_write_b16 v151, v137 offset:352
	ds_write_b16_d16_hi v151, v137 offset:496
	v_cvt_pk_bf16_f32 v136, v12, v13
	v_cvt_pk_bf16_f32 v137, v14, v15
	ds_write_b16 v151, v136 offset:96
	ds_write_b16_d16_hi v151, v136 offset:240
	ds_write_b16 v151, v137 offset:384
	ds_write_b16_d16_hi v151, v137 offset:528
	ds_read_b128 v[136:139], v155
	s_waitcnt lgkmcnt(0)
	global_store_dwordx4 v[140:141], v[136:139], off offset:256
	ds_read_b128 v[136:139], v156
	s_waitcnt lgkmcnt(0)
	global_store_dwordx4 v[142:143], v[136:139], off offset:256
	s_nop 1
	v_cvt_pk_bf16_f32 v136, v48, v49
	v_cvt_pk_bf16_f32 v137, v50, v51
	ds_write_b16 v151, v136
	ds_write_b16_d16_hi v151, v136 offset:144
	ds_write_b16 v151, v137 offset:288
	ds_write_b16_d16_hi v151, v137 offset:432
	v_cvt_pk_bf16_f32 v136, v32, v33
	v_cvt_pk_bf16_f32 v137, v34, v35
	ds_write_b16 v151, v136 offset:32
	ds_write_b16_d16_hi v151, v136 offset:176
	ds_write_b16 v151, v137 offset:320
	ds_write_b16_d16_hi v151, v137 offset:464
	v_cvt_pk_bf16_f32 v136, v16, v17
	v_cvt_pk_bf16_f32 v137, v18, v19
	ds_write_b16 v151, v136 offset:64
	ds_write_b16_d16_hi v151, v136 offset:208
	ds_write_b16 v151, v137 offset:352
	ds_write_b16_d16_hi v151, v137 offset:496
	v_cvt_pk_bf16_f32 v136, v4, v5
	v_cvt_pk_bf16_f32 v137, v6, v7
	ds_write_b16 v151, v136 offset:96
	ds_write_b16_d16_hi v151, v136 offset:240
	ds_write_b16 v151, v137 offset:384
	ds_write_b16_d16_hi v151, v137 offset:528
	ds_read_b128 v[136:139], v155
	s_waitcnt lgkmcnt(0)
	global_store_dwordx4 v[146:147], v[136:139], off offset:256
	ds_read_b128 v[136:139], v156
	s_waitcnt lgkmcnt(0)
	global_store_dwordx4 v[164:165], v[136:139], off offset:256
	s_nop 1
	v_cvt_pk_bf16_f32 v136, v40, v41
	v_cvt_pk_bf16_f32 v137, v42, v43
	ds_write_b16 v151, v136
	ds_write_b16_d16_hi v151, v136 offset:144
	ds_write_b16 v151, v137 offset:288
	ds_write_b16_d16_hi v151, v137 offset:432
	v_cvt_pk_bf16_f32 v136, v24, v25
	v_cvt_pk_bf16_f32 v137, v26, v27
	ds_write_b16 v151, v136 offset:32
	ds_write_b16_d16_hi v151, v136 offset:176
	ds_write_b16 v151, v137 offset:320
	ds_write_b16_d16_hi v151, v137 offset:464
	v_cvt_pk_bf16_f32 v136, v8, v9
	v_cvt_pk_bf16_f32 v137, v10, v11
	ds_write_b16 v151, v136 offset:64
	ds_write_b16_d16_hi v151, v136 offset:208
	ds_write_b16 v151, v137 offset:352
	ds_write_b16_d16_hi v151, v137 offset:496
	v_cvt_pk_bf16_f32 v136, v0, v1
	v_cvt_pk_bf16_f32 v137, v2, v3
	ds_write_b16 v151, v136 offset:96
	ds_write_b16_d16_hi v151, v136 offset:240
	ds_write_b16 v151, v137 offset:384
	ds_write_b16_d16_hi v151, v137 offset:528
	ds_read_b128 v[136:139], v155
	s_waitcnt lgkmcnt(0)
	global_store_dwordx4 v[166:167], v[136:139], off offset:256
	ds_read_b128 v[136:139], v156
	s_waitcnt lgkmcnt(0)
	global_store_dwordx4 v[162:163], v[136:139], off offset:256

; #define PG8_STAGE(bufoff, gbase, voff) do { _Pragma("unroll") for (int _i = 0; _i < 2; ++_i) \
;         __builtin_amdgcn_global_load_lds((const unsigned*)((const char*)(gbase) + (voff)[_i]), (LAS unsigned*)(lds + (bufoff) + ldsw + _i * 8192), 16, 0, 0); } while (0)
; #define PG8_LDA(dst, b, h) do { _Pragma("unroll") for (int m = 0; m < 4; ++m) _Pragma("unroll") for (int k = 0; k < 2; ++k) dst[m][k] = *(const LAS bf16x8*)(lds + PG8_SA(b, h) + aoff + m * 2048 + k * 1024); } while (0)
; #define PG8_LDB(dst, b, h) do { _Pragma("unroll") for (int n = 0; n < 2; ++n) _Pragma("unroll") for (int k = 0; k < 2; ++k) dst[n][k] = *(const LAS bf16x8*)(lds + PG8_SB(b, h) + boff + n * 2048 + k * 1024); } while (0)
; #define PG8_MMA(ai, bj, At, Bt) do { __builtin_amdgcn_s_setprio(1); _Pragma("unroll") for (int m = 0; m < 4; ++m) _Pragma("unroll") for (int n = 0; n < 2; ++n) _Pragma("unroll") for (int k = 0; k < 2; ++k) \
;         acc[ai][bj][m][n] = __builtin_amdgcn_mfma_f32_16x16x32_bf16(Bt[n][k], At[m][k], acc[ai][bj][m][n], 0, 0, 0); __builtin_amdgcn_s_setprio(0); } while (0)
; #define PG8_WAIT_L(n) asm volatile("s_waitcnt lgkmcnt(" #n ")" ::: "memory")
; #define PG8_BAR __builtin_amdgcn_s_barrier()
; #define PG8_SCHED __builtin_amdgcn_sched_barrier(0)
; template <class Epi>
; __device__ __forceinline__ void gemm_phase(LAS unsigned char* lds, const Gemm g, const StaticOrder& S, const Epi& E) {
;     ...
;             PG8_LDB(B0, 0, 0); PG8_SCHED; PG8_LDA(At, 0, 0); PG8_STAGE(PG8_SA(1, 1), a1 + hA, voffA);
;             PG8_WAIT_L(8); PG8_BAR; PG8_WAIT_L(0); PG8_MMA(0, 0, At, B0); PG8_BAR; PG8_SCHED;
;             PG8_LDB(B1, 0, 1); PG8_STAGE(PG8_SB(0, 0), b2, voffB);
;             PG8_BAR; PG8_WAIT_L(0); PG8_MMA(0, 1, At, B1); PG8_BAR;
;             PG8_LDA(At, 0, 1); PG8_STAGE(PG8_SA(0, 0), a2, voffA);
;             PG8_BAR; PG8_WAIT_L(0); PG8_MMA(1, 0, At, B0); PG8_BAR; PG8_SCHED;
.LBB0_985:
	s_add_u32 s12, s10, 0x100
	s_addc_u32 s13, s11, 0
	s_add_i32 s26, 0, 0x10000
	v_add_u32_e32 v142, s26, v139
	ds_read_b128 v[134:137], v142
	ds_read_b128 v[146:149], v142 offset:1024
	ds_read_b128 v[150:153], v142 offset:2048
	ds_read_b128 v[154:157], v142 offset:3072
	s_cmp_eq_u32 s72, 20
	s_cselect_b32 s21, s5, s13
	s_cselect_b32 s20, s4, s12
	s_cselect_b32 s17, s7, s25
	s_cselect_b32 s16, s6, s24
	s_add_i32 m0, s61, 0xc000
	ds_read_b128 v[158:161], v141
	ds_read_b128 v[162:165], v141 offset:1024
	ds_read_b128 v[166:169], v141 offset:2048
	ds_read_b128 v[170:173], v141 offset:3072
	ds_read_b128 v[174:177], v141 offset:4096
	ds_read_b128 v[178:181], v141 offset:5120
	ds_read_b128 v[182:185], v141 offset:6144
	ds_read_b128 v[186:189], v141 offset:7168
	global_load_lds_dwordx4 v130, s[10:11]
	s_add_i32 m0, s61, 0xe000
	v_lshl_add_u64 v[142:143], s[10:11], 0, v[132:133]
	global_load_lds_dwordx4 v[142:143], off
	s_waitcnt lgkmcnt(8)
	s_barrier
	s_waitcnt lgkmcnt(0)
	v_mfma_f32_16x16x32_bf16 v[124:127], v[134:137], v[158:161], v[124:127]
	v_mfma_f32_16x16x32_bf16 v[120:123], v[150:153], v[158:161], v[120:123]
	v_mfma_f32_16x16x32_bf16 v[116:119], v[134:137], v[166:169], v[116:119]
	v_mfma_f32_16x16x32_bf16 v[108:111], v[150:153], v[166:169], v[108:111]
	v_mfma_f32_16x16x32_bf16 v[100:103], v[134:137], v[174:177], v[100:103]
	v_mfma_f32_16x16x32_bf16 v[92:95], v[150:153], v[174:177], v[92:95]
	v_mfma_f32_16x16x32_bf16 v[84:87], v[134:137], v[182:185], v[84:87]
	v_mfma_f32_16x16x32_bf16 v[76:79], v[150:153], v[182:185], v[76:79]
	v_mfma_f32_16x16x32_bf16 v[124:127], v[146:149], v[162:165], v[124:127]
	v_mfma_f32_16x16x32_bf16 v[120:123], v[154:157], v[162:165], v[120:123]
	v_mfma_f32_16x16x32_bf16 v[116:119], v[146:149], v[170:173], v[116:119]
	v_mfma_f32_16x16x32_bf16 v[108:111], v[154:157], v[170:173], v[108:111]
	v_mfma_f32_16x16x32_bf16 v[100:103], v[146:149], v[178:181], v[100:103]
	v_mfma_f32_16x16x32_bf16 v[92:95], v[154:157], v[178:181], v[92:95]
	v_mfma_f32_16x16x32_bf16 v[84:87], v[146:149], v[186:189], v[84:87]
	v_mfma_f32_16x16x32_bf16 v[76:79], v[154:157], v[186:189], v[76:79]
	s_barrier
	s_add_i32 s27, 0, 0x14000
	v_add_u32_e32 v142, s27, v139
	s_add_i32 s10, s26, s35
	ds_read_b128 v[196:199], v142
	ds_read_b128 v[200:203], v142 offset:1024
	ds_read_b128 v[204:207], v142 offset:2048
	ds_read_b128 v[214:217], v142 offset:3072
	v_lshl_add_u64 v[142:143], s[16:17], 0, v[144:145]
	s_mov_b32 m0, s10
	v_lshl_add_u64 v[192:193], s[16:17], 0, v[128:129]
	global_load_lds_dwordx4 v[142:143], off
	s_add_i32 m0, s10, 0x2000
	s_nop 0
	global_load_lds_dwordx4 v[192:193], off
	s_barrier
	s_waitcnt lgkmcnt(0)
	v_mfma_f32_16x16x32_bf16 v[112:115], v[196:199], v[158:161], v[112:115]
	v_mfma_f32_16x16x32_bf16 v[104:107], v[204:207], v[158:161], v[104:107]
	v_mfma_f32_16x16x32_bf16 v[96:99], v[196:199], v[166:169], v[96:99]
	v_mfma_f32_16x16x32_bf16 v[88:91], v[204:207], v[166:169], v[88:91]
	v_mfma_f32_16x16x32_bf16 v[80:83], v[196:199], v[174:177], v[80:83]
	v_mfma_f32_16x16x32_bf16 v[72:75], v[204:207], v[174:177], v[72:75]
	v_mfma_f32_16x16x32_bf16 v[68:71], v[196:199], v[182:185], v[68:71]
	v_mfma_f32_16x16x32_bf16 v[64:67], v[204:207], v[182:185], v[64:67]
	v_mfma_f32_16x16x32_bf16 v[112:115], v[200:203], v[162:165], v[112:115]
	v_mfma_f32_16x16x32_bf16 v[104:107], v[214:217], v[162:165], v[104:107]
	v_mfma_f32_16x16x32_bf16 v[96:99], v[200:203], v[170:173], v[96:99]
	v_mfma_f32_16x16x32_bf16 v[88:91], v[214:217], v[170:173], v[88:91]
	v_mfma_f32_16x16x32_bf16 v[80:83], v[200:203], v[178:181], v[80:83]
	v_mfma_f32_16x16x32_bf16 v[72:75], v[214:217], v[178:181], v[72:75]
	v_mfma_f32_16x16x32_bf16 v[68:71], v[200:203], v[186:189], v[68:71]
	v_mfma_f32_16x16x32_bf16 v[64:67], v[214:217], v[186:189], v[64:67]
	s_mov_b32 m0, s61
	v_lshl_add_u64 v[218:219], s[20:21], 0, v[144:145]
	s_barrier
	ds_read_b128 v[158:161], v141 offset:16384
	ds_read_b128 v[162:165], v141 offset:17408
	ds_read_b128 v[166:169], v141 offset:18432
	ds_read_b128 v[170:173], v141 offset:19456
	ds_read_b128 v[174:177], v141 offset:20480
	ds_read_b128 v[178:181], v141 offset:21504
	ds_read_b128 v[182:185], v141 offset:22528
	ds_read_b128 v[186:189], v141 offset:23552
	global_load_lds_dwordx4 v[218:219], off
	s_mov_b32 m0, s62
	v_lshl_add_u64 v[220:221], s[20:21], 0, v[128:129]
	global_load_lds_dwordx4 v[220:221], off
	s_barrier
	s_waitcnt lgkmcnt(0)
	v_mfma_f32_16x16x32_bf16 v[60:63], v[134:137], v[158:161], v[60:63]
	v_mfma_f32_16x16x32_bf16 v[56:59], v[150:153], v[158:161], v[56:59]
	v_mfma_f32_16x16x32_bf16 v[52:55], v[134:137], v[166:169], v[52:55]
	v_mfma_f32_16x16x32_bf16 v[44:47], v[150:153], v[166:169], v[44:47]
	v_mfma_f32_16x16x32_bf16 v[36:39], v[134:137], v[174:177], v[36:39]
	v_mfma_f32_16x16x32_bf16 v[28:31], v[150:153], v[174:177], v[28:31]
	v_mfma_f32_16x16x32_bf16 v[20:23], v[134:137], v[182:185], v[20:23]
	v_mfma_f32_16x16x32_bf16 v[12:15], v[150:153], v[182:185], v[12:15]
	v_mfma_f32_16x16x32_bf16 v[60:63], v[146:149], v[162:165], v[60:63]
	v_mfma_f32_16x16x32_bf16 v[56:59], v[154:157], v[162:165], v[56:59]
	v_mfma_f32_16x16x32_bf16 v[52:55], v[146:149], v[170:173], v[52:55]
	v_mfma_f32_16x16x32_bf16 v[44:47], v[154:157], v[170:173], v[44:47]
	v_mfma_f32_16x16x32_bf16 v[36:39], v[146:149], v[178:181], v[36:39]
	v_mfma_f32_16x16x32_bf16 v[28:31], v[154:157], v[178:181], v[28:31]
	v_mfma_f32_16x16x32_bf16 v[20:23], v[146:149], v[186:189], v[20:23]
	v_mfma_f32_16x16x32_bf16 v[12:15], v[154:157], v[186:189], v[12:15]
	s_barrier
; #define PG8_STAGE(bufoff, gbase, voff) do { _Pragma("unroll") for (int _i = 0; _i < 2; ++_i) \
;         __builtin_amdgcn_global_load_lds((const unsigned*)((const char*)(gbase) + (voff)[_i]), (LAS unsigned*)(lds + (bufoff) + ldsw + _i * 8192), 16, 0, 0); } while (0)
; #define PG8_LDA(dst, b, h) do { _Pragma("unroll") for (int m = 0; m < 4; ++m) _Pragma("unroll") for (int k = 0; k < 2; ++k) dst[m][k] = *(const LAS bf16x8*)(lds + PG8_SA(b, h) + aoff + m * 2048 + k * 1024); } while (0)
; #define PG8_LDB(dst, b, h) do { _Pragma("unroll") for (int n = 0; n < 2; ++n) _Pragma("unroll") for (int k = 0; k < 2; ++k) dst[n][k] = *(const LAS bf16x8*)(lds + PG8_SB(b, h) + boff + n * 2048 + k * 1024); } while (0)
; #define PG8_MMA(ai, bj, At, Bt) do { __builtin_amdgcn_s_setprio(1); _Pragma("unroll") for (int m = 0; m < 4; ++m) _Pragma("unroll") for (int n = 0; n < 2; ++n) _Pragma("unroll") for (int k = 0; k < 2; ++k) \
;         acc[ai][bj][m][n] = __builtin_amdgcn_mfma_f32_16x16x32_bf16(Bt[n][k], At[m][k], acc[ai][bj][m][n], 0, 0, 0); __builtin_amdgcn_s_setprio(0); } while (0)
; #define PG8_WAIT_V(n) asm volatile("s_waitcnt vmcnt(" #n ")" ::: "memory")
; #define PG8_WAIT_L(n) asm volatile("s_waitcnt lgkmcnt(" #n ")" ::: "memory")
; #define PG8_BAR __builtin_amdgcn_s_barrier()
; #define PG8_SCHED __builtin_amdgcn_sched_barrier(0)
; template <class Epi>
; __device__ __forceinline__ void gemm_phase(LAS unsigned char* lds, const Gemm g, const StaticOrder& S, const Epi& E) {
;     ...
;             PG8_STAGE(PG8_SB(0, 1), b2 + hB, voffB);
;             PG8_WAIT_V(6); PG8_BAR; PG8_MMA(1, 1, At, B1); PG8_BAR;
;             PG8_LDB(B0, 1, 0); PG8_SCHED; PG8_LDA(At, 1, 0); PG8_STAGE(PG8_SA(0, 1), a2 + hA, voffA);
;             PG8_WAIT_L(8); PG8_BAR; PG8_WAIT_L(0); PG8_MMA(0, 0, At, B0); PG8_BAR; PG8_SCHED;
;             PG8_LDB(B1, 1, 1); PG8_STAGE(PG8_SB(1, 0), b3, voffB);
	s_add_u32 s10, s16, 0x60000
	s_addc_u32 s11, s17, 0
	s_add_i32 s26, s27, s35
	s_mov_b32 m0, s26
	s_nop 0
	global_load_lds_dwordx4 v144, s[10:11]
	s_add_i32 m0, s26, 0x2000
	s_nop 0
	global_load_lds_dwordx4 v128, s[10:11]
	s_waitcnt vmcnt(6)
	s_barrier
	v_mfma_f32_16x16x32_bf16 v[48:51], v[196:199], v[158:161], v[48:51]
	v_mfma_f32_16x16x32_bf16 v[40:43], v[204:207], v[158:161], v[40:43]
	v_mfma_f32_16x16x32_bf16 v[32:35], v[196:199], v[166:169], v[32:35]
	v_mfma_f32_16x16x32_bf16 v[24:27], v[204:207], v[166:169], v[24:27]
	v_mfma_f32_16x16x32_bf16 v[16:19], v[196:199], v[174:177], v[16:19]
	v_mfma_f32_16x16x32_bf16 v[8:11], v[204:207], v[174:177], v[8:11]
	v_mfma_f32_16x16x32_bf16 v[4:7], v[196:199], v[182:185], v[4:7]
	v_mfma_f32_16x16x32_bf16 v[0:3], v[204:207], v[182:185], v[0:3]
	v_mfma_f32_16x16x32_bf16 v[48:51], v[200:203], v[162:165], v[48:51]
	v_mfma_f32_16x16x32_bf16 v[40:43], v[214:217], v[162:165], v[40:43]
	v_mfma_f32_16x16x32_bf16 v[32:35], v[200:203], v[170:173], v[32:35]
	v_mfma_f32_16x16x32_bf16 v[24:27], v[214:217], v[170:173], v[24:27]
	v_mfma_f32_16x16x32_bf16 v[16:19], v[200:203], v[178:181], v[16:19]
	v_mfma_f32_16x16x32_bf16 v[8:11], v[214:217], v[178:181], v[8:11]
	v_mfma_f32_16x16x32_bf16 v[4:7], v[200:203], v[186:189], v[4:7]
	v_mfma_f32_16x16x32_bf16 v[0:3], v[214:217], v[186:189], v[0:3]
	s_add_i32 s26, 0, 0x18000
	v_add_u32_e32 v154, s26, v139
	s_barrier
	ds_read_b128 v[134:137], v154
	ds_read_b128 v[146:149], v154 offset:1024
	ds_read_b128 v[150:153], v154 offset:2048
	ds_read_b128 v[154:157], v154 offset:3072
	s_add_u32 s10, s20, 0x60000
	s_addc_u32 s11, s21, 0
	s_mov_b32 m0, s63
	ds_read_b128 v[158:161], v141 offset:32768
	ds_read_b128 v[162:165], v141 offset:33792
	ds_read_b128 v[166:169], v141 offset:34816
	ds_read_b128 v[170:173], v141 offset:35840
	ds_read_b128 v[174:177], v141 offset:36864
	ds_read_b128 v[178:181], v141 offset:37888
	ds_read_b128 v[182:185], v141 offset:38912
	global_load_lds_dwordx4 v144, s[10:11]
	s_mov_b32 m0, s64
	ds_read_b128 v[186:189], v141 offset:39936
	global_load_lds_dwordx4 v128, s[10:11]
	s_waitcnt lgkmcnt(8)
	s_barrier
	s_waitcnt lgkmcnt(0)
	v_mfma_f32_16x16x32_bf16 v[124:127], v[134:137], v[158:161], v[124:127]
	v_mfma_f32_16x16x32_bf16 v[120:123], v[150:153], v[158:161], v[120:123]
	v_mfma_f32_16x16x32_bf16 v[116:119], v[134:137], v[166:169], v[116:119]
	v_mfma_f32_16x16x32_bf16 v[108:111], v[150:153], v[166:169], v[108:111]
	v_mfma_f32_16x16x32_bf16 v[100:103], v[134:137], v[174:177], v[100:103]
	v_mfma_f32_16x16x32_bf16 v[92:95], v[150:153], v[174:177], v[92:95]
	v_mfma_f32_16x16x32_bf16 v[84:87], v[134:137], v[182:185], v[84:87]
	v_mfma_f32_16x16x32_bf16 v[76:79], v[150:153], v[182:185], v[76:79]
	v_mfma_f32_16x16x32_bf16 v[124:127], v[146:149], v[162:165], v[124:127]
	v_mfma_f32_16x16x32_bf16 v[120:123], v[154:157], v[162:165], v[120:123]
	v_mfma_f32_16x16x32_bf16 v[116:119], v[146:149], v[170:173], v[116:119]
	v_mfma_f32_16x16x32_bf16 v[108:111], v[154:157], v[170:173], v[108:111]
	v_mfma_f32_16x16x32_bf16 v[100:103], v[146:149], v[178:181], v[100:103]
	v_mfma_f32_16x16x32_bf16 v[92:95], v[154:157], v[178:181], v[92:95]
	v_mfma_f32_16x16x32_bf16 v[84:87], v[146:149], v[186:189], v[84:87]
	v_mfma_f32_16x16x32_bf16 v[76:79], v[154:157], v[186:189], v[76:79]
	s_barrier
	s_add_i32 s20, 0, 0x1c000
	s_add_i32 s10, s26, s35
	v_add_u32_e32 v190, s20, v139
	v_lshl_add_u64 v[142:143], v[142:143], 0, s[88:89]
	s_mov_b32 m0, s10
	ds_read_b128 v[196:199], v190
	ds_read_b128 v[200:203], v190 offset:1024
	ds_read_b128 v[204:207], v190 offset:2048
	ds_read_b128 v[214:217], v190 offset:3072
	global_load_lds_dwordx4 v[142:143], off
	s_add_i32 m0, s10, 0x2000
	v_lshl_add_u64 v[142:143], v[192:193], 0, s[88:89]
	global_load_lds_dwordx4 v[142:143], off
	s_barrier
; #define PG8_STAGE(bufoff, gbase, voff) do { _Pragma("unroll") for (int _i = 0; _i < 2; ++_i) \
;         __builtin_amdgcn_global_load_lds((const unsigned*)((const char*)(gbase) + (voff)[_i]), (LAS unsigned*)(lds + (bufoff) + ldsw + _i * 8192), 16, 0, 0); } while (0)
; #define PG8_LDA(dst, b, h) do { _Pragma("unroll") for (int m = 0; m < 4; ++m) _Pragma("unroll") for (int k = 0; k < 2; ++k) dst[m][k] = *(const LAS bf16x8*)(lds + PG8_SA(b, h) + aoff + m * 2048 + k * 1024); } while (0)
; #define PG8_MMA(ai, bj, At, Bt) do { __builtin_amdgcn_s_setprio(1); _Pragma("unroll") for (int m = 0; m < 4; ++m) _Pragma("unroll") for (int n = 0; n < 2; ++n) _Pragma("unroll") for (int k = 0; k < 2; ++k) \
;         acc[ai][bj][m][n] = __builtin_amdgcn_mfma_f32_16x16x32_bf16(Bt[n][k], At[m][k], acc[ai][bj][m][n], 0, 0, 0); __builtin_amdgcn_s_setprio(0); } while (0)
; #define PG8_WAIT_V(n) asm volatile("s_waitcnt vmcnt(" #n ")" ::: "memory")
; #define PG8_WAIT_L(n) asm volatile("s_waitcnt lgkmcnt(" #n ")" ::: "memory")
; #define PG8_BAR __builtin_amdgcn_s_barrier()
; #define PG8_SCHED __builtin_amdgcn_sched_barrier(0)
; template <class Epi>
; __device__ __forceinline__ void gemm_phase(LAS unsigned char* lds, const Gemm g, const StaticOrder& S, const Epi& E) {
;     ...
;             PG8_BAR; PG8_WAIT_L(0); PG8_MMA(0, 1, At, B1); PG8_BAR;
;             PG8_LDA(At, 1, 1); PG8_STAGE(PG8_SA(1, 0), a3, voffA);
;             PG8_BAR; PG8_WAIT_L(0); PG8_MMA(1, 0, At, B0); PG8_BAR; PG8_SCHED;
;             PG8_STAGE(PG8_SB(1, 1), b3 + hB, voffB);
;             PG8_WAIT_V(6); PG8_BAR; PG8_MMA(1, 1, At, B1); PG8_BAR;
	s_waitcnt lgkmcnt(0)
	v_mfma_f32_16x16x32_bf16 v[112:115], v[196:199], v[158:161], v[112:115]
	v_mfma_f32_16x16x32_bf16 v[104:107], v[204:207], v[158:161], v[104:107]
	v_mfma_f32_16x16x32_bf16 v[96:99], v[196:199], v[166:169], v[96:99]
	v_mfma_f32_16x16x32_bf16 v[88:91], v[204:207], v[166:169], v[88:91]
	v_mfma_f32_16x16x32_bf16 v[80:83], v[196:199], v[174:177], v[80:83]
	v_mfma_f32_16x16x32_bf16 v[72:75], v[204:207], v[174:177], v[72:75]
	v_mfma_f32_16x16x32_bf16 v[68:71], v[196:199], v[182:185], v[68:71]
	v_mfma_f32_16x16x32_bf16 v[64:67], v[204:207], v[182:185], v[64:67]
	v_mfma_f32_16x16x32_bf16 v[112:115], v[200:203], v[162:165], v[112:115]
	v_mfma_f32_16x16x32_bf16 v[104:107], v[214:217], v[162:165], v[104:107]
	v_mfma_f32_16x16x32_bf16 v[96:99], v[200:203], v[170:173], v[96:99]
	v_mfma_f32_16x16x32_bf16 v[88:91], v[214:217], v[170:173], v[88:91]
	v_mfma_f32_16x16x32_bf16 v[80:83], v[200:203], v[178:181], v[80:83]
	v_mfma_f32_16x16x32_bf16 v[72:75], v[214:217], v[178:181], v[72:75]
	v_mfma_f32_16x16x32_bf16 v[68:71], v[200:203], v[186:189], v[68:71]
	v_mfma_f32_16x16x32_bf16 v[64:67], v[214:217], v[186:189], v[64:67]
	s_mov_b32 m0, s65
	v_lshl_add_u64 v[142:143], v[218:219], 0, s[88:89]
	s_barrier
	ds_read_b128 v[158:161], v141 offset:49152
	ds_read_b128 v[162:165], v141 offset:50176
	ds_read_b128 v[166:169], v141 offset:51200
	ds_read_b128 v[170:173], v141 offset:52224
	ds_read_b128 v[174:177], v141 offset:53248
	ds_read_b128 v[178:181], v141 offset:54272
	ds_read_b128 v[182:185], v141 offset:55296
	ds_read_b128 v[186:189], v141 offset:56320
	global_load_lds_dwordx4 v[142:143], off
	s_mov_b32 m0, s66
	v_lshl_add_u64 v[142:143], v[220:221], 0, s[88:89]
	global_load_lds_dwordx4 v[142:143], off
	s_barrier
	s_waitcnt lgkmcnt(0)
	v_mfma_f32_16x16x32_bf16 v[60:63], v[134:137], v[158:161], v[60:63]
	v_mfma_f32_16x16x32_bf16 v[56:59], v[150:153], v[158:161], v[56:59]
	v_mfma_f32_16x16x32_bf16 v[52:55], v[134:137], v[166:169], v[52:55]
	v_mfma_f32_16x16x32_bf16 v[44:47], v[150:153], v[166:169], v[44:47]
	v_mfma_f32_16x16x32_bf16 v[36:39], v[134:137], v[174:177], v[36:39]
	v_mfma_f32_16x16x32_bf16 v[28:31], v[150:153], v[174:177], v[28:31]
	v_mfma_f32_16x16x32_bf16 v[20:23], v[134:137], v[182:185], v[20:23]
	v_mfma_f32_16x16x32_bf16 v[12:15], v[150:153], v[182:185], v[12:15]
	v_mfma_f32_16x16x32_bf16 v[60:63], v[146:149], v[162:165], v[60:63]
	v_mfma_f32_16x16x32_bf16 v[56:59], v[154:157], v[162:165], v[56:59]
	v_mfma_f32_16x16x32_bf16 v[52:55], v[146:149], v[170:173], v[52:55]
	v_mfma_f32_16x16x32_bf16 v[44:47], v[154:157], v[170:173], v[44:47]
	v_mfma_f32_16x16x32_bf16 v[36:39], v[146:149], v[178:181], v[36:39]
	v_mfma_f32_16x16x32_bf16 v[28:31], v[154:157], v[178:181], v[28:31]
	v_mfma_f32_16x16x32_bf16 v[20:23], v[146:149], v[186:189], v[20:23]
	v_mfma_f32_16x16x32_bf16 v[12:15], v[154:157], v[186:189], v[12:15]
	s_barrier
	s_add_u32 s10, s16, 0x60080
	s_addc_u32 s11, s17, 0
	s_add_i32 s16, s20, s35
	s_mov_b32 m0, s16
	s_nop 0
	global_load_lds_dwordx4 v144, s[10:11]
	s_add_i32 m0, s16, 0x2000
	s_nop 0
	global_load_lds_dwordx4 v128, s[10:11]
	s_waitcnt vmcnt(6)
	s_barrier
	v_mfma_f32_16x16x32_bf16 v[48:51], v[196:199], v[158:161], v[48:51]
	v_mfma_f32_16x16x32_bf16 v[40:43], v[204:207], v[158:161], v[40:43]
	v_mfma_f32_16x16x32_bf16 v[32:35], v[196:199], v[166:169], v[32:35]
	v_mfma_f32_16x16x32_bf16 v[24:27], v[204:207], v[166:169], v[24:27]
	v_mfma_f32_16x16x32_bf16 v[16:19], v[196:199], v[174:177], v[16:19]
	v_mfma_f32_16x16x32_bf16 v[8:11], v[204:207], v[174:177], v[8:11]
	v_mfma_f32_16x16x32_bf16 v[4:7], v[196:199], v[182:185], v[4:7]
	v_mfma_f32_16x16x32_bf16 v[0:3], v[204:207], v[182:185], v[0:3]
	v_mfma_f32_16x16x32_bf16 v[48:51], v[200:203], v[162:165], v[48:51]
	v_mfma_f32_16x16x32_bf16 v[40:43], v[214:217], v[162:165], v[40:43]
	v_mfma_f32_16x16x32_bf16 v[32:35], v[200:203], v[170:173], v[32:35]
	v_mfma_f32_16x16x32_bf16 v[24:27], v[214:217], v[170:173], v[24:27]
	v_mfma_f32_16x16x32_bf16 v[16:19], v[200:203], v[178:181], v[16:19]
	v_mfma_f32_16x16x32_bf16 v[8:11], v[214:217], v[178:181], v[8:11]
	v_mfma_f32_16x16x32_bf16 v[4:7], v[200:203], v[186:189], v[4:7]
	v_mfma_f32_16x16x32_bf16 v[0:3], v[214:217], v[186:189], v[0:3]
	s_add_i32 s72, s72, 2
	s_add_u32 s24, s24, 0x100
	s_addc_u32 s25, s25, 0
	s_cmp_gt_u32 s72, 21
	s_mov_b64 s[10:11], s[12:13]
	s_barrier
	s_cbranch_scc0 .LBB0_985
	s_mul_hi_i32 s10, s71, 0x3e0f83e1
	s_lshr_b32 s11, s10, 31
	s_ashr_i32 s10, s10, 5
	s_add_i32 s11, s10, s11
	s_mul_i32 s10, s11, 0x84
	s_sub_i32 s10, s71, s10
	s_mul_i32 s12, s10, 0x7c2
	s_lshr_b32 s13, s12, 31
	s_lshr_b32 s12, s12, 16
	s_add_i32 s12, s12, s13
	s_sext_i32_i16 s12, s12
	s_mul_i32 s13, s12, 0xffffffdf
	s_lshl_b32 s11, s11, 2
	s_add_i32 s10, s13, s10
	s_add_i32 s12, s11, s12
	s_cmp_lg_u32 s10, 0
	s_cbranch_scc0 .LBB0_988
	s_lshl_b32 s11, s12, 13
	s_lshl_b32 s10, s10, 8
	s_add_i32 s10, s11, s10
	s_add_i32 s13, s10, 0xffffff00
	s_cbranch_execnz .LBB0_977
	s_branch .LBB0_976

; #define PG8_STAGE(bufoff, gbase, voff) do { _Pragma("unroll") for (int _i = 0; _i < 2; ++_i) \
;         __builtin_amdgcn_global_load_lds((const unsigned*)((const char*)(gbase) + (voff)[_i]), (LAS unsigned*)(lds + (bufoff) + ldsw + _i * 8192), 16, 0, 0); } while (0)
; #define PG8_LDA(dst, b, h) do { _Pragma("unroll") for (int m = 0; m < 4; ++m) _Pragma("unroll") for (int k = 0; k < 2; ++k) dst[m][k] = *(const LAS bf16x8*)(lds + PG8_SA(b, h) + aoff + m * 2048 + k * 1024); } while (0)
; #define PG8_LDB(dst, b, h) do { _Pragma("unroll") for (int n = 0; n < 2; ++n) _Pragma("unroll") for (int k = 0; k < 2; ++k) dst[n][k] = *(const LAS bf16x8*)(lds + PG8_SB(b, h) + boff + n * 2048 + k * 1024); } while (0)
; #define PG8_MMA(ai, bj, At, Bt) do { __builtin_amdgcn_s_setprio(1); _Pragma("unroll") for (int m = 0; m < 4; ++m) _Pragma("unroll") for (int n = 0; n < 2; ++n) _Pragma("unroll") for (int k = 0; k < 2; ++k) \
;         acc[ai][bj][m][n] = __builtin_amdgcn_mfma_f32_16x16x32_bf16(Bt[n][k], At[m][k], acc[ai][bj][m][n], 0, 0, 0); __builtin_amdgcn_s_setprio(0); } while (0)
; #define PG8_WAIT_L(n) asm volatile("s_waitcnt lgkmcnt(" #n ")" ::: "memory")
; #define PG8_BAR __builtin_amdgcn_s_barrier()
; #define PG8_SCHED __builtin_amdgcn_sched_barrier(0)
; template <class Epi>
; __device__ __forceinline__ void gemm_phase(LAS unsigned char* lds, const Gemm g, const StaticOrder& S, const Epi& E) {
;     ...
;             PG8_LDB(B0, 0, 0); PG8_SCHED; PG8_LDA(At, 0, 0); PG8_STAGE(PG8_SA(1, 1), a1 + hA, voffA);
;             PG8_WAIT_L(8); PG8_BAR; PG8_WAIT_L(0); PG8_MMA(0, 0, At, B0); PG8_BAR; PG8_SCHED;
;             PG8_LDB(B1, 0, 1); PG8_STAGE(PG8_SB(0, 0), b2, voffB);
;             PG8_BAR; PG8_WAIT_L(0); PG8_MMA(0, 1, At, B1); PG8_BAR;
;             PG8_LDA(At, 0, 1); PG8_STAGE(PG8_SA(0, 0), a2, voffA);
;             PG8_BAR; PG8_WAIT_L(0); PG8_MMA(1, 0, At, B0); PG8_BAR; PG8_SCHED;
.LBB0_1013:
	s_add_u32 s12, s10, 0x100
	s_addc_u32 s13, s11, 0
	s_add_i32 s26, 0, 0x10000
	v_add_u32_e32 v142, s26, v139
	ds_read_b128 v[134:137], v142
	ds_read_b128 v[146:149], v142 offset:1024
	ds_read_b128 v[150:153], v142 offset:2048
	ds_read_b128 v[154:157], v142 offset:3072
	s_cmp_eq_u32 s72, 20
	s_cselect_b32 s21, s5, s13
	s_cselect_b32 s20, s4, s12
	s_cselect_b32 s17, s7, s25
	s_cselect_b32 s16, s6, s24
	s_add_i32 m0, s61, 0xc000
	ds_read_b128 v[158:161], v141
	ds_read_b128 v[162:165], v141 offset:1024
	ds_read_b128 v[166:169], v141 offset:2048
	ds_read_b128 v[170:173], v141 offset:3072
	ds_read_b128 v[174:177], v141 offset:4096
	ds_read_b128 v[178:181], v141 offset:5120
	ds_read_b128 v[182:185], v141 offset:6144
	ds_read_b128 v[186:189], v141 offset:7168
	global_load_lds_dwordx4 v130, s[10:11]
	s_add_i32 m0, s61, 0xe000
	v_lshl_add_u64 v[142:143], s[10:11], 0, v[132:133]
	global_load_lds_dwordx4 v[142:143], off
	s_waitcnt lgkmcnt(8)
	s_barrier
	s_waitcnt lgkmcnt(0)
	v_mfma_f32_16x16x32_bf16 v[124:127], v[134:137], v[158:161], v[124:127]
	v_mfma_f32_16x16x32_bf16 v[120:123], v[150:153], v[158:161], v[120:123]
	v_mfma_f32_16x16x32_bf16 v[116:119], v[134:137], v[166:169], v[116:119]
	v_mfma_f32_16x16x32_bf16 v[108:111], v[150:153], v[166:169], v[108:111]
	v_mfma_f32_16x16x32_bf16 v[100:103], v[134:137], v[174:177], v[100:103]
	v_mfma_f32_16x16x32_bf16 v[92:95], v[150:153], v[174:177], v[92:95]
	v_mfma_f32_16x16x32_bf16 v[84:87], v[134:137], v[182:185], v[84:87]
	v_mfma_f32_16x16x32_bf16 v[76:79], v[150:153], v[182:185], v[76:79]
	v_mfma_f32_16x16x32_bf16 v[124:127], v[146:149], v[162:165], v[124:127]
	v_mfma_f32_16x16x32_bf16 v[120:123], v[154:157], v[162:165], v[120:123]
	v_mfma_f32_16x16x32_bf16 v[116:119], v[146:149], v[170:173], v[116:119]
	v_mfma_f32_16x16x32_bf16 v[108:111], v[154:157], v[170:173], v[108:111]
	v_mfma_f32_16x16x32_bf16 v[100:103], v[146:149], v[178:181], v[100:103]
	v_mfma_f32_16x16x32_bf16 v[92:95], v[154:157], v[178:181], v[92:95]
	v_mfma_f32_16x16x32_bf16 v[84:87], v[146:149], v[186:189], v[84:87]
	v_mfma_f32_16x16x32_bf16 v[76:79], v[154:157], v[186:189], v[76:79]
	s_barrier
	s_add_i32 s27, 0, 0x14000
	v_add_u32_e32 v142, s27, v139
	s_add_i32 s10, s26, s60
	ds_read_b128 v[196:199], v142
	ds_read_b128 v[200:203], v142 offset:1024
	ds_read_b128 v[204:207], v142 offset:2048
	ds_read_b128 v[214:217], v142 offset:3072
	v_lshl_add_u64 v[142:143], s[16:17], 0, v[144:145]
	s_mov_b32 m0, s10
	v_lshl_add_u64 v[192:193], s[16:17], 0, v[128:129]
	global_load_lds_dwordx4 v[142:143], off
	s_add_i32 m0, s10, 0x2000
	s_nop 0
	global_load_lds_dwordx4 v[192:193], off
	s_barrier
	s_waitcnt lgkmcnt(0)
	v_mfma_f32_16x16x32_bf16 v[112:115], v[196:199], v[158:161], v[112:115]
	v_mfma_f32_16x16x32_bf16 v[104:107], v[204:207], v[158:161], v[104:107]
	v_mfma_f32_16x16x32_bf16 v[96:99], v[196:199], v[166:169], v[96:99]
	v_mfma_f32_16x16x32_bf16 v[88:91], v[204:207], v[166:169], v[88:91]
	v_mfma_f32_16x16x32_bf16 v[80:83], v[196:199], v[174:177], v[80:83]
	v_mfma_f32_16x16x32_bf16 v[72:75], v[204:207], v[174:177], v[72:75]
	v_mfma_f32_16x16x32_bf16 v[68:71], v[196:199], v[182:185], v[68:71]
	v_mfma_f32_16x16x32_bf16 v[64:67], v[204:207], v[182:185], v[64:67]
	v_mfma_f32_16x16x32_bf16 v[112:115], v[200:203], v[162:165], v[112:115]
	v_mfma_f32_16x16x32_bf16 v[104:107], v[214:217], v[162:165], v[104:107]
	v_mfma_f32_16x16x32_bf16 v[96:99], v[200:203], v[170:173], v[96:99]
	v_mfma_f32_16x16x32_bf16 v[88:91], v[214:217], v[170:173], v[88:91]
	v_mfma_f32_16x16x32_bf16 v[80:83], v[200:203], v[178:181], v[80:83]
	v_mfma_f32_16x16x32_bf16 v[72:75], v[214:217], v[178:181], v[72:75]
	v_mfma_f32_16x16x32_bf16 v[68:71], v[200:203], v[186:189], v[68:71]
	v_mfma_f32_16x16x32_bf16 v[64:67], v[214:217], v[186:189], v[64:67]
	s_mov_b32 m0, s61
	v_lshl_add_u64 v[218:219], s[20:21], 0, v[144:145]
	s_barrier
	ds_read_b128 v[158:161], v141 offset:16384
	ds_read_b128 v[162:165], v141 offset:17408
	ds_read_b128 v[166:169], v141 offset:18432
	ds_read_b128 v[170:173], v141 offset:19456
	ds_read_b128 v[174:177], v141 offset:20480
	ds_read_b128 v[178:181], v141 offset:21504
	ds_read_b128 v[182:185], v141 offset:22528
	ds_read_b128 v[186:189], v141 offset:23552
	global_load_lds_dwordx4 v[218:219], off
	s_mov_b32 m0, s62
	v_lshl_add_u64 v[220:221], s[20:21], 0, v[128:129]
	global_load_lds_dwordx4 v[220:221], off
	s_barrier
	s_waitcnt lgkmcnt(0)
	v_mfma_f32_16x16x32_bf16 v[60:63], v[134:137], v[158:161], v[60:63]
	v_mfma_f32_16x16x32_bf16 v[56:59], v[150:153], v[158:161], v[56:59]
	v_mfma_f32_16x16x32_bf16 v[52:55], v[134:137], v[166:169], v[52:55]
	v_mfma_f32_16x16x32_bf16 v[44:47], v[150:153], v[166:169], v[44:47]
	v_mfma_f32_16x16x32_bf16 v[36:39], v[134:137], v[174:177], v[36:39]
	v_mfma_f32_16x16x32_bf16 v[28:31], v[150:153], v[174:177], v[28:31]
	v_mfma_f32_16x16x32_bf16 v[20:23], v[134:137], v[182:185], v[20:23]
	v_mfma_f32_16x16x32_bf16 v[12:15], v[150:153], v[182:185], v[12:15]
	v_mfma_f32_16x16x32_bf16 v[60:63], v[146:149], v[162:165], v[60:63]
	v_mfma_f32_16x16x32_bf16 v[56:59], v[154:157], v[162:165], v[56:59]
	v_mfma_f32_16x16x32_bf16 v[52:55], v[146:149], v[170:173], v[52:55]
	v_mfma_f32_16x16x32_bf16 v[44:47], v[154:157], v[170:173], v[44:47]
	v_mfma_f32_16x16x32_bf16 v[36:39], v[146:149], v[178:181], v[36:39]
	v_mfma_f32_16x16x32_bf16 v[28:31], v[154:157], v[178:181], v[28:31]
	v_mfma_f32_16x16x32_bf16 v[20:23], v[146:149], v[186:189], v[20:23]
	v_mfma_f32_16x16x32_bf16 v[12:15], v[154:157], v[186:189], v[12:15]
	s_barrier
; #define PG8_STAGE(bufoff, gbase, voff) do { _Pragma("unroll") for (int _i = 0; _i < 2; ++_i) \
;         __builtin_amdgcn_global_load_lds((const unsigned*)((const char*)(gbase) + (voff)[_i]), (LAS unsigned*)(lds + (bufoff) + ldsw + _i * 8192), 16, 0, 0); } while (0)
; #define PG8_LDA(dst, b, h) do { _Pragma("unroll") for (int m = 0; m < 4; ++m) _Pragma("unroll") for (int k = 0; k < 2; ++k) dst[m][k] = *(const LAS bf16x8*)(lds + PG8_SA(b, h) + aoff + m * 2048 + k * 1024); } while (0)
; #define PG8_LDB(dst, b, h) do { _Pragma("unroll") for (int n = 0; n < 2; ++n) _Pragma("unroll") for (int k = 0; k < 2; ++k) dst[n][k] = *(const LAS bf16x8*)(lds + PG8_SB(b, h) + boff + n * 2048 + k * 1024); } while (0)
; #define PG8_MMA(ai, bj, At, Bt) do { __builtin_amdgcn_s_setprio(1); _Pragma("unroll") for (int m = 0; m < 4; ++m) _Pragma("unroll") for (int n = 0; n < 2; ++n) _Pragma("unroll") for (int k = 0; k < 2; ++k) \
;         acc[ai][bj][m][n] = __builtin_amdgcn_mfma_f32_16x16x32_bf16(Bt[n][k], At[m][k], acc[ai][bj][m][n], 0, 0, 0); __builtin_amdgcn_s_setprio(0); } while (0)
; #define PG8_WAIT_V(n) asm volatile("s_waitcnt vmcnt(" #n ")" ::: "memory")
; #define PG8_WAIT_L(n) asm volatile("s_waitcnt lgkmcnt(" #n ")" ::: "memory")
; #define PG8_BAR __builtin_amdgcn_s_barrier()
; #define PG8_SCHED __builtin_amdgcn_sched_barrier(0)
; template <class Epi>
; __device__ __forceinline__ void gemm_phase(LAS unsigned char* lds, const Gemm g, const StaticOrder& S, const Epi& E) {
;     ...
;             PG8_STAGE(PG8_SB(0, 1), b2 + hB, voffB);
;             PG8_WAIT_V(6); PG8_BAR; PG8_MMA(1, 1, At, B1); PG8_BAR;
;             PG8_LDB(B0, 1, 0); PG8_SCHED; PG8_LDA(At, 1, 0); PG8_STAGE(PG8_SA(0, 1), a2 + hA, voffA);
;             PG8_WAIT_L(8); PG8_BAR; PG8_WAIT_L(0); PG8_MMA(0, 0, At, B0); PG8_BAR; PG8_SCHED;
;             PG8_LDB(B1, 1, 1); PG8_STAGE(PG8_SB(1, 0), b3, voffB);
;             PG8_BAR; PG8_WAIT_L(0); PG8_MMA(0, 1, At, B1); PG8_BAR;
;             PG8_LDA(At, 1, 1); PG8_STAGE(PG8_SA(1, 0), a3, voffA);
	s_add_u32 s10, s16, 0x60000
	s_addc_u32 s11, s17, 0
	s_add_i32 s26, s27, s60
	s_mov_b32 m0, s26
	s_nop 0
	global_load_lds_dwordx4 v144, s[10:11]
	s_add_i32 m0, s26, 0x2000
	s_nop 0
	global_load_lds_dwordx4 v128, s[10:11]
	s_waitcnt vmcnt(6)
	s_barrier
	v_mfma_f32_16x16x32_bf16 v[48:51], v[196:199], v[158:161], v[48:51]
	v_mfma_f32_16x16x32_bf16 v[40:43], v[204:207], v[158:161], v[40:43]
	v_mfma_f32_16x16x32_bf16 v[32:35], v[196:199], v[166:169], v[32:35]
	v_mfma_f32_16x16x32_bf16 v[24:27], v[204:207], v[166:169], v[24:27]
	v_mfma_f32_16x16x32_bf16 v[16:19], v[196:199], v[174:177], v[16:19]
	v_mfma_f32_16x16x32_bf16 v[8:11], v[204:207], v[174:177], v[8:11]
	v_mfma_f32_16x16x32_bf16 v[4:7], v[196:199], v[182:185], v[4:7]
	v_mfma_f32_16x16x32_bf16 v[0:3], v[204:207], v[182:185], v[0:3]
	v_mfma_f32_16x16x32_bf16 v[48:51], v[200:203], v[162:165], v[48:51]
	v_mfma_f32_16x16x32_bf16 v[40:43], v[214:217], v[162:165], v[40:43]
	v_mfma_f32_16x16x32_bf16 v[32:35], v[200:203], v[170:173], v[32:35]
	v_mfma_f32_16x16x32_bf16 v[24:27], v[214:217], v[170:173], v[24:27]
	v_mfma_f32_16x16x32_bf16 v[16:19], v[200:203], v[178:181], v[16:19]
	v_mfma_f32_16x16x32_bf16 v[8:11], v[214:217], v[178:181], v[8:11]
	v_mfma_f32_16x16x32_bf16 v[4:7], v[200:203], v[186:189], v[4:7]
	v_mfma_f32_16x16x32_bf16 v[0:3], v[214:217], v[186:189], v[0:3]
	s_add_i32 s26, 0, 0x18000
	v_add_u32_e32 v154, s26, v139
	s_barrier
	ds_read_b128 v[134:137], v154
	ds_read_b128 v[146:149], v154 offset:1024
	ds_read_b128 v[150:153], v154 offset:2048
	ds_read_b128 v[154:157], v154 offset:3072
	s_add_u32 s10, s20, 0x60000
	s_addc_u32 s11, s21, 0
	s_mov_b32 m0, s63
	ds_read_b128 v[158:161], v141 offset:32768
	ds_read_b128 v[162:165], v141 offset:33792
	ds_read_b128 v[166:169], v141 offset:34816
	ds_read_b128 v[170:173], v141 offset:35840
	ds_read_b128 v[174:177], v141 offset:36864
	ds_read_b128 v[178:181], v141 offset:37888
	ds_read_b128 v[182:185], v141 offset:38912
	global_load_lds_dwordx4 v144, s[10:11]
	s_mov_b32 m0, s64
	ds_read_b128 v[186:189], v141 offset:39936
	global_load_lds_dwordx4 v128, s[10:11]
	s_waitcnt lgkmcnt(8)
	s_barrier
	s_waitcnt lgkmcnt(0)
	v_mfma_f32_16x16x32_bf16 v[124:127], v[134:137], v[158:161], v[124:127]
	v_mfma_f32_16x16x32_bf16 v[120:123], v[150:153], v[158:161], v[120:123]
	v_mfma_f32_16x16x32_bf16 v[116:119], v[134:137], v[166:169], v[116:119]
	v_mfma_f32_16x16x32_bf16 v[108:111], v[150:153], v[166:169], v[108:111]
	v_mfma_f32_16x16x32_bf16 v[100:103], v[134:137], v[174:177], v[100:103]
	v_mfma_f32_16x16x32_bf16 v[92:95], v[150:153], v[174:177], v[92:95]
	v_mfma_f32_16x16x32_bf16 v[84:87], v[134:137], v[182:185], v[84:87]
	v_mfma_f32_16x16x32_bf16 v[76:79], v[150:153], v[182:185], v[76:79]
	v_mfma_f32_16x16x32_bf16 v[124:127], v[146:149], v[162:165], v[124:127]
	v_mfma_f32_16x16x32_bf16 v[120:123], v[154:157], v[162:165], v[120:123]
	v_mfma_f32_16x16x32_bf16 v[116:119], v[146:149], v[170:173], v[116:119]
	v_mfma_f32_16x16x32_bf16 v[108:111], v[154:157], v[170:173], v[108:111]
	v_mfma_f32_16x16x32_bf16 v[100:103], v[146:149], v[178:181], v[100:103]
	v_mfma_f32_16x16x32_bf16 v[92:95], v[154:157], v[178:181], v[92:95]
	v_mfma_f32_16x16x32_bf16 v[84:87], v[146:149], v[186:189], v[84:87]
	v_mfma_f32_16x16x32_bf16 v[76:79], v[154:157], v[186:189], v[76:79]
	s_barrier
	s_add_i32 s20, 0, 0x1c000
	s_add_i32 s10, s26, s60
	v_add_u32_e32 v190, s20, v139
	v_lshl_add_u64 v[142:143], v[142:143], 0, s[88:89]
	s_mov_b32 m0, s10
	ds_read_b128 v[196:199], v190
	ds_read_b128 v[200:203], v190 offset:1024
	ds_read_b128 v[204:207], v190 offset:2048
	ds_read_b128 v[214:217], v190 offset:3072
	global_load_lds_dwordx4 v[142:143], off
	s_add_i32 m0, s10, 0x2000
	v_lshl_add_u64 v[142:143], v[192:193], 0, s[88:89]
	global_load_lds_dwordx4 v[142:143], off
	s_barrier
	s_waitcnt lgkmcnt(0)
	v_mfma_f32_16x16x32_bf16 v[112:115], v[196:199], v[158:161], v[112:115]
	v_mfma_f32_16x16x32_bf16 v[104:107], v[204:207], v[158:161], v[104:107]
	v_mfma_f32_16x16x32_bf16 v[96:99], v[196:199], v[166:169], v[96:99]
	v_mfma_f32_16x16x32_bf16 v[88:91], v[204:207], v[166:169], v[88:91]
	v_mfma_f32_16x16x32_bf16 v[80:83], v[196:199], v[174:177], v[80:83]
	v_mfma_f32_16x16x32_bf16 v[72:75], v[204:207], v[174:177], v[72:75]
	v_mfma_f32_16x16x32_bf16 v[68:71], v[196:199], v[182:185], v[68:71]
	v_mfma_f32_16x16x32_bf16 v[64:67], v[204:207], v[182:185], v[64:67]
	v_mfma_f32_16x16x32_bf16 v[112:115], v[200:203], v[162:165], v[112:115]
	v_mfma_f32_16x16x32_bf16 v[104:107], v[214:217], v[162:165], v[104:107]
	v_mfma_f32_16x16x32_bf16 v[96:99], v[200:203], v[170:173], v[96:99]
	v_mfma_f32_16x16x32_bf16 v[88:91], v[214:217], v[170:173], v[88:91]
	v_mfma_f32_16x16x32_bf16 v[80:83], v[200:203], v[178:181], v[80:83]
	v_mfma_f32_16x16x32_bf16 v[72:75], v[214:217], v[178:181], v[72:75]
	v_mfma_f32_16x16x32_bf16 v[68:71], v[200:203], v[186:189], v[68:71]
	v_mfma_f32_16x16x32_bf16 v[64:67], v[214:217], v[186:189], v[64:67]
	s_mov_b32 m0, s65
	v_lshl_add_u64 v[142:143], v[218:219], 0, s[88:89]
	s_barrier
	ds_read_b128 v[158:161], v141 offset:49152
	ds_read_b128 v[162:165], v141 offset:50176
	ds_read_b128 v[166:169], v141 offset:51200
	ds_read_b128 v[170:173], v141 offset:52224
	ds_read_b128 v[174:177], v141 offset:53248
	ds_read_b128 v[178:181], v141 offset:54272
	ds_read_b128 v[182:185], v141 offset:55296
	ds_read_b128 v[186:189], v141 offset:56320
	global_load_lds_dwordx4 v[142:143], off
	s_mov_b32 m0, s66
	v_lshl_add_u64 v[142:143], v[220:221], 0, s[88:89]
	global_load_lds_dwordx4 v[142:143], off
	s_barrier
; #define PG8_STAGE(bufoff, gbase, voff) do { _Pragma("unroll") for (int _i = 0; _i < 2; ++_i) \
;         __builtin_amdgcn_global_load_lds((const unsigned*)((const char*)(gbase) + (voff)[_i]), (LAS unsigned*)(lds + (bufoff) + ldsw + _i * 8192), 16, 0, 0); } while (0)
; #define PG8_MMA(ai, bj, At, Bt) do { __builtin_amdgcn_s_setprio(1); _Pragma("unroll") for (int m = 0; m < 4; ++m) _Pragma("unroll") for (int n = 0; n < 2; ++n) _Pragma("unroll") for (int k = 0; k < 2; ++k) \
;         acc[ai][bj][m][n] = __builtin_amdgcn_mfma_f32_16x16x32_bf16(Bt[n][k], At[m][k], acc[ai][bj][m][n], 0, 0, 0); __builtin_amdgcn_s_setprio(0); } while (0)
; #define PG8_WAIT_V(n) asm volatile("s_waitcnt vmcnt(" #n ")" ::: "memory")
; #define PG8_WAIT_L(n) asm volatile("s_waitcnt lgkmcnt(" #n ")" ::: "memory")
; #define PG8_BAR __builtin_amdgcn_s_barrier()
; #define PG8_SCHED __builtin_amdgcn_sched_barrier(0)
; template <class Epi>
; __device__ __forceinline__ void gemm_phase(LAS unsigned char* lds, const Gemm g, const StaticOrder& S, const Epi& E) {
;     ...
;             PG8_BAR; PG8_WAIT_L(0); PG8_MMA(1, 0, At, B0); PG8_BAR; PG8_SCHED;
;             PG8_STAGE(PG8_SB(1, 1), b3 + hB, voffB);
;             PG8_WAIT_V(6); PG8_BAR; PG8_MMA(1, 1, At, B1); PG8_BAR;
	s_waitcnt lgkmcnt(0)
	v_mfma_f32_16x16x32_bf16 v[60:63], v[134:137], v[158:161], v[60:63]
	v_mfma_f32_16x16x32_bf16 v[56:59], v[150:153], v[158:161], v[56:59]
	v_mfma_f32_16x16x32_bf16 v[52:55], v[134:137], v[166:169], v[52:55]
	v_mfma_f32_16x16x32_bf16 v[44:47], v[150:153], v[166:169], v[44:47]
	v_mfma_f32_16x16x32_bf16 v[36:39], v[134:137], v[174:177], v[36:39]
	v_mfma_f32_16x16x32_bf16 v[28:31], v[150:153], v[174:177], v[28:31]
	v_mfma_f32_16x16x32_bf16 v[20:23], v[134:137], v[182:185], v[20:23]
	v_mfma_f32_16x16x32_bf16 v[12:15], v[150:153], v[182:185], v[12:15]
	v_mfma_f32_16x16x32_bf16 v[60:63], v[146:149], v[162:165], v[60:63]
	v_mfma_f32_16x16x32_bf16 v[56:59], v[154:157], v[162:165], v[56:59]
	v_mfma_f32_16x16x32_bf16 v[52:55], v[146:149], v[170:173], v[52:55]
	v_mfma_f32_16x16x32_bf16 v[44:47], v[154:157], v[170:173], v[44:47]
	v_mfma_f32_16x16x32_bf16 v[36:39], v[146:149], v[178:181], v[36:39]
	v_mfma_f32_16x16x32_bf16 v[28:31], v[154:157], v[178:181], v[28:31]
	v_mfma_f32_16x16x32_bf16 v[20:23], v[146:149], v[186:189], v[20:23]
	v_mfma_f32_16x16x32_bf16 v[12:15], v[154:157], v[186:189], v[12:15]
	s_barrier
	s_add_u32 s10, s16, 0x60080
	s_addc_u32 s11, s17, 0
	s_add_i32 s16, s20, s60
	s_mov_b32 m0, s16
	s_nop 0
	global_load_lds_dwordx4 v144, s[10:11]
	s_add_i32 m0, s16, 0x2000
	s_nop 0
	global_load_lds_dwordx4 v128, s[10:11]
	s_waitcnt vmcnt(6)
	s_barrier
	v_mfma_f32_16x16x32_bf16 v[48:51], v[196:199], v[158:161], v[48:51]
	v_mfma_f32_16x16x32_bf16 v[40:43], v[204:207], v[158:161], v[40:43]
	v_mfma_f32_16x16x32_bf16 v[32:35], v[196:199], v[166:169], v[32:35]
	v_mfma_f32_16x16x32_bf16 v[24:27], v[204:207], v[166:169], v[24:27]
	v_mfma_f32_16x16x32_bf16 v[16:19], v[196:199], v[174:177], v[16:19]
	v_mfma_f32_16x16x32_bf16 v[8:11], v[204:207], v[174:177], v[8:11]
	v_mfma_f32_16x16x32_bf16 v[4:7], v[196:199], v[182:185], v[4:7]
	v_mfma_f32_16x16x32_bf16 v[0:3], v[204:207], v[182:185], v[0:3]
	v_mfma_f32_16x16x32_bf16 v[48:51], v[200:203], v[162:165], v[48:51]
	v_mfma_f32_16x16x32_bf16 v[40:43], v[214:217], v[162:165], v[40:43]
	v_mfma_f32_16x16x32_bf16 v[32:35], v[200:203], v[170:173], v[32:35]
	v_mfma_f32_16x16x32_bf16 v[24:27], v[214:217], v[170:173], v[24:27]
	v_mfma_f32_16x16x32_bf16 v[16:19], v[200:203], v[178:181], v[16:19]
	v_mfma_f32_16x16x32_bf16 v[8:11], v[214:217], v[178:181], v[8:11]
	v_mfma_f32_16x16x32_bf16 v[4:7], v[200:203], v[186:189], v[4:7]
	v_mfma_f32_16x16x32_bf16 v[0:3], v[214:217], v[186:189], v[0:3]
	s_add_i32 s72, s72, 2
	s_add_u32 s24, s24, 0x100
	s_addc_u32 s25, s25, 0
	s_cmp_gt_u32 s72, 21
	s_mov_b64 s[10:11], s[12:13]
	s_barrier
	s_cbranch_scc0 .LBB0_1013
; __device__ __forceinline__ unsigned pk2(float lo, float hi) { unsigned r; asm("v_cvt_pk_bf16_f32 %0, %1, %2" : "=v"(r) : "v"(lo), "v"(hi)); return r; }
; #define PG8_WAIT_V(n) asm volatile("s_waitcnt vmcnt(" #n ")" ::: "memory")
; #define PG8_BAR __builtin_amdgcn_s_barrier()
; template <class Epi>
; __device__ __forceinline__ void gemm_phase(LAS unsigned char* lds, const Gemm g, const StaticOrder& S, const Epi& E) {
;     ...
;         if (!has_next) break;
; #pragma unroll
;         for (int a = 0; a < 2; ++a)
; #pragma unroll
;             for (int b = 0; b < 2; ++b)
; #pragma unroll
;                 for (int m = 0; m < 4; ++m)
; #pragma unroll
;                     for (int n = 0; n < 2; ++n) acc[a][b][m][n] = (f32x4){0.f, 0.f, 0.f, 0.f};
;         cur = nxt; cA = nA; cB = nB; ++ui;
;     }
;     PG8_WAIT_V(0);
;     if (wr == 0) PG8_BAR;
;     PG8_BAR;
;     __device__ __forceinline__ void operator()(const f32x4 (&acc)[2][2][4][2], const Unit& u, int wr, int wc, int fr, int fq) const {
;     ...
;         const int row_t = rmap == 1 ? odd_phys_row0(u.pm, grp) : (rmap == 2 ? odd_phys_row0(u.pm % (BG * TPB), u.pm / (BG * TPB)) : u.pm * BM);
;         int c = col_t + 64 * wc + 16 * fq;
;         if (mode == 2) c = (c >> 6) * 96 + (c & 63);
; #pragma unroll
;         for (int ai = 0; ai < 2; ++ai)
; #pragma unroll
;             for (int m = 0; m < 4; ++m) {
;                 const int row = row_t + ai * HALF + wr * 64 + m * 16 + fr;
;                 bf16_t* rp = O + (size_t)row * ldc + c;
; #pragma unroll
;                 for (int bj = 0; bj < 2; ++bj) {
;                     const f32x4 v0 = acc[ai][bj][m][0], v1 = acc[ai][bj][m][1];
;                     u32x4 o; o.x = pk2(v0[0], v0[1]); o.y = pk2(v0[2], v0[3]); o.z = pk2(v1[0], v1[1]); o.w = pk2(v1[2], v1[3]);
;                     *(u32x4*)(rp + 8 * bj) = o;
;                 }
;             }
	v_lshl_add_u32 v134, s71, 8, v138
	v_cvt_pk_bf16_f32 v68, v68, v69
	v_cvt_pk_bf16_f32 v69, v70, v71
	v_cvt_pk_bf16_f32 v70, v64, v65
	v_add_u32_e32 v64, 0x80, v134
	v_lshl_or_b32 v136, s15, 8, v140
	v_ashrrev_i32_e32 v135, 31, v134
	v_cvt_pk_bf16_f32 v112, v112, v113
	v_cvt_pk_bf16_f32 v113, v114, v115
	v_cvt_pk_bf16_f32 v114, v104, v105
	v_or_b32_e32 v104, 16, v134
	v_ashrrev_i32_e32 v65, 31, v64
	v_cvt_pk_bf16_f32 v48, v48, v49
	v_cvt_pk_bf16_f32 v49, v50, v51
	v_cvt_pk_bf16_f32 v50, v40, v41
	v_add_u32_e32 v40, 0x90, v134
	v_ashrrev_i32_e32 v137, 31, v136
	v_lshlrev_b64 v[142:143], 11, v[134:135]
	v_ashrrev_i32_e32 v105, 31, v104
	v_cvt_pk_bf16_f32 v96, v96, v97
	v_cvt_pk_bf16_f32 v97, v98, v99
	v_cvt_pk_bf16_f32 v98, v88, v89
	v_or_b32_e32 v88, 32, v134
	v_lshlrev_b64 v[64:65], 11, v[64:65]
	v_ashrrev_i32_e32 v41, 31, v40
	v_cvt_pk_bf16_f32 v32, v32, v33
	v_cvt_pk_bf16_f32 v33, v34, v35
	v_cvt_pk_bf16_f32 v34, v24, v25
	v_add_u32_e32 v24, 0xa0, v134
	v_lshl_add_u64 v[142:143], s[8:9], 0, v[142:143]
	v_lshlrev_b64 v[136:137], 1, v[136:137]
	v_lshlrev_b64 v[104:105], 11, v[104:105]
	v_ashrrev_i32_e32 v89, 31, v88
	v_cvt_pk_bf16_f32 v80, v80, v81
	v_cvt_pk_bf16_f32 v81, v82, v83
	v_cvt_pk_bf16_f32 v82, v72, v73
	v_or_b32_e32 v72, 48, v134
	v_lshl_add_u64 v[64:65], s[8:9], 0, v[64:65]
	v_lshlrev_b64 v[40:41], 11, v[40:41]
	v_ashrrev_i32_e32 v25, 31, v24
	v_cvt_pk_bf16_f32 v16, v16, v17
	v_cvt_pk_bf16_f32 v17, v18, v19
	v_cvt_pk_bf16_f32 v18, v8, v9
	v_add_u32_e32 v8, 0xb0, v134
	v_lshl_add_u64 v[142:143], v[142:143], 0, v[136:137]
	v_lshl_add_u64 v[104:105], s[8:9], 0, v[104:105]
	v_lshlrev_b64 v[88:89], 11, v[88:89]
	v_ashrrev_i32_e32 v73, 31, v72
	v_lshl_add_u64 v[64:65], v[64:65], 0, v[136:137]
	v_lshl_add_u64 v[40:41], s[8:9], 0, v[40:41]
	v_lshlrev_b64 v[24:25], 11, v[24:25]
	v_ashrrev_i32_e32 v9, 31, v8
	v_cvt_pk_bf16_f32 v115, v106, v107
	global_store_dwordx4 v[142:143], v[112:115], off offset:16
	v_lshl_add_u64 v[88:89], s[8:9], 0, v[88:89]
	v_lshlrev_b64 v[72:73], 11, v[72:73]
	v_lshl_add_u64 v[112:113], v[104:105], 0, v[136:137]
	v_cvt_pk_bf16_f32 v51, v42, v43
	global_store_dwordx4 v[64:65], v[48:51], off offset:16
	v_lshl_add_u64 v[24:25], s[8:9], 0, v[24:25]
	v_lshlrev_b64 v[8:9], 11, v[8:9]
	v_lshl_add_u64 v[48:49], v[40:41], 0, v[136:137]
	v_cvt_pk_bf16_f32 v99, v90, v91
	global_store_dwordx4 v[112:113], v[96:99], off offset:16
	v_lshl_add_u64 v[72:73], s[8:9], 0, v[72:73]
	v_cvt_pk_bf16_f32 v35, v26, v27
	global_store_dwordx4 v[48:49], v[32:35], off offset:16
	v_lshl_add_u64 v[96:97], v[88:89], 0, v[136:137]
	v_lshl_add_u64 v[8:9], s[8:9], 0, v[8:9]
	v_lshl_add_u64 v[32:33], v[24:25], 0, v[136:137]
	v_cvt_pk_bf16_f32 v83, v74, v75
	global_store_dwordx4 v[96:97], v[80:83], off offset:16
	v_cvt_pk_bf16_f32 v19, v10, v11
	global_store_dwordx4 v[32:33], v[16:19], off offset:16
	s_and_b64 vcc, exec, s[0:1]
	v_lshl_add_u64 v[80:81], v[72:73], 0, v[136:137]
	v_lshl_add_u64 v[16:17], v[8:9], 0, v[136:137]
	s_mov_b32 s15, s69
	s_mov_b32 s71, s70
	s_mov_b64 s[12:13], s[6:7]
	s_mov_b64 s[10:11], s[4:5]
	v_cvt_pk_bf16_f32 v124, v124, v125
	v_cvt_pk_bf16_f32 v125, v126, v127
	v_cvt_pk_bf16_f32 v126, v120, v121
	v_cvt_pk_bf16_f32 v127, v122, v123
	global_store_dwordx4 v[142:143], v[124:127], off
	v_cvt_pk_bf16_f32 v104, v116, v117
	v_cvt_pk_bf16_f32 v105, v118, v119
	v_cvt_pk_bf16_f32 v106, v108, v109
	v_cvt_pk_bf16_f32 v107, v110, v111
	global_store_dwordx4 v[112:113], v[104:107], off
	v_cvt_pk_bf16_f32 v88, v100, v101
	v_cvt_pk_bf16_f32 v89, v102, v103
	v_cvt_pk_bf16_f32 v90, v92, v93
	v_cvt_pk_bf16_f32 v91, v94, v95
	global_store_dwordx4 v[96:97], v[88:91], off
	v_cvt_pk_bf16_f32 v72, v84, v85
	v_cvt_pk_bf16_f32 v73, v86, v87
	v_cvt_pk_bf16_f32 v74, v76, v77
	v_cvt_pk_bf16_f32 v75, v78, v79
	global_store_dwordx4 v[80:81], v[72:75], off
	v_cvt_pk_bf16_f32 v71, v66, v67
	global_store_dwordx4 v[80:81], v[68:71], off offset:16
	v_cvt_pk_bf16_f32 v60, v60, v61
	v_cvt_pk_bf16_f32 v61, v62, v63
	v_cvt_pk_bf16_f32 v62, v56, v57
	v_cvt_pk_bf16_f32 v63, v58, v59
	global_store_dwordx4 v[64:65], v[60:63], off
	v_cvt_pk_bf16_f32 v40, v52, v53
	v_cvt_pk_bf16_f32 v41, v54, v55
	v_cvt_pk_bf16_f32 v42, v44, v45
	v_cvt_pk_bf16_f32 v43, v46, v47
	global_store_dwordx4 v[48:49], v[40:43], off
	v_cvt_pk_bf16_f32 v24, v36, v37
	v_cvt_pk_bf16_f32 v25, v38, v39
	v_cvt_pk_bf16_f32 v26, v28, v29
	v_cvt_pk_bf16_f32 v27, v30, v31
	global_store_dwordx4 v[32:33], v[24:27], off
	v_cvt_pk_bf16_f32 v8, v20, v21
	v_cvt_pk_bf16_f32 v9, v22, v23
	v_cvt_pk_bf16_f32 v10, v12, v13
	v_cvt_pk_bf16_f32 v11, v14, v15
	global_store_dwordx4 v[16:17], v[8:11], off
	v_cvt_pk_bf16_f32 v4, v4, v5
	v_cvt_pk_bf16_f32 v5, v6, v7
	v_cvt_pk_bf16_f32 v6, v0, v1
	v_cvt_pk_bf16_f32 v7, v2, v3
	global_store_dwordx4 v[16:17], v[4:7], off offset:16
	s_cbranch_vccz .LBB0_1002
	s_waitcnt vmcnt(0)
	s_cmpk_gt_u32 s34, 0xff
	s_cbranch_scc1 .LBB0_1017
	s_barrier

; #define PG8_STAGE(bufoff, gbase, voff) do { _Pragma("unroll") for (int _i = 0; _i < 2; ++_i) \
;         __builtin_amdgcn_global_load_lds((const unsigned*)((const char*)(gbase) + (voff)[_i]), (LAS unsigned*)(lds + (bufoff) + ldsw + _i * 8192), 16, 0, 0); } while (0)
; #define PG8_LDA(dst, b, h) do { _Pragma("unroll") for (int m = 0; m < 4; ++m) _Pragma("unroll") for (int k = 0; k < 2; ++k) dst[m][k] = *(const LAS bf16x8*)(lds + PG8_SA(b, h) + aoff + m * 2048 + k * 1024); } while (0)
; #define PG8_LDB(dst, b, h) do { _Pragma("unroll") for (int n = 0; n < 2; ++n) _Pragma("unroll") for (int k = 0; k < 2; ++k) dst[n][k] = *(const LAS bf16x8*)(lds + PG8_SB(b, h) + boff + n * 2048 + k * 1024); } while (0)
; #define PG8_MMA(ai, bj, At, Bt) do { __builtin_amdgcn_s_setprio(1); _Pragma("unroll") for (int m = 0; m < 4; ++m) _Pragma("unroll") for (int n = 0; n < 2; ++n) _Pragma("unroll") for (int k = 0; k < 2; ++k) \
;         acc[ai][bj][m][n] = __builtin_amdgcn_mfma_f32_16x16x32_bf16(Bt[n][k], At[m][k], acc[ai][bj][m][n], 0, 0, 0); __builtin_amdgcn_s_setprio(0); } while (0)
; #define PG8_WAIT_L(n) asm volatile("s_waitcnt lgkmcnt(" #n ")" ::: "memory")
; #define PG8_BAR __builtin_amdgcn_s_barrier()
; #define PG8_SCHED __builtin_amdgcn_sched_barrier(0)
; template <class Epi>
; __device__ __forceinline__ void gemm_phase(LAS unsigned char* lds, const Gemm g, const StaticOrder& S, const Epi& E) {
;     ...
;             const bool last = (t == nt - 2);
;             const char* a1 = cA + (size_t)(t + 1) * kstep;
;             const char* a2 = last ? nA : cA + (size_t)(t + 2) * kstep; const char* b2 = last ? nB : cB + (size_t)(t + 2) * kstep;
;             const char* a3 = a2 + kstep; const char* b3 = b2 + kstep;
;             PG8_LDB(B0, 0, 0); PG8_SCHED; PG8_LDA(At, 0, 0); PG8_STAGE(PG8_SA(1, 1), a1 + hA, voffA);
;             PG8_WAIT_L(8); PG8_BAR; PG8_WAIT_L(0); PG8_MMA(0, 0, At, B0); PG8_BAR; PG8_SCHED;
;             PG8_LDB(B1, 0, 1); PG8_STAGE(PG8_SB(0, 0), b2, voffB);
;             PG8_BAR; PG8_WAIT_L(0); PG8_MMA(0, 1, At, B1); PG8_BAR;
;             PG8_LDA(At, 0, 1); PG8_STAGE(PG8_SA(0, 0), a2, voffA);
;             PG8_BAR; PG8_WAIT_L(0); PG8_MMA(1, 0, At, B0); PG8_BAR; PG8_SCHED;
.LBB0_1079:
	s_add_u32 s16, s12, 0xfffc0080
	s_addc_u32 s17, s13, -1
	s_add_i32 s26, 0, 0x10000
	v_add_u32_e32 v142, s26, v139
	ds_read_b128 v[134:137], v142
	ds_read_b128 v[146:149], v142 offset:1024
	ds_read_b128 v[150:153], v142 offset:2048
	ds_read_b128 v[154:157], v142 offset:3072
	s_cmp_eq_u32 s77, 12
	s_cselect_b32 s21, s71, s17
	s_cselect_b32 s20, s72, s16
	s_cselect_b32 s17, s7, s76
	s_cselect_b32 s16, s24, s25
	s_add_i32 m0, s61, 0xc000
	ds_read_b128 v[158:161], v141
	ds_read_b128 v[162:165], v141 offset:1024
	ds_read_b128 v[166:169], v141 offset:2048
	ds_read_b128 v[170:173], v141 offset:3072
	ds_read_b128 v[174:177], v141 offset:4096
	ds_read_b128 v[178:181], v141 offset:5120
	ds_read_b128 v[182:185], v141 offset:6144
	ds_read_b128 v[196:199], v141 offset:7168
	global_load_lds_dwordx4 v130, s[12:13]
	s_add_i32 m0, s61, 0xe000
	v_lshl_add_u64 v[142:143], s[12:13], 0, v[132:133]
	global_load_lds_dwordx4 v[142:143], off
	s_waitcnt lgkmcnt(8)
	s_barrier
	s_waitcnt lgkmcnt(0)
	v_mfma_f32_16x16x32_bf16 v[124:127], v[134:137], v[158:161], v[124:127]
	v_mfma_f32_16x16x32_bf16 v[120:123], v[150:153], v[158:161], v[120:123]
	v_mfma_f32_16x16x32_bf16 v[116:119], v[134:137], v[166:169], v[116:119]
	v_mfma_f32_16x16x32_bf16 v[108:111], v[150:153], v[166:169], v[108:111]
	v_mfma_f32_16x16x32_bf16 v[100:103], v[134:137], v[174:177], v[100:103]
	v_mfma_f32_16x16x32_bf16 v[92:95], v[150:153], v[174:177], v[92:95]
	v_mfma_f32_16x16x32_bf16 v[84:87], v[134:137], v[182:185], v[84:87]
	v_mfma_f32_16x16x32_bf16 v[76:79], v[150:153], v[182:185], v[76:79]
	v_mfma_f32_16x16x32_bf16 v[124:127], v[146:149], v[162:165], v[124:127]
	v_mfma_f32_16x16x32_bf16 v[120:123], v[154:157], v[162:165], v[120:123]
	v_mfma_f32_16x16x32_bf16 v[116:119], v[146:149], v[170:173], v[116:119]
	v_mfma_f32_16x16x32_bf16 v[108:111], v[154:157], v[170:173], v[108:111]
	v_mfma_f32_16x16x32_bf16 v[100:103], v[146:149], v[178:181], v[100:103]
	v_mfma_f32_16x16x32_bf16 v[92:95], v[154:157], v[178:181], v[92:95]
	v_mfma_f32_16x16x32_bf16 v[84:87], v[146:149], v[196:199], v[84:87]
	v_mfma_f32_16x16x32_bf16 v[76:79], v[154:157], v[196:199], v[76:79]
	s_barrier
	s_add_i32 s28, 0, 0x14000
	v_add_u32_e32 v142, s28, v139
	s_add_i32 s26, s26, s35
	ds_read_b128 v[200:203], v142
	ds_read_b128 v[204:207], v142 offset:1024
	ds_read_b128 v[214:217], v142 offset:2048
	ds_read_b128 v[218:221], v142 offset:3072
	v_lshl_add_u64 v[142:143], s[16:17], 0, v[144:145]
	s_mov_b32 m0, s26
	v_lshl_add_u64 v[186:187], s[16:17], 0, v[128:129]
	global_load_lds_dwordx4 v[142:143], off
	s_add_i32 m0, s26, 0x2000
	s_nop 0
	global_load_lds_dwordx4 v[186:187], off
	s_barrier
	s_waitcnt lgkmcnt(0)
	v_mfma_f32_16x16x32_bf16 v[112:115], v[200:203], v[158:161], v[112:115]
	v_mfma_f32_16x16x32_bf16 v[104:107], v[214:217], v[158:161], v[104:107]
	v_mfma_f32_16x16x32_bf16 v[96:99], v[200:203], v[166:169], v[96:99]
	v_mfma_f32_16x16x32_bf16 v[88:91], v[214:217], v[166:169], v[88:91]
	v_mfma_f32_16x16x32_bf16 v[80:83], v[200:203], v[174:177], v[80:83]
	v_mfma_f32_16x16x32_bf16 v[72:75], v[214:217], v[174:177], v[72:75]
	v_mfma_f32_16x16x32_bf16 v[68:71], v[200:203], v[182:185], v[68:71]
	v_mfma_f32_16x16x32_bf16 v[64:67], v[214:217], v[182:185], v[64:67]
	v_mfma_f32_16x16x32_bf16 v[112:115], v[204:207], v[162:165], v[112:115]
	v_mfma_f32_16x16x32_bf16 v[104:107], v[218:221], v[162:165], v[104:107]
	v_mfma_f32_16x16x32_bf16 v[96:99], v[204:207], v[170:173], v[96:99]
	v_mfma_f32_16x16x32_bf16 v[88:91], v[218:221], v[170:173], v[88:91]
	v_mfma_f32_16x16x32_bf16 v[80:83], v[204:207], v[178:181], v[80:83]
	v_mfma_f32_16x16x32_bf16 v[72:75], v[218:221], v[178:181], v[72:75]
	v_mfma_f32_16x16x32_bf16 v[68:71], v[204:207], v[196:199], v[68:71]
	v_mfma_f32_16x16x32_bf16 v[64:67], v[218:221], v[196:199], v[64:67]
	s_mov_b32 m0, s61
	v_lshl_add_u64 v[188:189], s[20:21], 0, v[144:145]
	s_barrier
	ds_read_b128 v[158:161], v141 offset:16384
	ds_read_b128 v[162:165], v141 offset:17408
	ds_read_b128 v[166:169], v141 offset:18432
	ds_read_b128 v[170:173], v141 offset:19456
	ds_read_b128 v[174:177], v141 offset:20480
	ds_read_b128 v[178:181], v141 offset:21504
	ds_read_b128 v[182:185], v141 offset:22528
	ds_read_b128 v[196:199], v141 offset:23552
	global_load_lds_dwordx4 v[188:189], off
	s_mov_b32 m0, s62
	v_lshl_add_u64 v[192:193], s[20:21], 0, v[128:129]
	global_load_lds_dwordx4 v[192:193], off
	s_barrier
	s_waitcnt lgkmcnt(0)
	v_mfma_f32_16x16x32_bf16 v[60:63], v[134:137], v[158:161], v[60:63]
	v_mfma_f32_16x16x32_bf16 v[56:59], v[150:153], v[158:161], v[56:59]
	v_mfma_f32_16x16x32_bf16 v[52:55], v[134:137], v[166:169], v[52:55]
	v_mfma_f32_16x16x32_bf16 v[44:47], v[150:153], v[166:169], v[44:47]
	v_mfma_f32_16x16x32_bf16 v[36:39], v[134:137], v[174:177], v[36:39]
	v_mfma_f32_16x16x32_bf16 v[28:31], v[150:153], v[174:177], v[28:31]
	v_mfma_f32_16x16x32_bf16 v[20:23], v[134:137], v[182:185], v[20:23]
	v_mfma_f32_16x16x32_bf16 v[12:15], v[150:153], v[182:185], v[12:15]
	v_mfma_f32_16x16x32_bf16 v[60:63], v[146:149], v[162:165], v[60:63]
	v_mfma_f32_16x16x32_bf16 v[56:59], v[154:157], v[162:165], v[56:59]
	v_mfma_f32_16x16x32_bf16 v[52:55], v[146:149], v[170:173], v[52:55]
	v_mfma_f32_16x16x32_bf16 v[44:47], v[154:157], v[170:173], v[44:47]
	v_mfma_f32_16x16x32_bf16 v[36:39], v[146:149], v[178:181], v[36:39]
	v_mfma_f32_16x16x32_bf16 v[28:31], v[154:157], v[178:181], v[28:31]
	v_mfma_f32_16x16x32_bf16 v[20:23], v[146:149], v[196:199], v[20:23]
	v_mfma_f32_16x16x32_bf16 v[12:15], v[154:157], v[196:199], v[12:15]
	s_barrier
; #define PG8_STAGE(bufoff, gbase, voff) do { _Pragma("unroll") for (int _i = 0; _i < 2; ++_i) \
;         __builtin_amdgcn_global_load_lds((const unsigned*)((const char*)(gbase) + (voff)[_i]), (LAS unsigned*)(lds + (bufoff) + ldsw + _i * 8192), 16, 0, 0); } while (0)
; #define PG8_LDA(dst, b, h) do { _Pragma("unroll") for (int m = 0; m < 4; ++m) _Pragma("unroll") for (int k = 0; k < 2; ++k) dst[m][k] = *(const LAS bf16x8*)(lds + PG8_SA(b, h) + aoff + m * 2048 + k * 1024); } while (0)
; #define PG8_LDB(dst, b, h) do { _Pragma("unroll") for (int n = 0; n < 2; ++n) _Pragma("unroll") for (int k = 0; k < 2; ++k) dst[n][k] = *(const LAS bf16x8*)(lds + PG8_SB(b, h) + boff + n * 2048 + k * 1024); } while (0)
; #define PG8_MMA(ai, bj, At, Bt) do { __builtin_amdgcn_s_setprio(1); _Pragma("unroll") for (int m = 0; m < 4; ++m) _Pragma("unroll") for (int n = 0; n < 2; ++n) _Pragma("unroll") for (int k = 0; k < 2; ++k) \
;         acc[ai][bj][m][n] = __builtin_amdgcn_mfma_f32_16x16x32_bf16(Bt[n][k], At[m][k], acc[ai][bj][m][n], 0, 0, 0); __builtin_amdgcn_s_setprio(0); } while (0)
; #define PG8_WAIT_V(n) asm volatile("s_waitcnt vmcnt(" #n ")" ::: "memory")
; #define PG8_WAIT_L(n) asm volatile("s_waitcnt lgkmcnt(" #n ")" ::: "memory")
; #define PG8_BAR __builtin_amdgcn_s_barrier()
; #define PG8_SCHED __builtin_amdgcn_sched_barrier(0)
; template <class Epi>
; __device__ __forceinline__ void gemm_phase(LAS unsigned char* lds, const Gemm g, const StaticOrder& S, const Epi& E) {
;     ...
;             PG8_STAGE(PG8_SB(0, 1), b2 + hB, voffB);
;             PG8_WAIT_V(6); PG8_BAR; PG8_MMA(1, 1, At, B1); PG8_BAR;
;             PG8_LDB(B0, 1, 0); PG8_SCHED; PG8_LDA(At, 1, 0); PG8_STAGE(PG8_SA(0, 1), a2 + hA, voffA);
;             PG8_WAIT_L(8); PG8_BAR; PG8_WAIT_L(0); PG8_MMA(0, 0, At, B0); PG8_BAR; PG8_SCHED;
;             PG8_LDB(B1, 1, 1); PG8_STAGE(PG8_SB(1, 0), b3, voffB);
;             PG8_BAR; PG8_WAIT_L(0); PG8_MMA(0, 1, At, B1); PG8_BAR;
;             PG8_LDA(At, 1, 1); PG8_STAGE(PG8_SA(1, 0), a3, voffA);
	s_add_u32 s26, s16, 0x40000
	s_addc_u32 s27, s17, 0
	s_add_i32 s28, s28, s35
	s_mov_b32 m0, s28
	s_nop 0
	global_load_lds_dwordx4 v144, s[26:27]
	s_add_i32 m0, s28, 0x2000
	s_nop 0
	global_load_lds_dwordx4 v128, s[26:27]
	s_waitcnt vmcnt(6)
	s_barrier
	v_mfma_f32_16x16x32_bf16 v[48:51], v[200:203], v[158:161], v[48:51]
	v_mfma_f32_16x16x32_bf16 v[40:43], v[214:217], v[158:161], v[40:43]
	v_mfma_f32_16x16x32_bf16 v[32:35], v[200:203], v[166:169], v[32:35]
	v_mfma_f32_16x16x32_bf16 v[24:27], v[214:217], v[166:169], v[24:27]
	v_mfma_f32_16x16x32_bf16 v[16:19], v[200:203], v[174:177], v[16:19]
	v_mfma_f32_16x16x32_bf16 v[8:11], v[214:217], v[174:177], v[8:11]
	v_mfma_f32_16x16x32_bf16 v[4:7], v[200:203], v[182:185], v[4:7]
	v_mfma_f32_16x16x32_bf16 v[0:3], v[214:217], v[182:185], v[0:3]
	v_mfma_f32_16x16x32_bf16 v[48:51], v[204:207], v[162:165], v[48:51]
	v_mfma_f32_16x16x32_bf16 v[40:43], v[218:221], v[162:165], v[40:43]
	v_mfma_f32_16x16x32_bf16 v[32:35], v[204:207], v[170:173], v[32:35]
	v_mfma_f32_16x16x32_bf16 v[24:27], v[218:221], v[170:173], v[24:27]
	v_mfma_f32_16x16x32_bf16 v[16:19], v[204:207], v[178:181], v[16:19]
	v_mfma_f32_16x16x32_bf16 v[8:11], v[218:221], v[178:181], v[8:11]
	v_mfma_f32_16x16x32_bf16 v[4:7], v[204:207], v[196:199], v[4:7]
	v_mfma_f32_16x16x32_bf16 v[0:3], v[218:221], v[196:199], v[0:3]
	s_add_i32 s26, 0, 0x18000
	v_add_u32_e32 v154, s26, v139
	s_barrier
	ds_read_b128 v[134:137], v154
	ds_read_b128 v[146:149], v154 offset:1024
	ds_read_b128 v[150:153], v154 offset:2048
	ds_read_b128 v[154:157], v154 offset:3072
	s_add_u32 s20, s20, 0x40000
	s_addc_u32 s21, s21, 0
	s_mov_b32 m0, s63
	ds_read_b128 v[158:161], v141 offset:32768
	ds_read_b128 v[162:165], v141 offset:33792
	ds_read_b128 v[166:169], v141 offset:34816
	ds_read_b128 v[170:173], v141 offset:35840
	ds_read_b128 v[174:177], v141 offset:36864
	ds_read_b128 v[178:181], v141 offset:37888
	ds_read_b128 v[182:185], v141 offset:38912
	global_load_lds_dwordx4 v144, s[20:21]
	s_mov_b32 m0, s64
	ds_read_b128 v[196:199], v141 offset:39936
	global_load_lds_dwordx4 v128, s[20:21]
	s_waitcnt lgkmcnt(8)
	s_barrier
	s_waitcnt lgkmcnt(0)
	v_mfma_f32_16x16x32_bf16 v[124:127], v[134:137], v[158:161], v[124:127]
	v_mfma_f32_16x16x32_bf16 v[120:123], v[150:153], v[158:161], v[120:123]
	v_mfma_f32_16x16x32_bf16 v[116:119], v[134:137], v[166:169], v[116:119]
	v_mfma_f32_16x16x32_bf16 v[108:111], v[150:153], v[166:169], v[108:111]
	v_mfma_f32_16x16x32_bf16 v[100:103], v[134:137], v[174:177], v[100:103]
	v_mfma_f32_16x16x32_bf16 v[92:95], v[150:153], v[174:177], v[92:95]
	v_mfma_f32_16x16x32_bf16 v[84:87], v[134:137], v[182:185], v[84:87]
	v_mfma_f32_16x16x32_bf16 v[76:79], v[150:153], v[182:185], v[76:79]
	v_mfma_f32_16x16x32_bf16 v[124:127], v[146:149], v[162:165], v[124:127]
	v_mfma_f32_16x16x32_bf16 v[120:123], v[154:157], v[162:165], v[120:123]
	v_mfma_f32_16x16x32_bf16 v[116:119], v[146:149], v[170:173], v[116:119]
	v_mfma_f32_16x16x32_bf16 v[108:111], v[154:157], v[170:173], v[108:111]
	v_mfma_f32_16x16x32_bf16 v[100:103], v[146:149], v[178:181], v[100:103]
	v_mfma_f32_16x16x32_bf16 v[92:95], v[154:157], v[178:181], v[92:95]
	v_mfma_f32_16x16x32_bf16 v[84:87], v[146:149], v[196:199], v[84:87]
	v_mfma_f32_16x16x32_bf16 v[76:79], v[154:157], v[196:199], v[76:79]
	s_barrier
	s_add_i32 s20, 0, 0x1c000
	s_add_i32 s21, s26, s35
	v_add_u32_e32 v190, s20, v139
	v_lshl_add_u64 v[142:143], v[142:143], 0, s[88:89]
	s_mov_b32 m0, s21
	ds_read_b128 v[200:203], v190
	ds_read_b128 v[204:207], v190 offset:1024
	ds_read_b128 v[214:217], v190 offset:2048
	ds_read_b128 v[218:221], v190 offset:3072
	global_load_lds_dwordx4 v[142:143], off
	s_add_i32 m0, s21, 0x2000
	v_lshl_add_u64 v[142:143], v[186:187], 0, s[88:89]
	global_load_lds_dwordx4 v[142:143], off
	s_barrier
	s_waitcnt lgkmcnt(0)
	v_mfma_f32_16x16x32_bf16 v[112:115], v[200:203], v[158:161], v[112:115]
	v_mfma_f32_16x16x32_bf16 v[104:107], v[214:217], v[158:161], v[104:107]
	v_mfma_f32_16x16x32_bf16 v[96:99], v[200:203], v[166:169], v[96:99]
	v_mfma_f32_16x16x32_bf16 v[88:91], v[214:217], v[166:169], v[88:91]
	v_mfma_f32_16x16x32_bf16 v[80:83], v[200:203], v[174:177], v[80:83]
	v_mfma_f32_16x16x32_bf16 v[72:75], v[214:217], v[174:177], v[72:75]
	v_mfma_f32_16x16x32_bf16 v[68:71], v[200:203], v[182:185], v[68:71]
	v_mfma_f32_16x16x32_bf16 v[64:67], v[214:217], v[182:185], v[64:67]
	v_mfma_f32_16x16x32_bf16 v[112:115], v[204:207], v[162:165], v[112:115]
	v_mfma_f32_16x16x32_bf16 v[104:107], v[218:221], v[162:165], v[104:107]
	v_mfma_f32_16x16x32_bf16 v[96:99], v[204:207], v[170:173], v[96:99]
	v_mfma_f32_16x16x32_bf16 v[88:91], v[218:221], v[170:173], v[88:91]
	v_mfma_f32_16x16x32_bf16 v[80:83], v[204:207], v[178:181], v[80:83]
	v_mfma_f32_16x16x32_bf16 v[72:75], v[218:221], v[178:181], v[72:75]
	v_mfma_f32_16x16x32_bf16 v[68:71], v[204:207], v[196:199], v[68:71]
	v_mfma_f32_16x16x32_bf16 v[64:67], v[218:221], v[196:199], v[64:67]
	s_mov_b32 m0, s65
	v_lshl_add_u64 v[142:143], v[188:189], 0, s[88:89]
	s_barrier
	ds_read_b128 v[158:161], v141 offset:49152
	ds_read_b128 v[162:165], v141 offset:50176
	ds_read_b128 v[166:169], v141 offset:51200
	ds_read_b128 v[170:173], v141 offset:52224
	ds_read_b128 v[174:177], v141 offset:53248
	ds_read_b128 v[178:181], v141 offset:54272
	ds_read_b128 v[182:185], v141 offset:55296
	ds_read_b128 v[196:199], v141 offset:56320
	global_load_lds_dwordx4 v[142:143], off
	s_mov_b32 m0, s66
	v_lshl_add_u64 v[142:143], v[192:193], 0, s[88:89]
	global_load_lds_dwordx4 v[142:143], off
	s_barrier
; #define PG8_STAGE(bufoff, gbase, voff) do { _Pragma("unroll") for (int _i = 0; _i < 2; ++_i) \
;         __builtin_amdgcn_global_load_lds((const unsigned*)((const char*)(gbase) + (voff)[_i]), (LAS unsigned*)(lds + (bufoff) + ldsw + _i * 8192), 16, 0, 0); } while (0)
; #define PG8_MMA(ai, bj, At, Bt) do { __builtin_amdgcn_s_setprio(1); _Pragma("unroll") for (int m = 0; m < 4; ++m) _Pragma("unroll") for (int n = 0; n < 2; ++n) _Pragma("unroll") for (int k = 0; k < 2; ++k) \
;         acc[ai][bj][m][n] = __builtin_amdgcn_mfma_f32_16x16x32_bf16(Bt[n][k], At[m][k], acc[ai][bj][m][n], 0, 0, 0); __builtin_amdgcn_s_setprio(0); } while (0)
; #define PG8_WAIT_V(n) asm volatile("s_waitcnt vmcnt(" #n ")" ::: "memory")
; #define PG8_WAIT_L(n) asm volatile("s_waitcnt lgkmcnt(" #n ")" ::: "memory")
; #define PG8_BAR __builtin_amdgcn_s_barrier()
; #define PG8_SCHED __builtin_amdgcn_sched_barrier(0)
; template <class Epi>
; __device__ __forceinline__ void gemm_phase(LAS unsigned char* lds, const Gemm g, const StaticOrder& S, const Epi& E) {
;     ...
;             PG8_BAR; PG8_WAIT_L(0); PG8_MMA(1, 0, At, B0); PG8_BAR; PG8_SCHED;
;             PG8_STAGE(PG8_SB(1, 1), b3 + hB, voffB);
;             PG8_WAIT_V(6); PG8_BAR; PG8_MMA(1, 1, At, B1); PG8_BAR;
	s_waitcnt lgkmcnt(0)
	v_mfma_f32_16x16x32_bf16 v[60:63], v[134:137], v[158:161], v[60:63]
	v_mfma_f32_16x16x32_bf16 v[56:59], v[150:153], v[158:161], v[56:59]
	v_mfma_f32_16x16x32_bf16 v[52:55], v[134:137], v[166:169], v[52:55]
	v_mfma_f32_16x16x32_bf16 v[44:47], v[150:153], v[166:169], v[44:47]
	v_mfma_f32_16x16x32_bf16 v[36:39], v[134:137], v[174:177], v[36:39]
	v_mfma_f32_16x16x32_bf16 v[28:31], v[150:153], v[174:177], v[28:31]
	v_mfma_f32_16x16x32_bf16 v[20:23], v[134:137], v[182:185], v[20:23]
	v_mfma_f32_16x16x32_bf16 v[12:15], v[150:153], v[182:185], v[12:15]
	v_mfma_f32_16x16x32_bf16 v[60:63], v[146:149], v[162:165], v[60:63]
	v_mfma_f32_16x16x32_bf16 v[56:59], v[154:157], v[162:165], v[56:59]
	v_mfma_f32_16x16x32_bf16 v[52:55], v[146:149], v[170:173], v[52:55]
	v_mfma_f32_16x16x32_bf16 v[44:47], v[154:157], v[170:173], v[44:47]
	v_mfma_f32_16x16x32_bf16 v[36:39], v[146:149], v[178:181], v[36:39]
	v_mfma_f32_16x16x32_bf16 v[28:31], v[154:157], v[178:181], v[28:31]
	v_mfma_f32_16x16x32_bf16 v[20:23], v[146:149], v[196:199], v[20:23]
	v_mfma_f32_16x16x32_bf16 v[12:15], v[154:157], v[196:199], v[12:15]
	s_barrier
	s_add_u32 s16, s16, 0x40080
	s_addc_u32 s17, s17, 0
	s_add_i32 s20, s20, s35
	s_mov_b32 m0, s20
	s_nop 0
	global_load_lds_dwordx4 v144, s[16:17]
	s_add_i32 m0, s20, 0x2000
	s_nop 0
	global_load_lds_dwordx4 v128, s[16:17]
	s_waitcnt vmcnt(6)
	s_barrier
	v_mfma_f32_16x16x32_bf16 v[48:51], v[200:203], v[158:161], v[48:51]
	v_mfma_f32_16x16x32_bf16 v[40:43], v[214:217], v[158:161], v[40:43]
	v_mfma_f32_16x16x32_bf16 v[32:35], v[200:203], v[166:169], v[32:35]
	v_mfma_f32_16x16x32_bf16 v[24:27], v[214:217], v[166:169], v[24:27]
	v_mfma_f32_16x16x32_bf16 v[16:19], v[200:203], v[174:177], v[16:19]
	v_mfma_f32_16x16x32_bf16 v[8:11], v[214:217], v[174:177], v[8:11]
	v_mfma_f32_16x16x32_bf16 v[4:7], v[200:203], v[182:185], v[4:7]
	v_mfma_f32_16x16x32_bf16 v[0:3], v[214:217], v[182:185], v[0:3]
	v_mfma_f32_16x16x32_bf16 v[48:51], v[204:207], v[162:165], v[48:51]
	v_mfma_f32_16x16x32_bf16 v[40:43], v[218:221], v[162:165], v[40:43]
	v_mfma_f32_16x16x32_bf16 v[32:35], v[204:207], v[170:173], v[32:35]
	v_mfma_f32_16x16x32_bf16 v[24:27], v[218:221], v[170:173], v[24:27]
	v_mfma_f32_16x16x32_bf16 v[16:19], v[204:207], v[178:181], v[16:19]
	v_mfma_f32_16x16x32_bf16 v[8:11], v[218:221], v[178:181], v[8:11]
	v_mfma_f32_16x16x32_bf16 v[4:7], v[204:207], v[196:199], v[4:7]
	v_mfma_f32_16x16x32_bf16 v[0:3], v[218:221], v[196:199], v[0:3]
	s_add_i32 s77, s77, 2
	s_add_u32 s12, s12, 0x100
	s_addc_u32 s13, s13, 0
	s_add_u32 s25, s25, 0x100
	s_addc_u32 s76, s76, 0
	s_cmp_gt_u32 s77, 13
	s_barrier
	s_cbranch_scc0 .LBB0_1079
; __device__ __forceinline__ unsigned pk2(float lo, float hi) { unsigned r; asm("v_cvt_pk_bf16_f32 %0, %1, %2" : "=v"(r) : "v"(lo), "v"(hi)); return r; }
; #define PG8_WAIT_V(n) asm volatile("s_waitcnt vmcnt(" #n ")" ::: "memory")
; #define PG8_BAR __builtin_amdgcn_s_barrier()
; template <class Epi>
; __device__ __forceinline__ void gemm_phase(LAS unsigned char* lds, const Gemm g, const StaticOrder& S, const Epi& E) {
;     ...
;         if (!has_next) break;
; #pragma unroll
;         for (int a = 0; a < 2; ++a)
; #pragma unroll
;             for (int b = 0; b < 2; ++b)
; #pragma unroll
;                 for (int m = 0; m < 4; ++m)
; #pragma unroll
;                     for (int n = 0; n < 2; ++n) acc[a][b][m][n] = (f32x4){0.f, 0.f, 0.f, 0.f};
;         cur = nxt; cA = nA; cB = nB; ++ui;
;     }
;     PG8_WAIT_V(0);
;     if (wr == 0) PG8_BAR;
;     PG8_BAR;
;     __device__ __forceinline__ void operator()(const f32x4 (&acc)[2][2][4][2], const Unit& u, int wr, int wc, int fr, int fq) const {
;     ...
;         const int row_t = rmap == 1 ? odd_phys_row0(u.pm, grp) : (rmap == 2 ? odd_phys_row0(u.pm % (BG * TPB), u.pm / (BG * TPB)) : u.pm * BM);
;         int c = col_t + 64 * wc + 16 * fq;
;         if (mode == 2) c = (c >> 6) * 96 + (c & 63);
; #pragma unroll
;         for (int ai = 0; ai < 2; ++ai)
; #pragma unroll
;             for (int m = 0; m < 4; ++m) {
;                 const int row = row_t + ai * HALF + wr * 64 + m * 16 + fr;
;                 bf16_t* rp = O + (size_t)row * ldc + c;
; #pragma unroll
;                 for (int bj = 0; bj < 2; ++bj) {
;                     const f32x4 v0 = acc[ai][bj][m][0], v1 = acc[ai][bj][m][1];
;                     u32x4 o; o.x = pk2(v0[0], v0[1]); o.y = pk2(v0[2], v0[3]); o.z = pk2(v1[0], v1[1]); o.w = pk2(v1[2], v1[3]);
;                     *(u32x4*)(rp + 8 * bj) = o;
;                 }
;             }
	v_lshl_or_b32 v136, s15, 8, v140
	v_lshl_add_u32 v146, s70, 8, v138
	v_ashrrev_i32_e32 v137, 31, v136
	v_mov_b64_e32 v[134:135], s[4:5]
	s_movk_i32 s7, 0x1400
	v_cvt_pk_bf16_f32 v68, v68, v69
	v_cvt_pk_bf16_f32 v69, v70, v71
	v_cvt_pk_bf16_f32 v70, v64, v65
	v_add_u32_e32 v64, 0x80, v146
	v_mad_i64_i32 v[142:143], s[12:13], v146, s7, v[134:135]
	v_lshlrev_b64 v[136:137], 1, v[136:137]
	v_cvt_pk_bf16_f32 v112, v112, v113
	v_cvt_pk_bf16_f32 v113, v114, v115
	v_cvt_pk_bf16_f32 v114, v104, v105
	v_or_b32_e32 v104, 16, v146
	v_mad_i64_i32 v[64:65], s[12:13], v64, s7, v[134:135]
	v_cvt_pk_bf16_f32 v48, v48, v49
	v_cvt_pk_bf16_f32 v49, v50, v51
	v_cvt_pk_bf16_f32 v50, v40, v41
	v_add_u32_e32 v40, 0x90, v146
	v_lshl_add_u64 v[142:143], v[142:143], 0, v[136:137]
	v_mad_i64_i32 v[104:105], s[12:13], v104, s7, v[134:135]
	v_cvt_pk_bf16_f32 v96, v96, v97
	v_cvt_pk_bf16_f32 v97, v98, v99
	v_cvt_pk_bf16_f32 v98, v88, v89
	v_or_b32_e32 v88, 32, v146
	v_lshl_add_u64 v[64:65], v[64:65], 0, v[136:137]
	v_mad_i64_i32 v[40:41], s[12:13], v40, s7, v[134:135]
	v_cvt_pk_bf16_f32 v32, v32, v33
	v_cvt_pk_bf16_f32 v33, v34, v35
	v_cvt_pk_bf16_f32 v34, v24, v25
	v_add_u32_e32 v24, 0xa0, v146
	v_cvt_pk_bf16_f32 v115, v106, v107
	global_store_dwordx4 v[142:143], v[112:115], off offset:16
	v_mad_i64_i32 v[88:89], s[12:13], v88, s7, v[134:135]
	s_nop 0
	v_lshl_add_u64 v[112:113], v[104:105], 0, v[136:137]
	v_cvt_pk_bf16_f32 v80, v80, v81
	v_cvt_pk_bf16_f32 v81, v82, v83
	v_cvt_pk_bf16_f32 v82, v72, v73
	v_or_b32_e32 v72, 48, v146
	v_cvt_pk_bf16_f32 v51, v42, v43
	global_store_dwordx4 v[64:65], v[48:51], off offset:16
	v_mad_i64_i32 v[24:25], s[12:13], v24, s7, v[134:135]
	s_nop 0
	v_lshl_add_u64 v[48:49], v[40:41], 0, v[136:137]
	v_cvt_pk_bf16_f32 v16, v16, v17
	v_cvt_pk_bf16_f32 v17, v18, v19
	v_cvt_pk_bf16_f32 v18, v8, v9
	v_add_u32_e32 v8, 0xb0, v146
	v_cvt_pk_bf16_f32 v99, v90, v91
	global_store_dwordx4 v[112:113], v[96:99], off offset:16
	v_mad_i64_i32 v[72:73], s[12:13], v72, s7, v[134:135]
	s_nop 0
	v_lshl_add_u64 v[96:97], v[88:89], 0, v[136:137]
	v_cvt_pk_bf16_f32 v35, v26, v27
	global_store_dwordx4 v[48:49], v[32:35], off offset:16
	v_mad_i64_i32 v[8:9], s[12:13], v8, s7, v[134:135]
	s_nop 0
	v_lshl_add_u64 v[32:33], v[24:25], 0, v[136:137]
	v_cvt_pk_bf16_f32 v83, v74, v75
	global_store_dwordx4 v[96:97], v[80:83], off offset:16
	v_cvt_pk_bf16_f32 v19, v10, v11
	global_store_dwordx4 v[32:33], v[16:19], off offset:16
	s_and_b64 vcc, exec, s[0:1]
	v_lshl_add_u64 v[80:81], v[72:73], 0, v[136:137]
	v_lshl_add_u64 v[16:17], v[8:9], 0, v[136:137]
	s_mov_b32 s15, s6
	s_mov_b32 s70, s69
	s_mov_b64 s[16:17], s[10:11]
	s_mov_b64 s[12:13], s[8:9]
	v_cvt_pk_bf16_f32 v124, v124, v125
	v_cvt_pk_bf16_f32 v125, v126, v127
	v_cvt_pk_bf16_f32 v126, v120, v121
	v_cvt_pk_bf16_f32 v127, v122, v123
	global_store_dwordx4 v[142:143], v[124:127], off
	v_cvt_pk_bf16_f32 v104, v116, v117
	v_cvt_pk_bf16_f32 v105, v118, v119
	v_cvt_pk_bf16_f32 v106, v108, v109
	v_cvt_pk_bf16_f32 v107, v110, v111
	global_store_dwordx4 v[112:113], v[104:107], off
	v_cvt_pk_bf16_f32 v88, v100, v101
	v_cvt_pk_bf16_f32 v89, v102, v103
	v_cvt_pk_bf16_f32 v90, v92, v93
	v_cvt_pk_bf16_f32 v91, v94, v95
	global_store_dwordx4 v[96:97], v[88:91], off
	v_cvt_pk_bf16_f32 v72, v84, v85
	v_cvt_pk_bf16_f32 v73, v86, v87
	v_cvt_pk_bf16_f32 v74, v76, v77
	v_cvt_pk_bf16_f32 v75, v78, v79
	global_store_dwordx4 v[80:81], v[72:75], off
	v_cvt_pk_bf16_f32 v71, v66, v67
	global_store_dwordx4 v[80:81], v[68:71], off offset:16
	v_cvt_pk_bf16_f32 v60, v60, v61
	v_cvt_pk_bf16_f32 v61, v62, v63
	v_cvt_pk_bf16_f32 v62, v56, v57
	v_cvt_pk_bf16_f32 v63, v58, v59
	global_store_dwordx4 v[64:65], v[60:63], off
	v_cvt_pk_bf16_f32 v40, v52, v53
	v_cvt_pk_bf16_f32 v41, v54, v55
	v_cvt_pk_bf16_f32 v42, v44, v45
	v_cvt_pk_bf16_f32 v43, v46, v47
	global_store_dwordx4 v[48:49], v[40:43], off
	v_cvt_pk_bf16_f32 v24, v36, v37
	v_cvt_pk_bf16_f32 v25, v38, v39
	v_cvt_pk_bf16_f32 v26, v28, v29
	v_cvt_pk_bf16_f32 v27, v30, v31
	global_store_dwordx4 v[32:33], v[24:27], off
	v_cvt_pk_bf16_f32 v8, v20, v21
	v_cvt_pk_bf16_f32 v9, v22, v23
	v_cvt_pk_bf16_f32 v10, v12, v13
	v_cvt_pk_bf16_f32 v11, v14, v15
	global_store_dwordx4 v[16:17], v[8:11], off
	v_cvt_pk_bf16_f32 v4, v4, v5
	v_cvt_pk_bf16_f32 v5, v6, v7
	v_cvt_pk_bf16_f32 v6, v0, v1
	v_cvt_pk_bf16_f32 v7, v2, v3
	global_store_dwordx4 v[16:17], v[4:7], off offset:16
	s_cbranch_vccz .LBB0_1076
	s_waitcnt vmcnt(0)
	s_cmpk_gt_u32 s3, 0xff
	s_cbranch_scc1 .LBB0_1083
	s_barrier

; #define PG8_STAGE(bufoff, gbase, voff) do { _Pragma("unroll") for (int _i = 0; _i < 2; ++_i) \
;         __builtin_amdgcn_global_load_lds((const unsigned*)((const char*)(gbase) + (voff)[_i]), (LAS unsigned*)(lds + (bufoff) + ldsw + _i * 8192), 16, 0, 0); } while (0)
; #define PG8_LDA(dst, b, h) do { _Pragma("unroll") for (int m = 0; m < 4; ++m) _Pragma("unroll") for (int k = 0; k < 2; ++k) dst[m][k] = *(const LAS bf16x8*)(lds + PG8_SA(b, h) + aoff + m * 2048 + k * 1024); } while (0)
; #define PG8_LDB(dst, b, h) do { _Pragma("unroll") for (int n = 0; n < 2; ++n) _Pragma("unroll") for (int k = 0; k < 2; ++k) dst[n][k] = *(const LAS bf16x8*)(lds + PG8_SB(b, h) + boff + n * 2048 + k * 1024); } while (0)
; #define PG8_MMA(ai, bj, At, Bt) do { __builtin_amdgcn_s_setprio(1); _Pragma("unroll") for (int m = 0; m < 4; ++m) _Pragma("unroll") for (int n = 0; n < 2; ++n) _Pragma("unroll") for (int k = 0; k < 2; ++k) \
;         acc[ai][bj][m][n] = __builtin_amdgcn_mfma_f32_16x16x32_bf16(Bt[n][k], At[m][k], acc[ai][bj][m][n], 0, 0, 0); __builtin_amdgcn_s_setprio(0); } while (0)
; #define PG8_WAIT_L(n) asm volatile("s_waitcnt lgkmcnt(" #n ")" ::: "memory")
; #define PG8_BAR __builtin_amdgcn_s_barrier()
; #define PG8_SCHED __builtin_amdgcn_sched_barrier(0)
; template <class Epi>
; __device__ __forceinline__ void gemm_phase(LAS unsigned char* lds, const Gemm g, const StaticOrder& S, const Epi& E) {
;     ...
;             const bool last = (t == nt - 2);
;             const char* a1 = cA + (size_t)(t + 1) * kstep;
;             const char* a2 = last ? nA : cA + (size_t)(t + 2) * kstep; const char* b2 = last ? nB : cB + (size_t)(t + 2) * kstep;
;             const char* a3 = a2 + kstep; const char* b3 = b2 + kstep;
;             PG8_LDB(B0, 0, 0); PG8_SCHED; PG8_LDA(At, 0, 0); PG8_STAGE(PG8_SA(1, 1), a1 + hA, voffA);
;             PG8_WAIT_L(8); PG8_BAR; PG8_WAIT_L(0); PG8_MMA(0, 0, At, B0); PG8_BAR; PG8_SCHED;
;             PG8_LDB(B1, 0, 1); PG8_STAGE(PG8_SB(0, 0), b2, voffB);
;             PG8_BAR; PG8_WAIT_L(0); PG8_MMA(0, 1, At, B1); PG8_BAR;
;             PG8_LDA(At, 0, 1); PG8_STAGE(PG8_SA(0, 0), a2, voffA);
;             PG8_BAR; PG8_WAIT_L(0); PG8_MMA(1, 0, At, B0); PG8_BAR; PG8_SCHED;
.LBB0_1270:
	s_add_u32 s16, s12, 0xfffc0080
	s_addc_u32 s17, s13, -1
	s_add_i32 s26, 0, 0x10000
	v_add_u32_e32 v142, s26, v139
	ds_read_b128 v[134:137], v142
	ds_read_b128 v[146:149], v142 offset:1024
	ds_read_b128 v[150:153], v142 offset:2048
	ds_read_b128 v[154:157], v142 offset:3072
	s_cmp_eq_u32 s77, 12
	s_cselect_b32 s21, s71, s17
	s_cselect_b32 s20, s72, s16
	s_cselect_b32 s17, s7, s76
	s_cselect_b32 s16, s24, s25
	s_add_i32 m0, s61, 0xc000
	ds_read_b128 v[158:161], v141
	ds_read_b128 v[162:165], v141 offset:1024
	ds_read_b128 v[166:169], v141 offset:2048
	ds_read_b128 v[170:173], v141 offset:3072
	ds_read_b128 v[174:177], v141 offset:4096
	ds_read_b128 v[178:181], v141 offset:5120
	ds_read_b128 v[182:185], v141 offset:6144
	ds_read_b128 v[196:199], v141 offset:7168
	global_load_lds_dwordx4 v130, s[12:13]
	s_add_i32 m0, s61, 0xe000
	v_lshl_add_u64 v[142:143], s[12:13], 0, v[132:133]
	global_load_lds_dwordx4 v[142:143], off
	s_waitcnt lgkmcnt(8)
	s_barrier
	s_waitcnt lgkmcnt(0)
	v_mfma_f32_16x16x32_bf16 v[124:127], v[134:137], v[158:161], v[124:127]
	v_mfma_f32_16x16x32_bf16 v[120:123], v[150:153], v[158:161], v[120:123]
	v_mfma_f32_16x16x32_bf16 v[116:119], v[134:137], v[166:169], v[116:119]
	v_mfma_f32_16x16x32_bf16 v[108:111], v[150:153], v[166:169], v[108:111]
	v_mfma_f32_16x16x32_bf16 v[100:103], v[134:137], v[174:177], v[100:103]
	v_mfma_f32_16x16x32_bf16 v[92:95], v[150:153], v[174:177], v[92:95]
	v_mfma_f32_16x16x32_bf16 v[84:87], v[134:137], v[182:185], v[84:87]
	v_mfma_f32_16x16x32_bf16 v[76:79], v[150:153], v[182:185], v[76:79]
	v_mfma_f32_16x16x32_bf16 v[124:127], v[146:149], v[162:165], v[124:127]
	v_mfma_f32_16x16x32_bf16 v[120:123], v[154:157], v[162:165], v[120:123]
	v_mfma_f32_16x16x32_bf16 v[116:119], v[146:149], v[170:173], v[116:119]
	v_mfma_f32_16x16x32_bf16 v[108:111], v[154:157], v[170:173], v[108:111]
	v_mfma_f32_16x16x32_bf16 v[100:103], v[146:149], v[178:181], v[100:103]
	v_mfma_f32_16x16x32_bf16 v[92:95], v[154:157], v[178:181], v[92:95]
	v_mfma_f32_16x16x32_bf16 v[84:87], v[146:149], v[196:199], v[84:87]
	v_mfma_f32_16x16x32_bf16 v[76:79], v[154:157], v[196:199], v[76:79]
	s_barrier
	s_add_i32 s28, 0, 0x14000
	v_add_u32_e32 v142, s28, v139
	s_add_i32 s26, s26, s35
	ds_read_b128 v[200:203], v142
	ds_read_b128 v[204:207], v142 offset:1024
	ds_read_b128 v[214:217], v142 offset:2048
	ds_read_b128 v[218:221], v142 offset:3072
	v_lshl_add_u64 v[142:143], s[16:17], 0, v[144:145]
	s_mov_b32 m0, s26
	v_lshl_add_u64 v[186:187], s[16:17], 0, v[128:129]
	global_load_lds_dwordx4 v[142:143], off
	s_add_i32 m0, s26, 0x2000
	s_nop 0
	global_load_lds_dwordx4 v[186:187], off
	s_barrier
	s_waitcnt lgkmcnt(0)
	v_mfma_f32_16x16x32_bf16 v[112:115], v[200:203], v[158:161], v[112:115]
	v_mfma_f32_16x16x32_bf16 v[104:107], v[214:217], v[158:161], v[104:107]
	v_mfma_f32_16x16x32_bf16 v[96:99], v[200:203], v[166:169], v[96:99]
	v_mfma_f32_16x16x32_bf16 v[88:91], v[214:217], v[166:169], v[88:91]
	v_mfma_f32_16x16x32_bf16 v[80:83], v[200:203], v[174:177], v[80:83]
	v_mfma_f32_16x16x32_bf16 v[72:75], v[214:217], v[174:177], v[72:75]
	v_mfma_f32_16x16x32_bf16 v[68:71], v[200:203], v[182:185], v[68:71]
	v_mfma_f32_16x16x32_bf16 v[64:67], v[214:217], v[182:185], v[64:67]
	v_mfma_f32_16x16x32_bf16 v[112:115], v[204:207], v[162:165], v[112:115]
	v_mfma_f32_16x16x32_bf16 v[104:107], v[218:221], v[162:165], v[104:107]
	v_mfma_f32_16x16x32_bf16 v[96:99], v[204:207], v[170:173], v[96:99]
	v_mfma_f32_16x16x32_bf16 v[88:91], v[218:221], v[170:173], v[88:91]
	v_mfma_f32_16x16x32_bf16 v[80:83], v[204:207], v[178:181], v[80:83]
	v_mfma_f32_16x16x32_bf16 v[72:75], v[218:221], v[178:181], v[72:75]
	v_mfma_f32_16x16x32_bf16 v[68:71], v[204:207], v[196:199], v[68:71]
	v_mfma_f32_16x16x32_bf16 v[64:67], v[218:221], v[196:199], v[64:67]
	s_mov_b32 m0, s61
	v_lshl_add_u64 v[188:189], s[20:21], 0, v[144:145]
	s_barrier
	ds_read_b128 v[158:161], v141 offset:16384
	ds_read_b128 v[162:165], v141 offset:17408
	ds_read_b128 v[166:169], v141 offset:18432
	ds_read_b128 v[170:173], v141 offset:19456
	ds_read_b128 v[174:177], v141 offset:20480
	ds_read_b128 v[178:181], v141 offset:21504
	ds_read_b128 v[182:185], v141 offset:22528
	ds_read_b128 v[196:199], v141 offset:23552
	global_load_lds_dwordx4 v[188:189], off
	s_mov_b32 m0, s62
	v_lshl_add_u64 v[192:193], s[20:21], 0, v[128:129]
	global_load_lds_dwordx4 v[192:193], off
	s_barrier
	s_waitcnt lgkmcnt(0)
	v_mfma_f32_16x16x32_bf16 v[60:63], v[134:137], v[158:161], v[60:63]
	v_mfma_f32_16x16x32_bf16 v[56:59], v[150:153], v[158:161], v[56:59]
	v_mfma_f32_16x16x32_bf16 v[52:55], v[134:137], v[166:169], v[52:55]
	v_mfma_f32_16x16x32_bf16 v[44:47], v[150:153], v[166:169], v[44:47]
	v_mfma_f32_16x16x32_bf16 v[36:39], v[134:137], v[174:177], v[36:39]
	v_mfma_f32_16x16x32_bf16 v[28:31], v[150:153], v[174:177], v[28:31]
	v_mfma_f32_16x16x32_bf16 v[20:23], v[134:137], v[182:185], v[20:23]
	v_mfma_f32_16x16x32_bf16 v[12:15], v[150:153], v[182:185], v[12:15]
	v_mfma_f32_16x16x32_bf16 v[60:63], v[146:149], v[162:165], v[60:63]
	v_mfma_f32_16x16x32_bf16 v[56:59], v[154:157], v[162:165], v[56:59]
	v_mfma_f32_16x16x32_bf16 v[52:55], v[146:149], v[170:173], v[52:55]
	v_mfma_f32_16x16x32_bf16 v[44:47], v[154:157], v[170:173], v[44:47]
	v_mfma_f32_16x16x32_bf16 v[36:39], v[146:149], v[178:181], v[36:39]
	v_mfma_f32_16x16x32_bf16 v[28:31], v[154:157], v[178:181], v[28:31]
	v_mfma_f32_16x16x32_bf16 v[20:23], v[146:149], v[196:199], v[20:23]
	v_mfma_f32_16x16x32_bf16 v[12:15], v[154:157], v[196:199], v[12:15]
	s_barrier
; #define PG8_STAGE(bufoff, gbase, voff) do { _Pragma("unroll") for (int _i = 0; _i < 2; ++_i) \
;         __builtin_amdgcn_global_load_lds((const unsigned*)((const char*)(gbase) + (voff)[_i]), (LAS unsigned*)(lds + (bufoff) + ldsw + _i * 8192), 16, 0, 0); } while (0)
; #define PG8_LDA(dst, b, h) do { _Pragma("unroll") for (int m = 0; m < 4; ++m) _Pragma("unroll") for (int k = 0; k < 2; ++k) dst[m][k] = *(const LAS bf16x8*)(lds + PG8_SA(b, h) + aoff + m * 2048 + k * 1024); } while (0)
; #define PG8_LDB(dst, b, h) do { _Pragma("unroll") for (int n = 0; n < 2; ++n) _Pragma("unroll") for (int k = 0; k < 2; ++k) dst[n][k] = *(const LAS bf16x8*)(lds + PG8_SB(b, h) + boff + n * 2048 + k * 1024); } while (0)
; #define PG8_MMA(ai, bj, At, Bt) do { __builtin_amdgcn_s_setprio(1); _Pragma("unroll") for (int m = 0; m < 4; ++m) _Pragma("unroll") for (int n = 0; n < 2; ++n) _Pragma("unroll") for (int k = 0; k < 2; ++k) \
;         acc[ai][bj][m][n] = __builtin_amdgcn_mfma_f32_16x16x32_bf16(Bt[n][k], At[m][k], acc[ai][bj][m][n], 0, 0, 0); __builtin_amdgcn_s_setprio(0); } while (0)
; #define PG8_WAIT_V(n) asm volatile("s_waitcnt vmcnt(" #n ")" ::: "memory")
; #define PG8_WAIT_L(n) asm volatile("s_waitcnt lgkmcnt(" #n ")" ::: "memory")
; #define PG8_BAR __builtin_amdgcn_s_barrier()
; #define PG8_SCHED __builtin_amdgcn_sched_barrier(0)
; template <class Epi>
; __device__ __forceinline__ void gemm_phase(LAS unsigned char* lds, const Gemm g, const StaticOrder& S, const Epi& E) {
;     ...
;             PG8_STAGE(PG8_SB(0, 1), b2 + hB, voffB);
;             PG8_WAIT_V(6); PG8_BAR; PG8_MMA(1, 1, At, B1); PG8_BAR;
;             PG8_LDB(B0, 1, 0); PG8_SCHED; PG8_LDA(At, 1, 0); PG8_STAGE(PG8_SA(0, 1), a2 + hA, voffA);
;             PG8_WAIT_L(8); PG8_BAR; PG8_WAIT_L(0); PG8_MMA(0, 0, At, B0); PG8_BAR; PG8_SCHED;
;             PG8_LDB(B1, 1, 1); PG8_STAGE(PG8_SB(1, 0), b3, voffB);
;             PG8_BAR; PG8_WAIT_L(0); PG8_MMA(0, 1, At, B1); PG8_BAR;
;             PG8_LDA(At, 1, 1); PG8_STAGE(PG8_SA(1, 0), a3, voffA);
	s_add_u32 s26, s16, 0x40000
	s_addc_u32 s27, s17, 0
	s_add_i32 s28, s28, s35
	s_mov_b32 m0, s28
	s_nop 0
	global_load_lds_dwordx4 v144, s[26:27]
	s_add_i32 m0, s28, 0x2000
	s_nop 0
	global_load_lds_dwordx4 v128, s[26:27]
	s_waitcnt vmcnt(6)
	s_barrier
	v_mfma_f32_16x16x32_bf16 v[48:51], v[200:203], v[158:161], v[48:51]
	v_mfma_f32_16x16x32_bf16 v[40:43], v[214:217], v[158:161], v[40:43]
	v_mfma_f32_16x16x32_bf16 v[32:35], v[200:203], v[166:169], v[32:35]
	v_mfma_f32_16x16x32_bf16 v[24:27], v[214:217], v[166:169], v[24:27]
	v_mfma_f32_16x16x32_bf16 v[16:19], v[200:203], v[174:177], v[16:19]
	v_mfma_f32_16x16x32_bf16 v[8:11], v[214:217], v[174:177], v[8:11]
	v_mfma_f32_16x16x32_bf16 v[4:7], v[200:203], v[182:185], v[4:7]
	v_mfma_f32_16x16x32_bf16 v[0:3], v[214:217], v[182:185], v[0:3]
	v_mfma_f32_16x16x32_bf16 v[48:51], v[204:207], v[162:165], v[48:51]
	v_mfma_f32_16x16x32_bf16 v[40:43], v[218:221], v[162:165], v[40:43]
	v_mfma_f32_16x16x32_bf16 v[32:35], v[204:207], v[170:173], v[32:35]
	v_mfma_f32_16x16x32_bf16 v[24:27], v[218:221], v[170:173], v[24:27]
	v_mfma_f32_16x16x32_bf16 v[16:19], v[204:207], v[178:181], v[16:19]
	v_mfma_f32_16x16x32_bf16 v[8:11], v[218:221], v[178:181], v[8:11]
	v_mfma_f32_16x16x32_bf16 v[4:7], v[204:207], v[196:199], v[4:7]
	v_mfma_f32_16x16x32_bf16 v[0:3], v[218:221], v[196:199], v[0:3]
	s_add_i32 s26, 0, 0x18000
	v_add_u32_e32 v154, s26, v139
	s_barrier
	ds_read_b128 v[134:137], v154
	ds_read_b128 v[146:149], v154 offset:1024
	ds_read_b128 v[150:153], v154 offset:2048
	ds_read_b128 v[154:157], v154 offset:3072
	s_add_u32 s20, s20, 0x40000
	s_addc_u32 s21, s21, 0
	s_mov_b32 m0, s63
	ds_read_b128 v[158:161], v141 offset:32768
	ds_read_b128 v[162:165], v141 offset:33792
	ds_read_b128 v[166:169], v141 offset:34816
	ds_read_b128 v[170:173], v141 offset:35840
	ds_read_b128 v[174:177], v141 offset:36864
	ds_read_b128 v[178:181], v141 offset:37888
	ds_read_b128 v[182:185], v141 offset:38912
	global_load_lds_dwordx4 v144, s[20:21]
	s_mov_b32 m0, s64
	ds_read_b128 v[196:199], v141 offset:39936
	global_load_lds_dwordx4 v128, s[20:21]
	s_waitcnt lgkmcnt(8)
	s_barrier
	s_waitcnt lgkmcnt(0)
	v_mfma_f32_16x16x32_bf16 v[124:127], v[134:137], v[158:161], v[124:127]
	v_mfma_f32_16x16x32_bf16 v[120:123], v[150:153], v[158:161], v[120:123]
	v_mfma_f32_16x16x32_bf16 v[116:119], v[134:137], v[166:169], v[116:119]
	v_mfma_f32_16x16x32_bf16 v[108:111], v[150:153], v[166:169], v[108:111]
	v_mfma_f32_16x16x32_bf16 v[100:103], v[134:137], v[174:177], v[100:103]
	v_mfma_f32_16x16x32_bf16 v[92:95], v[150:153], v[174:177], v[92:95]
	v_mfma_f32_16x16x32_bf16 v[84:87], v[134:137], v[182:185], v[84:87]
	v_mfma_f32_16x16x32_bf16 v[76:79], v[150:153], v[182:185], v[76:79]
	v_mfma_f32_16x16x32_bf16 v[124:127], v[146:149], v[162:165], v[124:127]
	v_mfma_f32_16x16x32_bf16 v[120:123], v[154:157], v[162:165], v[120:123]
	v_mfma_f32_16x16x32_bf16 v[116:119], v[146:149], v[170:173], v[116:119]
	v_mfma_f32_16x16x32_bf16 v[108:111], v[154:157], v[170:173], v[108:111]
	v_mfma_f32_16x16x32_bf16 v[100:103], v[146:149], v[178:181], v[100:103]
	v_mfma_f32_16x16x32_bf16 v[92:95], v[154:157], v[178:181], v[92:95]
	v_mfma_f32_16x16x32_bf16 v[84:87], v[146:149], v[196:199], v[84:87]
	v_mfma_f32_16x16x32_bf16 v[76:79], v[154:157], v[196:199], v[76:79]
	s_barrier
	s_add_i32 s20, 0, 0x1c000
	s_add_i32 s21, s26, s35
	v_add_u32_e32 v190, s20, v139
	v_lshl_add_u64 v[142:143], v[142:143], 0, s[88:89]
	s_mov_b32 m0, s21
	ds_read_b128 v[200:203], v190
	ds_read_b128 v[204:207], v190 offset:1024
	ds_read_b128 v[214:217], v190 offset:2048
	ds_read_b128 v[218:221], v190 offset:3072
	global_load_lds_dwordx4 v[142:143], off
	s_add_i32 m0, s21, 0x2000
	v_lshl_add_u64 v[142:143], v[186:187], 0, s[88:89]
	global_load_lds_dwordx4 v[142:143], off
	s_barrier
	s_waitcnt lgkmcnt(0)
	v_mfma_f32_16x16x32_bf16 v[112:115], v[200:203], v[158:161], v[112:115]
	v_mfma_f32_16x16x32_bf16 v[104:107], v[214:217], v[158:161], v[104:107]
	v_mfma_f32_16x16x32_bf16 v[96:99], v[200:203], v[166:169], v[96:99]
	v_mfma_f32_16x16x32_bf16 v[88:91], v[214:217], v[166:169], v[88:91]
	v_mfma_f32_16x16x32_bf16 v[80:83], v[200:203], v[174:177], v[80:83]
	v_mfma_f32_16x16x32_bf16 v[72:75], v[214:217], v[174:177], v[72:75]
	v_mfma_f32_16x16x32_bf16 v[68:71], v[200:203], v[182:185], v[68:71]
	v_mfma_f32_16x16x32_bf16 v[64:67], v[214:217], v[182:185], v[64:67]
	v_mfma_f32_16x16x32_bf16 v[112:115], v[204:207], v[162:165], v[112:115]
	v_mfma_f32_16x16x32_bf16 v[104:107], v[218:221], v[162:165], v[104:107]
	v_mfma_f32_16x16x32_bf16 v[96:99], v[204:207], v[170:173], v[96:99]
	v_mfma_f32_16x16x32_bf16 v[88:91], v[218:221], v[170:173], v[88:91]
	v_mfma_f32_16x16x32_bf16 v[80:83], v[204:207], v[178:181], v[80:83]
	v_mfma_f32_16x16x32_bf16 v[72:75], v[218:221], v[178:181], v[72:75]
	v_mfma_f32_16x16x32_bf16 v[68:71], v[204:207], v[196:199], v[68:71]
	v_mfma_f32_16x16x32_bf16 v[64:67], v[218:221], v[196:199], v[64:67]
	s_mov_b32 m0, s65
	v_lshl_add_u64 v[142:143], v[188:189], 0, s[88:89]
	s_barrier
	ds_read_b128 v[158:161], v141 offset:49152
	ds_read_b128 v[162:165], v141 offset:50176
	ds_read_b128 v[166:169], v141 offset:51200
	ds_read_b128 v[170:173], v141 offset:52224
	ds_read_b128 v[174:177], v141 offset:53248
	ds_read_b128 v[178:181], v141 offset:54272
	ds_read_b128 v[182:185], v141 offset:55296
	ds_read_b128 v[196:199], v141 offset:56320
	global_load_lds_dwordx4 v[142:143], off
	s_mov_b32 m0, s66
	v_lshl_add_u64 v[142:143], v[192:193], 0, s[88:89]
	global_load_lds_dwordx4 v[142:143], off
	s_barrier
; #define PG8_STAGE(bufoff, gbase, voff) do { _Pragma("unroll") for (int _i = 0; _i < 2; ++_i) \
;         __builtin_amdgcn_global_load_lds((const unsigned*)((const char*)(gbase) + (voff)[_i]), (LAS unsigned*)(lds + (bufoff) + ldsw + _i * 8192), 16, 0, 0); } while (0)
; #define PG8_MMA(ai, bj, At, Bt) do { __builtin_amdgcn_s_setprio(1); _Pragma("unroll") for (int m = 0; m < 4; ++m) _Pragma("unroll") for (int n = 0; n < 2; ++n) _Pragma("unroll") for (int k = 0; k < 2; ++k) \
;         acc[ai][bj][m][n] = __builtin_amdgcn_mfma_f32_16x16x32_bf16(Bt[n][k], At[m][k], acc[ai][bj][m][n], 0, 0, 0); __builtin_amdgcn_s_setprio(0); } while (0)
; #define PG8_WAIT_V(n) asm volatile("s_waitcnt vmcnt(" #n ")" ::: "memory")
; #define PG8_WAIT_L(n) asm volatile("s_waitcnt lgkmcnt(" #n ")" ::: "memory")
; #define PG8_BAR __builtin_amdgcn_s_barrier()
; #define PG8_SCHED __builtin_amdgcn_sched_barrier(0)
; template <class Epi>
; __device__ __forceinline__ void gemm_phase(LAS unsigned char* lds, const Gemm g, const StaticOrder& S, const Epi& E) {
;     ...
;             PG8_BAR; PG8_WAIT_L(0); PG8_MMA(1, 0, At, B0); PG8_BAR; PG8_SCHED;
;             PG8_STAGE(PG8_SB(1, 1), b3 + hB, voffB);
;             PG8_WAIT_V(6); PG8_BAR; PG8_MMA(1, 1, At, B1); PG8_BAR;
	s_waitcnt lgkmcnt(0)
	v_mfma_f32_16x16x32_bf16 v[60:63], v[134:137], v[158:161], v[60:63]
	v_mfma_f32_16x16x32_bf16 v[56:59], v[150:153], v[158:161], v[56:59]
	v_mfma_f32_16x16x32_bf16 v[52:55], v[134:137], v[166:169], v[52:55]
	v_mfma_f32_16x16x32_bf16 v[44:47], v[150:153], v[166:169], v[44:47]
	v_mfma_f32_16x16x32_bf16 v[36:39], v[134:137], v[174:177], v[36:39]
	v_mfma_f32_16x16x32_bf16 v[28:31], v[150:153], v[174:177], v[28:31]
	v_mfma_f32_16x16x32_bf16 v[20:23], v[134:137], v[182:185], v[20:23]
	v_mfma_f32_16x16x32_bf16 v[12:15], v[150:153], v[182:185], v[12:15]
	v_mfma_f32_16x16x32_bf16 v[60:63], v[146:149], v[162:165], v[60:63]
	v_mfma_f32_16x16x32_bf16 v[56:59], v[154:157], v[162:165], v[56:59]
	v_mfma_f32_16x16x32_bf16 v[52:55], v[146:149], v[170:173], v[52:55]
	v_mfma_f32_16x16x32_bf16 v[44:47], v[154:157], v[170:173], v[44:47]
	v_mfma_f32_16x16x32_bf16 v[36:39], v[146:149], v[178:181], v[36:39]
	v_mfma_f32_16x16x32_bf16 v[28:31], v[154:157], v[178:181], v[28:31]
	v_mfma_f32_16x16x32_bf16 v[20:23], v[146:149], v[196:199], v[20:23]
	v_mfma_f32_16x16x32_bf16 v[12:15], v[154:157], v[196:199], v[12:15]
	s_barrier
	s_add_u32 s16, s16, 0x40080
	s_addc_u32 s17, s17, 0
	s_add_i32 s20, s20, s35
	s_mov_b32 m0, s20
	s_nop 0
	global_load_lds_dwordx4 v144, s[16:17]
	s_add_i32 m0, s20, 0x2000
	s_nop 0
	global_load_lds_dwordx4 v128, s[16:17]
	s_waitcnt vmcnt(6)
	s_barrier
	v_mfma_f32_16x16x32_bf16 v[48:51], v[200:203], v[158:161], v[48:51]
	v_mfma_f32_16x16x32_bf16 v[40:43], v[214:217], v[158:161], v[40:43]
	v_mfma_f32_16x16x32_bf16 v[32:35], v[200:203], v[166:169], v[32:35]
	v_mfma_f32_16x16x32_bf16 v[24:27], v[214:217], v[166:169], v[24:27]
	v_mfma_f32_16x16x32_bf16 v[16:19], v[200:203], v[174:177], v[16:19]
	v_mfma_f32_16x16x32_bf16 v[8:11], v[214:217], v[174:177], v[8:11]
	v_mfma_f32_16x16x32_bf16 v[4:7], v[200:203], v[182:185], v[4:7]
	v_mfma_f32_16x16x32_bf16 v[0:3], v[214:217], v[182:185], v[0:3]
	v_mfma_f32_16x16x32_bf16 v[48:51], v[204:207], v[162:165], v[48:51]
	v_mfma_f32_16x16x32_bf16 v[40:43], v[218:221], v[162:165], v[40:43]
	v_mfma_f32_16x16x32_bf16 v[32:35], v[204:207], v[170:173], v[32:35]
	v_mfma_f32_16x16x32_bf16 v[24:27], v[218:221], v[170:173], v[24:27]
	v_mfma_f32_16x16x32_bf16 v[16:19], v[204:207], v[178:181], v[16:19]
	v_mfma_f32_16x16x32_bf16 v[8:11], v[218:221], v[178:181], v[8:11]
	v_mfma_f32_16x16x32_bf16 v[4:7], v[204:207], v[196:199], v[4:7]
	v_mfma_f32_16x16x32_bf16 v[0:3], v[218:221], v[196:199], v[0:3]
	s_add_i32 s77, s77, 2
	s_add_u32 s12, s12, 0x100
	s_addc_u32 s13, s13, 0
	s_add_u32 s25, s25, 0x100
	s_addc_u32 s76, s76, 0
	s_cmp_gt_u32 s77, 13
	s_barrier
	s_cbranch_scc0 .LBB0_1270
; __device__ __forceinline__ unsigned pk2(float lo, float hi) { unsigned r; asm("v_cvt_pk_bf16_f32 %0, %1, %2" : "=v"(r) : "v"(lo), "v"(hi)); return r; }
; #define PG8_WAIT_V(n) asm volatile("s_waitcnt vmcnt(" #n ")" ::: "memory")
; #define PG8_BAR __builtin_amdgcn_s_barrier()
; template <class Epi>
; __device__ __forceinline__ void gemm_phase(LAS unsigned char* lds, const Gemm g, const StaticOrder& S, const Epi& E) {
;     ...
;         if (!has_next) break;
; #pragma unroll
;         for (int a = 0; a < 2; ++a)
; #pragma unroll
;             for (int b = 0; b < 2; ++b)
; #pragma unroll
;                 for (int m = 0; m < 4; ++m)
; #pragma unroll
;                     for (int n = 0; n < 2; ++n) acc[a][b][m][n] = (f32x4){0.f, 0.f, 0.f, 0.f};
;         cur = nxt; cA = nA; cB = nB; ++ui;
;     }
;     PG8_WAIT_V(0);
;     if (wr == 0) PG8_BAR;
;     PG8_BAR;
;     __device__ __forceinline__ void operator()(const f32x4 (&acc)[2][2][4][2], const Unit& u, int wr, int wc, int fr, int fq) const {
;     ...
;         const int row_t = rmap == 1 ? odd_phys_row0(u.pm, grp) : (rmap == 2 ? odd_phys_row0(u.pm % (BG * TPB), u.pm / (BG * TPB)) : u.pm * BM);
;         int c = col_t + 64 * wc + 16 * fq;
;         if (mode == 2) c = (c >> 6) * 96 + (c & 63);
; #pragma unroll
;         for (int ai = 0; ai < 2; ++ai)
; #pragma unroll
;             for (int m = 0; m < 4; ++m) {
;                 const int row = row_t + ai * HALF + wr * 64 + m * 16 + fr;
;                 bf16_t* rp = O + (size_t)row * ldc + c;
; #pragma unroll
;                 for (int bj = 0; bj < 2; ++bj) {
;                     const f32x4 v0 = acc[ai][bj][m][0], v1 = acc[ai][bj][m][1];
;                     u32x4 o; o.x = pk2(v0[0], v0[1]); o.y = pk2(v0[2], v0[3]); o.z = pk2(v1[0], v1[1]); o.w = pk2(v1[2], v1[3]);
;                     *(u32x4*)(rp + 8 * bj) = o;
;                 }
;             }
	v_lshl_add_u32 v134, s70, 8, v138
	v_cvt_pk_bf16_f32 v68, v68, v69
	v_cvt_pk_bf16_f32 v69, v70, v71
	v_cvt_pk_bf16_f32 v70, v64, v65
	v_add_u32_e32 v64, 0x80, v134
	v_lshl_or_b32 v136, s15, 8, v140
	v_ashrrev_i32_e32 v135, 31, v134
	v_cvt_pk_bf16_f32 v112, v112, v113
	v_cvt_pk_bf16_f32 v113, v114, v115
	v_cvt_pk_bf16_f32 v114, v104, v105
	v_or_b32_e32 v104, 16, v134
	v_ashrrev_i32_e32 v65, 31, v64
	v_cvt_pk_bf16_f32 v48, v48, v49
	v_cvt_pk_bf16_f32 v49, v50, v51
	v_cvt_pk_bf16_f32 v50, v40, v41
	v_add_u32_e32 v40, 0x90, v134
	v_ashrrev_i32_e32 v137, 31, v136
	v_lshlrev_b64 v[142:143], 11, v[134:135]
	v_ashrrev_i32_e32 v105, 31, v104
	v_cvt_pk_bf16_f32 v96, v96, v97
	v_cvt_pk_bf16_f32 v97, v98, v99
	v_cvt_pk_bf16_f32 v98, v88, v89
	v_or_b32_e32 v88, 32, v134
	v_lshlrev_b64 v[64:65], 11, v[64:65]
	v_ashrrev_i32_e32 v41, 31, v40
	v_cvt_pk_bf16_f32 v32, v32, v33
	v_cvt_pk_bf16_f32 v33, v34, v35
	v_cvt_pk_bf16_f32 v34, v24, v25
	v_add_u32_e32 v24, 0xa0, v134
	v_lshl_add_u64 v[142:143], s[4:5], 0, v[142:143]
	v_lshlrev_b64 v[136:137], 1, v[136:137]
	v_lshlrev_b64 v[104:105], 11, v[104:105]
	v_ashrrev_i32_e32 v89, 31, v88
	v_cvt_pk_bf16_f32 v80, v80, v81
	v_cvt_pk_bf16_f32 v81, v82, v83
	v_cvt_pk_bf16_f32 v82, v72, v73
	v_or_b32_e32 v72, 48, v134
	v_lshl_add_u64 v[64:65], s[4:5], 0, v[64:65]
	v_lshlrev_b64 v[40:41], 11, v[40:41]
	v_ashrrev_i32_e32 v25, 31, v24
	v_cvt_pk_bf16_f32 v16, v16, v17
	v_cvt_pk_bf16_f32 v17, v18, v19
	v_cvt_pk_bf16_f32 v18, v8, v9
	v_add_u32_e32 v8, 0xb0, v134
	v_lshl_add_u64 v[142:143], v[142:143], 0, v[136:137]
	v_lshl_add_u64 v[104:105], s[4:5], 0, v[104:105]
	v_lshlrev_b64 v[88:89], 11, v[88:89]
	v_ashrrev_i32_e32 v73, 31, v72
	v_lshl_add_u64 v[64:65], v[64:65], 0, v[136:137]
	v_lshl_add_u64 v[40:41], s[4:5], 0, v[40:41]
	v_lshlrev_b64 v[24:25], 11, v[24:25]
	v_ashrrev_i32_e32 v9, 31, v8
	v_cvt_pk_bf16_f32 v115, v106, v107
	global_store_dwordx4 v[142:143], v[112:115], off offset:16
	v_lshl_add_u64 v[88:89], s[4:5], 0, v[88:89]
	v_lshlrev_b64 v[72:73], 11, v[72:73]
	v_lshl_add_u64 v[112:113], v[104:105], 0, v[136:137]
	v_cvt_pk_bf16_f32 v51, v42, v43
	global_store_dwordx4 v[64:65], v[48:51], off offset:16
	v_lshl_add_u64 v[24:25], s[4:5], 0, v[24:25]
	v_lshlrev_b64 v[8:9], 11, v[8:9]
	v_lshl_add_u64 v[48:49], v[40:41], 0, v[136:137]
	v_cvt_pk_bf16_f32 v99, v90, v91
	global_store_dwordx4 v[112:113], v[96:99], off offset:16
	v_lshl_add_u64 v[72:73], s[4:5], 0, v[72:73]
	v_cvt_pk_bf16_f32 v35, v26, v27
	global_store_dwordx4 v[48:49], v[32:35], off offset:16
	v_lshl_add_u64 v[96:97], v[88:89], 0, v[136:137]
	v_lshl_add_u64 v[8:9], s[4:5], 0, v[8:9]
	v_lshl_add_u64 v[32:33], v[24:25], 0, v[136:137]
	v_cvt_pk_bf16_f32 v83, v74, v75
	global_store_dwordx4 v[96:97], v[80:83], off offset:16
	v_cvt_pk_bf16_f32 v19, v10, v11
	global_store_dwordx4 v[32:33], v[16:19], off offset:16
	s_and_b64 vcc, exec, s[0:1]
	v_lshl_add_u64 v[80:81], v[72:73], 0, v[136:137]
	v_lshl_add_u64 v[16:17], v[8:9], 0, v[136:137]
	s_mov_b32 s15, s6
	s_mov_b32 s70, s69
	s_mov_b64 s[16:17], s[10:11]
	s_mov_b64 s[12:13], s[8:9]
	v_cvt_pk_bf16_f32 v124, v124, v125
	v_cvt_pk_bf16_f32 v125, v126, v127
	v_cvt_pk_bf16_f32 v126, v120, v121
	v_cvt_pk_bf16_f32 v127, v122, v123
	global_store_dwordx4 v[142:143], v[124:127], off
	v_cvt_pk_bf16_f32 v104, v116, v117
	v_cvt_pk_bf16_f32 v105, v118, v119
	v_cvt_pk_bf16_f32 v106, v108, v109
	v_cvt_pk_bf16_f32 v107, v110, v111
	global_store_dwordx4 v[112:113], v[104:107], off
	v_cvt_pk_bf16_f32 v88, v100, v101
	v_cvt_pk_bf16_f32 v89, v102, v103
	v_cvt_pk_bf16_f32 v90, v92, v93
	v_cvt_pk_bf16_f32 v91, v94, v95
	global_store_dwordx4 v[96:97], v[88:91], off
	v_cvt_pk_bf16_f32 v72, v84, v85
	v_cvt_pk_bf16_f32 v73, v86, v87
	v_cvt_pk_bf16_f32 v74, v76, v77
	v_cvt_pk_bf16_f32 v75, v78, v79
	global_store_dwordx4 v[80:81], v[72:75], off
	v_cvt_pk_bf16_f32 v71, v66, v67
	global_store_dwordx4 v[80:81], v[68:71], off offset:16
	v_cvt_pk_bf16_f32 v60, v60, v61
	v_cvt_pk_bf16_f32 v61, v62, v63
	v_cvt_pk_bf16_f32 v62, v56, v57
	v_cvt_pk_bf16_f32 v63, v58, v59
	global_store_dwordx4 v[64:65], v[60:63], off
	v_cvt_pk_bf16_f32 v40, v52, v53
	v_cvt_pk_bf16_f32 v41, v54, v55
	v_cvt_pk_bf16_f32 v42, v44, v45
	v_cvt_pk_bf16_f32 v43, v46, v47
	global_store_dwordx4 v[48:49], v[40:43], off
	v_cvt_pk_bf16_f32 v24, v36, v37
	v_cvt_pk_bf16_f32 v25, v38, v39
	v_cvt_pk_bf16_f32 v26, v28, v29
	v_cvt_pk_bf16_f32 v27, v30, v31
	global_store_dwordx4 v[32:33], v[24:27], off
	v_cvt_pk_bf16_f32 v8, v20, v21
	v_cvt_pk_bf16_f32 v9, v22, v23
	v_cvt_pk_bf16_f32 v10, v12, v13
	v_cvt_pk_bf16_f32 v11, v14, v15
	global_store_dwordx4 v[16:17], v[8:11], off
	v_cvt_pk_bf16_f32 v4, v4, v5
	v_cvt_pk_bf16_f32 v5, v6, v7
	v_cvt_pk_bf16_f32 v6, v0, v1
	v_cvt_pk_bf16_f32 v7, v2, v3
	global_store_dwordx4 v[16:17], v[4:7], off offset:16
	s_cbranch_vccz .LBB0_1267
	s_waitcnt vmcnt(0)
	s_cmpk_gt_u32 s3, 0xff
	s_cbranch_scc1 .LBB0_1274
	s_barrier

; #define PG8_STAGE(bufoff, gbase, voff) do { _Pragma("unroll") for (int _i = 0; _i < 2; ++_i) \
;         __builtin_amdgcn_global_load_lds((const unsigned*)((const char*)(gbase) + (voff)[_i]), (LAS unsigned*)(lds + (bufoff) + ldsw + _i * 8192), 16, 0, 0); } while (0)
; #define PG8_LDA(dst, b, h) do { _Pragma("unroll") for (int m = 0; m < 4; ++m) _Pragma("unroll") for (int k = 0; k < 2; ++k) dst[m][k] = *(const LAS bf16x8*)(lds + PG8_SA(b, h) + aoff + m * 2048 + k * 1024); } while (0)
; #define PG8_LDB(dst, b, h) do { _Pragma("unroll") for (int n = 0; n < 2; ++n) _Pragma("unroll") for (int k = 0; k < 2; ++k) dst[n][k] = *(const LAS bf16x8*)(lds + PG8_SB(b, h) + boff + n * 2048 + k * 1024); } while (0)
; #define PG8_MMA(ai, bj, At, Bt) do { __builtin_amdgcn_s_setprio(1); _Pragma("unroll") for (int m = 0; m < 4; ++m) _Pragma("unroll") for (int n = 0; n < 2; ++n) _Pragma("unroll") for (int k = 0; k < 2; ++k) \
;         acc[ai][bj][m][n] = __builtin_amdgcn_mfma_f32_16x16x32_bf16(Bt[n][k], At[m][k], acc[ai][bj][m][n], 0, 0, 0); __builtin_amdgcn_s_setprio(0); } while (0)
; #define PG8_WAIT_V(n) asm volatile("s_waitcnt vmcnt(" #n ")" ::: "memory")
; #define PG8_WAIT_L(n) asm volatile("s_waitcnt lgkmcnt(" #n ")" ::: "memory")
; #define PG8_BAR __builtin_amdgcn_s_barrier()
; template <class Epi>
; __device__ __forceinline__ void gemm_phase(LAS unsigned char* lds, const Gemm g, const StaticOrder& S, const Epi& E) {
;     ...
;             const bool last = (t == nt - 2);
;             const char* a1 = cA + (size_t)(t + 1) * kstep;
;             const char* a2 = last ? nA : cA + (size_t)(t + 2) * kstep; const char* b2 = last ? nB : cB + (size_t)(t + 2) * kstep;
;             const char* a3 = a2 + kstep; const char* b3 = b2 + kstep;
;             PG8_LDB(B0, 0, 0); PG8_SCHED; PG8_LDA(At, 0, 0); PG8_STAGE(PG8_SA(1, 1), a1 + hA, voffA);
;             PG8_WAIT_L(8); PG8_BAR; PG8_WAIT_L(0); PG8_MMA(0, 0, At, B0); PG8_BAR; PG8_SCHED;
;             PG8_LDB(B1, 0, 1); PG8_STAGE(PG8_SB(0, 0), b2, voffB);
;             PG8_BAR; PG8_WAIT_L(0); PG8_MMA(0, 1, At, B1); PG8_BAR;
;             PG8_LDA(At, 0, 1); PG8_STAGE(PG8_SA(0, 0), a2, voffA);
;             PG8_BAR; PG8_WAIT_L(0); PG8_MMA(1, 0, At, B0); PG8_BAR; PG8_SCHED;
;             PG8_STAGE(PG8_SB(0, 1), b2 + hB, voffB);
;             PG8_WAIT_V(6); PG8_BAR; PG8_MMA(1, 1, At, B1); PG8_BAR;
.LBB0_1394:
	s_add_u32 s20, s16, 0xfffc0080
	s_addc_u32 s21, s17, -1
	s_add_i32 s26, 0, 0x10000
	v_add_u32_e32 v139, s26, v137
	ds_read_b128 v[140:143], v139
	ds_read_b128 v[146:149], v139 offset:1024
	ds_read_b128 v[150:153], v139 offset:2048
	ds_read_b128 v[154:157], v139 offset:3072
	s_cmp_eq_u32 s85, 12
	s_cselect_b32 s35, s82, s21
	s_cselect_b32 s34, s83, s20
	s_cselect_b32 s21, s9, s84
	s_cselect_b32 s20, s24, s25
	s_add_i32 m0, s70, 0xc000
	ds_read_b128 v[158:161], v138
	ds_read_b128 v[162:165], v138 offset:1024
	ds_read_b128 v[166:169], v138 offset:2048
	ds_read_b128 v[170:173], v138 offset:3072
	ds_read_b128 v[174:177], v138 offset:4096
	ds_read_b128 v[178:181], v138 offset:5120
	ds_read_b128 v[182:185], v138 offset:6144
	global_load_lds_dwordx4 v132, s[16:17]
	s_add_i32 m0, s70, 0xe000
	ds_read_b128 v[186:189], v138 offset:7168
	global_load_lds_dwordx4 v134, s[16:17]
	s_waitcnt lgkmcnt(8)
	s_barrier
	s_waitcnt lgkmcnt(0)
	v_mfma_f32_16x16x32_bf16 v[120:123], v[140:143], v[158:161], v[120:123]
	v_mfma_f32_16x16x32_bf16 v[124:127], v[150:153], v[158:161], v[124:127]
	v_mfma_f32_16x16x32_bf16 v[104:107], v[140:143], v[166:169], v[104:107]
	v_mfma_f32_16x16x32_bf16 v[108:111], v[150:153], v[166:169], v[108:111]
	v_mfma_f32_16x16x32_bf16 v[88:91], v[140:143], v[174:177], v[88:91]
	v_mfma_f32_16x16x32_bf16 v[92:95], v[150:153], v[174:177], v[92:95]
	v_mfma_f32_16x16x32_bf16 v[72:75], v[140:143], v[182:185], v[72:75]
	v_mfma_f32_16x16x32_bf16 v[76:79], v[150:153], v[182:185], v[76:79]
	v_mfma_f32_16x16x32_bf16 v[120:123], v[146:149], v[162:165], v[120:123]
	v_mfma_f32_16x16x32_bf16 v[124:127], v[154:157], v[162:165], v[124:127]
	v_mfma_f32_16x16x32_bf16 v[104:107], v[146:149], v[170:173], v[104:107]
	v_mfma_f32_16x16x32_bf16 v[108:111], v[154:157], v[170:173], v[108:111]
	v_mfma_f32_16x16x32_bf16 v[88:91], v[146:149], v[178:181], v[88:91]
	v_mfma_f32_16x16x32_bf16 v[92:95], v[154:157], v[178:181], v[92:95]
	v_mfma_f32_16x16x32_bf16 v[72:75], v[146:149], v[186:189], v[72:75]
	v_mfma_f32_16x16x32_bf16 v[76:79], v[154:157], v[186:189], v[76:79]
	s_barrier
	s_add_i32 s28, 0, 0x14000
	s_add_i32 s26, s26, s64
	v_add_u32_e32 v139, s28, v137
	v_lshl_add_u64 v[192:193], s[20:21], 0, v[130:131]
	s_mov_b32 m0, s26
	ds_read_b128 v[196:199], v139
	ds_read_b128 v[200:203], v139 offset:1024
	ds_read_b128 v[204:207], v139 offset:2048
	ds_read_b128 v[214:217], v139 offset:3072
	global_load_lds_dwordx4 v[192:193], off
	s_add_i32 m0, s26, 0x2000
	v_lshl_add_u64 v[218:219], s[20:21], 0, v[128:129]
	global_load_lds_dwordx4 v[218:219], off
	s_barrier
	s_waitcnt lgkmcnt(0)
	v_mfma_f32_16x16x32_bf16 v[112:115], v[196:199], v[158:161], v[112:115]
	v_mfma_f32_16x16x32_bf16 v[116:119], v[204:207], v[158:161], v[116:119]
	v_mfma_f32_16x16x32_bf16 v[96:99], v[196:199], v[166:169], v[96:99]
	v_mfma_f32_16x16x32_bf16 v[100:103], v[204:207], v[166:169], v[100:103]
	v_mfma_f32_16x16x32_bf16 v[80:83], v[196:199], v[174:177], v[80:83]
	v_mfma_f32_16x16x32_bf16 v[84:87], v[204:207], v[174:177], v[84:87]
	v_mfma_f32_16x16x32_bf16 v[64:67], v[196:199], v[182:185], v[64:67]
	v_mfma_f32_16x16x32_bf16 v[68:71], v[204:207], v[182:185], v[68:71]
	v_mfma_f32_16x16x32_bf16 v[112:115], v[200:203], v[162:165], v[112:115]
	v_mfma_f32_16x16x32_bf16 v[116:119], v[214:217], v[162:165], v[116:119]
	v_mfma_f32_16x16x32_bf16 v[96:99], v[200:203], v[170:173], v[96:99]
	v_mfma_f32_16x16x32_bf16 v[100:103], v[214:217], v[170:173], v[100:103]
	v_mfma_f32_16x16x32_bf16 v[80:83], v[200:203], v[178:181], v[80:83]
	v_mfma_f32_16x16x32_bf16 v[84:87], v[214:217], v[178:181], v[84:87]
	v_mfma_f32_16x16x32_bf16 v[64:67], v[200:203], v[186:189], v[64:67]
	v_mfma_f32_16x16x32_bf16 v[68:71], v[214:217], v[186:189], v[68:71]
	s_mov_b32 m0, s70
	v_lshl_add_u64 v[220:221], s[34:35], 0, v[130:131]
	s_barrier
	ds_read_b128 v[158:161], v138 offset:16384
	ds_read_b128 v[162:165], v138 offset:17408
	ds_read_b128 v[166:169], v138 offset:18432
	ds_read_b128 v[170:173], v138 offset:19456
	ds_read_b128 v[174:177], v138 offset:20480
	ds_read_b128 v[178:181], v138 offset:21504
	ds_read_b128 v[182:185], v138 offset:22528
	ds_read_b128 v[186:189], v138 offset:23552
	global_load_lds_dwordx4 v[220:221], off
	s_mov_b32 m0, s71
	v_lshl_add_u64 v[222:223], s[34:35], 0, v[128:129]
	global_load_lds_dwordx4 v[222:223], off
	s_barrier
	s_waitcnt lgkmcnt(0)
	v_mfma_f32_16x16x32_bf16 v[56:59], v[140:143], v[158:161], v[56:59]
	v_mfma_f32_16x16x32_bf16 v[60:63], v[150:153], v[158:161], v[60:63]
	v_mfma_f32_16x16x32_bf16 v[40:43], v[140:143], v[166:169], v[40:43]
	v_mfma_f32_16x16x32_bf16 v[44:47], v[150:153], v[166:169], v[44:47]
	v_mfma_f32_16x16x32_bf16 v[24:27], v[140:143], v[174:177], v[24:27]
	v_mfma_f32_16x16x32_bf16 v[28:31], v[150:153], v[174:177], v[28:31]
	v_mfma_f32_16x16x32_bf16 v[8:11], v[140:143], v[182:185], v[8:11]
	v_mfma_f32_16x16x32_bf16 v[12:15], v[150:153], v[182:185], v[12:15]
	v_mfma_f32_16x16x32_bf16 v[56:59], v[146:149], v[162:165], v[56:59]
	v_mfma_f32_16x16x32_bf16 v[60:63], v[154:157], v[162:165], v[60:63]
	v_mfma_f32_16x16x32_bf16 v[40:43], v[146:149], v[170:173], v[40:43]
	v_mfma_f32_16x16x32_bf16 v[44:47], v[154:157], v[170:173], v[44:47]
	v_mfma_f32_16x16x32_bf16 v[24:27], v[146:149], v[178:181], v[24:27]
	v_mfma_f32_16x16x32_bf16 v[28:31], v[154:157], v[178:181], v[28:31]
	v_mfma_f32_16x16x32_bf16 v[8:11], v[146:149], v[186:189], v[8:11]
	v_mfma_f32_16x16x32_bf16 v[12:15], v[154:157], v[186:189], v[12:15]
	s_barrier
	s_add_u32 s26, s20, 0x40000
	s_addc_u32 s27, s21, 0
	s_add_i32 s28, s28, s64
	s_mov_b32 m0, s28
	s_nop 0
	global_load_lds_dwordx4 v130, s[26:27]
	s_add_i32 m0, s28, 0x2000
	s_nop 0
	global_load_lds_dwordx4 v128, s[26:27]
	s_waitcnt vmcnt(6)
	s_barrier
; #define PG8_STAGE(bufoff, gbase, voff) do { _Pragma("unroll") for (int _i = 0; _i < 2; ++_i) \
;         __builtin_amdgcn_global_load_lds((const unsigned*)((const char*)(gbase) + (voff)[_i]), (LAS unsigned*)(lds + (bufoff) + ldsw + _i * 8192), 16, 0, 0); } while (0)
; #define PG8_LDA(dst, b, h) do { _Pragma("unroll") for (int m = 0; m < 4; ++m) _Pragma("unroll") for (int k = 0; k < 2; ++k) dst[m][k] = *(const LAS bf16x8*)(lds + PG8_SA(b, h) + aoff + m * 2048 + k * 1024); } while (0)
; #define PG8_LDB(dst, b, h) do { _Pragma("unroll") for (int n = 0; n < 2; ++n) _Pragma("unroll") for (int k = 0; k < 2; ++k) dst[n][k] = *(const LAS bf16x8*)(lds + PG8_SB(b, h) + boff + n * 2048 + k * 1024); } while (0)
; #define PG8_MMA(ai, bj, At, Bt) do { __builtin_amdgcn_s_setprio(1); _Pragma("unroll") for (int m = 0; m < 4; ++m) _Pragma("unroll") for (int n = 0; n < 2; ++n) _Pragma("unroll") for (int k = 0; k < 2; ++k) \
;         acc[ai][bj][m][n] = __builtin_amdgcn_mfma_f32_16x16x32_bf16(Bt[n][k], At[m][k], acc[ai][bj][m][n], 0, 0, 0); __builtin_amdgcn_s_setprio(0); } while (0)
; #define PG8_WAIT_V(n) asm volatile("s_waitcnt vmcnt(" #n ")" ::: "memory")
; #define PG8_WAIT_L(n) asm volatile("s_waitcnt lgkmcnt(" #n ")" ::: "memory")
; #define PG8_BAR __builtin_amdgcn_s_barrier()
; #define PG8_SCHED __builtin_amdgcn_sched_barrier(0)
; template <class Epi>
; __device__ __forceinline__ void gemm_phase(LAS unsigned char* lds, const Gemm g, const StaticOrder& S, const Epi& E) {
;     ...
;             PG8_WAIT_V(6); PG8_BAR; PG8_MMA(1, 1, At, B1); PG8_BAR;
;             PG8_LDB(B0, 1, 0); PG8_SCHED; PG8_LDA(At, 1, 0); PG8_STAGE(PG8_SA(0, 1), a2 + hA, voffA);
;             PG8_WAIT_L(8); PG8_BAR; PG8_WAIT_L(0); PG8_MMA(0, 0, At, B0); PG8_BAR; PG8_SCHED;
;             PG8_LDB(B1, 1, 1); PG8_STAGE(PG8_SB(1, 0), b3, voffB);
;             PG8_BAR; PG8_WAIT_L(0); PG8_MMA(0, 1, At, B1); PG8_BAR;
;             PG8_LDA(At, 1, 1); PG8_STAGE(PG8_SA(1, 0), a3, voffA);
	v_mfma_f32_16x16x32_bf16 v[48:51], v[196:199], v[158:161], v[48:51]
	v_mfma_f32_16x16x32_bf16 v[52:55], v[204:207], v[158:161], v[52:55]
	v_mfma_f32_16x16x32_bf16 v[32:35], v[196:199], v[166:169], v[32:35]
	v_mfma_f32_16x16x32_bf16 v[36:39], v[204:207], v[166:169], v[36:39]
	v_mfma_f32_16x16x32_bf16 v[16:19], v[196:199], v[174:177], v[16:19]
	v_mfma_f32_16x16x32_bf16 v[20:23], v[204:207], v[174:177], v[20:23]
	v_mfma_f32_16x16x32_bf16 v[0:3], v[196:199], v[182:185], v[0:3]
	v_mfma_f32_16x16x32_bf16 v[4:7], v[204:207], v[182:185], v[4:7]
	v_mfma_f32_16x16x32_bf16 v[48:51], v[200:203], v[162:165], v[48:51]
	v_mfma_f32_16x16x32_bf16 v[52:55], v[214:217], v[162:165], v[52:55]
	v_mfma_f32_16x16x32_bf16 v[32:35], v[200:203], v[170:173], v[32:35]
	v_mfma_f32_16x16x32_bf16 v[36:39], v[214:217], v[170:173], v[36:39]
	v_mfma_f32_16x16x32_bf16 v[16:19], v[200:203], v[178:181], v[16:19]
	v_mfma_f32_16x16x32_bf16 v[20:23], v[214:217], v[178:181], v[20:23]
	v_mfma_f32_16x16x32_bf16 v[0:3], v[200:203], v[186:189], v[0:3]
	v_mfma_f32_16x16x32_bf16 v[4:7], v[214:217], v[186:189], v[4:7]
	s_add_i32 s28, 0, 0x18000
	v_add_u32_e32 v139, s28, v137
	s_barrier
	ds_read_b128 v[140:143], v139
	ds_read_b128 v[146:149], v139 offset:1024
	ds_read_b128 v[150:153], v139 offset:2048
	ds_read_b128 v[154:157], v139 offset:3072
	s_add_u32 s26, s34, 0x40000
	s_addc_u32 s27, s35, 0
	s_mov_b32 m0, s72
	ds_read_b128 v[158:161], v138 offset:32768
	ds_read_b128 v[162:165], v138 offset:33792
	ds_read_b128 v[166:169], v138 offset:34816
	ds_read_b128 v[170:173], v138 offset:35840
	ds_read_b128 v[174:177], v138 offset:36864
	ds_read_b128 v[178:181], v138 offset:37888
	ds_read_b128 v[182:185], v138 offset:38912
	global_load_lds_dwordx4 v130, s[26:27]
	s_mov_b32 m0, s76
	ds_read_b128 v[186:189], v138 offset:39936
	global_load_lds_dwordx4 v128, s[26:27]
	s_waitcnt lgkmcnt(8)
	s_barrier
	s_waitcnt lgkmcnt(0)
	v_mfma_f32_16x16x32_bf16 v[120:123], v[140:143], v[158:161], v[120:123]
	v_mfma_f32_16x16x32_bf16 v[124:127], v[150:153], v[158:161], v[124:127]
	v_mfma_f32_16x16x32_bf16 v[104:107], v[140:143], v[166:169], v[104:107]
	v_mfma_f32_16x16x32_bf16 v[108:111], v[150:153], v[166:169], v[108:111]
	v_mfma_f32_16x16x32_bf16 v[88:91], v[140:143], v[174:177], v[88:91]
	v_mfma_f32_16x16x32_bf16 v[92:95], v[150:153], v[174:177], v[92:95]
	v_mfma_f32_16x16x32_bf16 v[72:75], v[140:143], v[182:185], v[72:75]
	v_mfma_f32_16x16x32_bf16 v[76:79], v[150:153], v[182:185], v[76:79]
	v_mfma_f32_16x16x32_bf16 v[120:123], v[146:149], v[162:165], v[120:123]
	v_mfma_f32_16x16x32_bf16 v[124:127], v[154:157], v[162:165], v[124:127]
	v_mfma_f32_16x16x32_bf16 v[104:107], v[146:149], v[170:173], v[104:107]
	v_mfma_f32_16x16x32_bf16 v[108:111], v[154:157], v[170:173], v[108:111]
	v_mfma_f32_16x16x32_bf16 v[88:91], v[146:149], v[178:181], v[88:91]
	v_mfma_f32_16x16x32_bf16 v[92:95], v[154:157], v[178:181], v[92:95]
	v_mfma_f32_16x16x32_bf16 v[72:75], v[146:149], v[186:189], v[72:75]
	v_mfma_f32_16x16x32_bf16 v[76:79], v[154:157], v[186:189], v[76:79]
	s_barrier
	s_add_i32 s26, 0, 0x1c000
	s_add_i32 s27, s28, s64
	v_add_u32_e32 v139, s26, v137
	v_lshl_add_u64 v[192:193], v[192:193], 0, s[88:89]
	s_mov_b32 m0, s27
	ds_read_b128 v[196:199], v139
	ds_read_b128 v[200:203], v139 offset:1024
	ds_read_b128 v[204:207], v139 offset:2048
	ds_read_b128 v[214:217], v139 offset:3072
	global_load_lds_dwordx4 v[192:193], off
	s_add_i32 m0, s27, 0x2000
	v_lshl_add_u64 v[192:193], v[218:219], 0, s[88:89]
	global_load_lds_dwordx4 v[192:193], off
	s_barrier
	s_waitcnt lgkmcnt(0)
	v_mfma_f32_16x16x32_bf16 v[112:115], v[196:199], v[158:161], v[112:115]
	v_mfma_f32_16x16x32_bf16 v[116:119], v[204:207], v[158:161], v[116:119]
	v_mfma_f32_16x16x32_bf16 v[96:99], v[196:199], v[166:169], v[96:99]
	v_mfma_f32_16x16x32_bf16 v[100:103], v[204:207], v[166:169], v[100:103]
	v_mfma_f32_16x16x32_bf16 v[80:83], v[196:199], v[174:177], v[80:83]
	v_mfma_f32_16x16x32_bf16 v[84:87], v[204:207], v[174:177], v[84:87]
	v_mfma_f32_16x16x32_bf16 v[64:67], v[196:199], v[182:185], v[64:67]
	v_mfma_f32_16x16x32_bf16 v[68:71], v[204:207], v[182:185], v[68:71]
	v_mfma_f32_16x16x32_bf16 v[112:115], v[200:203], v[162:165], v[112:115]
	v_mfma_f32_16x16x32_bf16 v[116:119], v[214:217], v[162:165], v[116:119]
	v_mfma_f32_16x16x32_bf16 v[96:99], v[200:203], v[170:173], v[96:99]
	v_mfma_f32_16x16x32_bf16 v[100:103], v[214:217], v[170:173], v[100:103]
	v_mfma_f32_16x16x32_bf16 v[80:83], v[200:203], v[178:181], v[80:83]
	v_mfma_f32_16x16x32_bf16 v[84:87], v[214:217], v[178:181], v[84:87]
	v_mfma_f32_16x16x32_bf16 v[64:67], v[200:203], v[186:189], v[64:67]
	v_mfma_f32_16x16x32_bf16 v[68:71], v[214:217], v[186:189], v[68:71]
	s_mov_b32 m0, s77
	v_lshl_add_u64 v[192:193], v[220:221], 0, s[88:89]
	s_barrier
	ds_read_b128 v[158:161], v138 offset:49152
	ds_read_b128 v[162:165], v138 offset:50176
	ds_read_b128 v[166:169], v138 offset:51200
	ds_read_b128 v[170:173], v138 offset:52224
	ds_read_b128 v[174:177], v138 offset:53248
	ds_read_b128 v[178:181], v138 offset:54272
	ds_read_b128 v[182:185], v138 offset:55296
	ds_read_b128 v[186:189], v138 offset:56320
	global_load_lds_dwordx4 v[192:193], off
	s_mov_b32 m0, s78
	v_lshl_add_u64 v[192:193], v[222:223], 0, s[88:89]
	global_load_lds_dwordx4 v[192:193], off
	s_barrier
; __device__ __forceinline__ unsigned pk2(float lo, float hi) { unsigned r; asm("v_cvt_pk_bf16_f32 %0, %1, %2" : "=v"(r) : "v"(lo), "v"(hi)); return r; }
; #define PG8_STAGE(bufoff, gbase, voff) do { _Pragma("unroll") for (int _i = 0; _i < 2; ++_i) \
;         __builtin_amdgcn_global_load_lds((const unsigned*)((const char*)(gbase) + (voff)[_i]), (LAS unsigned*)(lds + (bufoff) + ldsw + _i * 8192), 16, 0, 0); } while (0)
; #define PG8_MMA(ai, bj, At, Bt) do { __builtin_amdgcn_s_setprio(1); _Pragma("unroll") for (int m = 0; m < 4; ++m) _Pragma("unroll") for (int n = 0; n < 2; ++n) _Pragma("unroll") for (int k = 0; k < 2; ++k) \
;         acc[ai][bj][m][n] = __builtin_amdgcn_mfma_f32_16x16x32_bf16(Bt[n][k], At[m][k], acc[ai][bj][m][n], 0, 0, 0); __builtin_amdgcn_s_setprio(0); } while (0)
; #define PG8_WAIT_V(n) asm volatile("s_waitcnt vmcnt(" #n ")" ::: "memory")
; #define PG8_WAIT_L(n) asm volatile("s_waitcnt lgkmcnt(" #n ")" ::: "memory")
; #define PG8_BAR __builtin_amdgcn_s_barrier()
; #define PG8_SCHED __builtin_amdgcn_sched_barrier(0)
; template <class Epi>
; __device__ __forceinline__ void gemm_phase(LAS unsigned char* lds, const Gemm g, const StaticOrder& S, const Epi& E) {
;     ...
;             PG8_BAR; PG8_WAIT_L(0); PG8_MMA(1, 0, At, B0); PG8_BAR; PG8_SCHED;
;             PG8_STAGE(PG8_SB(1, 1), b3 + hB, voffB);
;             PG8_WAIT_V(6); PG8_BAR; PG8_MMA(1, 1, At, B1); PG8_BAR;
;     static __device__ __forceinline__ float sg(float g, float u) { return (g * u) * __builtin_amdgcn_rcpf(1.f + __builtin_amdgcn_exp2f(-g)); }
;     __device__ __forceinline__ void operator()(const f32x4 (&acc)[2][2][4][2], const Unit& u, int wr, int wc, int fr, int fq) const {
; #pragma unroll
;         for (int ai = 0; ai < 2; ++ai)
; #pragma unroll
;             for (int m = 0; m < 4; ++m) {
;                 const int row = u.pm * BM + ai * HALF + wr * 64 + m * 16 + fr;
;                 const f32x4 g0 = acc[ai][0][m][0], u0 = acc[ai][0][m][1], g1 = acc[ai][1][m][0], u1 = acc[ai][1][m][1];
;                 u32x4 o; o.x = pk2(sg(g0[0], u0[0]), sg(g0[1], u0[1])); o.y = pk2(sg(g0[2], u0[2]), sg(g0[3], u0[3]));
;                 o.z = pk2(sg(g1[0], u1[0]), sg(g1[1], u1[1])); o.w = pk2(sg(g1[2], u1[2]), sg(g1[3], u1[3]));
;                 *(u32x4*)(O + (size_t)row * DFF + u.pn * 128 + wc * 32 + fq * 8) = o;
;             }
	s_waitcnt lgkmcnt(0)
	v_mfma_f32_16x16x32_bf16 v[56:59], v[140:143], v[158:161], v[56:59]
	v_mfma_f32_16x16x32_bf16 v[60:63], v[150:153], v[158:161], v[60:63]
	v_mfma_f32_16x16x32_bf16 v[40:43], v[140:143], v[166:169], v[40:43]
	v_mfma_f32_16x16x32_bf16 v[44:47], v[150:153], v[166:169], v[44:47]
	v_mfma_f32_16x16x32_bf16 v[24:27], v[140:143], v[174:177], v[24:27]
	v_mfma_f32_16x16x32_bf16 v[28:31], v[150:153], v[174:177], v[28:31]
	v_mfma_f32_16x16x32_bf16 v[8:11], v[140:143], v[182:185], v[8:11]
	v_mfma_f32_16x16x32_bf16 v[12:15], v[150:153], v[182:185], v[12:15]
	v_mfma_f32_16x16x32_bf16 v[56:59], v[146:149], v[162:165], v[56:59]
	v_mfma_f32_16x16x32_bf16 v[60:63], v[154:157], v[162:165], v[60:63]
	v_mfma_f32_16x16x32_bf16 v[40:43], v[146:149], v[170:173], v[40:43]
	v_mfma_f32_16x16x32_bf16 v[44:47], v[154:157], v[170:173], v[44:47]
	v_mfma_f32_16x16x32_bf16 v[24:27], v[146:149], v[178:181], v[24:27]
	v_mfma_f32_16x16x32_bf16 v[28:31], v[154:157], v[178:181], v[28:31]
	v_mfma_f32_16x16x32_bf16 v[8:11], v[146:149], v[186:189], v[8:11]
	v_mfma_f32_16x16x32_bf16 v[12:15], v[154:157], v[186:189], v[12:15]
	s_barrier
	s_add_u32 s20, s20, 0x40080
	s_addc_u32 s21, s21, 0
	s_add_i32 s26, s26, s64
	s_mov_b32 m0, s26
	s_nop 0
	global_load_lds_dwordx4 v130, s[20:21]
	s_add_i32 m0, s26, 0x2000
	s_nop 0
	global_load_lds_dwordx4 v128, s[20:21]
	s_waitcnt vmcnt(6)
	s_barrier
	v_mfma_f32_16x16x32_bf16 v[48:51], v[196:199], v[158:161], v[48:51]
	v_mfma_f32_16x16x32_bf16 v[52:55], v[204:207], v[158:161], v[52:55]
	v_mfma_f32_16x16x32_bf16 v[32:35], v[196:199], v[166:169], v[32:35]
	v_mfma_f32_16x16x32_bf16 v[36:39], v[204:207], v[166:169], v[36:39]
	v_mfma_f32_16x16x32_bf16 v[16:19], v[196:199], v[174:177], v[16:19]
	v_mfma_f32_16x16x32_bf16 v[20:23], v[204:207], v[174:177], v[20:23]
	v_mfma_f32_16x16x32_bf16 v[0:3], v[196:199], v[182:185], v[0:3]
	v_mfma_f32_16x16x32_bf16 v[4:7], v[204:207], v[182:185], v[4:7]
	v_mfma_f32_16x16x32_bf16 v[48:51], v[200:203], v[162:165], v[48:51]
	v_mfma_f32_16x16x32_bf16 v[52:55], v[214:217], v[162:165], v[52:55]
	v_mfma_f32_16x16x32_bf16 v[32:35], v[200:203], v[170:173], v[32:35]
	v_mfma_f32_16x16x32_bf16 v[36:39], v[214:217], v[170:173], v[36:39]
	v_mfma_f32_16x16x32_bf16 v[16:19], v[200:203], v[178:181], v[16:19]
	v_mfma_f32_16x16x32_bf16 v[20:23], v[214:217], v[178:181], v[20:23]
	v_mfma_f32_16x16x32_bf16 v[0:3], v[200:203], v[186:189], v[0:3]
	v_mfma_f32_16x16x32_bf16 v[4:7], v[214:217], v[186:189], v[4:7]
	s_add_i32 s85, s85, 2
	s_add_u32 s16, s16, 0x100
	s_addc_u32 s17, s17, 0
	s_add_u32 s25, s25, 0x100
	s_addc_u32 s84, s84, 0
	s_cmp_gt_u32 s85, 13
	s_barrier
	s_cbranch_scc0 .LBB0_1394
	v_mul_f32_e32 v124, v120, v124
	v_exp_f32_e64 v120, -v120
	v_mul_f32_e32 v108, v104, v108
	v_exp_f32_e64 v104, -v104
	v_mul_f32_e32 v92, v88, v92
	v_add_f32_e32 v120, 1.0, v120
	v_rcp_f32_e32 v120, v120
	v_add_f32_e32 v104, 1.0, v104
	v_rcp_f32_e32 v104, v104
	v_exp_f32_e64 v88, -v88
	v_mul_f32_e32 v120, v124, v120
	v_mul_f32_e32 v124, v121, v125
	v_exp_f32_e64 v121, -v121
	v_mul_f32_e32 v104, v108, v104
	v_mul_f32_e32 v108, v105, v109
	v_exp_f32_e64 v105, -v105
	v_add_f32_e32 v121, 1.0, v121
	v_rcp_f32_e32 v121, v121
	v_add_f32_e32 v88, 1.0, v88
	v_rcp_f32_e32 v88, v88
	v_mul_f32_e32 v76, v72, v76
	v_exp_f32_e64 v72, -v72
	v_mul_f32_e32 v121, v124, v121
	v_cvt_pk_bf16_f32 v120, v120, v121
	v_mul_f32_e32 v121, v122, v126
	v_exp_f32_e64 v122, -v122
	v_mul_f32_e32 v116, v112, v116
	v_exp_f32_e64 v112, -v112
	v_add_f32_e32 v105, 1.0, v105
	v_rcp_f32_e32 v105, v105
	v_mul_f32_e32 v88, v92, v88
	v_mul_f32_e32 v92, v89, v93
	v_exp_f32_e64 v89, -v89
	v_add_f32_e32 v72, 1.0, v72
	v_rcp_f32_e32 v72, v72
	v_mul_f32_e32 v60, v56, v60
	v_exp_f32_e64 v56, -v56
	v_add_f32_e32 v122, 1.0, v122
	v_add_f32_e32 v112, 1.0, v112
	v_rcp_f32_e32 v122, v122
	v_rcp_f32_e32 v112, v112
	v_mul_f32_e32 v105, v108, v105
	v_add_f32_e32 v89, 1.0, v89
	v_cvt_pk_bf16_f32 v104, v104, v105
	v_mul_f32_e32 v105, v106, v110
	v_exp_f32_e64 v106, -v106
	v_mul_f32_e32 v100, v96, v100
	v_exp_f32_e64 v96, -v96
	v_rcp_f32_e32 v89, v89
	v_mul_f32_e32 v72, v76, v72
	v_mul_f32_e32 v76, v73, v77
	v_exp_f32_e64 v73, -v73
	v_add_f32_e32 v56, 1.0, v56
	v_rcp_f32_e32 v56, v56
	v_mul_f32_e32 v44, v40, v44
	v_exp_f32_e64 v40, -v40
	v_mul_f32_e32 v121, v121, v122
	v_mul_f32_e32 v122, v123, v127
	v_exp_f32_e64 v123, -v123
	v_mul_f32_e32 v112, v116, v112
	v_mul_f32_e32 v116, v113, v117
	v_exp_f32_e64 v113, -v113
	v_add_f32_e32 v106, 1.0, v106
	v_add_f32_e32 v96, 1.0, v96
	v_mul_f32_e32 v89, v92, v89
	v_add_f32_e32 v73, 1.0, v73
	v_rcp_f32_e32 v106, v106
	v_rcp_f32_e32 v96, v96
	v_cvt_pk_bf16_f32 v88, v88, v89
	v_mul_f32_e32 v89, v90, v94
	v_exp_f32_e64 v90, -v90
	v_mul_f32_e32 v84, v80, v84
	v_exp_f32_e64 v80, -v80
	v_rcp_f32_e32 v73, v73
	v_mul_f32_e32 v56, v60, v56
	v_mul_f32_e32 v60, v57, v61
	v_exp_f32_e64 v57, -v57
	v_add_f32_e32 v40, 1.0, v40
	v_rcp_f32_e32 v40, v40
	v_mul_f32_e32 v28, v24, v28
	v_exp_f32_e64 v24, -v24
	v_add_f32_e32 v123, 1.0, v123
	v_add_f32_e32 v113, 1.0, v113
	v_rcp_f32_e32 v123, v123
	v_rcp_f32_e32 v113, v113
	v_mul_f32_e32 v105, v105, v106
	v_mul_f32_e32 v106, v107, v111
	v_exp_f32_e64 v107, -v107
	v_mul_f32_e32 v96, v100, v96
	v_mul_f32_e32 v100, v97, v101
	v_exp_f32_e64 v97, -v97
	v_add_f32_e32 v90, 1.0, v90
	v_add_f32_e32 v80, 1.0, v80
	v_mul_f32_e32 v73, v76, v73
	v_add_f32_e32 v57, 1.0, v57
	v_rcp_f32_e32 v90, v90
	v_rcp_f32_e32 v80, v80
	v_cvt_pk_bf16_f32 v72, v72, v73
	v_mul_f32_e32 v73, v74, v78
	v_exp_f32_e64 v74, -v74
	v_mul_f32_e32 v68, v64, v68
	v_exp_f32_e64 v64, -v64
	v_rcp_f32_e32 v57, v57
	v_mul_f32_e32 v40, v44, v40
	v_mul_f32_e32 v44, v41, v45
; __device__ __forceinline__ unsigned pk2(float lo, float hi) { unsigned r; asm("v_cvt_pk_bf16_f32 %0, %1, %2" : "=v"(r) : "v"(lo), "v"(hi)); return r; }
;     static __device__ __forceinline__ float sg(float g, float u) { return (g * u) * __builtin_amdgcn_rcpf(1.f + __builtin_amdgcn_exp2f(-g)); }
;     __device__ __forceinline__ void operator()(const f32x4 (&acc)[2][2][4][2], const Unit& u, int wr, int wc, int fr, int fq) const {
; #pragma unroll
;         for (int ai = 0; ai < 2; ++ai)
; #pragma unroll
;             for (int m = 0; m < 4; ++m) {
;                 const int row = u.pm * BM + ai * HALF + wr * 64 + m * 16 + fr;
;                 const f32x4 g0 = acc[ai][0][m][0], u0 = acc[ai][0][m][1], g1 = acc[ai][1][m][0], u1 = acc[ai][1][m][1];
;                 u32x4 o; o.x = pk2(sg(g0[0], u0[0]), sg(g0[1], u0[1])); o.y = pk2(sg(g0[2], u0[2]), sg(g0[3], u0[3]));
;                 o.z = pk2(sg(g1[0], u1[0]), sg(g1[1], u1[1])); o.w = pk2(sg(g1[2], u1[2]), sg(g1[3], u1[3]));
;                 *(u32x4*)(O + (size_t)row * DFF + u.pn * 128 + wc * 32 + fq * 8) = o;
;             }
	v_exp_f32_e64 v41, -v41
	v_add_f32_e32 v24, 1.0, v24
	v_rcp_f32_e32 v24, v24
	v_mul_f32_e32 v12, v8, v12
	v_exp_f32_e64 v8, -v8
	v_mul_f32_e32 v122, v122, v123
	v_mul_f32_e32 v113, v116, v113
	v_cvt_pk_bf16_f32 v121, v121, v122
	v_cvt_pk_bf16_f32 v122, v112, v113
	v_exp_f32_e64 v113, -v114
	v_add_f32_e32 v107, 1.0, v107
	v_add_f32_e32 v97, 1.0, v97
	v_mul_f32_e32 v112, v114, v118
	v_exp_f32_e64 v114, -v115
	v_rcp_f32_e32 v107, v107
	v_rcp_f32_e32 v97, v97
	v_mul_f32_e32 v89, v89, v90
	v_mul_f32_e32 v90, v91, v95
	v_exp_f32_e64 v91, -v91
	v_mul_f32_e32 v80, v84, v80
	v_mul_f32_e32 v84, v81, v85
	v_exp_f32_e64 v81, -v81
	v_add_f32_e32 v74, 1.0, v74
	v_add_f32_e32 v64, 1.0, v64
	v_mul_f32_e32 v57, v60, v57
	v_add_f32_e32 v41, 1.0, v41
	v_rcp_f32_e32 v74, v74
	v_rcp_f32_e32 v64, v64
	v_cvt_pk_bf16_f32 v56, v56, v57
	v_mul_f32_e32 v57, v58, v62
	v_exp_f32_e64 v58, -v58
	v_mul_f32_e32 v52, v48, v52
	v_exp_f32_e64 v48, -v48
	v_rcp_f32_e32 v41, v41
	v_mul_f32_e32 v24, v28, v24
	v_mul_f32_e32 v28, v25, v29
	v_exp_f32_e64 v25, -v25
	v_add_f32_e32 v8, 1.0, v8
	v_rcp_f32_e32 v8, v8
	v_add_f32_e32 v113, 1.0, v113
	v_rcp_f32_e32 v113, v113
	v_add_f32_e32 v114, 1.0, v114
	v_mul_f32_e32 v106, v106, v107
	v_mul_f32_e32 v97, v100, v97
	v_add_f32_e32 v91, 1.0, v91
	v_add_f32_e32 v81, 1.0, v81
	v_rcp_f32_e32 v114, v114
	v_cvt_pk_bf16_f32 v105, v105, v106
	v_cvt_pk_bf16_f32 v106, v96, v97
	v_exp_f32_e64 v97, -v98
	v_rcp_f32_e32 v91, v91
	v_rcp_f32_e32 v81, v81
	v_mul_f32_e32 v73, v73, v74
	v_mul_f32_e32 v74, v75, v79
	v_exp_f32_e64 v75, -v75
	v_mul_f32_e32 v64, v68, v64
	v_mul_f32_e32 v68, v65, v69
	v_exp_f32_e64 v65, -v65
	v_add_f32_e32 v58, 1.0, v58
	v_add_f32_e32 v48, 1.0, v48
	v_mul_f32_e32 v41, v44, v41
	v_add_f32_e32 v25, 1.0, v25
	v_mul_f32_e32 v96, v98, v102
	v_exp_f32_e64 v98, -v99
	v_rcp_f32_e32 v58, v58
	v_rcp_f32_e32 v48, v48
	v_cvt_pk_bf16_f32 v40, v40, v41
	v_mul_f32_e32 v41, v42, v46
	v_exp_f32_e64 v42, -v42
	v_mul_f32_e32 v36, v32, v36
	v_exp_f32_e64 v32, -v32
	v_rcp_f32_e32 v25, v25
	v_mul_f32_e32 v8, v12, v8
	v_mul_f32_e32 v12, v9, v13
	v_exp_f32_e64 v9, -v9
	v_mul_f32_e32 v112, v112, v113
	v_mul_f32_e32 v113, v115, v119
	s_lshl_b32 s16, s15, 7
	v_mul_f32_e32 v113, v113, v114
	v_add_f32_e32 v97, 1.0, v97
	v_mul_f32_e32 v90, v90, v91
	v_mul_f32_e32 v81, v84, v81
	v_add_f32_e32 v75, 1.0, v75
	v_add_f32_e32 v65, 1.0, v65
	v_lshl_add_u32 v139, s81, 8, v136
	s_ashr_i32 s17, s16, 31
	v_cvt_pk_bf16_f32 v123, v112, v113
	v_mov_b64_e32 v[112:113], s[6:7]
	v_rcp_f32_e32 v97, v97
	v_add_f32_e32 v98, 1.0, v98
	v_cvt_pk_bf16_f32 v89, v89, v90
	v_cvt_pk_bf16_f32 v90, v80, v81
	v_exp_f32_e64 v81, -v82
	v_rcp_f32_e32 v75, v75
	v_rcp_f32_e32 v65, v65
	v_mul_f32_e32 v57, v57, v58
	v_mul_f32_e32 v58, v59, v63
	v_exp_f32_e64 v59, -v59
	v_mul_f32_e32 v48, v52, v48
	v_mul_f32_e32 v52, v49, v53
	v_exp_f32_e64 v49, -v49
	v_add_f32_e32 v42, 1.0, v42
	v_add_f32_e32 v32, 1.0, v32
	v_mul_f32_e32 v25, v28, v25
	v_add_f32_e32 v9, 1.0, v9
	v_mad_i64_i32 v[114:115], s[20:21], v139, s33, v[112:113]
	s_lshl_b64 s[16:17], s[16:17], 1
	v_rcp_f32_e32 v98, v98
	v_mul_f32_e32 v80, v82, v86
	v_exp_f32_e64 v82, -v83
	v_rcp_f32_e32 v42, v42
	v_rcp_f32_e32 v32, v32
	v_cvt_pk_bf16_f32 v24, v24, v25
	v_mul_f32_e32 v25, v26, v30
	v_exp_f32_e64 v26, -v26
	v_mul_f32_e32 v20, v16, v20
	v_exp_f32_e64 v16, -v16
	v_rcp_f32_e32 v9, v9
	v_lshl_add_u64 v[114:115], v[114:115], 0, s[16:17]
	v_lshl_add_u64 v[114:115], v[114:115], 0, s[66:67]
	v_lshl_add_u64 v[114:115], v[114:115], 0, v[144:145]
	v_mul_f32_e32 v96, v96, v97
	v_mul_f32_e32 v97, v99, v103
	v_add_f32_e32 v81, 1.0, v81
	v_mul_f32_e32 v74, v74, v75
	v_mul_f32_e32 v65, v68, v65
	v_add_f32_e32 v59, 1.0, v59
	v_add_f32_e32 v49, 1.0, v49
	global_store_dwordx4 v[114:115], v[120:123], off
	v_or_b32_e32 v114, 16, v139
	v_mul_f32_e32 v97, v97, v98
	v_rcp_f32_e32 v81, v81
	v_add_f32_e32 v82, 1.0, v82
	v_cvt_pk_bf16_f32 v73, v73, v74
	v_cvt_pk_bf16_f32 v74, v64, v65
	v_exp_f32_e64 v65, -v66
	v_rcp_f32_e32 v59, v59
	v_rcp_f32_e32 v49, v49
	v_mul_f32_e32 v41, v41, v42
	v_mul_f32_e32 v42, v43, v47
	v_exp_f32_e64 v43, -v43
	v_mul_f32_e32 v32, v36, v32
	v_mul_f32_e32 v36, v33, v37
	v_exp_f32_e64 v33, -v33
	v_add_f32_e32 v26, 1.0, v26
	v_add_f32_e32 v16, 1.0, v16
	v_mul_f32_e32 v9, v12, v9
	v_cvt_pk_bf16_f32 v107, v96, v97
	v_mad_i64_i32 v[96:97], s[20:21], v114, s33, v[112:113]
	v_rcp_f32_e32 v82, v82
	v_mul_f32_e32 v64, v66, v70
	v_exp_f32_e64 v66, -v67
	v_rcp_f32_e32 v26, v26
	v_rcp_f32_e32 v16, v16
	v_cvt_pk_bf16_f32 v8, v8, v9
	v_mul_f32_e32 v9, v10, v14
	v_exp_f32_e64 v10, -v10
	v_mul_f32_e32 v4, v0, v4
	v_exp_f32_e64 v0, -v0
	v_lshl_add_u64 v[96:97], v[96:97], 0, s[16:17]
	v_lshl_add_u64 v[96:97], v[96:97], 0, s[66:67]
	v_lshl_add_u64 v[96:97], v[96:97], 0, v[144:145]
; __device__ __forceinline__ unsigned pk2(float lo, float hi) { unsigned r; asm("v_cvt_pk_bf16_f32 %0, %1, %2" : "=v"(r) : "v"(lo), "v"(hi)); return r; }
; #define PG8_WAIT_V(n) asm volatile("s_waitcnt vmcnt(" #n ")" ::: "memory")
; #define PG8_BAR __builtin_amdgcn_s_barrier()
; template <class Epi>
; __device__ __forceinline__ void gemm_phase(LAS unsigned char* lds, const Gemm g, const StaticOrder& S, const Epi& E) {
;     ...
;         if (!has_next) break;
; #pragma unroll
;         for (int a = 0; a < 2; ++a)
; #pragma unroll
;             for (int b = 0; b < 2; ++b)
; #pragma unroll
;                 for (int m = 0; m < 4; ++m)
; #pragma unroll
;                     for (int n = 0; n < 2; ++n) acc[a][b][m][n] = (f32x4){0.f, 0.f, 0.f, 0.f};
;         cur = nxt; cA = nA; cB = nB; ++ui;
;     }
;     PG8_WAIT_V(0);
;     if (wr == 0) PG8_BAR;
;     PG8_BAR;
;     static __device__ __forceinline__ float sg(float g, float u) { return (g * u) * __builtin_amdgcn_rcpf(1.f + __builtin_amdgcn_exp2f(-g)); }
;     __device__ __forceinline__ void operator()(const f32x4 (&acc)[2][2][4][2], const Unit& u, int wr, int wc, int fr, int fq) const {
; #pragma unroll
;         for (int ai = 0; ai < 2; ++ai)
; #pragma unroll
;             for (int m = 0; m < 4; ++m) {
;                 const int row = u.pm * BM + ai * HALF + wr * 64 + m * 16 + fr;
;                 const f32x4 g0 = acc[ai][0][m][0], u0 = acc[ai][0][m][1], g1 = acc[ai][1][m][0], u1 = acc[ai][1][m][1];
;                 u32x4 o; o.x = pk2(sg(g0[0], u0[0]), sg(g0[1], u0[1])); o.y = pk2(sg(g0[2], u0[2]), sg(g0[3], u0[3]));
;                 o.z = pk2(sg(g1[0], u1[0]), sg(g1[1], u1[1])); o.w = pk2(sg(g1[2], u1[2]), sg(g1[3], u1[3]));
;                 *(u32x4*)(O + (size_t)row * DFF + u.pn * 128 + wc * 32 + fq * 8) = o;
;             }
	v_mul_f32_e32 v80, v80, v81
	v_mul_f32_e32 v81, v83, v87
	v_add_f32_e32 v65, 1.0, v65
	v_mul_f32_e32 v58, v58, v59
	v_mul_f32_e32 v49, v52, v49
	v_add_f32_e32 v43, 1.0, v43
	v_add_f32_e32 v33, 1.0, v33
	global_store_dwordx4 v[96:97], v[104:107], off
	v_or_b32_e32 v96, 32, v139
	v_mul_f32_e32 v81, v81, v82
	v_rcp_f32_e32 v65, v65
	v_add_f32_e32 v66, 1.0, v66
	v_cvt_pk_bf16_f32 v57, v57, v58
	v_cvt_pk_bf16_f32 v58, v48, v49
	v_exp_f32_e64 v49, -v50
	v_rcp_f32_e32 v43, v43
	v_rcp_f32_e32 v33, v33
	v_mul_f32_e32 v25, v25, v26
	v_mul_f32_e32 v26, v27, v31
	v_exp_f32_e64 v27, -v27
	v_mul_f32_e32 v16, v20, v16
	v_mul_f32_e32 v20, v17, v21
	v_exp_f32_e64 v17, -v17
	v_add_f32_e32 v10, 1.0, v10
	v_add_f32_e32 v0, 1.0, v0
	v_cvt_pk_bf16_f32 v91, v80, v81
	v_mad_i64_i32 v[80:81], s[20:21], v96, s33, v[112:113]
	v_rcp_f32_e32 v66, v66
	v_mul_f32_e32 v48, v50, v54
	v_exp_f32_e64 v50, -v51
	v_rcp_f32_e32 v10, v10
	v_rcp_f32_e32 v0, v0
	v_lshl_add_u64 v[80:81], v[80:81], 0, s[16:17]
	v_lshl_add_u64 v[80:81], v[80:81], 0, s[66:67]
	v_lshl_add_u64 v[80:81], v[80:81], 0, v[144:145]
	v_mul_f32_e32 v64, v64, v65
	v_mul_f32_e32 v65, v67, v71
	v_add_f32_e32 v49, 1.0, v49
	v_mul_f32_e32 v42, v42, v43
	v_mul_f32_e32 v33, v36, v33
	v_add_f32_e32 v27, 1.0, v27
	v_add_f32_e32 v17, 1.0, v17
	global_store_dwordx4 v[80:81], v[88:91], off
	v_or_b32_e32 v80, 48, v139
	v_mul_f32_e32 v65, v65, v66
	v_rcp_f32_e32 v49, v49
	v_add_f32_e32 v50, 1.0, v50
	v_cvt_pk_bf16_f32 v41, v41, v42
	v_cvt_pk_bf16_f32 v42, v32, v33
	v_exp_f32_e64 v33, -v34
	v_rcp_f32_e32 v27, v27
	v_rcp_f32_e32 v17, v17
	v_mul_f32_e32 v9, v9, v10
	v_mul_f32_e32 v10, v11, v15
	v_exp_f32_e64 v11, -v11
	v_mul_f32_e32 v0, v4, v0
	v_mul_f32_e32 v4, v1, v5
	v_exp_f32_e64 v1, -v1
	v_cvt_pk_bf16_f32 v75, v64, v65
	v_mad_i64_i32 v[64:65], s[20:21], v80, s33, v[112:113]
	v_rcp_f32_e32 v50, v50
	v_mul_f32_e32 v32, v34, v38
	v_exp_f32_e64 v34, -v35
	v_lshl_add_u64 v[64:65], v[64:65], 0, s[16:17]
	v_lshl_add_u64 v[64:65], v[64:65], 0, s[66:67]
	v_lshl_add_u64 v[64:65], v[64:65], 0, v[144:145]
	v_mul_f32_e32 v48, v48, v49
	v_mul_f32_e32 v49, v51, v55
	v_add_f32_e32 v33, 1.0, v33
	v_mul_f32_e32 v26, v26, v27
	v_mul_f32_e32 v17, v20, v17
	v_add_f32_e32 v11, 1.0, v11
	v_add_f32_e32 v1, 1.0, v1
	global_store_dwordx4 v[64:65], v[72:75], off
	v_add_u32_e32 v64, 0x80, v139
	v_mul_f32_e32 v49, v49, v50
	v_rcp_f32_e32 v33, v33
	v_add_f32_e32 v34, 1.0, v34
	v_cvt_pk_bf16_f32 v25, v25, v26
	v_cvt_pk_bf16_f32 v26, v16, v17
	v_exp_f32_e64 v17, -v18
	v_rcp_f32_e32 v11, v11
	v_rcp_f32_e32 v1, v1
	v_cvt_pk_bf16_f32 v59, v48, v49
	v_mad_i64_i32 v[48:49], s[20:21], v64, s33, v[112:113]
	v_rcp_f32_e32 v34, v34
	v_mul_f32_e32 v16, v18, v22
	v_exp_f32_e64 v18, -v19
	v_lshl_add_u64 v[48:49], v[48:49], 0, s[16:17]
	v_lshl_add_u64 v[48:49], v[48:49], 0, s[66:67]
	v_lshl_add_u64 v[48:49], v[48:49], 0, v[144:145]
	v_mul_f32_e32 v32, v32, v33
	v_mul_f32_e32 v33, v35, v39
	v_add_f32_e32 v17, 1.0, v17
	v_mul_f32_e32 v10, v10, v11
	v_mul_f32_e32 v1, v4, v1
	global_store_dwordx4 v[48:49], v[56:59], off
	v_add_u32_e32 v48, 0x90, v139
	v_mul_f32_e32 v33, v33, v34
	v_rcp_f32_e32 v17, v17
	v_add_f32_e32 v18, 1.0, v18
	v_cvt_pk_bf16_f32 v9, v9, v10
	v_cvt_pk_bf16_f32 v10, v0, v1
	v_exp_f32_e64 v1, -v2
	v_cvt_pk_bf16_f32 v43, v32, v33
	v_mad_i64_i32 v[32:33], s[20:21], v48, s33, v[112:113]
	v_rcp_f32_e32 v18, v18
	v_mul_f32_e32 v0, v2, v6
	v_exp_f32_e64 v2, -v3
	v_lshl_add_u64 v[32:33], v[32:33], 0, s[16:17]
	v_lshl_add_u64 v[32:33], v[32:33], 0, s[66:67]
	v_lshl_add_u64 v[32:33], v[32:33], 0, v[144:145]
	v_mul_f32_e32 v16, v16, v17
	v_mul_f32_e32 v17, v19, v23
	v_add_f32_e32 v1, 1.0, v1
	global_store_dwordx4 v[32:33], v[40:43], off
	v_add_u32_e32 v32, 0xa0, v139
	v_mul_f32_e32 v17, v17, v18
	v_rcp_f32_e32 v1, v1
	v_add_f32_e32 v2, 1.0, v2
	v_cvt_pk_bf16_f32 v27, v16, v17
	v_mad_i64_i32 v[16:17], s[20:21], v32, s33, v[112:113]
	v_rcp_f32_e32 v2, v2
	v_lshl_add_u64 v[16:17], v[16:17], 0, s[16:17]
	v_lshl_add_u64 v[16:17], v[16:17], 0, s[66:67]
	v_lshl_add_u64 v[16:17], v[16:17], 0, v[144:145]
	v_mul_f32_e32 v0, v0, v1
	v_mul_f32_e32 v1, v3, v7
	global_store_dwordx4 v[16:17], v[24:27], off
	v_add_u32_e32 v16, 0xb0, v139
	v_mul_f32_e32 v1, v1, v2
	v_cvt_pk_bf16_f32 v11, v0, v1
	v_mad_i64_i32 v[0:1], s[20:21], v16, s33, v[112:113]
	v_lshl_add_u64 v[0:1], v[0:1], 0, s[16:17]
	v_lshl_add_u64 v[0:1], v[0:1], 0, s[66:67]
	v_lshl_add_u64 v[0:1], v[0:1], 0, v[144:145]
	s_and_b64 vcc, exec, s[0:1]
	s_mov_b32 s15, s8
	s_mov_b32 s81, s80
	s_mov_b64 s[20:21], s[12:13]
	s_mov_b64 s[16:17], s[10:11]
	global_store_dwordx4 v[0:1], v[8:11], off
	s_cbranch_vccz .LBB0_1391
	s_waitcnt vmcnt(0)
	s_cmpk_gt_u32 s23, 0xff
	s_cbranch_scc1 .LBB0_1398
	s_barrier

; #define PG8_STAGE(bufoff, gbase, voff) do { _Pragma("unroll") for (int _i = 0; _i < 2; ++_i) \
;         __builtin_amdgcn_global_load_lds((const unsigned*)((const char*)(gbase) + (voff)[_i]), (LAS unsigned*)(lds + (bufoff) + ldsw + _i * 8192), 16, 0, 0); } while (0)
; #define PG8_LDA(dst, b, h) do { _Pragma("unroll") for (int m = 0; m < 4; ++m) _Pragma("unroll") for (int k = 0; k < 2; ++k) dst[m][k] = *(const LAS bf16x8*)(lds + PG8_SA(b, h) + aoff + m * 2048 + k * 1024); } while (0)
; #define PG8_LDB(dst, b, h) do { _Pragma("unroll") for (int n = 0; n < 2; ++n) _Pragma("unroll") for (int k = 0; k < 2; ++k) dst[n][k] = *(const LAS bf16x8*)(lds + PG8_SB(b, h) + boff + n * 2048 + k * 1024); } while (0)
; #define PG8_MMA(ai, bj, At, Bt) do { __builtin_amdgcn_s_setprio(1); _Pragma("unroll") for (int m = 0; m < 4; ++m) _Pragma("unroll") for (int n = 0; n < 2; ++n) _Pragma("unroll") for (int k = 0; k < 2; ++k) \
;         acc[ai][bj][m][n] = __builtin_amdgcn_mfma_f32_16x16x32_bf16(Bt[n][k], At[m][k], acc[ai][bj][m][n], 0, 0, 0); __builtin_amdgcn_s_setprio(0); } while (0)
; #define PG8_WAIT_L(n) asm volatile("s_waitcnt lgkmcnt(" #n ")" ::: "memory")
; #define PG8_BAR __builtin_amdgcn_s_barrier()
; #define PG8_SCHED __builtin_amdgcn_sched_barrier(0)
; template <class Epi>
; __device__ __forceinline__ void gemm_phase(LAS unsigned char* lds, const Gemm g, const StaticOrder& S, const Epi& E) {
;     ...
;             const bool last = (t == nt - 2);
;             const char* a1 = cA + (size_t)(t + 1) * kstep;
;             const char* a2 = last ? nA : cA + (size_t)(t + 2) * kstep; const char* b2 = last ? nB : cB + (size_t)(t + 2) * kstep;
;             const char* a3 = a2 + kstep; const char* b3 = b2 + kstep;
;             PG8_LDB(B0, 0, 0); PG8_SCHED; PG8_LDA(At, 0, 0); PG8_STAGE(PG8_SA(1, 1), a1 + hA, voffA);
;             PG8_WAIT_L(8); PG8_BAR; PG8_WAIT_L(0); PG8_MMA(0, 0, At, B0); PG8_BAR; PG8_SCHED;
;             PG8_LDB(B1, 0, 1); PG8_STAGE(PG8_SB(0, 0), b2, voffB);
;             PG8_BAR; PG8_WAIT_L(0); PG8_MMA(0, 1, At, B1); PG8_BAR;
;             PG8_LDA(At, 0, 1); PG8_STAGE(PG8_SA(0, 0), a2, voffA);
;             PG8_BAR; PG8_WAIT_L(0); PG8_MMA(1, 0, At, B0); PG8_BAR; PG8_SCHED;
.LBB0_1462:
	s_add_u32 s12, s10, 0x100
	s_addc_u32 s13, s11, 0
	s_add_i32 s26, 0, 0x10000
	v_add_u32_e32 v142, s26, v139
	ds_read_b128 v[134:137], v142
	ds_read_b128 v[146:149], v142 offset:1024
	ds_read_b128 v[150:153], v142 offset:2048
	ds_read_b128 v[154:157], v142 offset:3072
	s_cmp_eq_u32 s78, 40
	s_cselect_b32 s21, s5, s13
	s_cselect_b32 s20, s4, s12
	s_cselect_b32 s17, s7, s25
	s_cselect_b32 s16, s6, s24
	s_add_i32 m0, s63, 0xc000
	ds_read_b128 v[158:161], v141
	ds_read_b128 v[162:165], v141 offset:1024
	ds_read_b128 v[166:169], v141 offset:2048
	ds_read_b128 v[170:173], v141 offset:3072
	ds_read_b128 v[174:177], v141 offset:4096
	ds_read_b128 v[178:181], v141 offset:5120
	ds_read_b128 v[182:185], v141 offset:6144
	ds_read_b128 v[186:189], v141 offset:7168
	global_load_lds_dwordx4 v130, s[10:11]
	s_add_i32 m0, s63, 0xe000
	v_lshl_add_u64 v[142:143], s[10:11], 0, v[132:133]
	global_load_lds_dwordx4 v[142:143], off
	s_waitcnt lgkmcnt(8)
	s_barrier
	s_waitcnt lgkmcnt(0)
	v_mfma_f32_16x16x32_bf16 v[124:127], v[134:137], v[158:161], v[124:127]
	v_mfma_f32_16x16x32_bf16 v[120:123], v[150:153], v[158:161], v[120:123]
	v_mfma_f32_16x16x32_bf16 v[116:119], v[134:137], v[166:169], v[116:119]
	v_mfma_f32_16x16x32_bf16 v[108:111], v[150:153], v[166:169], v[108:111]
	v_mfma_f32_16x16x32_bf16 v[100:103], v[134:137], v[174:177], v[100:103]
	v_mfma_f32_16x16x32_bf16 v[92:95], v[150:153], v[174:177], v[92:95]
	v_mfma_f32_16x16x32_bf16 v[84:87], v[134:137], v[182:185], v[84:87]
	v_mfma_f32_16x16x32_bf16 v[76:79], v[150:153], v[182:185], v[76:79]
	v_mfma_f32_16x16x32_bf16 v[124:127], v[146:149], v[162:165], v[124:127]
	v_mfma_f32_16x16x32_bf16 v[120:123], v[154:157], v[162:165], v[120:123]
	v_mfma_f32_16x16x32_bf16 v[116:119], v[146:149], v[170:173], v[116:119]
	v_mfma_f32_16x16x32_bf16 v[108:111], v[154:157], v[170:173], v[108:111]
	v_mfma_f32_16x16x32_bf16 v[100:103], v[146:149], v[178:181], v[100:103]
	v_mfma_f32_16x16x32_bf16 v[92:95], v[154:157], v[178:181], v[92:95]
	v_mfma_f32_16x16x32_bf16 v[84:87], v[146:149], v[186:189], v[84:87]
	v_mfma_f32_16x16x32_bf16 v[76:79], v[154:157], v[186:189], v[76:79]
	s_barrier
	s_add_i32 s27, 0, 0x14000
	v_add_u32_e32 v142, s27, v139
	s_add_i32 s10, s26, s61
	ds_read_b128 v[196:199], v142
	ds_read_b128 v[200:203], v142 offset:1024
	ds_read_b128 v[204:207], v142 offset:2048
	ds_read_b128 v[214:217], v142 offset:3072
	v_lshl_add_u64 v[142:143], s[16:17], 0, v[144:145]
	s_mov_b32 m0, s10
	v_lshl_add_u64 v[192:193], s[16:17], 0, v[128:129]
	global_load_lds_dwordx4 v[142:143], off
	s_add_i32 m0, s10, 0x2000
	s_nop 0
	global_load_lds_dwordx4 v[192:193], off
	s_barrier
	s_waitcnt lgkmcnt(0)
	v_mfma_f32_16x16x32_bf16 v[112:115], v[196:199], v[158:161], v[112:115]
	v_mfma_f32_16x16x32_bf16 v[104:107], v[204:207], v[158:161], v[104:107]
	v_mfma_f32_16x16x32_bf16 v[96:99], v[196:199], v[166:169], v[96:99]
	v_mfma_f32_16x16x32_bf16 v[88:91], v[204:207], v[166:169], v[88:91]
	v_mfma_f32_16x16x32_bf16 v[80:83], v[196:199], v[174:177], v[80:83]
	v_mfma_f32_16x16x32_bf16 v[72:75], v[204:207], v[174:177], v[72:75]
	v_mfma_f32_16x16x32_bf16 v[68:71], v[196:199], v[182:185], v[68:71]
	v_mfma_f32_16x16x32_bf16 v[64:67], v[204:207], v[182:185], v[64:67]
	v_mfma_f32_16x16x32_bf16 v[112:115], v[200:203], v[162:165], v[112:115]
	v_mfma_f32_16x16x32_bf16 v[104:107], v[214:217], v[162:165], v[104:107]
	v_mfma_f32_16x16x32_bf16 v[96:99], v[200:203], v[170:173], v[96:99]
	v_mfma_f32_16x16x32_bf16 v[88:91], v[214:217], v[170:173], v[88:91]
	v_mfma_f32_16x16x32_bf16 v[80:83], v[200:203], v[178:181], v[80:83]
	v_mfma_f32_16x16x32_bf16 v[72:75], v[214:217], v[178:181], v[72:75]
	v_mfma_f32_16x16x32_bf16 v[68:71], v[200:203], v[186:189], v[68:71]
	v_mfma_f32_16x16x32_bf16 v[64:67], v[214:217], v[186:189], v[64:67]
	s_mov_b32 m0, s63
	v_lshl_add_u64 v[218:219], s[20:21], 0, v[144:145]
	s_barrier
	ds_read_b128 v[158:161], v141 offset:16384
	ds_read_b128 v[162:165], v141 offset:17408
	ds_read_b128 v[166:169], v141 offset:18432
	ds_read_b128 v[170:173], v141 offset:19456
	ds_read_b128 v[174:177], v141 offset:20480
	ds_read_b128 v[178:181], v141 offset:21504
	ds_read_b128 v[182:185], v141 offset:22528
	ds_read_b128 v[186:189], v141 offset:23552
	global_load_lds_dwordx4 v[218:219], off
	s_mov_b32 m0, s64
	v_lshl_add_u64 v[220:221], s[20:21], 0, v[128:129]
	global_load_lds_dwordx4 v[220:221], off
	s_barrier
	s_waitcnt lgkmcnt(0)
	v_mfma_f32_16x16x32_bf16 v[60:63], v[134:137], v[158:161], v[60:63]
	v_mfma_f32_16x16x32_bf16 v[56:59], v[150:153], v[158:161], v[56:59]
	v_mfma_f32_16x16x32_bf16 v[52:55], v[134:137], v[166:169], v[52:55]
	v_mfma_f32_16x16x32_bf16 v[44:47], v[150:153], v[166:169], v[44:47]
	v_mfma_f32_16x16x32_bf16 v[36:39], v[134:137], v[174:177], v[36:39]
	v_mfma_f32_16x16x32_bf16 v[28:31], v[150:153], v[174:177], v[28:31]
	v_mfma_f32_16x16x32_bf16 v[20:23], v[134:137], v[182:185], v[20:23]
	v_mfma_f32_16x16x32_bf16 v[12:15], v[150:153], v[182:185], v[12:15]
	v_mfma_f32_16x16x32_bf16 v[60:63], v[146:149], v[162:165], v[60:63]
	v_mfma_f32_16x16x32_bf16 v[56:59], v[154:157], v[162:165], v[56:59]
	v_mfma_f32_16x16x32_bf16 v[52:55], v[146:149], v[170:173], v[52:55]
	v_mfma_f32_16x16x32_bf16 v[44:47], v[154:157], v[170:173], v[44:47]
	v_mfma_f32_16x16x32_bf16 v[36:39], v[146:149], v[178:181], v[36:39]
	v_mfma_f32_16x16x32_bf16 v[28:31], v[154:157], v[178:181], v[28:31]
	v_mfma_f32_16x16x32_bf16 v[20:23], v[146:149], v[186:189], v[20:23]
	v_mfma_f32_16x16x32_bf16 v[12:15], v[154:157], v[186:189], v[12:15]
	s_barrier
; #define PG8_STAGE(bufoff, gbase, voff) do { _Pragma("unroll") for (int _i = 0; _i < 2; ++_i) \
;         __builtin_amdgcn_global_load_lds((const unsigned*)((const char*)(gbase) + (voff)[_i]), (LAS unsigned*)(lds + (bufoff) + ldsw + _i * 8192), 16, 0, 0); } while (0)
; #define PG8_LDA(dst, b, h) do { _Pragma("unroll") for (int m = 0; m < 4; ++m) _Pragma("unroll") for (int k = 0; k < 2; ++k) dst[m][k] = *(const LAS bf16x8*)(lds + PG8_SA(b, h) + aoff + m * 2048 + k * 1024); } while (0)
; #define PG8_LDB(dst, b, h) do { _Pragma("unroll") for (int n = 0; n < 2; ++n) _Pragma("unroll") for (int k = 0; k < 2; ++k) dst[n][k] = *(const LAS bf16x8*)(lds + PG8_SB(b, h) + boff + n * 2048 + k * 1024); } while (0)
; #define PG8_MMA(ai, bj, At, Bt) do { __builtin_amdgcn_s_setprio(1); _Pragma("unroll") for (int m = 0; m < 4; ++m) _Pragma("unroll") for (int n = 0; n < 2; ++n) _Pragma("unroll") for (int k = 0; k < 2; ++k) \
;         acc[ai][bj][m][n] = __builtin_amdgcn_mfma_f32_16x16x32_bf16(Bt[n][k], At[m][k], acc[ai][bj][m][n], 0, 0, 0); __builtin_amdgcn_s_setprio(0); } while (0)
; #define PG8_WAIT_V(n) asm volatile("s_waitcnt vmcnt(" #n ")" ::: "memory")
; #define PG8_WAIT_L(n) asm volatile("s_waitcnt lgkmcnt(" #n ")" ::: "memory")
; #define PG8_BAR __builtin_amdgcn_s_barrier()
; #define PG8_SCHED __builtin_amdgcn_sched_barrier(0)
; template <class Epi>
; __device__ __forceinline__ void gemm_phase(LAS unsigned char* lds, const Gemm g, const StaticOrder& S, const Epi& E) {
;     ...
;             PG8_STAGE(PG8_SB(0, 1), b2 + hB, voffB);
;             PG8_WAIT_V(6); PG8_BAR; PG8_MMA(1, 1, At, B1); PG8_BAR;
;             PG8_LDB(B0, 1, 0); PG8_SCHED; PG8_LDA(At, 1, 0); PG8_STAGE(PG8_SA(0, 1), a2 + hA, voffA);
;             PG8_WAIT_L(8); PG8_BAR; PG8_WAIT_L(0); PG8_MMA(0, 0, At, B0); PG8_BAR; PG8_SCHED;
;             PG8_LDB(B1, 1, 1); PG8_STAGE(PG8_SB(1, 0), b3, voffB);
;             PG8_BAR; PG8_WAIT_L(0); PG8_MMA(0, 1, At, B1); PG8_BAR;
;             PG8_LDA(At, 1, 1); PG8_STAGE(PG8_SA(1, 0), a3, voffA);
	s_add_u32 s10, s16, 0xb0000
	s_addc_u32 s11, s17, 0
	s_add_i32 s26, s27, s61
	s_mov_b32 m0, s26
	s_nop 0
	global_load_lds_dwordx4 v144, s[10:11]
	s_add_i32 m0, s26, 0x2000
	s_nop 0
	global_load_lds_dwordx4 v128, s[10:11]
	s_waitcnt vmcnt(6)
	s_barrier
	v_mfma_f32_16x16x32_bf16 v[48:51], v[196:199], v[158:161], v[48:51]
	v_mfma_f32_16x16x32_bf16 v[40:43], v[204:207], v[158:161], v[40:43]
	v_mfma_f32_16x16x32_bf16 v[32:35], v[196:199], v[166:169], v[32:35]
	v_mfma_f32_16x16x32_bf16 v[24:27], v[204:207], v[166:169], v[24:27]
	v_mfma_f32_16x16x32_bf16 v[16:19], v[196:199], v[174:177], v[16:19]
	v_mfma_f32_16x16x32_bf16 v[8:11], v[204:207], v[174:177], v[8:11]
	v_mfma_f32_16x16x32_bf16 v[4:7], v[196:199], v[182:185], v[4:7]
	v_mfma_f32_16x16x32_bf16 v[0:3], v[204:207], v[182:185], v[0:3]
	v_mfma_f32_16x16x32_bf16 v[48:51], v[200:203], v[162:165], v[48:51]
	v_mfma_f32_16x16x32_bf16 v[40:43], v[214:217], v[162:165], v[40:43]
	v_mfma_f32_16x16x32_bf16 v[32:35], v[200:203], v[170:173], v[32:35]
	v_mfma_f32_16x16x32_bf16 v[24:27], v[214:217], v[170:173], v[24:27]
	v_mfma_f32_16x16x32_bf16 v[16:19], v[200:203], v[178:181], v[16:19]
	v_mfma_f32_16x16x32_bf16 v[8:11], v[214:217], v[178:181], v[8:11]
	v_mfma_f32_16x16x32_bf16 v[4:7], v[200:203], v[186:189], v[4:7]
	v_mfma_f32_16x16x32_bf16 v[0:3], v[214:217], v[186:189], v[0:3]
	s_add_i32 s26, 0, 0x18000
	v_add_u32_e32 v154, s26, v139
	s_barrier
	ds_read_b128 v[134:137], v154
	ds_read_b128 v[146:149], v154 offset:1024
	ds_read_b128 v[150:153], v154 offset:2048
	ds_read_b128 v[154:157], v154 offset:3072
	s_add_u32 s10, s20, 0xb0000
	s_addc_u32 s11, s21, 0
	s_mov_b32 m0, s65
	ds_read_b128 v[158:161], v141 offset:32768
	ds_read_b128 v[162:165], v141 offset:33792
	ds_read_b128 v[166:169], v141 offset:34816
	ds_read_b128 v[170:173], v141 offset:35840
	ds_read_b128 v[174:177], v141 offset:36864
	ds_read_b128 v[178:181], v141 offset:37888
	ds_read_b128 v[182:185], v141 offset:38912
	global_load_lds_dwordx4 v144, s[10:11]
	s_mov_b32 m0, s68
	ds_read_b128 v[186:189], v141 offset:39936
	global_load_lds_dwordx4 v128, s[10:11]
	s_waitcnt lgkmcnt(8)
	s_barrier
	s_waitcnt lgkmcnt(0)
	v_mfma_f32_16x16x32_bf16 v[124:127], v[134:137], v[158:161], v[124:127]
	v_mfma_f32_16x16x32_bf16 v[120:123], v[150:153], v[158:161], v[120:123]
	v_mfma_f32_16x16x32_bf16 v[116:119], v[134:137], v[166:169], v[116:119]
	v_mfma_f32_16x16x32_bf16 v[108:111], v[150:153], v[166:169], v[108:111]
	v_mfma_f32_16x16x32_bf16 v[100:103], v[134:137], v[174:177], v[100:103]
	v_mfma_f32_16x16x32_bf16 v[92:95], v[150:153], v[174:177], v[92:95]
	v_mfma_f32_16x16x32_bf16 v[84:87], v[134:137], v[182:185], v[84:87]
	v_mfma_f32_16x16x32_bf16 v[76:79], v[150:153], v[182:185], v[76:79]
	v_mfma_f32_16x16x32_bf16 v[124:127], v[146:149], v[162:165], v[124:127]
	v_mfma_f32_16x16x32_bf16 v[120:123], v[154:157], v[162:165], v[120:123]
	v_mfma_f32_16x16x32_bf16 v[116:119], v[146:149], v[170:173], v[116:119]
	v_mfma_f32_16x16x32_bf16 v[108:111], v[154:157], v[170:173], v[108:111]
	v_mfma_f32_16x16x32_bf16 v[100:103], v[146:149], v[178:181], v[100:103]
	v_mfma_f32_16x16x32_bf16 v[92:95], v[154:157], v[178:181], v[92:95]
	v_mfma_f32_16x16x32_bf16 v[84:87], v[146:149], v[186:189], v[84:87]
	v_mfma_f32_16x16x32_bf16 v[76:79], v[154:157], v[186:189], v[76:79]
	s_barrier
	s_add_i32 s20, 0, 0x1c000
	s_add_i32 s10, s26, s61
	v_add_u32_e32 v190, s20, v139
	v_lshl_add_u64 v[142:143], v[142:143], 0, s[88:89]
	s_mov_b32 m0, s10
	ds_read_b128 v[196:199], v190
	ds_read_b128 v[200:203], v190 offset:1024
	ds_read_b128 v[204:207], v190 offset:2048
	ds_read_b128 v[214:217], v190 offset:3072
	global_load_lds_dwordx4 v[142:143], off
	s_add_i32 m0, s10, 0x2000
	v_lshl_add_u64 v[142:143], v[192:193], 0, s[88:89]
	global_load_lds_dwordx4 v[142:143], off
	s_barrier
	s_waitcnt lgkmcnt(0)
	v_mfma_f32_16x16x32_bf16 v[112:115], v[196:199], v[158:161], v[112:115]
	v_mfma_f32_16x16x32_bf16 v[104:107], v[204:207], v[158:161], v[104:107]
	v_mfma_f32_16x16x32_bf16 v[96:99], v[196:199], v[166:169], v[96:99]
	v_mfma_f32_16x16x32_bf16 v[88:91], v[204:207], v[166:169], v[88:91]
	v_mfma_f32_16x16x32_bf16 v[80:83], v[196:199], v[174:177], v[80:83]
	v_mfma_f32_16x16x32_bf16 v[72:75], v[204:207], v[174:177], v[72:75]
	v_mfma_f32_16x16x32_bf16 v[68:71], v[196:199], v[182:185], v[68:71]
	v_mfma_f32_16x16x32_bf16 v[64:67], v[204:207], v[182:185], v[64:67]
	v_mfma_f32_16x16x32_bf16 v[112:115], v[200:203], v[162:165], v[112:115]
	v_mfma_f32_16x16x32_bf16 v[104:107], v[214:217], v[162:165], v[104:107]
	v_mfma_f32_16x16x32_bf16 v[96:99], v[200:203], v[170:173], v[96:99]
	v_mfma_f32_16x16x32_bf16 v[88:91], v[214:217], v[170:173], v[88:91]
	v_mfma_f32_16x16x32_bf16 v[80:83], v[200:203], v[178:181], v[80:83]
	v_mfma_f32_16x16x32_bf16 v[72:75], v[214:217], v[178:181], v[72:75]
	v_mfma_f32_16x16x32_bf16 v[68:71], v[200:203], v[186:189], v[68:71]
	v_mfma_f32_16x16x32_bf16 v[64:67], v[214:217], v[186:189], v[64:67]
	s_mov_b32 m0, s69
	v_lshl_add_u64 v[142:143], v[218:219], 0, s[88:89]
	s_barrier
	ds_read_b128 v[158:161], v141 offset:49152
	ds_read_b128 v[162:165], v141 offset:50176
	ds_read_b128 v[166:169], v141 offset:51200
	ds_read_b128 v[170:173], v141 offset:52224
	ds_read_b128 v[174:177], v141 offset:53248
	ds_read_b128 v[178:181], v141 offset:54272
	ds_read_b128 v[182:185], v141 offset:55296
	ds_read_b128 v[186:189], v141 offset:56320
	global_load_lds_dwordx4 v[142:143], off
	s_mov_b32 m0, s70
	v_lshl_add_u64 v[142:143], v[220:221], 0, s[88:89]
	global_load_lds_dwordx4 v[142:143], off
	s_barrier
; #define PG8_STAGE(bufoff, gbase, voff) do { _Pragma("unroll") for (int _i = 0; _i < 2; ++_i) \
;         __builtin_amdgcn_global_load_lds((const unsigned*)((const char*)(gbase) + (voff)[_i]), (LAS unsigned*)(lds + (bufoff) + ldsw + _i * 8192), 16, 0, 0); } while (0)
; #define PG8_MMA(ai, bj, At, Bt) do { __builtin_amdgcn_s_setprio(1); _Pragma("unroll") for (int m = 0; m < 4; ++m) _Pragma("unroll") for (int n = 0; n < 2; ++n) _Pragma("unroll") for (int k = 0; k < 2; ++k) \
;         acc[ai][bj][m][n] = __builtin_amdgcn_mfma_f32_16x16x32_bf16(Bt[n][k], At[m][k], acc[ai][bj][m][n], 0, 0, 0); __builtin_amdgcn_s_setprio(0); } while (0)
; #define PG8_WAIT_V(n) asm volatile("s_waitcnt vmcnt(" #n ")" ::: "memory")
; #define PG8_WAIT_L(n) asm volatile("s_waitcnt lgkmcnt(" #n ")" ::: "memory")
; #define PG8_BAR __builtin_amdgcn_s_barrier()
; #define PG8_SCHED __builtin_amdgcn_sched_barrier(0)
; template <class Epi>
; __device__ __forceinline__ void gemm_phase(LAS unsigned char* lds, const Gemm g, const StaticOrder& S, const Epi& E) {
;     ...
;             PG8_BAR; PG8_WAIT_L(0); PG8_MMA(1, 0, At, B0); PG8_BAR; PG8_SCHED;
;             PG8_STAGE(PG8_SB(1, 1), b3 + hB, voffB);
;             PG8_WAIT_V(6); PG8_BAR; PG8_MMA(1, 1, At, B1); PG8_BAR;
	s_waitcnt lgkmcnt(0)
	v_mfma_f32_16x16x32_bf16 v[60:63], v[134:137], v[158:161], v[60:63]
	v_mfma_f32_16x16x32_bf16 v[56:59], v[150:153], v[158:161], v[56:59]
	v_mfma_f32_16x16x32_bf16 v[52:55], v[134:137], v[166:169], v[52:55]
	v_mfma_f32_16x16x32_bf16 v[44:47], v[150:153], v[166:169], v[44:47]
	v_mfma_f32_16x16x32_bf16 v[36:39], v[134:137], v[174:177], v[36:39]
	v_mfma_f32_16x16x32_bf16 v[28:31], v[150:153], v[174:177], v[28:31]
	v_mfma_f32_16x16x32_bf16 v[20:23], v[134:137], v[182:185], v[20:23]
	v_mfma_f32_16x16x32_bf16 v[12:15], v[150:153], v[182:185], v[12:15]
	v_mfma_f32_16x16x32_bf16 v[60:63], v[146:149], v[162:165], v[60:63]
	v_mfma_f32_16x16x32_bf16 v[56:59], v[154:157], v[162:165], v[56:59]
	v_mfma_f32_16x16x32_bf16 v[52:55], v[146:149], v[170:173], v[52:55]
	v_mfma_f32_16x16x32_bf16 v[44:47], v[154:157], v[170:173], v[44:47]
	v_mfma_f32_16x16x32_bf16 v[36:39], v[146:149], v[178:181], v[36:39]
	v_mfma_f32_16x16x32_bf16 v[28:31], v[154:157], v[178:181], v[28:31]
	v_mfma_f32_16x16x32_bf16 v[20:23], v[146:149], v[186:189], v[20:23]
	v_mfma_f32_16x16x32_bf16 v[12:15], v[154:157], v[186:189], v[12:15]
	s_barrier
	s_add_u32 s10, s16, 0xb0080
	s_addc_u32 s11, s17, 0
	s_add_i32 s16, s20, s61
	s_mov_b32 m0, s16
	s_nop 0
	global_load_lds_dwordx4 v144, s[10:11]
	s_add_i32 m0, s16, 0x2000
	s_nop 0
	global_load_lds_dwordx4 v128, s[10:11]
	s_waitcnt vmcnt(6)
	s_barrier
	v_mfma_f32_16x16x32_bf16 v[48:51], v[196:199], v[158:161], v[48:51]
	v_mfma_f32_16x16x32_bf16 v[40:43], v[204:207], v[158:161], v[40:43]
	v_mfma_f32_16x16x32_bf16 v[32:35], v[196:199], v[166:169], v[32:35]
	v_mfma_f32_16x16x32_bf16 v[24:27], v[204:207], v[166:169], v[24:27]
	v_mfma_f32_16x16x32_bf16 v[16:19], v[196:199], v[174:177], v[16:19]
	v_mfma_f32_16x16x32_bf16 v[8:11], v[204:207], v[174:177], v[8:11]
	v_mfma_f32_16x16x32_bf16 v[4:7], v[196:199], v[182:185], v[4:7]
	v_mfma_f32_16x16x32_bf16 v[0:3], v[204:207], v[182:185], v[0:3]
	v_mfma_f32_16x16x32_bf16 v[48:51], v[200:203], v[162:165], v[48:51]
	v_mfma_f32_16x16x32_bf16 v[40:43], v[214:217], v[162:165], v[40:43]
	v_mfma_f32_16x16x32_bf16 v[32:35], v[200:203], v[170:173], v[32:35]
	v_mfma_f32_16x16x32_bf16 v[24:27], v[214:217], v[170:173], v[24:27]
	v_mfma_f32_16x16x32_bf16 v[16:19], v[200:203], v[178:181], v[16:19]
	v_mfma_f32_16x16x32_bf16 v[8:11], v[214:217], v[178:181], v[8:11]
	v_mfma_f32_16x16x32_bf16 v[4:7], v[200:203], v[186:189], v[4:7]
	v_mfma_f32_16x16x32_bf16 v[0:3], v[214:217], v[186:189], v[0:3]
	s_add_i32 s78, s78, 2
	s_add_u32 s24, s24, 0x100
	s_addc_u32 s25, s25, 0
	s_cmp_gt_u32 s78, 41
	s_mov_b64 s[10:11], s[12:13]
	s_barrier
	s_cbranch_scc0 .LBB0_1462
; __device__ __forceinline__ unsigned pk2(float lo, float hi) { unsigned r; asm("v_cvt_pk_bf16_f32 %0, %1, %2" : "=v"(r) : "v"(lo), "v"(hi)); return r; }
; #define PG8_WAIT_V(n) asm volatile("s_waitcnt vmcnt(" #n ")" ::: "memory")
; #define PG8_BAR __builtin_amdgcn_s_barrier()
; template <class Epi>
; __device__ __forceinline__ void gemm_phase(LAS unsigned char* lds, const Gemm g, const StaticOrder& S, const Epi& E) {
;     ...
;         if (!has_next) break;
; #pragma unroll
;         for (int a = 0; a < 2; ++a)
; #pragma unroll
;             for (int b = 0; b < 2; ++b)
; #pragma unroll
;                 for (int m = 0; m < 4; ++m)
; #pragma unroll
;                     for (int n = 0; n < 2; ++n) acc[a][b][m][n] = (f32x4){0.f, 0.f, 0.f, 0.f};
;         cur = nxt; cA = nA; cB = nB; ++ui;
;     }
;     PG8_WAIT_V(0);
;     if (wr == 0) PG8_BAR;
;     PG8_BAR;
;     __device__ __forceinline__ void operator()(const f32x4 (&acc)[2][2][4][2], const Unit& u, int wr, int wc, int fr, int fq) const {
;     ...
;         const int row_t = rmap == 1 ? odd_phys_row0(u.pm, grp) : (rmap == 2 ? odd_phys_row0(u.pm % (BG * TPB), u.pm / (BG * TPB)) : u.pm * BM);
;         int c = col_t + 64 * wc + 16 * fq;
;         if (mode == 2) c = (c >> 6) * 96 + (c & 63);
; #pragma unroll
;         for (int ai = 0; ai < 2; ++ai)
; #pragma unroll
;             for (int m = 0; m < 4; ++m) {
;                 const int row = row_t + ai * HALF + wr * 64 + m * 16 + fr;
;                 bf16_t* rp = O + (size_t)row * ldc + c;
; #pragma unroll
;                 for (int bj = 0; bj < 2; ++bj) {
;                     const f32x4 v0 = acc[ai][bj][m][0], v1 = acc[ai][bj][m][1];
;                     u32x4 o; o.x = pk2(v0[0], v0[1]); o.y = pk2(v0[2], v0[3]); o.z = pk2(v1[0], v1[1]); o.w = pk2(v1[2], v1[3]);
;                     *(u32x4*)(rp + 8 * bj) = o;
;                 }
;             }
	v_lshl_add_u32 v134, s77, 8, v138
	v_cvt_pk_bf16_f32 v68, v68, v69
	v_cvt_pk_bf16_f32 v69, v70, v71
	v_cvt_pk_bf16_f32 v70, v64, v65
	v_add_u32_e32 v64, 0x80, v134
	v_lshl_or_b32 v136, s15, 8, v140
	v_ashrrev_i32_e32 v135, 31, v134
	v_cvt_pk_bf16_f32 v112, v112, v113
	v_cvt_pk_bf16_f32 v113, v114, v115
	v_cvt_pk_bf16_f32 v114, v104, v105
	v_or_b32_e32 v104, 16, v134
	v_ashrrev_i32_e32 v65, 31, v64
	v_cvt_pk_bf16_f32 v48, v48, v49
	v_cvt_pk_bf16_f32 v49, v50, v51
	v_cvt_pk_bf16_f32 v50, v40, v41
	v_add_u32_e32 v40, 0x90, v134
	v_ashrrev_i32_e32 v137, 31, v136
	v_lshlrev_b64 v[142:143], 11, v[134:135]
	v_ashrrev_i32_e32 v105, 31, v104
	v_cvt_pk_bf16_f32 v96, v96, v97
	v_cvt_pk_bf16_f32 v97, v98, v99
	v_cvt_pk_bf16_f32 v98, v88, v89
	v_or_b32_e32 v88, 32, v134
	v_lshlrev_b64 v[64:65], 11, v[64:65]
	v_ashrrev_i32_e32 v41, 31, v40
	v_cvt_pk_bf16_f32 v32, v32, v33
	v_cvt_pk_bf16_f32 v33, v34, v35
	v_cvt_pk_bf16_f32 v34, v24, v25
	v_add_u32_e32 v24, 0xa0, v134
	v_lshl_add_u64 v[142:143], s[8:9], 0, v[142:143]
	v_lshlrev_b64 v[136:137], 1, v[136:137]
	v_lshlrev_b64 v[104:105], 11, v[104:105]
	v_ashrrev_i32_e32 v89, 31, v88
	v_cvt_pk_bf16_f32 v80, v80, v81
	v_cvt_pk_bf16_f32 v81, v82, v83
	v_cvt_pk_bf16_f32 v82, v72, v73
	v_or_b32_e32 v72, 48, v134
	v_lshl_add_u64 v[64:65], s[8:9], 0, v[64:65]
	v_lshlrev_b64 v[40:41], 11, v[40:41]
	v_ashrrev_i32_e32 v25, 31, v24
	v_cvt_pk_bf16_f32 v16, v16, v17
	v_cvt_pk_bf16_f32 v17, v18, v19
	v_cvt_pk_bf16_f32 v18, v8, v9
	v_add_u32_e32 v8, 0xb0, v134
	v_lshl_add_u64 v[142:143], v[142:143], 0, v[136:137]
	v_lshl_add_u64 v[104:105], s[8:9], 0, v[104:105]
	v_lshlrev_b64 v[88:89], 11, v[88:89]
	v_ashrrev_i32_e32 v73, 31, v72
	v_lshl_add_u64 v[64:65], v[64:65], 0, v[136:137]
	v_lshl_add_u64 v[40:41], s[8:9], 0, v[40:41]
	v_lshlrev_b64 v[24:25], 11, v[24:25]
	v_ashrrev_i32_e32 v9, 31, v8
	v_cvt_pk_bf16_f32 v115, v106, v107
	global_store_dwordx4 v[142:143], v[112:115], off offset:16
	v_lshl_add_u64 v[88:89], s[8:9], 0, v[88:89]
	v_lshlrev_b64 v[72:73], 11, v[72:73]
	v_lshl_add_u64 v[112:113], v[104:105], 0, v[136:137]
	v_cvt_pk_bf16_f32 v51, v42, v43
	global_store_dwordx4 v[64:65], v[48:51], off offset:16
	v_lshl_add_u64 v[24:25], s[8:9], 0, v[24:25]
	v_lshlrev_b64 v[8:9], 11, v[8:9]
	v_lshl_add_u64 v[48:49], v[40:41], 0, v[136:137]
	v_cvt_pk_bf16_f32 v99, v90, v91
	global_store_dwordx4 v[112:113], v[96:99], off offset:16
	v_lshl_add_u64 v[72:73], s[8:9], 0, v[72:73]
	v_cvt_pk_bf16_f32 v35, v26, v27
	global_store_dwordx4 v[48:49], v[32:35], off offset:16
	v_lshl_add_u64 v[96:97], v[88:89], 0, v[136:137]
	v_lshl_add_u64 v[8:9], s[8:9], 0, v[8:9]
	v_lshl_add_u64 v[32:33], v[24:25], 0, v[136:137]
	v_cvt_pk_bf16_f32 v83, v74, v75
	global_store_dwordx4 v[96:97], v[80:83], off offset:16
	v_cvt_pk_bf16_f32 v19, v10, v11
	global_store_dwordx4 v[32:33], v[16:19], off offset:16
	s_and_b64 vcc, exec, s[0:1]
	v_lshl_add_u64 v[80:81], v[72:73], 0, v[136:137]
	v_lshl_add_u64 v[16:17], v[8:9], 0, v[136:137]
	s_mov_b32 s15, s72
	s_mov_b32 s77, s76
	s_mov_b64 s[12:13], s[6:7]
	s_mov_b64 s[10:11], s[4:5]
	v_cvt_pk_bf16_f32 v124, v124, v125
	v_cvt_pk_bf16_f32 v125, v126, v127
	v_cvt_pk_bf16_f32 v126, v120, v121
	v_cvt_pk_bf16_f32 v127, v122, v123
	global_store_dwordx4 v[142:143], v[124:127], off
	v_cvt_pk_bf16_f32 v104, v116, v117
	v_cvt_pk_bf16_f32 v105, v118, v119
	v_cvt_pk_bf16_f32 v106, v108, v109
	v_cvt_pk_bf16_f32 v107, v110, v111
	global_store_dwordx4 v[112:113], v[104:107], off
	v_cvt_pk_bf16_f32 v88, v100, v101
	v_cvt_pk_bf16_f32 v89, v102, v103
	v_cvt_pk_bf16_f32 v90, v92, v93
	v_cvt_pk_bf16_f32 v91, v94, v95
	global_store_dwordx4 v[96:97], v[88:91], off
	v_cvt_pk_bf16_f32 v72, v84, v85
	v_cvt_pk_bf16_f32 v73, v86, v87
	v_cvt_pk_bf16_f32 v74, v76, v77
	v_cvt_pk_bf16_f32 v75, v78, v79
	global_store_dwordx4 v[80:81], v[72:75], off
	v_cvt_pk_bf16_f32 v71, v66, v67
	global_store_dwordx4 v[80:81], v[68:71], off offset:16
	v_cvt_pk_bf16_f32 v60, v60, v61
	v_cvt_pk_bf16_f32 v61, v62, v63
	v_cvt_pk_bf16_f32 v62, v56, v57
	v_cvt_pk_bf16_f32 v63, v58, v59
	global_store_dwordx4 v[64:65], v[60:63], off
	v_cvt_pk_bf16_f32 v40, v52, v53
	v_cvt_pk_bf16_f32 v41, v54, v55
	v_cvt_pk_bf16_f32 v42, v44, v45
	v_cvt_pk_bf16_f32 v43, v46, v47
	global_store_dwordx4 v[48:49], v[40:43], off
	v_cvt_pk_bf16_f32 v24, v36, v37
	v_cvt_pk_bf16_f32 v25, v38, v39
	v_cvt_pk_bf16_f32 v26, v28, v29
	v_cvt_pk_bf16_f32 v27, v30, v31
	global_store_dwordx4 v[32:33], v[24:27], off
	v_cvt_pk_bf16_f32 v8, v20, v21
	v_cvt_pk_bf16_f32 v9, v22, v23
	v_cvt_pk_bf16_f32 v10, v12, v13
	v_cvt_pk_bf16_f32 v11, v14, v15
	global_store_dwordx4 v[16:17], v[8:11], off
	v_cvt_pk_bf16_f32 v4, v4, v5
	v_cvt_pk_bf16_f32 v5, v6, v7
	v_cvt_pk_bf16_f32 v6, v0, v1
	v_cvt_pk_bf16_f32 v7, v2, v3
	global_store_dwordx4 v[16:17], v[4:7], off offset:16
	s_cbranch_vccz .LBB0_1455
	s_waitcnt vmcnt(0)
	s_cmpk_gt_u32 s23, 0xff
	s_cbranch_scc1 .LBB0_1466
	s_barrier
